# deferred unit publish (counted vmcnt in first K-iteration) + flipped blockIdx for small remainder phases
# speedup vs baseline: 1.0054x; 1.0054x over previous
_Z10fwd_kernel4Args:
	s_mov_b32 s99, 0
	s_xor_b32 s101, s2, 0xff
	s_load_dwordx8 s[20:27], s[0:1], 0xc0
	s_load_dword s33, s[0:1], 0xe0
	v_and_b32_e32 v1, 0x3ff, v0
	s_add_u32 s6, s0, 0xd8
	v_readfirstlane_b32 s10, v1
	v_mbcnt_lo_u32_b32 v2, -1, 0
	s_addc_u32 s7, s1, 0
	v_mbcnt_hi_u32_b32 v152, -1, v2
	s_and_b32 s3, s10, 0xffffffc0
	v_add_u32_e32 v153, s3, v152
	v_cmp_gt_i32_e32 vcc, 2, v153
	s_and_saveexec_b64 s[4:5], vcc
	v_lshl_add_u32 v2, v153, 2, 0
	v_add_u32_e32 v2, 0x20040, v2
	v_mov_b32_e32 v3, 0
	ds_write_b32 v2, v3
	s_or_b64 exec, exec, s[4:5]
	s_waitcnt lgkmcnt(0)
	s_barrier
	s_getreg_b32 s3, hwreg(HW_REG_XCC_ID, 0, 4)
	s_and_b32 s96, s3, 15
	v_cmp_eq_u32_e64 s[4:5], 0, v152
	s_cmp_lt_u32 s10, 64
	s_cselect_b64 s[8:9], -1, 0
	v_writelane_b32 v254, s4, 0
	s_nop 1
	v_writelane_b32 v254, s5, 1
	v_writelane_b32 v254, s8, 2
	s_and_b64 s[92:93], s[8:9], s[4:5]
	s_nop 0
	v_writelane_b32 v254, s9, 3
	s_and_saveexec_b64 s[4:5], s[92:93]
	s_cbranch_execz .LBB0_5
	s_mov_b64 s[12:13], exec
	v_mbcnt_lo_u32_b32 v2, s12, 0
	v_mbcnt_hi_u32_b32 v2, s13, v2
	v_cmp_eq_u32_e32 vcc, 0, v2
	s_and_b64 s[8:9], exec, vcc
	s_mov_b64 exec, s[8:9]
	s_cbranch_execz .LBB0_5
	s_lshl_b32 s3, s96, 8
	s_bcnt1_i32_b64 s8, s[12:13]
	v_mov_b32_e32 v2, s3
	v_mov_b32_e32 v3, s8
	global_atomic_add v2, v3, s[24:25] offset:1024

.LBB0_110:
	ds_read_b128 v[156:159], v150
	ds_read_b128 v[160:163], v150 offset:1024
	ds_read_b128 v[164:167], v150 offset:2048
	ds_read_b128 v[168:171], v150 offset:3072
	ds_read_b128 v[172:175], v151
	ds_read_b128 v[184:187], v151 offset:1024
	ds_read_b128 v[188:191], v151 offset:2048
	ds_read_b128 v[192:195], v151 offset:3072
	s_add_u32 s8, s94, 0xfffc0080
	s_addc_u32 s9, s95, -1
	s_cmp_eq_u32 s42, 12
	s_cselect_b32 s39, s7, s9
	s_cselect_b32 s38, s16, s8
	s_cselect_b32 s37, s17, s29
	s_cselect_b32 s36, s18, s28
	v_lshl_add_u64 v[146:147], s[94:95], 0, v[138:139]
	s_add_i32 m0, s15, 0xc000
	ds_read_b128 v[196:199], v154
	ds_read_b128 v[200:203], v154 offset:1024
	ds_read_b128 v[204:207], v154 offset:2048
	ds_read_b128 v[208:211], v154 offset:3072
	ds_read_b128 v[212:215], v154 offset:4096
	ds_read_b128 v[216:219], v154 offset:5120
	ds_read_b128 v[220:223], v154 offset:6144
	ds_read_b128 v[224:227], v154 offset:7168
	global_load_lds_dwordx4 v[146:147], off
	v_lshl_add_u64 v[146:147], s[94:95], 0, v[140:141]
	s_add_i32 m0, s15, 0xe000
	s_nop 0
	global_load_lds_dwordx4 v[146:147], off
	s_cmp_eq_u32 s99, 0
	s_cbranch_scc1 .Ldpw_0_0a
	s_waitcnt vmcnt(16)
	s_branch .Ldpw_0_0b
.Ldpw_0_0a:
	s_waitcnt vmcnt(8)
.Ldpw_0_0b:
	s_waitcnt lgkmcnt(0)
	s_barrier
	s_setprio 1
	s_waitcnt lgkmcnt(0)
	v_mfma_f32_16x16x32_bf16 v[124:127], v[156:159], v[196:199], v[124:127]
	v_mfma_f32_16x16x32_bf16 v[120:123], v[164:167], v[196:199], v[120:123]
	v_mfma_f32_16x16x32_bf16 v[108:111], v[156:159], v[204:207], v[108:111]
	v_mfma_f32_16x16x32_bf16 v[104:107], v[164:167], v[204:207], v[104:107]
	v_mfma_f32_16x16x32_bf16 v[92:95], v[156:159], v[212:215], v[92:95]
	v_mfma_f32_16x16x32_bf16 v[88:91], v[164:167], v[212:215], v[88:91]
	v_mfma_f32_16x16x32_bf16 v[76:79], v[156:159], v[220:223], v[76:79]
	v_mfma_f32_16x16x32_bf16 v[72:75], v[164:167], v[220:223], v[72:75]
	v_mfma_f32_16x16x32_bf16 v[124:127], v[160:163], v[200:203], v[124:127]
	v_mfma_f32_16x16x32_bf16 v[120:123], v[168:171], v[200:203], v[120:123]
	v_mfma_f32_16x16x32_bf16 v[108:111], v[160:163], v[208:211], v[108:111]
	v_mfma_f32_16x16x32_bf16 v[104:107], v[168:171], v[208:211], v[104:107]
	v_mfma_f32_16x16x32_bf16 v[92:95], v[160:163], v[216:219], v[92:95]
	v_mfma_f32_16x16x32_bf16 v[88:91], v[168:171], v[216:219], v[88:91]
	v_mfma_f32_16x16x32_bf16 v[76:79], v[160:163], v[224:227], v[76:79]
	v_mfma_f32_16x16x32_bf16 v[72:75], v[168:171], v[224:227], v[72:75]
	s_setprio 0
	s_setprio 1
	v_mfma_f32_16x16x32_bf16 v[116:119], v[172:175], v[196:199], v[116:119]
	v_mfma_f32_16x16x32_bf16 v[112:115], v[188:191], v[196:199], v[112:115]
	v_mfma_f32_16x16x32_bf16 v[100:103], v[172:175], v[204:207], v[100:103]
	v_mfma_f32_16x16x32_bf16 v[96:99], v[188:191], v[204:207], v[96:99]
	v_mfma_f32_16x16x32_bf16 v[84:87], v[172:175], v[212:215], v[84:87]
	v_mfma_f32_16x16x32_bf16 v[80:83], v[188:191], v[212:215], v[80:83]
	v_mfma_f32_16x16x32_bf16 v[68:71], v[172:175], v[220:223], v[68:71]
	v_mfma_f32_16x16x32_bf16 v[64:67], v[188:191], v[220:223], v[64:67]
	v_mfma_f32_16x16x32_bf16 v[116:119], v[184:187], v[200:203], v[116:119]
	v_mfma_f32_16x16x32_bf16 v[112:115], v[192:195], v[200:203], v[112:115]
	v_mfma_f32_16x16x32_bf16 v[100:103], v[184:187], v[208:211], v[100:103]
	v_mfma_f32_16x16x32_bf16 v[96:99], v[192:195], v[208:211], v[96:99]
	v_mfma_f32_16x16x32_bf16 v[84:87], v[184:187], v[216:219], v[84:87]
	v_mfma_f32_16x16x32_bf16 v[80:83], v[192:195], v[216:219], v[80:83]
	v_mfma_f32_16x16x32_bf16 v[68:71], v[184:187], v[224:227], v[68:71]
	v_mfma_f32_16x16x32_bf16 v[64:67], v[192:195], v[224:227], v[64:67]
	s_setprio 0
	s_barrier
	s_add_i32 s8, s74, s45
	v_lshl_add_u64 v[146:147], s[36:37], 0, v[130:131]
	s_mov_b32 m0, s8
	ds_read_b128 v[196:199], v154 offset:16384
	ds_read_b128 v[200:203], v154 offset:17408
	ds_read_b128 v[204:207], v154 offset:18432
	ds_read_b128 v[208:211], v154 offset:19456
	ds_read_b128 v[212:215], v154 offset:20480
	ds_read_b128 v[216:219], v154 offset:21504
	ds_read_b128 v[220:223], v154 offset:22528
	ds_read_b128 v[224:227], v154 offset:23552
	global_load_lds_dwordx4 v[146:147], off
	s_add_i32 m0, s8, 0x2000
	s_add_u32 s8, s36, 0x40000
	v_lshl_add_u64 v[228:229], s[36:37], 0, v[134:135]
	s_addc_u32 s9, s37, 0
	s_add_i32 s43, s75, s45
	global_load_lds_dwordx4 v[228:229], off
	v_lshl_add_u64 v[230:231], s[8:9], 0, v[130:131]
	s_mov_b32 m0, s43
	v_lshl_add_u64 v[232:233], s[38:39], 0, v[132:133]
	global_load_lds_dwordx4 v[230:231], off
	v_lshl_add_u64 v[230:231], s[8:9], 0, v[134:135]
	s_add_i32 m0, s43, 0x2000
	s_nop 0
	global_load_lds_dwordx4 v[230:231], off
	v_lshl_add_u64 v[230:231], s[38:39], 0, v[128:129]
	s_mov_b32 m0, s15
	s_nop 0
	global_load_lds_dwordx4 v[230:231], off
	s_mov_b32 m0, s48
	s_nop 0
	global_load_lds_dwordx4 v[232:233], off
	s_cmp_eq_u32 s99, 0
	s_cbranch_scc1 .Ldpw_0_1a
	s_waitcnt vmcnt(16)
	s_branch .Ldpw_0_1b

.Ldpw_0_1b:
	s_waitcnt lgkmcnt(0)
	s_barrier
	s_setprio 1
	s_waitcnt lgkmcnt(0)
	v_mfma_f32_16x16x32_bf16 v[60:63], v[156:159], v[196:199], v[60:63]
	v_mfma_f32_16x16x32_bf16 v[56:59], v[164:167], v[196:199], v[56:59]
	v_mfma_f32_16x16x32_bf16 v[44:47], v[156:159], v[204:207], v[44:47]
	v_mfma_f32_16x16x32_bf16 v[40:43], v[164:167], v[204:207], v[40:43]
	v_mfma_f32_16x16x32_bf16 v[28:31], v[156:159], v[212:215], v[28:31]
	v_mfma_f32_16x16x32_bf16 v[24:27], v[164:167], v[212:215], v[24:27]
	v_mfma_f32_16x16x32_bf16 v[12:15], v[156:159], v[220:223], v[12:15]
	v_mfma_f32_16x16x32_bf16 v[8:11], v[164:167], v[220:223], v[8:11]
	v_mfma_f32_16x16x32_bf16 v[60:63], v[160:163], v[200:203], v[60:63]
	v_mfma_f32_16x16x32_bf16 v[56:59], v[168:171], v[200:203], v[56:59]
	v_mfma_f32_16x16x32_bf16 v[44:47], v[160:163], v[208:211], v[44:47]
	v_mfma_f32_16x16x32_bf16 v[40:43], v[168:171], v[208:211], v[40:43]
	v_mfma_f32_16x16x32_bf16 v[28:31], v[160:163], v[216:219], v[28:31]
	v_mfma_f32_16x16x32_bf16 v[24:27], v[168:171], v[216:219], v[24:27]
	v_mfma_f32_16x16x32_bf16 v[12:15], v[160:163], v[224:227], v[12:15]
	v_mfma_f32_16x16x32_bf16 v[8:11], v[168:171], v[224:227], v[8:11]
	s_setprio 0
	s_setprio 1
	v_mfma_f32_16x16x32_bf16 v[52:55], v[172:175], v[196:199], v[52:55]
	v_mfma_f32_16x16x32_bf16 v[48:51], v[188:191], v[196:199], v[48:51]
	v_mfma_f32_16x16x32_bf16 v[36:39], v[172:175], v[204:207], v[36:39]
	v_mfma_f32_16x16x32_bf16 v[32:35], v[188:191], v[204:207], v[32:35]
	v_mfma_f32_16x16x32_bf16 v[20:23], v[172:175], v[212:215], v[20:23]
	v_mfma_f32_16x16x32_bf16 v[16:19], v[188:191], v[212:215], v[16:19]
	v_mfma_f32_16x16x32_bf16 v[4:7], v[172:175], v[220:223], v[4:7]
	v_mfma_f32_16x16x32_bf16 v[0:3], v[188:191], v[220:223], v[0:3]
	v_mfma_f32_16x16x32_bf16 v[52:55], v[184:187], v[200:203], v[52:55]
	v_mfma_f32_16x16x32_bf16 v[48:51], v[192:195], v[200:203], v[48:51]
	v_mfma_f32_16x16x32_bf16 v[36:39], v[184:187], v[208:211], v[36:39]
	v_mfma_f32_16x16x32_bf16 v[32:35], v[192:195], v[208:211], v[32:35]
	v_mfma_f32_16x16x32_bf16 v[20:23], v[184:187], v[216:219], v[20:23]
	v_mfma_f32_16x16x32_bf16 v[16:19], v[192:195], v[216:219], v[16:19]
	v_mfma_f32_16x16x32_bf16 v[4:7], v[184:187], v[224:227], v[4:7]
	v_mfma_f32_16x16x32_bf16 v[0:3], v[192:195], v[224:227], v[0:3]
	s_setprio 0
	s_barrier
	s_add_i32 s43, 0, 0x18000
	v_add_u32_e32 v155, s43, v149
	s_add_i32 s77, 0, 0x1c000
	ds_read_b128 v[156:159], v155
	ds_read_b128 v[160:163], v155 offset:1024
	ds_read_b128 v[164:167], v155 offset:2048
	ds_read_b128 v[168:171], v155 offset:3072
	v_add_u32_e32 v155, s77, v149
	ds_read_b128 v[172:175], v155
	ds_read_b128 v[184:187], v155 offset:1024
	ds_read_b128 v[188:191], v155 offset:2048
	ds_read_b128 v[192:195], v155 offset:3072
	s_add_u32 s8, s38, 0x40000
	s_addc_u32 s9, s39, 0
	s_mov_b32 m0, s49
	v_lshl_add_u64 v[234:235], s[8:9], 0, v[128:129]
	ds_read_b128 v[196:199], v154 offset:32768
	ds_read_b128 v[200:203], v154 offset:33792
	ds_read_b128 v[204:207], v154 offset:34816
	ds_read_b128 v[208:211], v154 offset:35840
	ds_read_b128 v[212:215], v154 offset:36864
	ds_read_b128 v[216:219], v154 offset:37888
	ds_read_b128 v[220:223], v154 offset:38912
	ds_read_b128 v[224:227], v154 offset:39936
	global_load_lds_dwordx4 v[234:235], off
	v_lshl_add_u64 v[234:235], s[8:9], 0, v[132:133]
	s_mov_b32 m0, s68
	s_nop 0
	global_load_lds_dwordx4 v[234:235], off
	s_waitcnt vmcnt(8)
	s_cmp_eq_u32 s99, 0
	s_cbranch_scc1 .Ldp_0_l
	v_readlane_b32 s100, v0, 0
	s_mov_b64 exec, 1
	v_writelane_b32 v0, 1, 0
	s_nop 1
	global_atomic_add v0, v0, s[98:99]
	s_nop 1
	v_writelane_b32 v0, s100, 0
	s_mov_b64 exec, -1
	s_mov_b32 s99, 0
.Ldp_0_l:
	s_waitcnt lgkmcnt(0)
	s_barrier
	s_setprio 1
	s_waitcnt lgkmcnt(0)
	v_mfma_f32_16x16x32_bf16 v[124:127], v[156:159], v[196:199], v[124:127]
	v_mfma_f32_16x16x32_bf16 v[120:123], v[164:167], v[196:199], v[120:123]
	v_mfma_f32_16x16x32_bf16 v[108:111], v[156:159], v[204:207], v[108:111]
	v_mfma_f32_16x16x32_bf16 v[104:107], v[164:167], v[204:207], v[104:107]
	v_mfma_f32_16x16x32_bf16 v[92:95], v[156:159], v[212:215], v[92:95]
	v_mfma_f32_16x16x32_bf16 v[88:91], v[164:167], v[212:215], v[88:91]
	v_mfma_f32_16x16x32_bf16 v[76:79], v[156:159], v[220:223], v[76:79]
	v_mfma_f32_16x16x32_bf16 v[72:75], v[164:167], v[220:223], v[72:75]
	v_mfma_f32_16x16x32_bf16 v[124:127], v[160:163], v[200:203], v[124:127]
	v_mfma_f32_16x16x32_bf16 v[120:123], v[168:171], v[200:203], v[120:123]
	v_mfma_f32_16x16x32_bf16 v[108:111], v[160:163], v[208:211], v[108:111]
	v_mfma_f32_16x16x32_bf16 v[104:107], v[168:171], v[208:211], v[104:107]
	v_mfma_f32_16x16x32_bf16 v[92:95], v[160:163], v[216:219], v[92:95]
	v_mfma_f32_16x16x32_bf16 v[88:91], v[168:171], v[216:219], v[88:91]
	v_mfma_f32_16x16x32_bf16 v[76:79], v[160:163], v[224:227], v[76:79]
	v_mfma_f32_16x16x32_bf16 v[72:75], v[168:171], v[224:227], v[72:75]
	s_setprio 0
	s_setprio 1
	v_mfma_f32_16x16x32_bf16 v[116:119], v[172:175], v[196:199], v[116:119]
	v_mfma_f32_16x16x32_bf16 v[112:115], v[188:191], v[196:199], v[112:115]
	v_mfma_f32_16x16x32_bf16 v[100:103], v[172:175], v[204:207], v[100:103]
	v_mfma_f32_16x16x32_bf16 v[96:99], v[188:191], v[204:207], v[96:99]
	v_mfma_f32_16x16x32_bf16 v[84:87], v[172:175], v[212:215], v[84:87]
	v_mfma_f32_16x16x32_bf16 v[80:83], v[188:191], v[212:215], v[80:83]
	v_mfma_f32_16x16x32_bf16 v[68:71], v[172:175], v[220:223], v[68:71]
	v_mfma_f32_16x16x32_bf16 v[64:67], v[188:191], v[220:223], v[64:67]
	v_mfma_f32_16x16x32_bf16 v[116:119], v[184:187], v[200:203], v[116:119]
	v_mfma_f32_16x16x32_bf16 v[112:115], v[192:195], v[200:203], v[112:115]
	v_mfma_f32_16x16x32_bf16 v[100:103], v[184:187], v[208:211], v[100:103]
	v_mfma_f32_16x16x32_bf16 v[96:99], v[192:195], v[208:211], v[96:99]
	v_mfma_f32_16x16x32_bf16 v[84:87], v[184:187], v[216:219], v[84:87]
	v_mfma_f32_16x16x32_bf16 v[80:83], v[192:195], v[216:219], v[80:83]
	v_mfma_f32_16x16x32_bf16 v[68:71], v[184:187], v[224:227], v[68:71]
	v_mfma_f32_16x16x32_bf16 v[64:67], v[192:195], v[224:227], v[64:67]
	s_setprio 0
	s_barrier
	s_add_i32 s8, s43, s45
	v_lshl_add_u64 v[146:147], v[146:147], 0, s[46:47]
	s_mov_b32 m0, s8
	ds_read_b128 v[196:199], v154 offset:49152
	ds_read_b128 v[200:203], v154 offset:50176
	ds_read_b128 v[204:207], v154 offset:51200
	ds_read_b128 v[208:211], v154 offset:52224
	ds_read_b128 v[212:215], v154 offset:53248
	ds_read_b128 v[216:219], v154 offset:54272
	ds_read_b128 v[220:223], v154 offset:55296
	ds_read_b128 v[224:227], v154 offset:56320
	global_load_lds_dwordx4 v[146:147], off
	s_add_i32 m0, s8, 0x2000
	s_add_u32 s8, s36, 0x40080
	v_lshl_add_u64 v[146:147], v[228:229], 0, s[46:47]
	s_addc_u32 s9, s37, 0
	s_add_i32 s36, s77, s45
	global_load_lds_dwordx4 v[146:147], off
	v_lshl_add_u64 v[146:147], s[8:9], 0, v[130:131]
	s_mov_b32 m0, s36
	s_nop 0
	global_load_lds_dwordx4 v[146:147], off
	v_lshl_add_u64 v[146:147], s[8:9], 0, v[134:135]
	s_add_i32 m0, s36, 0x2000
	s_nop 0
	global_load_lds_dwordx4 v[146:147], off
	v_lshl_add_u64 v[146:147], v[230:231], 0, s[46:47]
	s_mov_b32 m0, s69
	s_nop 0
	global_load_lds_dwordx4 v[146:147], off
	v_lshl_add_u64 v[146:147], v[232:233], 0, s[46:47]
	s_mov_b32 m0, s70
	s_nop 0
	global_load_lds_dwordx4 v[146:147], off
	s_waitcnt vmcnt(8)
	s_waitcnt lgkmcnt(0)
	s_barrier
	s_setprio 1
	s_waitcnt lgkmcnt(0)
	v_mfma_f32_16x16x32_bf16 v[60:63], v[156:159], v[196:199], v[60:63]
	v_mfma_f32_16x16x32_bf16 v[56:59], v[164:167], v[196:199], v[56:59]
	v_mfma_f32_16x16x32_bf16 v[44:47], v[156:159], v[204:207], v[44:47]
	v_mfma_f32_16x16x32_bf16 v[40:43], v[164:167], v[204:207], v[40:43]
	v_mfma_f32_16x16x32_bf16 v[28:31], v[156:159], v[212:215], v[28:31]
	v_mfma_f32_16x16x32_bf16 v[24:27], v[164:167], v[212:215], v[24:27]
	v_mfma_f32_16x16x32_bf16 v[12:15], v[156:159], v[220:223], v[12:15]
	v_mfma_f32_16x16x32_bf16 v[8:11], v[164:167], v[220:223], v[8:11]
	v_mfma_f32_16x16x32_bf16 v[60:63], v[160:163], v[200:203], v[60:63]
	v_mfma_f32_16x16x32_bf16 v[56:59], v[168:171], v[200:203], v[56:59]
	v_mfma_f32_16x16x32_bf16 v[44:47], v[160:163], v[208:211], v[44:47]
	v_mfma_f32_16x16x32_bf16 v[40:43], v[168:171], v[208:211], v[40:43]
	v_mfma_f32_16x16x32_bf16 v[28:31], v[160:163], v[216:219], v[28:31]
	v_mfma_f32_16x16x32_bf16 v[24:27], v[168:171], v[216:219], v[24:27]
	v_mfma_f32_16x16x32_bf16 v[12:15], v[160:163], v[224:227], v[12:15]
	v_mfma_f32_16x16x32_bf16 v[8:11], v[168:171], v[224:227], v[8:11]
	s_setprio 0
	s_setprio 1
	v_mfma_f32_16x16x32_bf16 v[52:55], v[172:175], v[196:199], v[52:55]
	v_mfma_f32_16x16x32_bf16 v[48:51], v[188:191], v[196:199], v[48:51]
	v_mfma_f32_16x16x32_bf16 v[36:39], v[172:175], v[204:207], v[36:39]
	v_mfma_f32_16x16x32_bf16 v[32:35], v[188:191], v[204:207], v[32:35]
	v_mfma_f32_16x16x32_bf16 v[20:23], v[172:175], v[212:215], v[20:23]
	v_mfma_f32_16x16x32_bf16 v[16:19], v[188:191], v[212:215], v[16:19]
	v_mfma_f32_16x16x32_bf16 v[4:7], v[172:175], v[220:223], v[4:7]
	v_mfma_f32_16x16x32_bf16 v[0:3], v[188:191], v[220:223], v[0:3]
	v_mfma_f32_16x16x32_bf16 v[52:55], v[184:187], v[200:203], v[52:55]
	v_mfma_f32_16x16x32_bf16 v[48:51], v[192:195], v[200:203], v[48:51]
	v_mfma_f32_16x16x32_bf16 v[36:39], v[184:187], v[208:211], v[36:39]
	v_mfma_f32_16x16x32_bf16 v[32:35], v[192:195], v[208:211], v[32:35]
	v_mfma_f32_16x16x32_bf16 v[20:23], v[184:187], v[216:219], v[20:23]
	v_mfma_f32_16x16x32_bf16 v[16:19], v[192:195], v[216:219], v[16:19]
	v_mfma_f32_16x16x32_bf16 v[4:7], v[184:187], v[224:227], v[4:7]
	v_mfma_f32_16x16x32_bf16 v[0:3], v[192:195], v[224:227], v[0:3]
	s_setprio 0
	s_barrier
	s_add_i32 s42, s42, 2
	s_add_u32 s94, s94, 0x100
	s_addc_u32 s95, s95, 0
	s_add_u32 s28, s28, 0x100
	s_addc_u32 s29, s29, 0
	s_cmp_gt_u32 s42, 13
	s_cbranch_scc0 .LBB0_110
	s_and_b64 vcc, exec, s[50:51]
	s_cbranch_vccz .LBB0_113
	s_barrier

.LBB0_145:
	s_mov_b64 s[6:7], 0x58100
	v_cvt_pk_bf16_f32 v4, v4, v5
	v_cvt_pk_bf16_f32 v5, v6, v7
	v_cvt_pk_bf16_f32 v6, v0, v1
	v_cvt_pk_bf16_f32 v7, v2, v3
	v_lshl_add_u64 v[0:1], v[146:147], 0, s[6:7]
	global_store_dwordx4 v[0:1], v[4:7], off sc0 sc1
	s_nop 1
	s_nop 0
	s_mov_b64 s[6:7], exec
	v_readlane_b32 s8, v254, 0
	v_readlane_b32 s9, v254, 1
	s_and_b64 s[8:9], s[6:7], s[8:9]
	s_mov_b64 exec, s[8:9]
	s_cbranch_execz .LBB0_148
	s_mov_b64 s[36:37], exec
	v_mbcnt_lo_u32_b32 v0, s36, 0
	v_mbcnt_hi_u32_b32 v0, s37, v0
	v_cmp_eq_u32_e32 vcc, 0, v0
	s_and_b64 s[8:9], exec, vcc
	s_mov_b64 exec, s[8:9]
	s_cbranch_execz .LBB0_148
	s_lshl_b32 s8, s14, 6
	s_ashr_i32 s9, s8, 31
	s_lshl_b64 s[8:9], s[8:9], 2
	s_add_u32 s8, s12, s8
	s_addc_u32 s9, s13, s9
	s_bcnt1_i32_b64 s14, s[36:37]
	v_mov_b32_e32 v0, s14
	s_sub_u32 s98, s8, 1
	s_subb_u32 s99, s9, 0

.LBB0_151:
	s_waitcnt vmcnt(0)
	s_cmp_eq_u32 s99, 0
	s_cbranch_scc1 .Ldp_0_x
	v_readlane_b32 s100, v0, 0
	s_mov_b64 exec, 1
	v_writelane_b32 v0, 1, 0
	s_nop 1
	global_atomic_add v0, v0, s[98:99]
	s_nop 1
	v_writelane_b32 v0, s100, 0
	s_mov_b64 exec, -1
	s_mov_b32 s99, 0
.Ldp_0_x:
	s_mov_b32 s91, s10
	s_mov_b64 s[92:93], s[78:79]
	s_barrier

.LBB0_449:
	s_or_b64 exec, exec, s[0:1]
	s_add_u32 s20, s24, 0x5a00000
	s_addc_u32 s21, s25, 0
	s_add_u32 s10, s24, 0xc000
	v_mov_b32_e32 v8, v153
	s_waitcnt lgkmcnt(0)
	s_barrier
	s_addc_u32 s11, s25, 0
	s_and_b64 vcc, exec, s[4:5]
	v_readfirstlane_b32 s4, v8
	s_cbranch_vccnz .LBB0_468
	v_lshlrev_b32_e32 v0, 4, v8
	v_add_u32_e32 v1, 0x2000, v0
	v_ashrrev_i32_e32 v2, 31, v1
	v_lshrrev_b32_e32 v2, 22, v2
	v_add_u32_e32 v2, v1, v2
	v_ashrrev_i32_e32 v2, 10, v2
	v_mul_i32_i24_e32 v3, 0x400, v2
	v_sub_u32_e32 v1, v1, v3
	v_lshrrev_b32_e32 v3, 4, v1
	v_bitop3_b32 v1, v3, v1, 32 bitop3:0x6c
	v_ashrrev_i32_e32 v3, 31, v1
	v_lshrrev_b32_e32 v3, 26, v3
	v_add_u32_e32 v3, v1, v3
	v_lshlrev_b32_e32 v5, 3, v2
	v_ashrrev_i32_e32 v4, 6, v3
	v_and_b32_e32 v5, -16, v5
	v_and_b32_e32 v3, 0xc0, v3
	v_add_u32_e32 v5, v4, v5
	v_sub_u32_e32 v1, v1, v3
	v_mov_b32_e32 v3, 1
	v_and_b32_e32 v4, 3, v4
	s_mov_b32 s0, 0x7fffe0
	v_lshrrev_b32_e32 v6, 2, v5
	v_lshlrev_b32_e32 v7, 1, v5
	v_lshlrev_b32_e32 v2, 5, v2
	v_ashrrev_i16_sdwa v1, v3, sext(v1) dst_sel:DWORD dst_unused:UNUSED_PAD src0_sel:DWORD src1_sel:BYTE_0
	v_and_or_b32 v4, v5, s0, v4
	v_and_b32_e32 v6, 4, v6
	v_and_b32_e32 v7, 24, v7
	v_and_b32_e32 v2, 32, v2
	v_bfe_i32 v1, v1, 0, 16
	v_or3_b32 v4, v4, v6, v7
	v_add_lshl_u32 v1, v2, v1, 1
	v_lshl_add_u32 v154, v4, 9, v1
	v_lshl_add_u32 v156, v5, 11, v1
	v_bfe_i32 v1, v8, 27, 1
	v_lshrrev_b32_e32 v1, 22, v1
	v_add_u32_e32 v1, v0, v1
	v_and_b32_e32 v1, 0xfffffc00, v1
	v_sub_u32_e32 v0, v0, v1
	v_lshrrev_b32_e32 v1, 4, v0
	v_ashrrev_i32_e32 v4, 31, v8
	v_bitop3_b32 v0, v1, v0, 32 bitop3:0x6c
	v_lshrrev_b32_e32 v4, 26, v4
	v_ashrrev_i32_e32 v1, 31, v0
	v_add_u32_e32 v4, v8, v4
	v_lshrrev_b32_e32 v1, 26, v1
	v_ashrrev_i32_e32 v4, 6, v4
	v_add_u32_e32 v1, v0, v1
	v_lshlrev_b32_e32 v5, 3, v4
	s_add_u32 s3, s24, 0x500000
	v_ashrrev_i32_e32 v2, 6, v1
	v_and_b32_e32 v5, -16, v5
	s_addc_u32 s27, s25, 0
	v_add_u32_e32 v5, v2, v5
	v_and_b32_e32 v2, 3, v2
	s_ashr_i32 s40, s101, 31
	v_and_or_b32 v2, v5, s0, v2
	s_lshr_b32 s0, s40, 29
	s_add_i32 s0, s101, s0
	s_ashr_i32 s8, s4, 6
	s_ashr_i32 s1, s0, 3
	s_and_b32 s0, s0, -8
	s_ashr_i32 s5, s4, 8
	s_lshl_b32 s33, s8, 10
	s_sub_i32 s0, s101, s0
	s_cmp_lt_i32 s0, 0
	s_movk_i32 s6, 0x44
	s_cselect_b32 s9, s6, 0x43
	s_mul_i32 s0, s0, s9
	s_add_i32 s1, s0, s1
	s_ashr_i32 s0, s1, 31
	s_lshr_b32 s0, s0, 29
	s_add_i32 s9, s1, s0
	s_ashr_i32 s0, s9, 3
	s_and_b32 s9, s9, -8
	s_sub_i32 s78, s1, s9
	v_and_b32_e32 v1, 0xc0, v1
	s_ashr_i32 s16, s78, 1
	v_sub_u32_e32 v0, v0, v1
	s_ashr_i32 s1, s0, 31
	s_ashr_i32 s17, s16, 31
	s_ashr_i32 s79, s78, 31
	v_lshrrev_b32_e32 v6, 2, v5
	v_lshlrev_b32_e32 v7, 1, v5
	v_lshlrev_b32_e32 v4, 5, v4
	v_ashrrev_i16_sdwa v0, v3, sext(v0) dst_sel:DWORD dst_unused:UNUSED_PAD src0_sel:DWORD src1_sel:BYTE_0
	s_lshl_b64 s[14:15], s[0:1], 19
	s_lshl_b64 s[16:17], s[16:17], 9
	s_lshl_b64 s[18:19], s[78:79], 17
	v_and_b32_e32 v6, 4, v6
	v_and_b32_e32 v7, 24, v7
	v_and_b32_e32 v4, 32, v4
	v_bfe_i32 v0, v0, 0, 16
	s_add_u32 s80, s3, s18
	v_or3_b32 v2, v2, v6, v7
	v_add_lshl_u32 v0, v4, v0, 1
	s_addc_u32 s81, s27, s19
	s_add_i32 s41, s33, 0
	v_lshl_add_u32 v158, v2, 9, v0
	s_add_i32 m0, s41, 0x10000
	v_lshl_add_u32 v160, v5, 11, v0
	global_load_lds_dwordx4 v158, s[80:81]
	s_add_i32 m0, s41, 0x12000
	s_add_u32 s1, s30, s14
	s_addc_u32 s9, s31, s15
	s_add_u32 s14, s80, 0x10000
	global_load_lds_dwordx4 v154, s[80:81]
	s_addc_u32 s15, s81, 0
	s_add_i32 m0, s41, 0x14000
	v_writelane_b32 v254, s10, 51
	global_load_lds_dwordx4 v158, s[14:15]
	s_add_i32 m0, s41, 0x16000
	s_add_u32 s82, s1, s16
	s_addc_u32 s83, s9, s17
	s_add_i32 s77, s41, 0x2000
	global_load_lds_dwordx4 v154, s[14:15]
	s_mov_b32 m0, s41
	s_add_u32 s14, s82, 0x40000
	global_load_lds_dwordx4 v160, s[82:83]
	s_mov_b32 m0, s77
	s_addc_u32 s15, s83, 0
	s_add_i32 s79, s41, 0x4000
	global_load_lds_dwordx4 v156, s[82:83]
	s_mov_b32 m0, s79
	s_add_i32 s86, s41, 0x6000
	global_load_lds_dwordx4 v160, s[14:15]
	s_mov_b32 m0, s86
	v_writelane_b32 v254, s11, 52
	global_load_lds_dwordx4 v156, s[14:15]
	v_writelane_b32 v254, s94, 53
	s_cmp_eq_u32 s5, 1
	v_mov_b32_e32 v159, 0
	v_writelane_b32 v254, s95, 54
	v_writelane_b32 v254, s92, 55
	s_cselect_b64 s[6:7], -1, 0
	v_mov_b32_e32 v155, v159
	v_writelane_b32 v254, s93, 56
	v_writelane_b32 v254, s91, 57
	v_mov_b32_e32 v161, v159
	v_mov_b32_e32 v157, v159
	v_writelane_b32 v254, s6, 58
	s_mov_b32 s87, 0
	v_lshl_add_u64 v[4:5], s[80:81], 0, v[158:159]
	v_lshl_add_u64 v[2:3], s[80:81], 0, v[154:155]
	v_lshl_add_u64 v[0:1], s[82:83], 0, v[160:161]
	v_writelane_b32 v254, s7, 59
	s_cmp_lg_u32 s5, 1
	v_lshl_add_u64 v[6:7], s[82:83], 0, v[156:157]
	s_cbranch_scc1 .LBB0_452
	s_barrier

.LBB0_455:
	s_add_i32 s87, s87, 1
	s_mul_i32 s1, s87, s90
	s_mul_hi_u32 s4, s87, s26
	s_add_i32 s4, s4, s1
	s_mul_i32 s1, s87, s26
	s_add_u32 s36, s1, s101
	s_addc_u32 s37, s4, s40
	v_cmp_gt_i64_e32 vcc, s[36:37], v[164:165]
	v_cmp_lt_i64_e64 s[44:45], s[36:37], v[162:163]
	s_cbranch_vccnz .LBB0_457
	s_ashr_i32 s1, s36, 31
	s_lshr_b32 s1, s1, 29
	s_add_i32 s1, s36, s1
	s_ashr_i32 s8, s1, 3
	s_and_b32 s1, s1, -8
	s_sub_i32 s1, s36, s1
	s_cmp_lt_i32 s1, 0
	s_movk_i32 s4, 0x44
	s_cselect_b32 s9, s4, 0x43
	s_mul_i32 s1, s1, s9
	s_add_i32 s1, s1, s8
	s_ashr_i32 s8, s1, 31
	s_lshr_b32 s8, s8, 29
	s_add_i32 s8, s1, s8
	s_ashr_i32 s9, s8, 3
	s_sub_i32 s16, 0x43, s9
	s_min_i32 s16, s16, 1
	s_abs_i32 s17, s16
	v_cvt_f32_u32_e32 v0, s17
	s_sub_i32 s19, 0, s17
	s_and_b32 s8, s8, -8
	s_sub_i32 s1, s1, s8
	v_rcp_iflag_f32_e32 v0, v0
	s_abs_i32 s8, s1
	s_xor_b32 s18, s1, s16
	s_ashr_i32 s18, s18, 31
	v_mul_f32_e32 v0, 0x4f7ffffe, v0
	v_cvt_u32_f32_e32 v0, v0
	s_nop 0
	v_readfirstlane_b32 s28, v0
	s_mul_i32 s19, s19, s28
	s_mul_hi_u32 s19, s28, s19
	s_add_i32 s28, s28, s19
	s_mul_hi_u32 s19, s8, s28
	s_mul_i32 s28, s19, s17
	s_sub_i32 s8, s8, s28
	s_add_i32 s29, s19, 1
	s_sub_i32 s28, s8, s17
	s_cmp_ge_u32 s8, s17
	s_cselect_b32 s19, s29, s19
	s_cselect_b32 s8, s28, s8
	s_add_i32 s28, s19, 1
	s_cmp_ge_u32 s8, s17
	s_cselect_b32 s8, s28, s19
	s_xor_b32 s8, s8, s18
	s_sub_i32 s46, s8, s18
	s_mul_i32 s8, s46, s16
	s_sub_i32 s1, s1, s8
	s_add_i32 s56, s9, s1

.LBB0_458:
	s_add_u32 s19, s82, s18
	s_addc_u32 s29, s83, 0
	s_add_u32 s38, s19, 0x100
	s_addc_u32 s39, s29, 0
	s_and_b64 s[8:9], s[36:37], exec
	s_cselect_b32 s49, s1, s39
	s_cselect_b32 s48, s16, s38
	s_add_u32 s8, s80, s18
	s_addc_u32 s9, s81, 0
	s_add_u32 s18, s8, 0x100
	s_addc_u32 s38, s9, 0
	s_and_b64 s[8:9], s[36:37], exec
	s_cselect_b32 s51, s17, s38
	s_cselect_b32 s50, s28, s18
	s_add_u32 s70, s19, 0x40080
	s_addc_u32 s71, s29, 0
	s_add_i32 vcc_hi, s91, s33
	ds_read_b128 v[28:31], v173
	ds_read_b128 v[32:35], v173 offset:1024
	ds_read_b128 v[40:43], v173 offset:2048
	ds_read_b128 v[44:47], v173 offset:3072
	ds_read_b128 v[144:147], v174
	ds_read_b128 v[148:151], v174 offset:1024
	ds_read_b128 v[166:169], v174 offset:2048
	ds_read_b128 v[188:191], v174 offset:3072
	s_add_i32 m0, s41, 0xc000
	s_add_i32 s76, s41, 0xe000
	s_add_i32 s97, vcc_hi, 0x2000
	s_add_u32 s68, s50, 0x10000
	s_addc_u32 s69, s51, 0
	s_add_i32 s9, s92, s33
	s_add_i32 s8, s9, 0x2000
	s_add_i32 vcc_lo, 0, 0x18000
	s_add_i32 s57, 0, 0x1c000
	s_add_u32 s38, s48, 0x40000
	s_addc_u32 s39, s49, 0
	s_add_i32 s47, vcc_lo, s33
	s_add_i32 s19, s47, 0x2000
	s_add_u32 s36, s50, 0x10080
	s_addc_u32 s37, s51, 0
	s_add_i32 s29, s57, s33
	s_add_i32 s18, s29, 0x2000
	v_lshl_add_u64 v[224:225], s[70:71], 0, v[160:161]
	ds_read_b128 v[192:195], v175
	ds_read_b128 v[196:199], v175 offset:1024
	ds_read_b128 v[200:203], v175 offset:2048
	ds_read_b128 v[204:207], v175 offset:3072
	ds_read_b128 v[208:211], v175 offset:4096
	ds_read_b128 v[212:215], v175 offset:5120
	ds_read_b128 v[216:219], v175 offset:6144
	ds_read_b128 v[220:223], v175 offset:7168
	global_load_lds_dwordx4 v[224:225], off
	v_lshl_add_u64 v[224:225], s[70:71], 0, v[156:157]
	s_mov_b32 m0, s76
	s_nop 0
	global_load_lds_dwordx4 v[224:225], off
	s_cmp_eq_u32 s99, 0
	s_cbranch_scc1 .Ldpw_1_0a
	s_waitcnt vmcnt(16)
	s_branch .Ldpw_1_0b

.Ldpw_1_0b:
	s_waitcnt lgkmcnt(0)
	s_barrier
	s_setprio 1
	s_waitcnt lgkmcnt(0)
	v_mfma_f32_16x16x32_bf16 v[140:143], v[28:31], v[192:195], v[140:143]
	v_mfma_f32_16x16x32_bf16 v[132:135], v[40:43], v[192:195], v[132:135]
	v_mfma_f32_16x16x32_bf16 v[124:127], v[28:31], v[200:203], v[124:127]
	v_mfma_f32_16x16x32_bf16 v[116:119], v[40:43], v[200:203], v[116:119]
	v_mfma_f32_16x16x32_bf16 v[108:111], v[28:31], v[208:211], v[108:111]
	v_mfma_f32_16x16x32_bf16 v[100:103], v[40:43], v[208:211], v[100:103]
	v_mfma_f32_16x16x32_bf16 v[92:95], v[28:31], v[216:219], v[92:95]
	v_mfma_f32_16x16x32_bf16 v[84:87], v[40:43], v[216:219], v[84:87]
	v_mfma_f32_16x16x32_bf16 v[140:143], v[32:35], v[196:199], v[140:143]
	v_mfma_f32_16x16x32_bf16 v[132:135], v[44:47], v[196:199], v[132:135]
	v_mfma_f32_16x16x32_bf16 v[124:127], v[32:35], v[204:207], v[124:127]
	v_mfma_f32_16x16x32_bf16 v[116:119], v[44:47], v[204:207], v[116:119]
	v_mfma_f32_16x16x32_bf16 v[108:111], v[32:35], v[212:215], v[108:111]
	v_mfma_f32_16x16x32_bf16 v[100:103], v[44:47], v[212:215], v[100:103]
	v_mfma_f32_16x16x32_bf16 v[92:95], v[32:35], v[220:223], v[92:95]
	v_mfma_f32_16x16x32_bf16 v[84:87], v[44:47], v[220:223], v[84:87]
	s_setprio 0
	s_setprio 1
	v_mfma_f32_16x16x32_bf16 v[136:139], v[144:147], v[192:195], v[136:139]
	v_mfma_f32_16x16x32_bf16 v[128:131], v[166:169], v[192:195], v[128:131]
	v_mfma_f32_16x16x32_bf16 v[120:123], v[144:147], v[200:203], v[120:123]
	v_mfma_f32_16x16x32_bf16 v[112:115], v[166:169], v[200:203], v[112:115]
	v_mfma_f32_16x16x32_bf16 v[104:107], v[144:147], v[208:211], v[104:107]
	v_mfma_f32_16x16x32_bf16 v[96:99], v[166:169], v[208:211], v[96:99]
	v_mfma_f32_16x16x32_bf16 v[88:91], v[144:147], v[216:219], v[88:91]
	v_mfma_f32_16x16x32_bf16 v[80:83], v[166:169], v[216:219], v[80:83]
	v_mfma_f32_16x16x32_bf16 v[136:139], v[148:151], v[196:199], v[136:139]
	v_mfma_f32_16x16x32_bf16 v[128:131], v[188:191], v[196:199], v[128:131]
	v_mfma_f32_16x16x32_bf16 v[120:123], v[148:151], v[204:207], v[120:123]
	v_mfma_f32_16x16x32_bf16 v[112:115], v[188:191], v[204:207], v[112:115]
	v_mfma_f32_16x16x32_bf16 v[104:107], v[148:151], v[212:215], v[104:107]
	v_mfma_f32_16x16x32_bf16 v[96:99], v[188:191], v[212:215], v[96:99]
	v_mfma_f32_16x16x32_bf16 v[88:91], v[148:151], v[220:223], v[88:91]
	v_mfma_f32_16x16x32_bf16 v[80:83], v[188:191], v[220:223], v[80:83]
	s_setprio 0
	s_barrier
	s_mov_b32 m0, vcc_hi
	v_lshl_add_u64 v[224:225], s[50:51], 0, v[158:159]
	ds_read_b128 v[192:195], v175 offset:16384
	ds_read_b128 v[196:199], v175 offset:17408
	ds_read_b128 v[200:203], v175 offset:18432
	ds_read_b128 v[204:207], v175 offset:19456
	ds_read_b128 v[208:211], v175 offset:20480
	ds_read_b128 v[212:215], v175 offset:21504
	ds_read_b128 v[216:219], v175 offset:22528
	ds_read_b128 v[220:223], v175 offset:23552
	global_load_lds_dwordx4 v[224:225], off
	v_lshl_add_u64 v[226:227], s[50:51], 0, v[154:155]
	s_mov_b32 m0, s97
	v_lshl_add_u64 v[228:229], s[68:69], 0, v[158:159]
	global_load_lds_dwordx4 v[226:227], off
	s_mov_b32 m0, s9
	v_lshl_add_u64 v[230:231], s[48:49], 0, v[156:157]
	global_load_lds_dwordx4 v[228:229], off
	v_lshl_add_u64 v[228:229], s[68:69], 0, v[154:155]
	s_mov_b32 m0, s8
	s_nop 0
	global_load_lds_dwordx4 v[228:229], off
	v_lshl_add_u64 v[228:229], s[48:49], 0, v[160:161]
	s_mov_b32 m0, s41
	s_nop 0
	global_load_lds_dwordx4 v[228:229], off
	s_mov_b32 m0, s77
	s_nop 0
	global_load_lds_dwordx4 v[230:231], off
	s_cmp_eq_u32 s99, 0
	s_cbranch_scc1 .Ldpw_1_1a
	s_waitcnt vmcnt(16)
	s_branch .Ldpw_1_1b

.Ldpw_1_1b:
	s_waitcnt lgkmcnt(0)
	s_barrier
	s_setprio 1
	s_waitcnt lgkmcnt(0)
	v_mfma_f32_16x16x32_bf16 v[76:79], v[28:31], v[192:195], v[76:79]
	v_mfma_f32_16x16x32_bf16 v[68:71], v[40:43], v[192:195], v[68:71]
	v_mfma_f32_16x16x32_bf16 v[60:63], v[28:31], v[200:203], v[60:63]
	v_mfma_f32_16x16x32_bf16 v[52:55], v[40:43], v[200:203], v[52:55]
	v_mfma_f32_16x16x32_bf16 v[36:39], v[28:31], v[208:211], v[36:39]
	v_mfma_f32_16x16x32_bf16 v[20:23], v[40:43], v[208:211], v[20:23]
	v_mfma_f32_16x16x32_bf16 v[12:15], v[28:31], v[216:219], v[12:15]
	v_mfma_f32_16x16x32_bf16 v[4:7], v[40:43], v[216:219], v[4:7]
	v_mfma_f32_16x16x32_bf16 v[76:79], v[32:35], v[196:199], v[76:79]
	v_mfma_f32_16x16x32_bf16 v[68:71], v[44:47], v[196:199], v[68:71]
	v_mfma_f32_16x16x32_bf16 v[60:63], v[32:35], v[204:207], v[60:63]
	v_mfma_f32_16x16x32_bf16 v[52:55], v[44:47], v[204:207], v[52:55]
	v_mfma_f32_16x16x32_bf16 v[36:39], v[32:35], v[212:215], v[36:39]
	v_mfma_f32_16x16x32_bf16 v[20:23], v[44:47], v[212:215], v[20:23]
	v_mfma_f32_16x16x32_bf16 v[12:15], v[32:35], v[220:223], v[12:15]
	v_mfma_f32_16x16x32_bf16 v[4:7], v[44:47], v[220:223], v[4:7]
	s_setprio 0
	s_setprio 1
	v_mfma_f32_16x16x32_bf16 v[24:27], v[144:147], v[208:211], v[24:27]
	v_mfma_f32_16x16x32_bf16 v[16:19], v[166:169], v[208:211], v[16:19]
	v_mfma_f32_16x16x32_bf16 v[8:11], v[144:147], v[216:219], v[8:11]
	v_mfma_f32_16x16x32_bf16 v[0:3], v[166:169], v[216:219], v[0:3]
	v_mfma_f32_16x16x32_bf16 v[28:31], v[144:147], v[192:195], v[72:75]
	v_mfma_f32_16x16x32_bf16 v[32:35], v[166:169], v[192:195], v[64:67]
	v_mfma_f32_16x16x32_bf16 v[40:43], v[144:147], v[200:203], v[56:59]
	v_mfma_f32_16x16x32_bf16 v[44:47], v[166:169], v[200:203], v[48:51]
	v_mfma_f32_16x16x32_bf16 v[24:27], v[148:151], v[212:215], v[24:27]
	v_mfma_f32_16x16x32_bf16 v[16:19], v[188:191], v[212:215], v[16:19]
	v_mfma_f32_16x16x32_bf16 v[8:11], v[148:151], v[220:223], v[8:11]
	v_mfma_f32_16x16x32_bf16 v[0:3], v[188:191], v[220:223], v[0:3]
	v_mfma_f32_16x16x32_bf16 v[28:31], v[148:151], v[196:199], v[28:31]
	v_mfma_f32_16x16x32_bf16 v[32:35], v[188:191], v[196:199], v[32:35]
	v_mfma_f32_16x16x32_bf16 v[40:43], v[148:151], v[204:207], v[40:43]
	v_mfma_f32_16x16x32_bf16 v[44:47], v[188:191], v[204:207], v[44:47]
	s_setprio 0
	s_barrier
	v_add_u32_e32 v72, vcc_lo, v171
	v_add_u32_e32 v187, s57, v171
	ds_read_b128 v[48:51], v72
	ds_read_b128 v[56:59], v72 offset:1024
	ds_read_b128 v[64:67], v72 offset:2048
	ds_read_b128 v[72:75], v72 offset:3072
	ds_read_b128 v[144:147], v187
	ds_read_b128 v[148:151], v187 offset:1024
	ds_read_b128 v[166:169], v187 offset:2048
	ds_read_b128 v[188:191], v187 offset:3072
	s_mov_b32 m0, s79
	v_lshl_add_u64 v[232:233], s[38:39], 0, v[160:161]
	ds_read_b128 v[192:195], v175 offset:32768
	ds_read_b128 v[196:199], v175 offset:33792
	ds_read_b128 v[200:203], v175 offset:34816
	ds_read_b128 v[204:207], v175 offset:35840
	ds_read_b128 v[208:211], v175 offset:36864
	ds_read_b128 v[212:215], v175 offset:37888
	ds_read_b128 v[216:219], v175 offset:38912
	ds_read_b128 v[220:223], v175 offset:39936
	global_load_lds_dwordx4 v[232:233], off
	v_lshl_add_u64 v[232:233], s[38:39], 0, v[156:157]
	s_mov_b32 m0, s86
	s_nop 0
	global_load_lds_dwordx4 v[232:233], off
	s_waitcnt vmcnt(8)
	s_cmp_eq_u32 s99, 0
	s_cbranch_scc1 .Ldp_1_l
	v_readlane_b32 s100, v0, 0
	s_mov_b64 exec, 1
	v_writelane_b32 v0, 1, 0
	s_nop 1
	global_atomic_add v0, v0, s[98:99]
	s_nop 1
	v_writelane_b32 v0, s100, 0
	s_mov_b64 exec, -1
	s_mov_b32 s99, 0
.Ldp_1_l:
	s_waitcnt lgkmcnt(0)
	s_barrier
	s_setprio 1
	s_waitcnt lgkmcnt(0)
	v_mfma_f32_16x16x32_bf16 v[140:143], v[48:51], v[192:195], v[140:143]
	v_mfma_f32_16x16x32_bf16 v[132:135], v[64:67], v[192:195], v[132:135]
	v_mfma_f32_16x16x32_bf16 v[124:127], v[48:51], v[200:203], v[124:127]
	v_mfma_f32_16x16x32_bf16 v[116:119], v[64:67], v[200:203], v[116:119]
	v_mfma_f32_16x16x32_bf16 v[108:111], v[48:51], v[208:211], v[108:111]
	v_mfma_f32_16x16x32_bf16 v[100:103], v[64:67], v[208:211], v[100:103]
	v_mfma_f32_16x16x32_bf16 v[92:95], v[48:51], v[216:219], v[92:95]
	v_mfma_f32_16x16x32_bf16 v[84:87], v[64:67], v[216:219], v[84:87]
	v_mfma_f32_16x16x32_bf16 v[140:143], v[56:59], v[196:199], v[140:143]
	v_mfma_f32_16x16x32_bf16 v[132:135], v[72:75], v[196:199], v[132:135]
	v_mfma_f32_16x16x32_bf16 v[124:127], v[56:59], v[204:207], v[124:127]
	v_mfma_f32_16x16x32_bf16 v[116:119], v[72:75], v[204:207], v[116:119]
	v_mfma_f32_16x16x32_bf16 v[108:111], v[56:59], v[212:215], v[108:111]
	v_mfma_f32_16x16x32_bf16 v[100:103], v[72:75], v[212:215], v[100:103]
	v_mfma_f32_16x16x32_bf16 v[92:95], v[56:59], v[220:223], v[92:95]
	v_mfma_f32_16x16x32_bf16 v[84:87], v[72:75], v[220:223], v[84:87]
	s_setprio 0
	s_setprio 1
	v_mfma_f32_16x16x32_bf16 v[136:139], v[144:147], v[192:195], v[136:139]
	v_mfma_f32_16x16x32_bf16 v[128:131], v[166:169], v[192:195], v[128:131]
	v_mfma_f32_16x16x32_bf16 v[120:123], v[144:147], v[200:203], v[120:123]
	v_mfma_f32_16x16x32_bf16 v[112:115], v[166:169], v[200:203], v[112:115]
	v_mfma_f32_16x16x32_bf16 v[104:107], v[144:147], v[208:211], v[104:107]
	v_mfma_f32_16x16x32_bf16 v[96:99], v[166:169], v[208:211], v[96:99]
	v_mfma_f32_16x16x32_bf16 v[88:91], v[144:147], v[216:219], v[88:91]
	v_mfma_f32_16x16x32_bf16 v[80:83], v[166:169], v[216:219], v[80:83]
	v_mfma_f32_16x16x32_bf16 v[136:139], v[148:151], v[196:199], v[136:139]
	v_mfma_f32_16x16x32_bf16 v[128:131], v[188:191], v[196:199], v[128:131]
	v_mfma_f32_16x16x32_bf16 v[120:123], v[148:151], v[204:207], v[120:123]
	v_mfma_f32_16x16x32_bf16 v[112:115], v[188:191], v[204:207], v[112:115]
	v_mfma_f32_16x16x32_bf16 v[104:107], v[148:151], v[212:215], v[104:107]
	v_mfma_f32_16x16x32_bf16 v[96:99], v[188:191], v[212:215], v[96:99]
	v_mfma_f32_16x16x32_bf16 v[88:91], v[148:151], v[220:223], v[88:91]
	v_mfma_f32_16x16x32_bf16 v[80:83], v[188:191], v[220:223], v[80:83]
	s_setprio 0
	s_barrier
	s_mov_b32 m0, s47
	v_lshl_add_u64 v[224:225], v[224:225], 0, s[42:43]
	ds_read_b128 v[192:195], v175 offset:49152
	ds_read_b128 v[196:199], v175 offset:50176
	ds_read_b128 v[200:203], v175 offset:51200
	ds_read_b128 v[204:207], v175 offset:52224
	ds_read_b128 v[208:211], v175 offset:53248
	ds_read_b128 v[212:215], v175 offset:54272
	ds_read_b128 v[216:219], v175 offset:55296
	ds_read_b128 v[220:223], v175 offset:56320
	global_load_lds_dwordx4 v[224:225], off
	v_lshl_add_u64 v[224:225], v[226:227], 0, s[42:43]
	s_mov_b32 m0, s19
	s_nop 0
	global_load_lds_dwordx4 v[224:225], off
	v_lshl_add_u64 v[224:225], s[36:37], 0, v[158:159]
	s_mov_b32 m0, s29
	s_nop 0
	global_load_lds_dwordx4 v[224:225], off
	v_lshl_add_u64 v[224:225], s[36:37], 0, v[154:155]
	s_mov_b32 m0, s18
	s_nop 0
	global_load_lds_dwordx4 v[224:225], off
	v_lshl_add_u64 v[224:225], v[228:229], 0, s[42:43]
	s_mov_b32 m0, s88
	s_nop 0
	global_load_lds_dwordx4 v[224:225], off
	v_lshl_add_u64 v[224:225], v[230:231], 0, s[42:43]
	s_mov_b32 m0, s89
	s_nop 0
	global_load_lds_dwordx4 v[224:225], off
	s_waitcnt vmcnt(8)
	s_waitcnt lgkmcnt(0)
	s_barrier
	s_setprio 1
	s_waitcnt lgkmcnt(0)
	v_mfma_f32_16x16x32_bf16 v[76:79], v[48:51], v[192:195], v[76:79]
	v_mfma_f32_16x16x32_bf16 v[68:71], v[64:67], v[192:195], v[68:71]
	v_mfma_f32_16x16x32_bf16 v[60:63], v[48:51], v[200:203], v[60:63]
	v_mfma_f32_16x16x32_bf16 v[52:55], v[64:67], v[200:203], v[52:55]
	v_mfma_f32_16x16x32_bf16 v[36:39], v[48:51], v[208:211], v[36:39]
	v_mfma_f32_16x16x32_bf16 v[20:23], v[64:67], v[208:211], v[20:23]
	v_mfma_f32_16x16x32_bf16 v[12:15], v[48:51], v[216:219], v[12:15]
	v_mfma_f32_16x16x32_bf16 v[4:7], v[64:67], v[216:219], v[4:7]
	v_mfma_f32_16x16x32_bf16 v[76:79], v[56:59], v[196:199], v[76:79]
	v_mfma_f32_16x16x32_bf16 v[68:71], v[72:75], v[196:199], v[68:71]
	v_mfma_f32_16x16x32_bf16 v[60:63], v[56:59], v[204:207], v[60:63]
	v_mfma_f32_16x16x32_bf16 v[52:55], v[72:75], v[204:207], v[52:55]
	v_mfma_f32_16x16x32_bf16 v[36:39], v[56:59], v[212:215], v[36:39]
	v_mfma_f32_16x16x32_bf16 v[20:23], v[72:75], v[212:215], v[20:23]
	v_mfma_f32_16x16x32_bf16 v[12:15], v[56:59], v[220:223], v[12:15]
	v_mfma_f32_16x16x32_bf16 v[4:7], v[72:75], v[220:223], v[4:7]
	s_setprio 0
	s_setprio 1
	v_mfma_f32_16x16x32_bf16 v[28:31], v[144:147], v[192:195], v[28:31]
	v_mfma_f32_16x16x32_bf16 v[72:75], v[148:151], v[196:199], v[28:31]
	v_mfma_f32_16x16x32_bf16 v[28:31], v[166:169], v[192:195], v[32:35]
	v_mfma_f32_16x16x32_bf16 v[64:67], v[188:191], v[196:199], v[28:31]
	v_mfma_f32_16x16x32_bf16 v[28:31], v[144:147], v[200:203], v[40:43]
	v_mfma_f32_16x16x32_bf16 v[56:59], v[148:151], v[204:207], v[28:31]
	v_mfma_f32_16x16x32_bf16 v[28:31], v[166:169], v[200:203], v[44:47]
	v_mfma_f32_16x16x32_bf16 v[24:27], v[144:147], v[208:211], v[24:27]
	v_mfma_f32_16x16x32_bf16 v[16:19], v[166:169], v[208:211], v[16:19]
	v_mfma_f32_16x16x32_bf16 v[8:11], v[144:147], v[216:219], v[8:11]
	v_mfma_f32_16x16x32_bf16 v[0:3], v[166:169], v[216:219], v[0:3]
	v_mfma_f32_16x16x32_bf16 v[48:51], v[188:191], v[204:207], v[28:31]
	v_mfma_f32_16x16x32_bf16 v[24:27], v[148:151], v[212:215], v[24:27]
	v_mfma_f32_16x16x32_bf16 v[16:19], v[188:191], v[212:215], v[16:19]
	v_mfma_f32_16x16x32_bf16 v[8:11], v[148:151], v[220:223], v[8:11]
	v_mfma_f32_16x16x32_bf16 v[0:3], v[188:191], v[220:223], v[0:3]
	s_setprio 0
	s_barrier
	s_movk_i32 s18, 0x100
	s_andn2_b64 vcc, exec, s[84:85]
	s_mov_b64 s[36:37], -1
	s_mov_b64 s[84:85], 0
	s_cbranch_vccz .LBB0_458
	v_readlane_b32 s4, v254, 60
	v_readlane_b32 s5, v254, 61
	s_and_b64 vcc, exec, s[4:5]
	s_cbranch_vccz .LBB0_461
	s_barrier
.LBB0_461:
	v_lshl_or_b32 v166, s78, 7, v172
	v_ashrrev_i32_e32 v167, 31, v166
	v_readlane_b32 s4, v254, 4
	v_lshlrev_b64 v[144:145], 2, v[166:167]
	v_readlane_b32 s5, v254, 5
	v_readlane_b32 s6, v254, 6
	v_readlane_b32 s7, v254, 7
	v_readlane_b32 s8, v254, 8
	v_readlane_b32 s9, v254, 9
	v_readlane_b32 s10, v254, 10
	v_readlane_b32 s11, v254, 11
	v_readlane_b32 s12, v254, 12
	v_readlane_b32 s13, v254, 13
	v_readlane_b32 s14, v254, 14
	v_readlane_b32 s15, v254, 15
	v_readlane_b32 s16, v254, 16
	v_readlane_b32 s17, v254, 17
	v_readlane_b32 s18, v254, 18
	v_readlane_b32 s19, v254, 19
	v_lshl_add_u64 v[32:33], s[16:17], 0, v[144:145]
	v_readlane_b32 s4, v254, 21
	v_readlane_b32 s5, v254, 22
	v_readlane_b32 s6, v254, 23
	v_readlane_b32 s7, v254, 24
	v_lshl_add_u64 v[44:45], s[4:5], 0, v[144:145]
	global_load_dwordx4 v[28:31], v[32:33], off offset:16
	global_load_dwordx4 v[40:43], v[32:33], off
	v_lshl_add_u64 v[148:149], s[6:7], 0, v[144:145]
	global_load_dwordx4 v[32:35], v[44:45], off offset:16
	s_nop 0
	global_load_dwordx4 v[44:47], v[44:45], off
	s_nop 0
	global_load_dwordx4 v[144:147], v[148:149], off offset:16
	s_nop 0
	global_load_dwordx4 v[148:151], v[148:149], off
	v_lshl_add_u32 v168, s0, 8, v170
	v_readlane_b32 s8, v254, 25
	v_readlane_b32 s9, v254, 26
	s_mov_b64 s[8:9], 0x40000
	v_readlane_b32 s10, v254, 27
	v_readlane_b32 s11, v254, 28
	v_readlane_b32 s12, v254, 29
	v_readlane_b32 s13, v254, 30
	v_readlane_b32 s14, v254, 31
	v_readlane_b32 s15, v254, 32
	v_readlane_b32 s16, v254, 33
	v_readlane_b32 s17, v254, 34
	v_readlane_b32 s18, v254, 35
	v_readlane_b32 s19, v254, 36
	s_waitcnt vmcnt(0)
	v_add_f32_e32 v132, v132, v28
	v_add_f32_e32 v140, v140, v40
	v_mul_f32_e32 v140, 0xbfb8aa3b, v140
	v_mul_f32_e32 v144, 0xbfb8aa3b, v144
	v_mul_f32_e32 v148, 0xbfb8aa3b, v148
	v_exp_f32_e32 v148, v148
	v_exp_f32_e32 v144, v144
	v_exp_f32_e32 v140, v140
	v_add_f32_e32 v136, v136, v44
	v_add_f32_e32 v169, 1.0, v148
	v_add_f32_e32 v187, -1.0, v169
	v_sub_f32_e32 v188, v187, v169
	v_add_f32_e32 v188, 1.0, v188
	v_sub_f32_e32 v187, v148, v187
	v_add_f32_e32 v187, v187, v188
	v_frexp_mant_f32_e32 v188, v169
	v_cmp_gt_f32_e32 vcc, s93, v188
	v_cvt_f64_f32_e32 v[188:189], v169
	v_frexp_exp_i32_f64_e32 v188, v[188:189]
	v_subbrev_co_u32_e32 v188, vcc, 0, v188, vcc
	v_sub_u32_e32 v189, 0, v188
	v_ldexp_f32 v169, v169, v189
	v_ldexp_f32 v187, v187, v189
	v_add_f32_e32 v189, -1.0, v169
	v_add_f32_e32 v190, 1.0, v189
	v_sub_f32_e32 v190, v169, v190
	v_add_f32_e32 v190, v187, v190
	v_add_f32_e32 v191, v189, v190
	v_sub_f32_e32 v189, v191, v189
	v_sub_f32_e32 v189, v190, v189
	v_add_f32_e32 v190, 1.0, v169
	v_add_f32_e32 v192, -1.0, v190
	v_sub_f32_e32 v169, v169, v192
	v_add_f32_e32 v169, v187, v169
	v_add_f32_e32 v187, v190, v169
	v_sub_f32_e32 v190, v187, v190
	v_sub_f32_e32 v169, v169, v190
	v_rcp_f32_e32 v190, v187
	v_cvt_f32_i32_e32 v188, v188
	v_cmp_neq_f32_e32 vcc, s95, v148
	v_add_f32_e32 v140, 1.0, v140
	v_mul_f32_e32 v192, v191, v190
	v_mul_f32_e32 v193, v187, v192
	v_fma_f32 v194, v192, v187, -v193
	v_fmac_f32_e32 v194, v192, v169
	v_add_f32_e32 v195, v193, v194
	v_sub_f32_e32 v196, v191, v195
	v_sub_f32_e32 v191, v191, v196
	v_sub_f32_e32 v193, v195, v193
	v_sub_f32_e32 v191, v191, v195
	v_add_f32_e32 v189, v189, v191
	v_sub_f32_e32 v191, v193, v194
	v_add_f32_e32 v189, v191, v189
	v_add_f32_e32 v191, v196, v189
	v_mul_f32_e32 v193, v190, v191
	v_mul_f32_e32 v194, v187, v193
	v_fma_f32 v187, v193, v187, -v194
	v_fmac_f32_e32 v187, v193, v169
	v_sub_f32_e32 v169, v196, v191
	v_add_f32_e32 v169, v189, v169
	v_add_f32_e32 v189, v194, v187
	v_sub_f32_e32 v195, v191, v189
	v_sub_f32_e32 v191, v191, v195
	v_sub_f32_e32 v194, v189, v194
	v_sub_f32_e32 v189, v191, v189
	v_add_f32_e32 v169, v169, v189
	v_sub_f32_e32 v187, v194, v187
	v_add_f32_e32 v169, v187, v169
	v_add_f32_e32 v187, v192, v193
	v_add_f32_e32 v169, v195, v169
	v_sub_f32_e32 v189, v187, v192
	v_mul_f32_e32 v169, v190, v169
	v_sub_f32_e32 v189, v193, v189
	v_add_f32_e32 v169, v189, v169
	v_mul_f32_e32 v192, 0x3f317218, v188
	v_add_f32_e32 v189, v187, v169
	v_fma_f32 v193, v188, s94, -v192
	v_mul_f32_e32 v190, v189, v189
	v_fmac_f32_e32 v193, 0xb102e308, v188
	v_sub_f32_e32 v187, v189, v187
	v_fmamk_f32 v191, v190, 0x3e9b6dac, v183
	v_sub_f32_e32 v169, v169, v187
	v_add_f32_e32 v187, v192, v193
	v_fmaak_f32 v191, v190, v191, 0x3f2aaada
	v_sub_f32_e32 v188, v187, v192
	v_ldexp_f32 v192, v189, 1
	v_mul_f32_e32 v189, v189, v190
	v_mul_f32_e32 v189, v189, v191
	v_add_f32_e32 v190, v192, v189
	v_sub_f32_e32 v191, v190, v192
	v_ldexp_f32 v169, v169, 1
	v_sub_f32_e32 v189, v189, v191
	v_add_f32_e32 v169, v169, v189
	v_add_f32_e32 v189, v190, v169
	v_sub_f32_e32 v190, v189, v190
	v_sub_f32_e32 v169, v169, v190
	v_add_f32_e32 v190, v187, v189
	v_sub_f32_e32 v191, v190, v187
	v_sub_f32_e32 v192, v190, v191
	v_sub_f32_e32 v188, v193, v188
	v_sub_f32_e32 v187, v187, v192
	v_sub_f32_e32 v189, v189, v191
	v_add_f32_e32 v187, v189, v187
	v_add_f32_e32 v189, v188, v169
	v_sub_f32_e32 v191, v189, v188
	v_sub_f32_e32 v192, v189, v191
	v_sub_f32_e32 v188, v188, v192
	v_sub_f32_e32 v169, v169, v191
	v_add_f32_e32 v187, v189, v187
	v_add_f32_e32 v169, v169, v188
	v_add_f32_e32 v188, v190, v187
	v_sub_f32_e32 v189, v188, v190
	v_sub_f32_e32 v187, v187, v189
	v_add_f32_e32 v169, v169, v187
	v_add_f32_e32 v169, v188, v169
	v_cndmask_b32_e32 v169, v184, v169, vcc
	v_cmp_ngt_f32_e32 vcc, -1.0, v148
	v_rcp_f32_e32 v140, v140
	v_mul_f32_e32 v136, 0xbfb8aa3b, v136
	v_cndmask_b32_e32 v169, v185, v169, vcc
	v_cmp_neq_f32_e32 vcc, -1.0, v148
	v_exp_f32_e32 v136, v136
	v_add_f32_e32 v137, v137, v45
	v_cndmask_b32_e32 v169, v186, v169, vcc
	v_cmp_lt_f32_e64 vcc, |v148|, s96
	v_add_f32_e32 v136, 1.0, v136
	v_rcp_f32_e32 v136, v136
	v_cndmask_b32_e32 v148, v169, v148, vcc
	v_add_f32_e32 v169, 1.0, v144
	v_mul_f32_e32 v187, 0xc1000000, v148
	v_add_f32_e32 v148, -1.0, v169
	v_sub_f32_e32 v188, v148, v169
	v_add_f32_e32 v188, 1.0, v188
	v_sub_f32_e32 v148, v144, v148
	v_add_f32_e32 v190, v148, v188
	v_frexp_mant_f32_e32 v148, v169
	v_cvt_f64_f32_e32 v[188:189], v169
	v_cmp_gt_f32_e32 vcc, s93, v148
	v_frexp_exp_i32_f64_e32 v148, v[188:189]
	v_mul_f32_e32 v140, v140, v187
	v_subbrev_co_u32_e32 v148, vcc, 0, v148, vcc
	v_sub_u32_e32 v188, 0, v148
	v_ldexp_f32 v169, v169, v188
	v_add_f32_e32 v189, -1.0, v169
	v_ldexp_f32 v188, v190, v188
	v_add_f32_e32 v190, 1.0, v189
	v_sub_f32_e32 v190, v169, v190
	v_add_f32_e32 v190, v188, v190
	v_add_f32_e32 v191, v189, v190
	v_sub_f32_e32 v189, v191, v189
	v_sub_f32_e32 v189, v190, v189
	v_add_f32_e32 v190, 1.0, v169
	v_add_f32_e32 v192, -1.0, v190
	v_sub_f32_e32 v169, v169, v192
	v_add_f32_e32 v169, v188, v169
	v_add_f32_e32 v188, v190, v169
	v_sub_f32_e32 v190, v188, v190
	v_sub_f32_e32 v169, v169, v190
	v_rcp_f32_e32 v190, v188
	v_cvt_f32_i32_e32 v148, v148
	v_cmp_neq_f32_e32 vcc, s95, v144
	v_mul_f32_e32 v140, 0x3fb8aa3b, v140
	v_mul_f32_e32 v192, v191, v190
	v_mul_f32_e32 v193, v188, v192
	v_fma_f32 v194, v192, v188, -v193
	v_fmac_f32_e32 v194, v192, v169
	v_add_f32_e32 v195, v193, v194
	v_sub_f32_e32 v196, v191, v195
	v_sub_f32_e32 v191, v191, v196
	v_sub_f32_e32 v193, v195, v193
	v_sub_f32_e32 v191, v191, v195
	v_add_f32_e32 v189, v189, v191
	v_sub_f32_e32 v191, v193, v194
	v_add_f32_e32 v189, v191, v189
	v_add_f32_e32 v191, v196, v189
	v_mul_f32_e32 v193, v190, v191
	v_mul_f32_e32 v194, v188, v193
	v_fma_f32 v188, v193, v188, -v194
	v_fmac_f32_e32 v188, v193, v169
	v_sub_f32_e32 v169, v196, v191
	v_add_f32_e32 v169, v189, v169
	v_add_f32_e32 v189, v194, v188
	v_sub_f32_e32 v195, v191, v189
	v_sub_f32_e32 v191, v191, v195
	v_sub_f32_e32 v194, v189, v194
	v_sub_f32_e32 v189, v191, v189
	v_add_f32_e32 v169, v169, v189
	v_sub_f32_e32 v188, v194, v188
	v_add_f32_e32 v169, v188, v169
	v_add_f32_e32 v188, v192, v193
	v_add_f32_e32 v169, v195, v169
	v_sub_f32_e32 v189, v188, v192
	v_mul_f32_e32 v169, v190, v169
	v_sub_f32_e32 v189, v193, v189
	v_add_f32_e32 v169, v189, v169
	v_mul_f32_e32 v192, 0x3f317218, v148
	v_add_f32_e32 v189, v188, v169
	v_fma_f32 v193, v148, s94, -v192
	v_mul_f32_e32 v190, v189, v189
	v_fmac_f32_e32 v193, 0xb102e308, v148
	v_sub_f32_e32 v148, v189, v188
	v_fmamk_f32 v191, v190, 0x3e9b6dac, v183
	v_sub_f32_e32 v148, v169, v148
	v_add_f32_e32 v169, v192, v193
	v_fmaak_f32 v191, v190, v191, 0x3f2aaada
	v_sub_f32_e32 v188, v169, v192
	v_ldexp_f32 v192, v189, 1
	v_mul_f32_e32 v189, v189, v190
	v_mul_f32_e32 v189, v189, v191
	v_add_f32_e32 v190, v192, v189
	v_sub_f32_e32 v191, v190, v192
	v_ldexp_f32 v148, v148, 1
	v_sub_f32_e32 v189, v189, v191
	v_add_f32_e32 v148, v148, v189
	v_add_f32_e32 v189, v190, v148
	v_sub_f32_e32 v190, v189, v190
	v_sub_f32_e32 v148, v148, v190
	v_add_f32_e32 v190, v169, v189
	v_sub_f32_e32 v191, v190, v169
	v_sub_f32_e32 v192, v190, v191
	v_sub_f32_e32 v188, v193, v188
	v_sub_f32_e32 v169, v169, v192
	v_sub_f32_e32 v189, v189, v191
	v_add_f32_e32 v169, v189, v169
	v_add_f32_e32 v189, v188, v148
	v_sub_f32_e32 v191, v189, v188
	v_sub_f32_e32 v192, v189, v191
	v_sub_f32_e32 v188, v188, v192
	v_sub_f32_e32 v148, v148, v191
	v_add_f32_e32 v169, v189, v169
	v_add_f32_e32 v148, v148, v188
	v_add_f32_e32 v188, v190, v169
	v_sub_f32_e32 v189, v188, v190
	v_sub_f32_e32 v169, v169, v189
	v_add_f32_e32 v148, v148, v169
	v_add_f32_e32 v148, v188, v148
	v_cndmask_b32_e32 v148, v184, v148, vcc
	v_cmp_ngt_f32_e32 vcc, -1.0, v144
	v_exp_f32_e32 v140, v140
	v_mul_f32_e32 v137, 0xbfb8aa3b, v137
	v_cndmask_b32_e32 v148, v185, v148, vcc
	v_cmp_neq_f32_e32 vcc, -1.0, v144
	v_exp_f32_e32 v137, v137
	v_add_f32_e32 v138, v138, v46
	v_cndmask_b32_e32 v148, v186, v148, vcc
	v_cmp_lt_f32_e64 vcc, |v144|, s96
	v_add_f32_e32 v137, 1.0, v137
	v_rcp_f32_e32 v137, v137
	v_cndmask_b32_e32 v144, v148, v144, vcc
	v_mul_f32_e32 v188, 0xc1000000, v144
	v_mul_f32_e32 v144, 0xbfb8aa3b, v149
	v_exp_f32_e32 v144, v144
	v_mul_f32_e32 v138, 0xbfb8aa3b, v138
	v_exp_f32_e32 v138, v138
	v_mul_f32_e32 v132, 0xbfb8aa3b, v132
	v_add_f32_e32 v169, 1.0, v144
	v_add_f32_e32 v148, -1.0, v169
	v_sub_f32_e32 v149, v148, v169
	v_add_f32_e32 v149, 1.0, v149
	v_sub_f32_e32 v148, v144, v148
	v_add_f32_e32 v189, v148, v149
	v_frexp_mant_f32_e32 v148, v169
	v_cmp_gt_f32_e32 vcc, s93, v148
	v_cvt_f64_f32_e32 v[148:149], v169
	v_frexp_exp_i32_f64_e32 v148, v[148:149]
	v_subbrev_co_u32_e32 v148, vcc, 0, v148, vcc
	v_sub_u32_e32 v149, 0, v148
	v_ldexp_f32 v169, v169, v149
	v_ldexp_f32 v149, v189, v149
	v_add_f32_e32 v189, -1.0, v169
	v_add_f32_e32 v190, 1.0, v189
	v_sub_f32_e32 v190, v169, v190
	v_add_f32_e32 v190, v149, v190
	v_add_f32_e32 v191, v189, v190
	v_sub_f32_e32 v189, v191, v189
	v_sub_f32_e32 v189, v190, v189
	v_add_f32_e32 v190, 1.0, v169
	v_add_f32_e32 v192, -1.0, v190
	v_sub_f32_e32 v169, v169, v192
	v_add_f32_e32 v149, v149, v169
	v_add_f32_e32 v169, v190, v149
	v_sub_f32_e32 v190, v169, v190
	v_sub_f32_e32 v149, v149, v190
	v_rcp_f32_e32 v190, v169
	v_cvt_f32_i32_e32 v148, v148
	v_cmp_neq_f32_e32 vcc, s95, v144
	v_add_f32_e32 v138, 1.0, v138
	v_mul_f32_e32 v192, v191, v190
	v_mul_f32_e32 v193, v169, v192
	v_fma_f32 v194, v192, v169, -v193
	v_fmac_f32_e32 v194, v192, v149
	v_add_f32_e32 v195, v193, v194
	v_sub_f32_e32 v196, v191, v195
	v_sub_f32_e32 v191, v191, v196
	v_sub_f32_e32 v193, v195, v193
	v_sub_f32_e32 v191, v191, v195
	v_add_f32_e32 v189, v189, v191
	v_sub_f32_e32 v191, v193, v194
	v_add_f32_e32 v189, v191, v189
	v_add_f32_e32 v191, v196, v189
	v_mul_f32_e32 v193, v190, v191
	v_mul_f32_e32 v194, v169, v193
	v_fma_f32 v169, v193, v169, -v194
	v_fmac_f32_e32 v169, v193, v149
	v_sub_f32_e32 v149, v196, v191
	v_add_f32_e32 v149, v189, v149
	v_add_f32_e32 v189, v194, v169
	v_sub_f32_e32 v195, v191, v189
	v_sub_f32_e32 v191, v191, v195
	v_sub_f32_e32 v194, v189, v194
	v_sub_f32_e32 v189, v191, v189
	v_add_f32_e32 v149, v149, v189
	v_sub_f32_e32 v169, v194, v169
	v_add_f32_e32 v149, v169, v149
	v_add_f32_e32 v169, v192, v193
	v_add_f32_e32 v149, v195, v149
	v_sub_f32_e32 v189, v169, v192
	v_mul_f32_e32 v149, v190, v149
	v_sub_f32_e32 v189, v193, v189
	v_add_f32_e32 v149, v189, v149
	v_mul_f32_e32 v192, 0x3f317218, v148
	v_add_f32_e32 v189, v169, v149
	v_fma_f32 v193, v148, s94, -v192
	v_mul_f32_e32 v190, v189, v189
	v_fmac_f32_e32 v193, 0xb102e308, v148
	v_sub_f32_e32 v148, v189, v169
	v_fmamk_f32 v191, v190, 0x3e9b6dac, v183
	v_sub_f32_e32 v148, v149, v148
	v_add_f32_e32 v149, v192, v193
	v_fmaak_f32 v191, v190, v191, 0x3f2aaada
	v_sub_f32_e32 v169, v149, v192
	v_ldexp_f32 v192, v189, 1
	v_mul_f32_e32 v189, v189, v190
	v_mul_f32_e32 v189, v189, v191
	v_add_f32_e32 v190, v192, v189
	v_sub_f32_e32 v191, v190, v192
	v_ldexp_f32 v148, v148, 1
	v_sub_f32_e32 v189, v189, v191
	v_add_f32_e32 v148, v148, v189
	v_add_f32_e32 v189, v190, v148
	v_sub_f32_e32 v190, v189, v190
	v_sub_f32_e32 v148, v148, v190
	v_add_f32_e32 v190, v149, v189
	v_sub_f32_e32 v191, v190, v149
	v_sub_f32_e32 v192, v190, v191
	v_sub_f32_e32 v169, v193, v169
	v_sub_f32_e32 v149, v149, v192
	v_sub_f32_e32 v189, v189, v191
	v_add_f32_e32 v149, v189, v149
	v_add_f32_e32 v189, v169, v148
	v_sub_f32_e32 v191, v189, v169
	v_sub_f32_e32 v192, v189, v191
	v_sub_f32_e32 v169, v169, v192
	v_sub_f32_e32 v148, v148, v191
	v_add_f32_e32 v149, v189, v149
	v_add_f32_e32 v148, v148, v169
	v_add_f32_e32 v169, v190, v149
	v_sub_f32_e32 v189, v169, v190
	v_sub_f32_e32 v149, v149, v189
	v_add_f32_e32 v148, v148, v149
	v_add_f32_e32 v148, v169, v148
	v_cndmask_b32_e32 v148, v184, v148, vcc
	v_cmp_ngt_f32_e32 vcc, -1.0, v144
	v_rcp_f32_e32 v138, v138
	v_exp_f32_e32 v132, v132
	v_cndmask_b32_e32 v148, v185, v148, vcc
	v_cmp_neq_f32_e32 vcc, -1.0, v144
	v_add_f32_e32 v139, v139, v47
	v_add_f32_e32 v132, 1.0, v132
	v_cndmask_b32_e32 v148, v186, v148, vcc
	v_cmp_lt_f32_e64 vcc, |v144|, s96
	v_mul_f32_e32 v139, 0xbfb8aa3b, v139
	v_rcp_f32_e32 v132, v132
	v_cndmask_b32_e32 v144, v148, v144, vcc
	v_mul_f32_e32 v190, 0xc1000000, v144
	v_mul_f32_e32 v144, 0xbfb8aa3b, v145
	v_exp_f32_e32 v148, v144
	v_exp_f32_e32 v139, v139
	v_mul_f32_e32 v132, v132, v188
	v_mul_f32_e32 v132, 0x3fb8aa3b, v132
	v_add_f32_e32 v149, 1.0, v148
	v_add_f32_e32 v144, -1.0, v149
	v_sub_f32_e32 v145, v144, v149
	v_add_f32_e32 v145, 1.0, v145
	v_sub_f32_e32 v144, v148, v144
	v_add_f32_e32 v169, v144, v145
	v_frexp_mant_f32_e32 v144, v149
	v_cmp_gt_f32_e32 vcc, s93, v144
	v_cvt_f64_f32_e32 v[144:145], v149
	v_frexp_exp_i32_f64_e32 v144, v[144:145]
	v_subbrev_co_u32_e32 v144, vcc, 0, v144, vcc
	v_sub_u32_e32 v145, 0, v144
	v_ldexp_f32 v149, v149, v145
	v_ldexp_f32 v145, v169, v145
	v_add_f32_e32 v169, -1.0, v149
	v_add_f32_e32 v189, 1.0, v169
	v_sub_f32_e32 v189, v149, v189
	v_add_f32_e32 v189, v145, v189
	v_add_f32_e32 v191, v169, v189
	v_sub_f32_e32 v169, v191, v169
	v_sub_f32_e32 v169, v189, v169
	v_add_f32_e32 v189, 1.0, v149
	v_add_f32_e32 v192, -1.0, v189
	v_sub_f32_e32 v149, v149, v192
	v_add_f32_e32 v145, v145, v149
	v_add_f32_e32 v149, v189, v145
	v_sub_f32_e32 v189, v149, v189
	v_sub_f32_e32 v145, v145, v189
	v_rcp_f32_e32 v189, v149
	v_cvt_f32_i32_e32 v144, v144
	v_cmp_neq_f32_e32 vcc, s95, v148
	v_add_f32_e32 v139, 1.0, v139
	v_mul_f32_e32 v192, v191, v189
	v_mul_f32_e32 v193, v149, v192
	v_fma_f32 v194, v192, v149, -v193
	v_fmac_f32_e32 v194, v192, v145
	v_add_f32_e32 v195, v193, v194
	v_sub_f32_e32 v196, v191, v195
	v_sub_f32_e32 v191, v191, v196
	v_sub_f32_e32 v193, v195, v193
	v_sub_f32_e32 v191, v191, v195
	v_add_f32_e32 v169, v169, v191
	v_sub_f32_e32 v191, v193, v194
	v_add_f32_e32 v169, v191, v169
	v_add_f32_e32 v191, v196, v169
	v_mul_f32_e32 v193, v189, v191
	v_mul_f32_e32 v194, v149, v193
	v_fma_f32 v149, v193, v149, -v194
	v_fmac_f32_e32 v149, v193, v145
	v_sub_f32_e32 v145, v196, v191
	v_add_f32_e32 v145, v169, v145
	v_add_f32_e32 v169, v194, v149
	v_sub_f32_e32 v195, v191, v169
	v_sub_f32_e32 v191, v191, v195
	v_sub_f32_e32 v194, v169, v194
	v_sub_f32_e32 v169, v191, v169
	v_add_f32_e32 v145, v145, v169
	v_sub_f32_e32 v149, v194, v149
	v_add_f32_e32 v145, v149, v145
	v_add_f32_e32 v149, v192, v193
	v_add_f32_e32 v145, v195, v145
	v_sub_f32_e32 v169, v149, v192
	v_mul_f32_e32 v145, v189, v145
	v_sub_f32_e32 v169, v193, v169
	v_add_f32_e32 v145, v169, v145
	v_mul_f32_e32 v192, 0x3f317218, v144
	v_add_f32_e32 v169, v149, v145
	v_fma_f32 v193, v144, s94, -v192
	v_mul_f32_e32 v189, v169, v169
	v_fmac_f32_e32 v193, 0xb102e308, v144
	v_sub_f32_e32 v144, v169, v149
	v_fmamk_f32 v191, v189, 0x3e9b6dac, v183
	v_sub_f32_e32 v144, v145, v144
	v_add_f32_e32 v145, v192, v193
	v_fmaak_f32 v191, v189, v191, 0x3f2aaada
	v_sub_f32_e32 v149, v145, v192
	v_ldexp_f32 v192, v169, 1
	v_mul_f32_e32 v169, v169, v189
	v_mul_f32_e32 v169, v169, v191
	v_add_f32_e32 v189, v192, v169
	v_sub_f32_e32 v191, v189, v192
	v_ldexp_f32 v144, v144, 1
	v_sub_f32_e32 v169, v169, v191
	v_add_f32_e32 v144, v144, v169
	v_add_f32_e32 v169, v189, v144
	v_sub_f32_e32 v189, v169, v189
	v_sub_f32_e32 v144, v144, v189
	v_add_f32_e32 v189, v145, v169
	v_sub_f32_e32 v191, v189, v145
	v_sub_f32_e32 v192, v189, v191
	v_sub_f32_e32 v149, v193, v149
	v_sub_f32_e32 v145, v145, v192
	v_sub_f32_e32 v169, v169, v191
	v_add_f32_e32 v145, v169, v145
	v_add_f32_e32 v169, v149, v144
	v_sub_f32_e32 v191, v169, v149
	v_sub_f32_e32 v192, v169, v191
	v_sub_f32_e32 v149, v149, v192
	v_sub_f32_e32 v144, v144, v191
	v_add_f32_e32 v145, v169, v145
	v_add_f32_e32 v144, v144, v149
	v_add_f32_e32 v149, v189, v145
	v_sub_f32_e32 v169, v149, v189
	v_sub_f32_e32 v145, v145, v169
	v_add_f32_e32 v144, v144, v145
	v_add_f32_e32 v144, v149, v144
	v_cndmask_b32_e32 v144, v184, v144, vcc
	v_cmp_ngt_f32_e32 vcc, -1.0, v148
	v_rcp_f32_e32 v139, v139
	v_add_f32_e32 v128, v128, v32
	v_cndmask_b32_e32 v144, v185, v144, vcc
	v_cmp_neq_f32_e32 vcc, -1.0, v148
	v_exp_f32_e32 v132, v132
	v_mul_f32_e32 v128, 0xbfb8aa3b, v128
	v_cndmask_b32_e32 v144, v186, v144, vcc
	v_cmp_lt_f32_e64 vcc, |v148|, s96
	v_exp_f32_e32 v128, v128
	v_add_f32_e32 v129, v129, v33
	v_cndmask_b32_e32 v144, v144, v148, vcc
	v_mul_f32_e32 v189, 0xc1000000, v144
	v_mul_f32_e32 v144, 0xbfb8aa3b, v150
	v_exp_f32_e32 v148, v144
	v_add_f32_e32 v128, 1.0, v128
	v_rcp_f32_e32 v128, v128
	v_mul_f32_e32 v129, 0xbfb8aa3b, v129
	v_add_f32_e32 v149, 1.0, v148
	v_add_f32_e32 v144, -1.0, v149
	v_sub_f32_e32 v145, v144, v149
	v_add_f32_e32 v145, 1.0, v145
	v_sub_f32_e32 v144, v148, v144
	v_add_f32_e32 v150, v144, v145
	v_frexp_mant_f32_e32 v144, v149
	v_cmp_gt_f32_e32 vcc, s93, v144
	v_cvt_f64_f32_e32 v[144:145], v149
	v_frexp_exp_i32_f64_e32 v144, v[144:145]
	v_subbrev_co_u32_e32 v144, vcc, 0, v144, vcc
	v_sub_u32_e32 v145, 0, v144
	v_ldexp_f32 v149, v149, v145
	v_ldexp_f32 v145, v150, v145
	v_add_f32_e32 v150, -1.0, v149
	v_add_f32_e32 v169, 1.0, v150
	v_sub_f32_e32 v169, v149, v169
	v_add_f32_e32 v169, v145, v169
	v_add_f32_e32 v191, v150, v169
	v_sub_f32_e32 v150, v191, v150
	v_sub_f32_e32 v150, v169, v150
	v_add_f32_e32 v169, 1.0, v149
	v_add_f32_e32 v192, -1.0, v169
	v_sub_f32_e32 v149, v149, v192
	v_add_f32_e32 v145, v145, v149
	v_add_f32_e32 v149, v169, v145
	v_sub_f32_e32 v169, v149, v169
	v_sub_f32_e32 v145, v145, v169
	v_rcp_f32_e32 v169, v149
	v_cvt_f32_i32_e32 v144, v144
	v_cmp_neq_f32_e32 vcc, s95, v148
	v_exp_f32_e32 v129, v129
	v_mul_f32_e32 v192, v191, v169
	v_mul_f32_e32 v193, v149, v192
	v_fma_f32 v194, v192, v149, -v193
	v_fmac_f32_e32 v194, v192, v145
	v_add_f32_e32 v195, v193, v194
	v_sub_f32_e32 v196, v191, v195
	v_sub_f32_e32 v191, v191, v196
	v_sub_f32_e32 v193, v195, v193
	v_sub_f32_e32 v191, v191, v195
	v_add_f32_e32 v150, v150, v191
	v_sub_f32_e32 v191, v193, v194
	v_add_f32_e32 v150, v191, v150
	v_add_f32_e32 v191, v196, v150
	v_mul_f32_e32 v193, v169, v191
	v_mul_f32_e32 v194, v149, v193
	v_fma_f32 v149, v193, v149, -v194
	v_fmac_f32_e32 v149, v193, v145
	v_sub_f32_e32 v145, v196, v191
	v_add_f32_e32 v145, v150, v145
	v_add_f32_e32 v150, v194, v149
	v_sub_f32_e32 v195, v191, v150
	v_sub_f32_e32 v191, v191, v195
	v_sub_f32_e32 v194, v150, v194
	v_sub_f32_e32 v150, v191, v150
	v_add_f32_e32 v145, v145, v150
	v_sub_f32_e32 v149, v194, v149
	v_add_f32_e32 v145, v149, v145
	v_add_f32_e32 v149, v192, v193
	v_add_f32_e32 v145, v195, v145
	v_sub_f32_e32 v150, v149, v192
	v_mul_f32_e32 v145, v169, v145
	v_sub_f32_e32 v150, v193, v150
	v_add_f32_e32 v145, v150, v145
	v_mul_f32_e32 v192, 0x3f317218, v144
	v_add_f32_e32 v150, v149, v145
	v_fma_f32 v193, v144, s94, -v192
	v_mul_f32_e32 v169, v150, v150
	v_fmac_f32_e32 v193, 0xb102e308, v144
	v_sub_f32_e32 v144, v150, v149
	v_fmamk_f32 v191, v169, 0x3e9b6dac, v183
	v_sub_f32_e32 v144, v145, v144
	v_add_f32_e32 v145, v192, v193
	v_fmaak_f32 v191, v169, v191, 0x3f2aaada
	v_sub_f32_e32 v149, v145, v192
	v_ldexp_f32 v192, v150, 1
	v_mul_f32_e32 v150, v150, v169
	v_mul_f32_e32 v150, v150, v191
	v_add_f32_e32 v169, v192, v150
	v_sub_f32_e32 v191, v169, v192
	v_ldexp_f32 v144, v144, 1
	v_sub_f32_e32 v150, v150, v191
	v_add_f32_e32 v144, v144, v150
	v_add_f32_e32 v150, v169, v144
	v_sub_f32_e32 v169, v150, v169
	v_sub_f32_e32 v144, v144, v169
	v_add_f32_e32 v169, v145, v150
	v_sub_f32_e32 v191, v169, v145
	v_sub_f32_e32 v192, v169, v191
	v_sub_f32_e32 v149, v193, v149
	v_sub_f32_e32 v145, v145, v192
	v_sub_f32_e32 v150, v150, v191
	v_add_f32_e32 v145, v150, v145
	v_add_f32_e32 v150, v149, v144
	v_sub_f32_e32 v191, v150, v149
	v_sub_f32_e32 v192, v150, v191
	v_sub_f32_e32 v149, v149, v192
	v_sub_f32_e32 v144, v144, v191
	v_add_f32_e32 v145, v150, v145
	v_add_f32_e32 v144, v144, v149
	v_add_f32_e32 v149, v169, v145
	v_sub_f32_e32 v150, v149, v169
	v_sub_f32_e32 v145, v145, v150
	v_add_f32_e32 v144, v144, v145
	v_add_f32_e32 v144, v149, v144
	v_cndmask_b32_e32 v144, v184, v144, vcc
	v_cmp_ngt_f32_e32 vcc, -1.0, v148
	v_add_f32_e32 v129, 1.0, v129
	v_rcp_f32_e32 v129, v129
	v_cndmask_b32_e32 v144, v185, v144, vcc
	v_cmp_neq_f32_e32 vcc, -1.0, v148
	v_add_f32_e32 v124, v124, v40
	v_mul_f32_e32 v124, 0xbfb8aa3b, v124
	v_cndmask_b32_e32 v144, v186, v144, vcc
	v_cmp_lt_f32_e64 vcc, |v148|, s96
	v_exp_f32_e32 v124, v124
	v_add_f32_e32 v120, v120, v44
	v_cndmask_b32_e32 v144, v144, v148, vcc
	v_mul_f32_e32 v191, 0xc1000000, v144
	v_mul_f32_e32 v144, 0xbfb8aa3b, v146
	v_exp_f32_e32 v146, v144
	v_add_f32_e32 v124, 1.0, v124
	v_rcp_f32_e32 v124, v124
	v_mul_f32_e32 v120, 0xbfb8aa3b, v120
	v_add_f32_e32 v148, 1.0, v146
	v_add_f32_e32 v144, -1.0, v148
	v_sub_f32_e32 v145, v144, v148
	v_add_f32_e32 v145, 1.0, v145
	v_sub_f32_e32 v144, v146, v144
	v_add_f32_e32 v149, v144, v145
	v_frexp_mant_f32_e32 v144, v148
	v_cmp_gt_f32_e32 vcc, s93, v144
	v_cvt_f64_f32_e32 v[144:145], v148
	v_frexp_exp_i32_f64_e32 v144, v[144:145]
	v_subbrev_co_u32_e32 v144, vcc, 0, v144, vcc
	v_sub_u32_e32 v145, 0, v144
	v_ldexp_f32 v148, v148, v145
	v_ldexp_f32 v145, v149, v145
	v_add_f32_e32 v149, -1.0, v148
	v_add_f32_e32 v150, 1.0, v149
	v_sub_f32_e32 v150, v148, v150
	v_add_f32_e32 v150, v145, v150
	v_add_f32_e32 v169, v149, v150
	v_sub_f32_e32 v149, v169, v149
	v_sub_f32_e32 v149, v150, v149
	v_add_f32_e32 v150, 1.0, v148
	v_add_f32_e32 v192, -1.0, v150
	v_sub_f32_e32 v148, v148, v192
	v_add_f32_e32 v145, v145, v148
	v_add_f32_e32 v148, v150, v145
	v_sub_f32_e32 v150, v148, v150
	v_sub_f32_e32 v145, v145, v150
	v_rcp_f32_e32 v150, v148
	v_cvt_f32_i32_e32 v144, v144
	v_cmp_neq_f32_e32 vcc, s95, v146
	v_mul_f32_e32 v124, v124, v187
	v_mul_f32_e32 v192, v169, v150
	v_mul_f32_e32 v193, v148, v192
	v_fma_f32 v194, v192, v148, -v193
	v_fmac_f32_e32 v194, v192, v145
	v_add_f32_e32 v195, v193, v194
	v_sub_f32_e32 v196, v169, v195
	v_sub_f32_e32 v169, v169, v196
	v_sub_f32_e32 v193, v195, v193
	v_sub_f32_e32 v169, v169, v195
	v_add_f32_e32 v149, v149, v169
	v_sub_f32_e32 v169, v193, v194
	v_add_f32_e32 v149, v169, v149
	v_add_f32_e32 v169, v196, v149
	v_mul_f32_e32 v193, v150, v169
	v_mul_f32_e32 v194, v148, v193
	v_fma_f32 v148, v193, v148, -v194
	v_fmac_f32_e32 v148, v193, v145
	v_sub_f32_e32 v145, v196, v169
	v_add_f32_e32 v145, v149, v145
	v_add_f32_e32 v149, v194, v148
	v_sub_f32_e32 v195, v169, v149
	v_sub_f32_e32 v169, v169, v195
	v_sub_f32_e32 v194, v149, v194
	v_sub_f32_e32 v149, v169, v149
	v_add_f32_e32 v145, v145, v149
	v_sub_f32_e32 v148, v194, v148
	v_add_f32_e32 v145, v148, v145
	v_add_f32_e32 v148, v192, v193
	v_add_f32_e32 v145, v195, v145
	v_sub_f32_e32 v149, v148, v192
	v_mul_f32_e32 v145, v150, v145
	v_sub_f32_e32 v149, v193, v149
	v_add_f32_e32 v145, v149, v145
	v_mul_f32_e32 v192, 0x3f317218, v144
	v_add_f32_e32 v149, v148, v145
	v_fma_f32 v193, v144, s94, -v192
	v_mul_f32_e32 v150, v149, v149
	v_fmac_f32_e32 v193, 0xb102e308, v144
	v_sub_f32_e32 v144, v149, v148
	v_fmamk_f32 v169, v150, 0x3e9b6dac, v183
	v_sub_f32_e32 v144, v145, v144
	v_add_f32_e32 v145, v192, v193
	v_fmaak_f32 v169, v150, v169, 0x3f2aaada
	v_sub_f32_e32 v148, v145, v192
	v_ldexp_f32 v192, v149, 1
	v_mul_f32_e32 v149, v149, v150
	v_mul_f32_e32 v149, v149, v169
	v_add_f32_e32 v150, v192, v149
	v_sub_f32_e32 v169, v150, v192
	v_ldexp_f32 v144, v144, 1
	v_sub_f32_e32 v149, v149, v169
	v_add_f32_e32 v144, v144, v149
	v_add_f32_e32 v149, v150, v144
	v_sub_f32_e32 v150, v149, v150
	v_sub_f32_e32 v144, v144, v150
	v_add_f32_e32 v150, v145, v149
	v_sub_f32_e32 v169, v150, v145
	v_sub_f32_e32 v192, v150, v169
	v_sub_f32_e32 v148, v193, v148
	v_sub_f32_e32 v145, v145, v192
	v_sub_f32_e32 v149, v149, v169
	v_add_f32_e32 v145, v149, v145
	v_add_f32_e32 v149, v148, v144
	v_sub_f32_e32 v169, v149, v148
	v_sub_f32_e32 v192, v149, v169
	v_sub_f32_e32 v148, v148, v192
	v_sub_f32_e32 v144, v144, v169
	v_add_f32_e32 v145, v149, v145
	v_add_f32_e32 v144, v144, v148
	v_add_f32_e32 v148, v150, v145
	v_sub_f32_e32 v149, v148, v150
	v_sub_f32_e32 v145, v145, v149
	v_add_f32_e32 v144, v144, v145
	v_add_f32_e32 v144, v148, v144
	v_cndmask_b32_e32 v144, v184, v144, vcc
	v_cmp_ngt_f32_e32 vcc, -1.0, v146
	v_mul_f32_e32 v124, 0x3fb8aa3b, v124
	v_exp_f32_e32 v124, v124
	v_cndmask_b32_e32 v144, v185, v144, vcc
	v_cmp_neq_f32_e32 vcc, -1.0, v146
	v_exp_f32_e32 v120, v120
	v_add_f32_e32 v121, v121, v45
	v_cndmask_b32_e32 v144, v186, v144, vcc
	v_cmp_lt_f32_e64 vcc, |v146|, s96
	v_add_f32_e32 v120, 1.0, v120
	v_rcp_f32_e32 v120, v120
	v_cndmask_b32_e32 v144, v144, v146, vcc
	v_mul_f32_e32 v150, 0xc1000000, v144
	v_mul_f32_e32 v144, 0xbfb8aa3b, v151
	v_exp_f32_e32 v146, v144
	v_mul_f32_e32 v121, 0xbfb8aa3b, v121
	v_exp_f32_e32 v121, v121
	v_add_f32_e32 v122, v122, v46
	v_add_f32_e32 v148, 1.0, v146
	v_add_f32_e32 v144, -1.0, v148
	v_sub_f32_e32 v145, v144, v148
	v_add_f32_e32 v145, 1.0, v145
	v_sub_f32_e32 v144, v146, v144
	v_add_f32_e32 v149, v144, v145
	v_frexp_mant_f32_e32 v144, v148
	v_cmp_gt_f32_e32 vcc, s93, v144
	v_cvt_f64_f32_e32 v[144:145], v148
	v_frexp_exp_i32_f64_e32 v144, v[144:145]
	v_subbrev_co_u32_e32 v144, vcc, 0, v144, vcc
	v_sub_u32_e32 v145, 0, v144
	v_ldexp_f32 v148, v148, v145
	v_ldexp_f32 v145, v149, v145
	v_add_f32_e32 v149, -1.0, v148
	v_add_f32_e32 v151, 1.0, v149
	v_sub_f32_e32 v151, v148, v151
	v_add_f32_e32 v151, v145, v151
	v_add_f32_e32 v169, v149, v151
	v_sub_f32_e32 v149, v169, v149
	v_sub_f32_e32 v149, v151, v149
	v_add_f32_e32 v151, 1.0, v148
	v_add_f32_e32 v192, -1.0, v151
	v_sub_f32_e32 v148, v148, v192
	v_add_f32_e32 v145, v145, v148
	v_add_f32_e32 v148, v151, v145
	v_sub_f32_e32 v151, v148, v151
	v_sub_f32_e32 v145, v145, v151
	v_rcp_f32_e32 v151, v148
	v_cvt_f32_i32_e32 v144, v144
	v_cmp_neq_f32_e32 vcc, s95, v146
	v_add_f32_e32 v121, 1.0, v121
	v_mul_f32_e32 v192, v169, v151
	v_mul_f32_e32 v193, v148, v192
	v_fma_f32 v194, v192, v148, -v193
	v_fmac_f32_e32 v194, v192, v145
	v_add_f32_e32 v195, v193, v194
	v_sub_f32_e32 v196, v169, v195
	v_sub_f32_e32 v169, v169, v196
	v_sub_f32_e32 v193, v195, v193
	v_sub_f32_e32 v169, v169, v195
	v_add_f32_e32 v149, v149, v169
	v_sub_f32_e32 v169, v193, v194
	v_add_f32_e32 v149, v169, v149
	v_add_f32_e32 v169, v196, v149
	v_mul_f32_e32 v193, v151, v169
	v_mul_f32_e32 v194, v148, v193
	v_fma_f32 v148, v193, v148, -v194
	v_fmac_f32_e32 v148, v193, v145
	v_sub_f32_e32 v145, v196, v169
	v_add_f32_e32 v145, v149, v145
	v_add_f32_e32 v149, v194, v148
	v_sub_f32_e32 v195, v169, v149
	v_sub_f32_e32 v169, v169, v195
	v_sub_f32_e32 v194, v149, v194
	v_sub_f32_e32 v149, v169, v149
	v_add_f32_e32 v145, v145, v149
	v_sub_f32_e32 v148, v194, v148
	v_add_f32_e32 v145, v148, v145
	v_add_f32_e32 v148, v192, v193
	v_add_f32_e32 v145, v195, v145
	v_sub_f32_e32 v149, v148, v192
	v_mul_f32_e32 v145, v151, v145
	v_sub_f32_e32 v149, v193, v149
	v_add_f32_e32 v145, v149, v145
	v_mul_f32_e32 v192, 0x3f317218, v144
	v_add_f32_e32 v149, v148, v145
	v_fma_f32 v193, v144, s94, -v192
	v_mul_f32_e32 v151, v149, v149
	v_fmac_f32_e32 v193, 0xb102e308, v144
	v_sub_f32_e32 v144, v149, v148
	v_fmamk_f32 v169, v151, 0x3e9b6dac, v183
	v_sub_f32_e32 v144, v145, v144
	v_add_f32_e32 v145, v192, v193
	v_fmaak_f32 v169, v151, v169, 0x3f2aaada
	v_sub_f32_e32 v148, v145, v192
	v_ldexp_f32 v192, v149, 1
	v_mul_f32_e32 v149, v149, v151
	v_mul_f32_e32 v149, v149, v169
	v_add_f32_e32 v151, v192, v149
	v_sub_f32_e32 v169, v151, v192
	v_ldexp_f32 v144, v144, 1
	v_sub_f32_e32 v149, v149, v169
	v_add_f32_e32 v144, v144, v149
	v_add_f32_e32 v149, v151, v144
	v_sub_f32_e32 v151, v149, v151
	v_sub_f32_e32 v144, v144, v151
	v_add_f32_e32 v151, v145, v149
	v_sub_f32_e32 v169, v151, v145
	v_sub_f32_e32 v192, v151, v169
	v_sub_f32_e32 v148, v193, v148
	v_sub_f32_e32 v145, v145, v192
	v_sub_f32_e32 v149, v149, v169
	v_add_f32_e32 v145, v149, v145
	v_add_f32_e32 v149, v148, v144
	v_sub_f32_e32 v169, v149, v148
	v_sub_f32_e32 v192, v149, v169
	v_sub_f32_e32 v148, v148, v192
	v_sub_f32_e32 v144, v144, v169
	v_add_f32_e32 v145, v149, v145
	v_add_f32_e32 v144, v144, v148
	v_add_f32_e32 v148, v151, v145
	v_sub_f32_e32 v149, v148, v151
	v_sub_f32_e32 v145, v145, v149
	v_add_f32_e32 v144, v144, v145
	v_add_f32_e32 v144, v148, v144
	v_cndmask_b32_e32 v144, v184, v144, vcc
	v_cmp_ngt_f32_e32 vcc, -1.0, v146
	v_rcp_f32_e32 v121, v121
	v_mul_f32_e32 v122, 0xbfb8aa3b, v122
	v_cndmask_b32_e32 v144, v185, v144, vcc
	v_cmp_neq_f32_e32 vcc, -1.0, v146
	v_exp_f32_e32 v122, v122
	v_add_f32_e32 v116, v116, v28
	v_cndmask_b32_e32 v144, v186, v144, vcc
	v_cmp_lt_f32_e64 vcc, |v146|, s96
	v_add_f32_e32 v122, 1.0, v122
	v_rcp_f32_e32 v122, v122
	v_cndmask_b32_e32 v144, v144, v146, vcc
	v_mul_f32_e32 v192, 0xc1000000, v144
	v_mul_f32_e32 v144, 0xbfb8aa3b, v147
	v_exp_f32_e32 v146, v144
	v_mul_f32_e32 v116, 0xbfb8aa3b, v116
	v_exp_f32_e32 v116, v116
	v_add_f32_e32 v123, v123, v47
	v_add_f32_e32 v147, 1.0, v146
	v_add_f32_e32 v144, -1.0, v147
	v_sub_f32_e32 v145, v144, v147
	v_add_f32_e32 v145, 1.0, v145
	v_sub_f32_e32 v144, v146, v144
	v_add_f32_e32 v148, v144, v145
	v_frexp_mant_f32_e32 v144, v147
	v_cmp_gt_f32_e32 vcc, s93, v144
	v_cvt_f64_f32_e32 v[144:145], v147
	v_frexp_exp_i32_f64_e32 v144, v[144:145]
	v_subbrev_co_u32_e32 v144, vcc, 0, v144, vcc
	v_sub_u32_e32 v145, 0, v144
	v_ldexp_f32 v147, v147, v145
	v_ldexp_f32 v145, v148, v145
	v_add_f32_e32 v148, -1.0, v147
	v_add_f32_e32 v149, 1.0, v148
	v_sub_f32_e32 v149, v147, v149
	v_add_f32_e32 v149, v145, v149
	v_add_f32_e32 v151, v148, v149
	v_sub_f32_e32 v148, v151, v148
	v_sub_f32_e32 v148, v149, v148
	v_add_f32_e32 v149, 1.0, v147
	v_add_f32_e32 v169, -1.0, v149
	v_sub_f32_e32 v147, v147, v169
	v_add_f32_e32 v145, v145, v147
	v_add_f32_e32 v147, v149, v145
	v_sub_f32_e32 v149, v147, v149
	v_sub_f32_e32 v145, v145, v149
	v_rcp_f32_e32 v149, v147
	v_cvt_f32_i32_e32 v144, v144
	v_cmp_neq_f32_e32 vcc, s95, v146
	v_add_f32_e32 v116, 1.0, v116
	v_mul_f32_e32 v169, v151, v149
	v_mul_f32_e32 v193, v147, v169
	v_fma_f32 v194, v169, v147, -v193
	v_fmac_f32_e32 v194, v169, v145
	v_add_f32_e32 v195, v193, v194
	v_sub_f32_e32 v196, v151, v195
	v_sub_f32_e32 v151, v151, v196
	v_sub_f32_e32 v193, v195, v193
	v_sub_f32_e32 v151, v151, v195
	v_add_f32_e32 v148, v148, v151
	v_sub_f32_e32 v151, v193, v194
	v_add_f32_e32 v148, v151, v148
	v_add_f32_e32 v151, v196, v148
	v_mul_f32_e32 v193, v149, v151
	v_mul_f32_e32 v194, v147, v193
	v_fma_f32 v147, v193, v147, -v194
	v_fmac_f32_e32 v147, v193, v145
	v_sub_f32_e32 v145, v196, v151
	v_add_f32_e32 v145, v148, v145
	v_add_f32_e32 v148, v194, v147
	v_sub_f32_e32 v195, v151, v148
	v_sub_f32_e32 v151, v151, v195
	v_sub_f32_e32 v194, v148, v194
	v_sub_f32_e32 v148, v151, v148
	v_add_f32_e32 v145, v145, v148
	v_sub_f32_e32 v147, v194, v147
	v_add_f32_e32 v145, v147, v145
	v_add_f32_e32 v147, v169, v193
	v_add_f32_e32 v145, v195, v145
	v_sub_f32_e32 v148, v147, v169
	v_mul_f32_e32 v145, v149, v145
	v_sub_f32_e32 v148, v193, v148
	v_add_f32_e32 v145, v148, v145
	v_mul_f32_e32 v169, 0x3f317218, v144
	v_add_f32_e32 v148, v147, v145
	v_fma_f32 v193, v144, s94, -v169
	v_mul_f32_e32 v149, v148, v148
	v_fmac_f32_e32 v193, 0xb102e308, v144
	v_sub_f32_e32 v144, v148, v147
	v_fmamk_f32 v151, v149, 0x3e9b6dac, v183
	v_sub_f32_e32 v144, v145, v144
	v_add_f32_e32 v145, v169, v193
	v_fmaak_f32 v151, v149, v151, 0x3f2aaada
	v_sub_f32_e32 v147, v145, v169
	v_ldexp_f32 v169, v148, 1
	v_mul_f32_e32 v148, v148, v149
	v_mul_f32_e32 v148, v148, v151
	v_add_f32_e32 v149, v169, v148
	v_sub_f32_e32 v151, v149, v169
	v_ldexp_f32 v144, v144, 1
	v_sub_f32_e32 v148, v148, v151
	v_add_f32_e32 v144, v144, v148
	v_add_f32_e32 v148, v149, v144
	v_sub_f32_e32 v149, v148, v149
	v_sub_f32_e32 v144, v144, v149
	v_add_f32_e32 v149, v145, v148
	v_sub_f32_e32 v151, v149, v145
	v_sub_f32_e32 v169, v149, v151
	v_sub_f32_e32 v147, v193, v147
	v_sub_f32_e32 v145, v145, v169
	v_sub_f32_e32 v148, v148, v151
	v_add_f32_e32 v145, v148, v145
	v_add_f32_e32 v148, v147, v144
	v_sub_f32_e32 v151, v148, v147
	v_sub_f32_e32 v169, v148, v151
	v_sub_f32_e32 v147, v147, v169
	v_sub_f32_e32 v144, v144, v151
	v_add_f32_e32 v145, v148, v145
	v_add_f32_e32 v144, v144, v147
	v_add_f32_e32 v147, v149, v145
	v_sub_f32_e32 v148, v147, v149
	v_sub_f32_e32 v145, v145, v148
	v_add_f32_e32 v144, v144, v145
	v_add_f32_e32 v144, v147, v144
	v_cndmask_b32_e32 v144, v184, v144, vcc
	v_cmp_ngt_f32_e32 vcc, -1.0, v146
	v_ashrrev_i32_e32 v169, 31, v168
	v_mul_f32_e32 v123, 0xbfb8aa3b, v123
	v_cndmask_b32_e32 v144, v185, v144, vcc
	v_cmp_neq_f32_e32 vcc, -1.0, v146
	v_rcp_f32_e32 v116, v116
	v_exp_f32_e32 v123, v123
	v_cndmask_b32_e32 v144, v186, v144, vcc
	v_cmp_lt_f32_e64 vcc, |v146|, s96
	v_mul_f32_e32 v116, v116, v188
	v_add_f32_e32 v123, 1.0, v123
	v_cndmask_b32_e32 v144, v144, v146, vcc
	v_mul_f32_e32 v151, 0xc1000000, v144
	v_lshlrev_b64 v[144:145], 10, v[168:169]
	v_lshl_add_u64 v[144:145], v[144:145], 0, v[166:167]
	v_lshlrev_b64 v[148:149], 1, v[144:145]
	v_lshl_add_u64 v[144:145], s[30:31], 0, v[148:149]
	global_load_dwordx4 v[144:147], v[144:145], off
	v_mul_f32_e32 v116, 0x3fb8aa3b, v116
	v_rcp_f32_e32 v123, v123
	v_add_f32_e32 v112, v112, v32
	v_exp_f32_e32 v116, v116
	v_mul_f32_e32 v112, 0xbfb8aa3b, v112
	v_exp_f32_e32 v112, v112
	v_add_f32_e32 v113, v113, v33
	v_mul_f32_e32 v113, 0xbfb8aa3b, v113
	v_exp_f32_e32 v113, v113
	v_add_f32_e32 v112, 1.0, v112
	v_rcp_f32_e32 v112, v112
	v_add_f32_e32 v108, v108, v40
	v_add_f32_e32 v113, 1.0, v113
	v_rcp_f32_e32 v113, v113
	v_mul_f32_e32 v108, 0xbfb8aa3b, v108
	v_exp_f32_e32 v108, v108
	v_add_f32_e32 v104, v104, v44
	v_mul_f32_e32 v104, 0xbfb8aa3b, v104
	v_exp_f32_e32 v104, v104
	v_add_f32_e32 v108, 1.0, v108
	v_rcp_f32_e32 v108, v108
	v_add_f32_e32 v105, v105, v45
	v_add_f32_e32 v104, 1.0, v104
	v_rcp_f32_e32 v104, v104
	v_mul_f32_e32 v108, v108, v187
	v_mul_f32_e32 v108, 0x3fb8aa3b, v108
	v_exp_f32_e32 v108, v108
	v_mul_f32_e32 v105, 0xbfb8aa3b, v105
	v_exp_f32_e32 v105, v105
	v_add_f32_e32 v106, v106, v46
	v_mul_f32_e32 v106, 0xbfb8aa3b, v106
	v_exp_f32_e32 v106, v106
	v_add_f32_e32 v105, 1.0, v105
	v_rcp_f32_e32 v105, v105
	v_add_f32_e32 v100, v100, v28
	v_add_f32_e32 v106, 1.0, v106
	v_rcp_f32_e32 v106, v106
	v_mul_f32_e32 v100, 0xbfb8aa3b, v100
	v_exp_f32_e32 v100, v100
	v_add_f32_e32 v107, v107, v47
	v_mul_f32_e32 v107, 0xbfb8aa3b, v107
	v_exp_f32_e32 v107, v107
	v_add_f32_e32 v100, 1.0, v100
	v_rcp_f32_e32 v100, v100
	v_add_f32_e32 v96, v96, v32
	v_add_f32_e32 v107, 1.0, v107
	v_rcp_f32_e32 v107, v107
	v_mul_f32_e32 v100, v100, v188
	v_mul_f32_e32 v100, 0x3fb8aa3b, v100
	v_exp_f32_e32 v100, v100
	v_mul_f32_e32 v96, 0xbfb8aa3b, v96
	v_exp_f32_e32 v96, v96
	v_add_f32_e32 v97, v97, v33
	v_mul_f32_e32 v97, 0xbfb8aa3b, v97
	v_exp_f32_e32 v97, v97
	v_add_f32_e32 v96, 1.0, v96
	v_rcp_f32_e32 v96, v96
	v_add_f32_e32 v92, v92, v40
	v_add_f32_e32 v97, 1.0, v97
	v_rcp_f32_e32 v97, v97
	v_mul_f32_e32 v92, 0xbfb8aa3b, v92
	v_exp_f32_e32 v92, v92
	v_add_f32_e32 v88, v88, v44
	v_mul_f32_e32 v88, 0xbfb8aa3b, v88
	v_exp_f32_e32 v88, v88
	v_add_f32_e32 v92, 1.0, v92
	v_rcp_f32_e32 v92, v92
	v_add_f32_e32 v89, v89, v45
	v_add_f32_e32 v88, 1.0, v88
	v_rcp_f32_e32 v88, v88
	v_mul_f32_e32 v92, v92, v187
	v_mul_f32_e32 v92, 0x3fb8aa3b, v92
	v_exp_f32_e32 v92, v92
	v_mul_f32_e32 v89, 0xbfb8aa3b, v89
	v_exp_f32_e32 v89, v89
	v_add_f32_e32 v90, v90, v46
	v_mul_f32_e32 v90, 0xbfb8aa3b, v90
	v_exp_f32_e32 v90, v90
	v_add_f32_e32 v89, 1.0, v89
	s_waitcnt vmcnt(0)
	v_lshlrev_b32_e32 v169, 16, v144
	v_and_b32_e32 v193, 0xffff0000, v144
	v_lshlrev_b32_e32 v196, 16, v147
	v_and_b32_e32 v144, 0xffff0000, v147
	v_sub_f32_e32 v147, 1.0, v140
	v_add_f32_e32 v140, 1.0, v140
	v_mul_f32_e32 v140, v147, v140
	v_max_f32_e32 v140, 0, v140
	v_sqrt_f32_e32 v140, v140
	v_lshlrev_b32_e32 v194, 16, v145
	v_and_b32_e32 v145, 0xffff0000, v145
	v_lshlrev_b32_e32 v195, 16, v146
	v_mul_f32_e32 v136, v136, v140
	v_add_f32_e32 v140, v141, v41
	v_mul_f32_e32 v140, 0xbfb8aa3b, v140
	v_exp_f32_e32 v140, v140
	v_and_b32_e32 v146, 0xffff0000, v146
	v_mul_f32_e32 v136, v136, v169
	v_rcp_f32_e32 v89, v89
	v_add_f32_e32 v140, 1.0, v140
	v_rcp_f32_e32 v140, v140
	v_add_f32_e32 v90, 1.0, v90
	v_rcp_f32_e32 v90, v90
	v_add_f32_e32 v84, v84, v28
	v_mul_f32_e32 v140, v140, v190
	v_mul_f32_e32 v140, 0x3fb8aa3b, v140
	v_exp_f32_e32 v140, v140
	v_mul_f32_e32 v84, 0xbfb8aa3b, v84
	v_exp_f32_e32 v84, v84
	v_add_f32_e32 v91, v91, v47
	v_sub_f32_e32 v141, 1.0, v140
	v_add_f32_e32 v140, 1.0, v140
	v_mul_f32_e32 v140, v141, v140
	v_max_f32_e32 v140, 0, v140
	v_sqrt_f32_e32 v140, v140
	v_add_f32_e32 v84, 1.0, v84
	v_mul_f32_e32 v91, 0xbfb8aa3b, v91
	v_rcp_f32_e32 v84, v84
	v_mul_f32_e32 v137, v137, v140
	v_add_f32_e32 v140, v142, v42
	v_mul_f32_e32 v140, 0xbfb8aa3b, v140
	v_exp_f32_e32 v140, v140
	v_mul_f32_e32 v137, v137, v193
	v_exp_f32_e32 v91, v91
	v_mul_f32_e32 v84, v84, v188
	v_add_f32_e32 v140, 1.0, v140
	v_rcp_f32_e32 v140, v140
	v_add_f32_e32 v91, 1.0, v91
	v_mul_f32_e32 v84, 0x3fb8aa3b, v84
	v_rcp_f32_e32 v91, v91
	v_mul_f32_e32 v140, v140, v191
	v_mul_f32_e32 v140, 0x3fb8aa3b, v140
	v_exp_f32_e32 v140, v140
	v_add_f32_e32 v80, v80, v32
	v_exp_f32_e32 v84, v84
	v_mul_f32_e32 v80, 0xbfb8aa3b, v80
	v_sub_f32_e32 v142, 1.0, v140
	v_add_f32_e32 v140, 1.0, v140
	v_mul_f32_e32 v140, v142, v140
	v_max_f32_e32 v140, 0, v140
	v_sqrt_f32_e32 v140, v140
	v_exp_f32_e32 v80, v80
	v_add_f32_e32 v81, v81, v33
	v_mul_f32_e32 v81, 0xbfb8aa3b, v81
	v_mul_f32_e32 v138, v138, v140
	v_add_f32_e32 v140, v143, v43
	v_mul_f32_e32 v140, 0xbfb8aa3b, v140
	v_exp_f32_e32 v140, v140
	v_mul_f32_e32 v138, v138, v194
	v_add_f32_e32 v80, 1.0, v80
	v_rcp_f32_e32 v80, v80
	v_add_f32_e32 v140, 1.0, v140
	v_rcp_f32_e32 v140, v140
	v_exp_f32_e32 v81, v81
	v_add_f32_e32 v76, v76, v40
	v_mul_f32_e32 v76, 0xbfb8aa3b, v76
	v_mul_f32_e32 v140, v140, v192
	v_mul_f32_e32 v140, 0x3fb8aa3b, v140
	v_exp_f32_e32 v140, v140
	v_add_f32_e32 v81, 1.0, v81
	v_rcp_f32_e32 v81, v81
	v_exp_f32_e32 v76, v76
	v_sub_f32_e32 v143, 1.0, v140
	v_add_f32_e32 v140, 1.0, v140
	v_mul_f32_e32 v140, v143, v140
	v_max_f32_e32 v140, 0, v140
	v_sqrt_f32_e32 v140, v140
	v_add_f32_e32 v76, 1.0, v76
	v_rcp_f32_e32 v76, v76
	v_add_f32_e32 v72, v72, v44
	v_mul_f32_e32 v139, v139, v140
	v_sub_f32_e32 v140, 1.0, v132
	v_add_f32_e32 v132, 1.0, v132
	v_mul_f32_e32 v132, v140, v132
	v_max_f32_e32 v132, 0, v132
	v_sqrt_f32_e32 v132, v132
	v_mul_f32_e32 v139, v139, v145
	v_mul_f32_e32 v76, v76, v187
	v_mul_f32_e32 v76, 0x3fb8aa3b, v76
	v_mul_f32_e32 v128, v128, v132
	v_mul_f32_e32 v145, v128, v195
	v_add_f32_e32 v128, v133, v29
	v_mul_f32_e32 v128, 0xbfb8aa3b, v128
	v_exp_f32_e32 v128, v128
	v_exp_f32_e32 v76, v76
	v_mul_f32_e32 v72, 0xbfb8aa3b, v72
	v_exp_f32_e32 v72, v72
	v_add_f32_e32 v128, 1.0, v128
	v_rcp_f32_e32 v128, v128
	v_add_f32_e32 v73, v73, v45
	v_add_f32_e32 v72, 1.0, v72
	v_rcp_f32_e32 v72, v72
	v_mul_f32_e32 v128, v128, v189
	v_mul_f32_e32 v128, 0x3fb8aa3b, v128
	v_exp_f32_e32 v128, v128
	v_mul_f32_e32 v73, 0xbfb8aa3b, v73
	v_exp_f32_e32 v73, v73
	v_add_f32_e32 v74, v74, v46
	v_sub_f32_e32 v132, 1.0, v128
	v_add_f32_e32 v128, 1.0, v128
	v_mul_f32_e32 v128, v132, v128
	v_max_f32_e32 v128, 0, v128
	v_sqrt_f32_e32 v128, v128
	v_add_f32_e32 v73, 1.0, v73
	v_rcp_f32_e32 v73, v73
	v_mul_f32_e32 v74, 0xbfb8aa3b, v74
	v_mul_f32_e32 v128, v129, v128
	v_mul_f32_e32 v146, v128, v146
	v_add_f32_e32 v128, v134, v30
	v_mul_f32_e32 v128, 0xbfb8aa3b, v128
	v_exp_f32_e32 v128, v128
	v_add_f32_e32 v129, v130, v34
	v_mul_f32_e32 v129, 0xbfb8aa3b, v129
	v_exp_f32_e32 v129, v129
	v_add_f32_e32 v128, 1.0, v128
	v_rcp_f32_e32 v128, v128
	v_exp_f32_e32 v74, v74
	v_add_f32_e32 v129, 1.0, v129
	v_rcp_f32_e32 v129, v129
	v_mul_f32_e32 v128, v128, v150
	v_mul_f32_e32 v128, 0x3fb8aa3b, v128
	v_exp_f32_e32 v128, v128
	v_add_f32_e32 v74, 1.0, v74
	v_rcp_f32_e32 v74, v74
	v_add_f32_e32 v68, v68, v28
	v_sub_f32_e32 v133, 1.0, v128
	v_add_f32_e32 v128, 1.0, v128
	v_mul_f32_e32 v128, v133, v128
	v_max_f32_e32 v128, 0, v128
	v_sqrt_f32_e32 v128, v128
	v_mul_f32_e32 v68, 0xbfb8aa3b, v68
	v_exp_f32_e32 v68, v68
	v_add_f32_e32 v75, v75, v47
	v_mul_f32_e32 v128, v129, v128
	v_mul_f32_e32 v134, v128, v196
	v_add_f32_e32 v128, v135, v31
	v_mul_f32_e32 v128, 0xbfb8aa3b, v128
	v_exp_f32_e32 v128, v128
	v_add_f32_e32 v129, v131, v35
	v_mul_f32_e32 v129, 0xbfb8aa3b, v129
	v_exp_f32_e32 v129, v129
	v_add_f32_e32 v128, 1.0, v128
	v_rcp_f32_e32 v128, v128
	v_add_f32_e32 v68, 1.0, v68
	v_add_f32_e32 v129, 1.0, v129
	v_rcp_f32_e32 v129, v129
	v_mul_f32_e32 v128, v128, v151
	v_mul_f32_e32 v128, 0x3fb8aa3b, v128
	v_exp_f32_e32 v128, v128
	v_mul_f32_e32 v75, 0xbfb8aa3b, v75
	v_rcp_f32_e32 v68, v68
	v_exp_f32_e32 v75, v75
	v_sub_f32_e32 v131, 1.0, v128
	v_add_f32_e32 v128, 1.0, v128
	v_mul_f32_e32 v128, v131, v128
	v_max_f32_e32 v128, 0, v128
	v_sqrt_f32_e32 v128, v128
	v_mul_f32_e32 v68, v68, v188
	v_add_f32_e32 v75, 1.0, v75
	v_mul_f32_e32 v68, 0x3fb8aa3b, v68
	v_mul_f32_e32 v128, v129, v128
	v_mul_f32_e32 v135, v128, v144
	v_cvt_pk_bf16_f32 v128, v147, v141
	v_cvt_pk_bf16_f32 v129, v142, v143
	v_cvt_pk_bf16_f32 v130, v140, v132
	v_cvt_pk_bf16_f32 v131, v133, v131
	v_lshl_add_u64 v[132:133], s[20:21], 0, v[148:149]
	global_store_dwordx4 v[132:133], v[128:131], off sc0 sc1
	s_nop 1
	v_cvt_pk_bf16_f32 v128, v136, v137
	v_cvt_pk_bf16_f32 v129, v138, v139
	v_cvt_pk_bf16_f32 v130, v145, v146
	v_cvt_pk_bf16_f32 v131, v134, v135
	v_lshl_add_u64 v[132:133], s[34:35], 0, v[148:149]
	global_store_dwordx4 v[132:133], v[128:131], off sc0 sc1
	s_nop 1
	v_or_b32_e32 v128, 16, v168
	v_ashrrev_i32_e32 v129, 31, v128
	v_lshlrev_b64 v[128:129], 10, v[128:129]
	v_lshl_add_u64 v[128:129], v[128:129], 0, v[166:167]
	v_lshlrev_b64 v[128:129], 1, v[128:129]
	v_lshl_add_u64 v[130:131], s[30:31], 0, v[128:129]
	global_load_dwordx4 v[130:133], v[130:131], off
	v_rcp_f32_e32 v75, v75
	v_add_f32_e32 v64, v64, v32
	v_exp_f32_e32 v68, v68
	v_mul_f32_e32 v64, 0xbfb8aa3b, v64
	v_exp_f32_e32 v64, v64
	v_add_f32_e32 v65, v65, v33
	v_mul_f32_e32 v65, 0xbfb8aa3b, v65
	v_exp_f32_e32 v65, v65
	v_add_f32_e32 v64, 1.0, v64
	v_rcp_f32_e32 v64, v64
	v_add_f32_e32 v60, v60, v40
	v_add_f32_e32 v65, 1.0, v65
	v_rcp_f32_e32 v65, v65
	v_mul_f32_e32 v60, 0xbfb8aa3b, v60
	v_exp_f32_e32 v60, v60
	v_add_f32_e32 v56, v56, v44
	v_mul_f32_e32 v56, 0xbfb8aa3b, v56
	v_exp_f32_e32 v56, v56
	v_add_f32_e32 v60, 1.0, v60
	v_rcp_f32_e32 v60, v60
	v_add_f32_e32 v57, v57, v45
	v_add_f32_e32 v56, 1.0, v56
	v_rcp_f32_e32 v56, v56
	v_mul_f32_e32 v60, v60, v187
	v_mul_f32_e32 v60, 0x3fb8aa3b, v60
	v_exp_f32_e32 v60, v60
	v_mul_f32_e32 v57, 0xbfb8aa3b, v57
	v_exp_f32_e32 v57, v57
	v_add_f32_e32 v58, v58, v46
	v_mul_f32_e32 v58, 0xbfb8aa3b, v58
	v_exp_f32_e32 v58, v58
	v_add_f32_e32 v57, 1.0, v57
	v_rcp_f32_e32 v57, v57
	v_add_f32_e32 v52, v52, v28
	v_add_f32_e32 v58, 1.0, v58
	v_rcp_f32_e32 v58, v58
	v_mul_f32_e32 v52, 0xbfb8aa3b, v52
	v_exp_f32_e32 v52, v52
	v_add_f32_e32 v59, v59, v47
	v_mul_f32_e32 v59, 0xbfb8aa3b, v59
	v_exp_f32_e32 v59, v59
	v_add_f32_e32 v52, 1.0, v52
	v_rcp_f32_e32 v52, v52
	v_add_f32_e32 v48, v48, v32
	v_add_f32_e32 v59, 1.0, v59
	v_rcp_f32_e32 v59, v59
	v_mul_f32_e32 v52, v52, v188
	v_mul_f32_e32 v52, 0x3fb8aa3b, v52
	v_exp_f32_e32 v52, v52
	v_mul_f32_e32 v48, 0xbfb8aa3b, v48
	v_exp_f32_e32 v48, v48
	v_add_f32_e32 v49, v49, v33
	v_mul_f32_e32 v49, 0xbfb8aa3b, v49
	v_exp_f32_e32 v49, v49
	v_add_f32_e32 v48, 1.0, v48
	v_rcp_f32_e32 v48, v48
	v_add_f32_e32 v36, v36, v40
	v_add_f32_e32 v49, 1.0, v49
	v_rcp_f32_e32 v49, v49
	v_mul_f32_e32 v36, 0xbfb8aa3b, v36
	v_exp_f32_e32 v36, v36
	v_add_f32_e32 v24, v24, v44
	v_mul_f32_e32 v24, 0xbfb8aa3b, v24
	v_exp_f32_e32 v24, v24
	v_add_f32_e32 v36, 1.0, v36
	v_rcp_f32_e32 v36, v36
	v_add_f32_e32 v25, v25, v45
	v_add_f32_e32 v24, 1.0, v24
	v_rcp_f32_e32 v24, v24
	v_mul_f32_e32 v36, v36, v187
	v_mul_f32_e32 v36, 0x3fb8aa3b, v36
	v_exp_f32_e32 v36, v36
	v_mul_f32_e32 v25, 0xbfb8aa3b, v25
	v_exp_f32_e32 v25, v25
	v_add_f32_e32 v26, v26, v46
	v_mul_f32_e32 v26, 0xbfb8aa3b, v26
	v_exp_f32_e32 v26, v26
	v_add_f32_e32 v25, 1.0, v25
	v_rcp_f32_e32 v25, v25
	s_waitcnt vmcnt(0)
	v_lshlrev_b32_e32 v134, 16, v130
	v_and_b32_e32 v135, 0xffff0000, v130
	v_lshlrev_b32_e32 v138, 16, v133
	v_and_b32_e32 v130, 0xffff0000, v133
	v_sub_f32_e32 v133, 1.0, v124
	v_add_f32_e32 v124, 1.0, v124
	v_mul_f32_e32 v124, v133, v124
	v_max_f32_e32 v124, 0, v124
	v_sqrt_f32_e32 v124, v124
	v_lshlrev_b32_e32 v136, 16, v131
	v_and_b32_e32 v131, 0xffff0000, v131
	v_lshlrev_b32_e32 v137, 16, v132
	v_mul_f32_e32 v120, v120, v124
	v_add_f32_e32 v124, v125, v41
	v_mul_f32_e32 v124, 0xbfb8aa3b, v124
	v_exp_f32_e32 v124, v124
	v_and_b32_e32 v132, 0xffff0000, v132
	v_mul_f32_e32 v120, v120, v134
	v_add_f32_e32 v26, 1.0, v26
	v_add_f32_e32 v124, 1.0, v124
	v_rcp_f32_e32 v124, v124
	v_rcp_f32_e32 v26, v26
	v_add_f32_e32 v20, v20, v28
	v_mul_f32_e32 v20, 0xbfb8aa3b, v20
	v_mul_f32_e32 v124, v124, v190
	v_mul_f32_e32 v124, 0x3fb8aa3b, v124
	v_exp_f32_e32 v124, v124
	v_exp_f32_e32 v20, v20
	v_add_f32_e32 v27, v27, v47
	v_mul_f32_e32 v27, 0xbfb8aa3b, v27
	v_sub_f32_e32 v125, 1.0, v124
	v_add_f32_e32 v124, 1.0, v124
	v_mul_f32_e32 v124, v125, v124
	v_max_f32_e32 v124, 0, v124
	v_sqrt_f32_e32 v124, v124
	v_add_f32_e32 v20, 1.0, v20
	v_rcp_f32_e32 v20, v20
	v_exp_f32_e32 v27, v27
	v_mul_f32_e32 v121, v121, v124
	v_add_f32_e32 v124, v126, v42
	v_mul_f32_e32 v124, 0xbfb8aa3b, v124
	v_exp_f32_e32 v124, v124
	v_mul_f32_e32 v121, v121, v135
	v_mul_f32_e32 v20, v20, v188
	v_add_f32_e32 v27, 1.0, v27
	v_add_f32_e32 v124, 1.0, v124
	v_rcp_f32_e32 v124, v124
	v_mul_f32_e32 v20, 0x3fb8aa3b, v20
	v_rcp_f32_e32 v27, v27
	v_add_f32_e32 v16, v16, v32
	v_mul_f32_e32 v124, v124, v191
	v_mul_f32_e32 v124, 0x3fb8aa3b, v124
	v_exp_f32_e32 v124, v124
	v_exp_f32_e32 v20, v20
	v_mul_f32_e32 v16, 0xbfb8aa3b, v16
	v_exp_f32_e32 v16, v16
	v_sub_f32_e32 v126, 1.0, v124
	v_add_f32_e32 v124, 1.0, v124
	v_mul_f32_e32 v124, v126, v124
	v_max_f32_e32 v124, 0, v124
	v_sqrt_f32_e32 v124, v124
	v_add_f32_e32 v16, 1.0, v16
	v_rcp_f32_e32 v16, v16
	v_add_f32_e32 v17, v17, v33
	v_mul_f32_e32 v122, v122, v124
	v_add_f32_e32 v124, v127, v43
	v_mul_f32_e32 v124, 0xbfb8aa3b, v124
	v_exp_f32_e32 v124, v124
	v_mul_f32_e32 v122, v122, v136
	v_mul_f32_e32 v17, 0xbfb8aa3b, v17
	v_exp_f32_e32 v17, v17
	v_add_f32_e32 v124, 1.0, v124
	v_rcp_f32_e32 v124, v124
	v_add_f32_e32 v12, v12, v40
	v_add_f32_e32 v17, 1.0, v17
	v_rcp_f32_e32 v17, v17
	v_mul_f32_e32 v124, v124, v192
	v_mul_f32_e32 v124, 0x3fb8aa3b, v124
	v_exp_f32_e32 v124, v124
	v_mul_f32_e32 v12, 0xbfb8aa3b, v12
	v_exp_f32_e32 v12, v12
	v_add_f32_e32 v8, v8, v44
	v_sub_f32_e32 v127, 1.0, v124
	v_add_f32_e32 v124, 1.0, v124
	v_mul_f32_e32 v124, v127, v124
	v_max_f32_e32 v124, 0, v124
	v_sqrt_f32_e32 v124, v124
	v_add_f32_e32 v12, 1.0, v12
	v_rcp_f32_e32 v12, v12
	v_mul_f32_e32 v8, 0xbfb8aa3b, v8
	v_mul_f32_e32 v123, v123, v124
	v_sub_f32_e32 v124, 1.0, v116
	v_add_f32_e32 v116, 1.0, v116
	v_mul_f32_e32 v116, v124, v116
	v_max_f32_e32 v116, 0, v116
	v_sqrt_f32_e32 v116, v116
	v_mul_f32_e32 v123, v123, v131
	v_mul_f32_e32 v12, v12, v187
	v_mul_f32_e32 v12, 0x3fb8aa3b, v12
	v_mul_f32_e32 v112, v112, v116
	v_mul_f32_e32 v131, v112, v137
	v_add_f32_e32 v112, v117, v29
	v_mul_f32_e32 v112, 0xbfb8aa3b, v112
	v_exp_f32_e32 v112, v112
	v_exp_f32_e32 v12, v12
	v_exp_f32_e32 v8, v8
	v_add_f32_e32 v9, v9, v45
	v_add_f32_e32 v112, 1.0, v112
	v_rcp_f32_e32 v112, v112
	v_add_f32_e32 v8, 1.0, v8
	v_rcp_f32_e32 v8, v8
	v_mul_f32_e32 v9, 0xbfb8aa3b, v9
	v_mul_f32_e32 v112, v112, v189
	v_mul_f32_e32 v112, 0x3fb8aa3b, v112
	v_exp_f32_e32 v112, v112
	v_exp_f32_e32 v9, v9
	v_add_f32_e32 v10, v10, v46
	v_mul_f32_e32 v10, 0xbfb8aa3b, v10
	v_sub_f32_e32 v116, 1.0, v112
	v_add_f32_e32 v112, 1.0, v112
	v_mul_f32_e32 v112, v116, v112
	v_max_f32_e32 v112, 0, v112
	v_sqrt_f32_e32 v112, v112
	v_add_f32_e32 v9, 1.0, v9
	v_rcp_f32_e32 v9, v9
	v_exp_f32_e32 v10, v10
	v_mul_f32_e32 v112, v113, v112
	v_mul_f32_e32 v132, v112, v132
	v_add_f32_e32 v112, v118, v30
	v_mul_f32_e32 v112, 0xbfb8aa3b, v112
	v_exp_f32_e32 v112, v112
	v_add_f32_e32 v113, v114, v34
	v_mul_f32_e32 v113, 0xbfb8aa3b, v113
	v_exp_f32_e32 v113, v113
	v_add_f32_e32 v112, 1.0, v112
	v_rcp_f32_e32 v112, v112
	v_add_f32_e32 v10, 1.0, v10
	v_add_f32_e32 v113, 1.0, v113
	v_rcp_f32_e32 v113, v113
	v_mul_f32_e32 v112, v112, v150
	v_mul_f32_e32 v112, 0x3fb8aa3b, v112
	v_exp_f32_e32 v112, v112
	v_rcp_f32_e32 v10, v10
	v_add_f32_e32 v4, v4, v28
	v_mul_f32_e32 v4, 0xbfb8aa3b, v4
	v_sub_f32_e32 v117, 1.0, v112
	v_add_f32_e32 v112, 1.0, v112
	v_mul_f32_e32 v112, v117, v112
	v_max_f32_e32 v112, 0, v112
	v_sqrt_f32_e32 v112, v112
	v_exp_f32_e32 v4, v4
	v_add_f32_e32 v11, v11, v47
	v_mul_f32_e32 v11, 0xbfb8aa3b, v11
	v_mul_f32_e32 v112, v113, v112
	v_mul_f32_e32 v118, v112, v138
	v_add_f32_e32 v112, v119, v31
	v_mul_f32_e32 v112, 0xbfb8aa3b, v112
	v_exp_f32_e32 v112, v112
	v_add_f32_e32 v113, v115, v35
	v_mul_f32_e32 v113, 0xbfb8aa3b, v113
	v_exp_f32_e32 v113, v113
	v_add_f32_e32 v112, 1.0, v112
	v_rcp_f32_e32 v112, v112
	v_add_f32_e32 v4, 1.0, v4
	v_add_f32_e32 v113, 1.0, v113
	v_rcp_f32_e32 v113, v113
	v_mul_f32_e32 v112, v112, v151
	v_mul_f32_e32 v112, 0x3fb8aa3b, v112
	v_exp_f32_e32 v112, v112
	v_rcp_f32_e32 v4, v4
	v_exp_f32_e32 v11, v11
	v_add_f32_e32 v0, v0, v32
	v_sub_f32_e32 v115, 1.0, v112
	v_add_f32_e32 v112, 1.0, v112
	v_mul_f32_e32 v112, v115, v112
	v_max_f32_e32 v112, 0, v112
	v_sqrt_f32_e32 v112, v112
	v_mul_f32_e32 v4, v4, v188
	v_add_f32_e32 v11, 1.0, v11
	v_mul_f32_e32 v4, 0x3fb8aa3b, v4
	v_mul_f32_e32 v112, v113, v112
	v_mul_f32_e32 v119, v112, v130
	v_cvt_pk_bf16_f32 v112, v133, v125
	v_cvt_pk_bf16_f32 v113, v126, v127
	v_cvt_pk_bf16_f32 v114, v124, v116
	v_cvt_pk_bf16_f32 v115, v117, v115
	v_lshl_add_u64 v[116:117], s[20:21], 0, v[128:129]
	global_store_dwordx4 v[116:117], v[112:115], off sc0 sc1
	s_nop 1
	v_cvt_pk_bf16_f32 v112, v120, v121
	v_cvt_pk_bf16_f32 v113, v122, v123
	v_cvt_pk_bf16_f32 v114, v131, v132
	v_cvt_pk_bf16_f32 v115, v118, v119
	v_lshl_add_u64 v[116:117], s[34:35], 0, v[128:129]
	global_store_dwordx4 v[116:117], v[112:115], off sc0 sc1
	s_nop 1
	v_or_b32_e32 v112, 32, v168
	v_ashrrev_i32_e32 v113, 31, v112
	v_lshlrev_b64 v[112:113], 10, v[112:113]
	v_lshl_add_u64 v[112:113], v[112:113], 0, v[166:167]
	v_lshlrev_b64 v[112:113], 1, v[112:113]
	v_lshl_add_u64 v[114:115], s[30:31], 0, v[112:113]
	global_load_dwordx4 v[114:117], v[114:115], off
	v_rcp_f32_e32 v11, v11
	v_exp_f32_e32 v4, v4
	v_mul_f32_e32 v0, 0xbfb8aa3b, v0
	v_exp_f32_e32 v0, v0
	v_add_f32_e32 v1, v1, v33
	v_mul_f32_e32 v1, 0xbfb8aa3b, v1
	v_exp_f32_e32 v1, v1
	v_add_f32_e32 v0, 1.0, v0
	v_rcp_f32_e32 v0, v0
	v_add_f32_e32 v1, 1.0, v1
	v_rcp_f32_e32 v1, v1
	s_waitcnt vmcnt(0)
	v_lshlrev_b32_e32 v118, 16, v114
	v_and_b32_e32 v119, 0xffff0000, v114
	v_lshlrev_b32_e32 v122, 16, v117
	v_and_b32_e32 v114, 0xffff0000, v117
	v_sub_f32_e32 v117, 1.0, v108
	v_add_f32_e32 v108, 1.0, v108
	v_mul_f32_e32 v108, v117, v108
	v_max_f32_e32 v108, 0, v108
	v_sqrt_f32_e32 v108, v108
	v_lshlrev_b32_e32 v120, 16, v115
	v_and_b32_e32 v115, 0xffff0000, v115
	v_lshlrev_b32_e32 v121, 16, v116
	v_mul_f32_e32 v104, v104, v108
	v_add_f32_e32 v108, v109, v41
	v_mul_f32_e32 v108, 0xbfb8aa3b, v108
	v_exp_f32_e32 v108, v108
	v_and_b32_e32 v116, 0xffff0000, v116
	v_mul_f32_e32 v104, v104, v118
	v_add_f32_e32 v108, 1.0, v108
	v_rcp_f32_e32 v108, v108
	s_nop 0
	v_mul_f32_e32 v108, v108, v190
	v_mul_f32_e32 v108, 0x3fb8aa3b, v108
	v_exp_f32_e32 v108, v108
	s_nop 0
	v_sub_f32_e32 v109, 1.0, v108
	v_add_f32_e32 v108, 1.0, v108
	v_mul_f32_e32 v108, v109, v108
	v_max_f32_e32 v108, 0, v108
	v_sqrt_f32_e32 v108, v108
	s_nop 0
	v_mul_f32_e32 v105, v105, v108
	v_add_f32_e32 v108, v110, v42
	v_mul_f32_e32 v108, 0xbfb8aa3b, v108
	v_exp_f32_e32 v108, v108
	v_mul_f32_e32 v105, v105, v119
	v_add_f32_e32 v108, 1.0, v108
	v_rcp_f32_e32 v108, v108
	s_nop 0
	v_mul_f32_e32 v108, v108, v191
	v_mul_f32_e32 v108, 0x3fb8aa3b, v108
	v_exp_f32_e32 v108, v108
	s_nop 0
	v_sub_f32_e32 v110, 1.0, v108
	v_add_f32_e32 v108, 1.0, v108
	v_mul_f32_e32 v108, v110, v108
	v_max_f32_e32 v108, 0, v108
	v_sqrt_f32_e32 v108, v108
	s_nop 0
	v_mul_f32_e32 v106, v106, v108
	v_add_f32_e32 v108, v111, v43
	v_mul_f32_e32 v108, 0xbfb8aa3b, v108
	v_exp_f32_e32 v108, v108
	v_mul_f32_e32 v106, v106, v120
	v_add_f32_e32 v108, 1.0, v108
	v_rcp_f32_e32 v108, v108
	s_nop 0
	v_mul_f32_e32 v108, v108, v192
	v_mul_f32_e32 v108, 0x3fb8aa3b, v108
	v_exp_f32_e32 v108, v108
	s_nop 0
	v_sub_f32_e32 v111, 1.0, v108
	v_add_f32_e32 v108, 1.0, v108
	v_mul_f32_e32 v108, v111, v108
	v_max_f32_e32 v108, 0, v108
	v_sqrt_f32_e32 v108, v108
	s_nop 0
	v_mul_f32_e32 v107, v107, v108
	v_sub_f32_e32 v108, 1.0, v100
	v_add_f32_e32 v100, 1.0, v100
	v_mul_f32_e32 v100, v108, v100
	v_max_f32_e32 v100, 0, v100
	v_sqrt_f32_e32 v100, v100
	v_mul_f32_e32 v107, v107, v115
	v_mul_f32_e32 v96, v96, v100
	v_mul_f32_e32 v115, v96, v121
	v_add_f32_e32 v96, v101, v29
	v_mul_f32_e32 v96, 0xbfb8aa3b, v96
	v_exp_f32_e32 v96, v96
	s_nop 0
	v_add_f32_e32 v96, 1.0, v96
	v_rcp_f32_e32 v96, v96
	s_nop 0
	v_mul_f32_e32 v96, v96, v189
	v_mul_f32_e32 v96, 0x3fb8aa3b, v96
	v_exp_f32_e32 v96, v96
	s_nop 0
	v_sub_f32_e32 v100, 1.0, v96
	v_add_f32_e32 v96, 1.0, v96
	v_mul_f32_e32 v96, v100, v96
	v_max_f32_e32 v96, 0, v96
	v_sqrt_f32_e32 v96, v96
	s_nop 0
	v_mul_f32_e32 v96, v97, v96
	v_mul_f32_e32 v116, v96, v116
	v_add_f32_e32 v96, v102, v30
	v_mul_f32_e32 v96, 0xbfb8aa3b, v96
	v_exp_f32_e32 v96, v96
	v_add_f32_e32 v97, v98, v34
	v_mul_f32_e32 v97, 0xbfb8aa3b, v97
	v_exp_f32_e32 v97, v97
	v_add_f32_e32 v96, 1.0, v96
	v_rcp_f32_e32 v96, v96
	v_add_f32_e32 v97, 1.0, v97
	v_rcp_f32_e32 v97, v97
	v_mul_f32_e32 v96, v96, v150
	v_mul_f32_e32 v96, 0x3fb8aa3b, v96
	v_exp_f32_e32 v96, v96
	s_nop 0
	v_sub_f32_e32 v101, 1.0, v96
	v_add_f32_e32 v96, 1.0, v96
	v_mul_f32_e32 v96, v101, v96
	v_max_f32_e32 v96, 0, v96
	v_sqrt_f32_e32 v96, v96
	s_nop 0
	v_mul_f32_e32 v96, v97, v96
	v_mul_f32_e32 v102, v96, v122
	v_add_f32_e32 v96, v103, v31
	v_mul_f32_e32 v96, 0xbfb8aa3b, v96
	v_exp_f32_e32 v96, v96
	v_add_f32_e32 v97, v99, v35
	v_mul_f32_e32 v97, 0xbfb8aa3b, v97
	v_exp_f32_e32 v97, v97
	v_add_f32_e32 v96, 1.0, v96
	v_rcp_f32_e32 v96, v96
	v_add_f32_e32 v97, 1.0, v97
	v_rcp_f32_e32 v97, v97
	v_mul_f32_e32 v96, v96, v151
	v_mul_f32_e32 v96, 0x3fb8aa3b, v96
	v_exp_f32_e32 v96, v96
	s_nop 0
	v_sub_f32_e32 v99, 1.0, v96
	v_add_f32_e32 v96, 1.0, v96
	v_mul_f32_e32 v96, v99, v96
	v_max_f32_e32 v96, 0, v96
	v_sqrt_f32_e32 v96, v96
	s_nop 0
	v_mul_f32_e32 v96, v97, v96
	v_mul_f32_e32 v103, v96, v114
	v_cvt_pk_bf16_f32 v96, v117, v109
	v_cvt_pk_bf16_f32 v97, v110, v111
	v_cvt_pk_bf16_f32 v98, v108, v100
	v_cvt_pk_bf16_f32 v99, v101, v99
	v_lshl_add_u64 v[100:101], s[20:21], 0, v[112:113]
	global_store_dwordx4 v[100:101], v[96:99], off sc0 sc1
	s_nop 1
	v_cvt_pk_bf16_f32 v96, v104, v105
	v_cvt_pk_bf16_f32 v97, v106, v107
	v_cvt_pk_bf16_f32 v98, v115, v116
	v_cvt_pk_bf16_f32 v99, v102, v103
	v_lshl_add_u64 v[100:101], s[34:35], 0, v[112:113]
	global_store_dwordx4 v[100:101], v[96:99], off sc0 sc1
	s_nop 1
	v_or_b32_e32 v96, 48, v168
	v_ashrrev_i32_e32 v97, 31, v96
	v_lshlrev_b64 v[96:97], 10, v[96:97]
	v_lshl_add_u64 v[96:97], v[96:97], 0, v[166:167]
	v_lshlrev_b64 v[96:97], 1, v[96:97]
	v_lshl_add_u64 v[98:99], s[30:31], 0, v[96:97]
	global_load_dwordx4 v[98:101], v[98:99], off
	s_waitcnt vmcnt(0)
	v_lshlrev_b32_e32 v102, 16, v98
	v_and_b32_e32 v103, 0xffff0000, v98
	v_lshlrev_b32_e32 v106, 16, v101
	v_and_b32_e32 v98, 0xffff0000, v101
	v_sub_f32_e32 v101, 1.0, v92
	v_add_f32_e32 v92, 1.0, v92
	v_mul_f32_e32 v92, v101, v92
	v_max_f32_e32 v92, 0, v92
	v_sqrt_f32_e32 v92, v92
	v_lshlrev_b32_e32 v104, 16, v99
	v_and_b32_e32 v99, 0xffff0000, v99
	v_lshlrev_b32_e32 v105, 16, v100
	v_mul_f32_e32 v88, v88, v92
	v_add_f32_e32 v92, v93, v41
	v_mul_f32_e32 v92, 0xbfb8aa3b, v92
	v_exp_f32_e32 v92, v92
	v_and_b32_e32 v100, 0xffff0000, v100
	v_mul_f32_e32 v88, v88, v102
	v_add_f32_e32 v92, 1.0, v92
	v_rcp_f32_e32 v92, v92
	s_nop 0
	v_mul_f32_e32 v92, v92, v190
	v_mul_f32_e32 v92, 0x3fb8aa3b, v92
	v_exp_f32_e32 v92, v92
	s_nop 0
	v_sub_f32_e32 v93, 1.0, v92
	v_add_f32_e32 v92, 1.0, v92
	v_mul_f32_e32 v92, v93, v92
	v_max_f32_e32 v92, 0, v92
	v_sqrt_f32_e32 v92, v92
	s_nop 0
	v_mul_f32_e32 v89, v89, v92
	v_add_f32_e32 v92, v94, v42
	v_mul_f32_e32 v92, 0xbfb8aa3b, v92
	v_exp_f32_e32 v92, v92
	v_mul_f32_e32 v89, v89, v103
	v_add_f32_e32 v92, 1.0, v92
	v_rcp_f32_e32 v92, v92
	s_nop 0
	v_mul_f32_e32 v92, v92, v191
	v_mul_f32_e32 v92, 0x3fb8aa3b, v92
	v_exp_f32_e32 v92, v92
	s_nop 0
	v_sub_f32_e32 v94, 1.0, v92
	v_add_f32_e32 v92, 1.0, v92
	v_mul_f32_e32 v92, v94, v92
	v_max_f32_e32 v92, 0, v92
	v_sqrt_f32_e32 v92, v92
	s_nop 0
	v_mul_f32_e32 v90, v90, v92
	v_add_f32_e32 v92, v95, v43
	v_mul_f32_e32 v92, 0xbfb8aa3b, v92
	v_exp_f32_e32 v92, v92
	v_mul_f32_e32 v90, v90, v104
	v_add_f32_e32 v92, 1.0, v92
	v_rcp_f32_e32 v92, v92
	s_nop 0
	v_mul_f32_e32 v92, v92, v192
	v_mul_f32_e32 v92, 0x3fb8aa3b, v92
	v_exp_f32_e32 v92, v92
	s_nop 0
	v_sub_f32_e32 v95, 1.0, v92
	v_add_f32_e32 v92, 1.0, v92
	v_mul_f32_e32 v92, v95, v92
	v_max_f32_e32 v92, 0, v92
	v_sqrt_f32_e32 v92, v92
	s_nop 0
	v_mul_f32_e32 v91, v91, v92
	v_sub_f32_e32 v92, 1.0, v84
	v_add_f32_e32 v84, 1.0, v84
	v_mul_f32_e32 v84, v92, v84
	v_max_f32_e32 v84, 0, v84
	v_sqrt_f32_e32 v84, v84
	v_mul_f32_e32 v91, v91, v99
	v_mul_f32_e32 v80, v80, v84
	v_mul_f32_e32 v99, v80, v105
	v_add_f32_e32 v80, v85, v29
	v_mul_f32_e32 v80, 0xbfb8aa3b, v80
	v_exp_f32_e32 v80, v80
	s_nop 0
	v_add_f32_e32 v80, 1.0, v80
	v_rcp_f32_e32 v80, v80
	s_nop 0
	v_mul_f32_e32 v80, v80, v189
	v_mul_f32_e32 v80, 0x3fb8aa3b, v80
	v_exp_f32_e32 v80, v80
	s_nop 0
	v_sub_f32_e32 v84, 1.0, v80
	v_add_f32_e32 v80, 1.0, v80
	v_mul_f32_e32 v80, v84, v80
	v_max_f32_e32 v80, 0, v80
	v_sqrt_f32_e32 v80, v80
	s_nop 0
	v_mul_f32_e32 v80, v81, v80
	v_mul_f32_e32 v100, v80, v100
	v_add_f32_e32 v80, v86, v30
	v_mul_f32_e32 v80, 0xbfb8aa3b, v80
	v_exp_f32_e32 v80, v80
	v_add_f32_e32 v81, v82, v34
	v_mul_f32_e32 v81, 0xbfb8aa3b, v81
	v_exp_f32_e32 v81, v81
	v_add_f32_e32 v80, 1.0, v80
	v_rcp_f32_e32 v80, v80
	v_add_f32_e32 v81, 1.0, v81
	v_rcp_f32_e32 v81, v81
	v_mul_f32_e32 v80, v80, v150
	v_mul_f32_e32 v80, 0x3fb8aa3b, v80
	v_exp_f32_e32 v80, v80
	s_nop 0
	v_sub_f32_e32 v85, 1.0, v80
	v_add_f32_e32 v80, 1.0, v80
	v_mul_f32_e32 v80, v85, v80
	v_max_f32_e32 v80, 0, v80
	v_sqrt_f32_e32 v80, v80
	s_nop 0
	v_mul_f32_e32 v80, v81, v80
	v_mul_f32_e32 v86, v80, v106
	v_add_f32_e32 v80, v87, v31
	v_mul_f32_e32 v80, 0xbfb8aa3b, v80
	v_exp_f32_e32 v80, v80
	v_add_f32_e32 v81, v83, v35
	v_mul_f32_e32 v81, 0xbfb8aa3b, v81
	v_exp_f32_e32 v81, v81
	v_add_f32_e32 v80, 1.0, v80
	v_rcp_f32_e32 v80, v80
	v_add_f32_e32 v81, 1.0, v81
	v_rcp_f32_e32 v81, v81
	v_mul_f32_e32 v80, v80, v151
	v_mul_f32_e32 v80, 0x3fb8aa3b, v80
	v_exp_f32_e32 v80, v80
	s_nop 0
	v_sub_f32_e32 v83, 1.0, v80
	v_add_f32_e32 v80, 1.0, v80
	v_mul_f32_e32 v80, v83, v80
	v_max_f32_e32 v80, 0, v80
	v_sqrt_f32_e32 v80, v80
	s_nop 0
	v_mul_f32_e32 v80, v81, v80
	v_mul_f32_e32 v87, v80, v98
	v_cvt_pk_bf16_f32 v80, v101, v93
	v_cvt_pk_bf16_f32 v81, v94, v95
	v_cvt_pk_bf16_f32 v82, v92, v84
	v_cvt_pk_bf16_f32 v83, v85, v83
	v_lshl_add_u64 v[84:85], s[20:21], 0, v[96:97]
	global_store_dwordx4 v[84:85], v[80:83], off sc0 sc1
	s_nop 1
	v_cvt_pk_bf16_f32 v80, v88, v89
	v_cvt_pk_bf16_f32 v81, v90, v91
	v_cvt_pk_bf16_f32 v82, v99, v100
	v_cvt_pk_bf16_f32 v83, v86, v87
	v_lshl_add_u64 v[84:85], s[34:35], 0, v[96:97]
	global_store_dwordx4 v[84:85], v[80:83], off sc0 sc1
	s_nop 1
	v_lshl_add_u64 v[80:81], v[148:149], 0, s[8:9]
	v_lshl_add_u64 v[82:83], s[30:31], 0, v[80:81]
	global_load_dwordx4 v[82:85], v[82:83], off
	s_mov_b64 s[8:9], 0x48000
	s_waitcnt vmcnt(0)
	v_lshlrev_b32_e32 v86, 16, v82
	v_and_b32_e32 v87, 0xffff0000, v82
	v_lshlrev_b32_e32 v90, 16, v85
	v_and_b32_e32 v82, 0xffff0000, v85
	v_sub_f32_e32 v85, 1.0, v76
	v_add_f32_e32 v76, 1.0, v76
	v_mul_f32_e32 v76, v85, v76
	v_max_f32_e32 v76, 0, v76
	v_sqrt_f32_e32 v76, v76
	v_lshlrev_b32_e32 v88, 16, v83
	v_and_b32_e32 v83, 0xffff0000, v83
	v_lshlrev_b32_e32 v89, 16, v84
	v_mul_f32_e32 v72, v72, v76
	v_add_f32_e32 v76, v77, v41
	v_mul_f32_e32 v76, 0xbfb8aa3b, v76
	v_exp_f32_e32 v76, v76
	v_and_b32_e32 v84, 0xffff0000, v84
	v_mul_f32_e32 v72, v72, v86
	v_add_f32_e32 v76, 1.0, v76
	v_rcp_f32_e32 v76, v76
	s_nop 0
	v_mul_f32_e32 v76, v76, v190
	v_mul_f32_e32 v76, 0x3fb8aa3b, v76
	v_exp_f32_e32 v76, v76
	s_nop 0
	v_sub_f32_e32 v77, 1.0, v76
	v_add_f32_e32 v76, 1.0, v76
	v_mul_f32_e32 v76, v77, v76
	v_max_f32_e32 v76, 0, v76
	v_sqrt_f32_e32 v76, v76
	s_nop 0
	v_mul_f32_e32 v73, v73, v76
	v_add_f32_e32 v76, v78, v42
	v_mul_f32_e32 v76, 0xbfb8aa3b, v76
	v_exp_f32_e32 v76, v76
	v_mul_f32_e32 v73, v73, v87
	v_add_f32_e32 v76, 1.0, v76
	v_rcp_f32_e32 v76, v76
	s_nop 0
	v_mul_f32_e32 v76, v76, v191
	v_mul_f32_e32 v76, 0x3fb8aa3b, v76
	v_exp_f32_e32 v76, v76
	s_nop 0
	v_sub_f32_e32 v78, 1.0, v76
	v_add_f32_e32 v76, 1.0, v76
	v_mul_f32_e32 v76, v78, v76
	v_max_f32_e32 v76, 0, v76
	v_sqrt_f32_e32 v76, v76
	s_nop 0
	v_mul_f32_e32 v74, v74, v76
	v_add_f32_e32 v76, v79, v43
	v_mul_f32_e32 v76, 0xbfb8aa3b, v76
	v_exp_f32_e32 v76, v76
	v_mul_f32_e32 v74, v74, v88
	v_add_f32_e32 v76, 1.0, v76
	v_rcp_f32_e32 v76, v76
	s_nop 0
	v_mul_f32_e32 v76, v76, v192
	v_mul_f32_e32 v76, 0x3fb8aa3b, v76
	v_exp_f32_e32 v76, v76
	s_nop 0
	v_sub_f32_e32 v79, 1.0, v76
	v_add_f32_e32 v76, 1.0, v76
	v_mul_f32_e32 v76, v79, v76
	v_max_f32_e32 v76, 0, v76
	v_sqrt_f32_e32 v76, v76
	s_nop 0
	v_mul_f32_e32 v75, v75, v76
	v_sub_f32_e32 v76, 1.0, v68
	v_add_f32_e32 v68, 1.0, v68
	v_mul_f32_e32 v68, v76, v68
	v_max_f32_e32 v68, 0, v68
	v_sqrt_f32_e32 v68, v68
	v_mul_f32_e32 v75, v75, v83
	v_mul_f32_e32 v64, v64, v68
	v_mul_f32_e32 v83, v64, v89
	v_add_f32_e32 v64, v69, v29
	v_mul_f32_e32 v64, 0xbfb8aa3b, v64
	v_exp_f32_e32 v64, v64
	s_nop 0
	v_add_f32_e32 v64, 1.0, v64
	v_rcp_f32_e32 v64, v64
	s_nop 0
	v_mul_f32_e32 v64, v64, v189
	v_mul_f32_e32 v64, 0x3fb8aa3b, v64
	v_exp_f32_e32 v64, v64
	s_nop 0
	v_sub_f32_e32 v68, 1.0, v64
	v_add_f32_e32 v64, 1.0, v64
	v_mul_f32_e32 v64, v68, v64
	v_max_f32_e32 v64, 0, v64
	v_sqrt_f32_e32 v64, v64
	s_nop 0
	v_mul_f32_e32 v64, v65, v64
	v_mul_f32_e32 v84, v64, v84
	v_add_f32_e32 v64, v70, v30
	v_mul_f32_e32 v64, 0xbfb8aa3b, v64
	v_exp_f32_e32 v64, v64
	v_add_f32_e32 v65, v66, v34
	v_mul_f32_e32 v65, 0xbfb8aa3b, v65
	v_exp_f32_e32 v65, v65
	v_add_f32_e32 v64, 1.0, v64
	v_rcp_f32_e32 v64, v64
	v_add_f32_e32 v65, 1.0, v65
	v_rcp_f32_e32 v65, v65
	v_mul_f32_e32 v64, v64, v150
	v_mul_f32_e32 v64, 0x3fb8aa3b, v64
	v_exp_f32_e32 v64, v64
	s_nop 0
	v_sub_f32_e32 v69, 1.0, v64
	v_add_f32_e32 v64, 1.0, v64
	v_mul_f32_e32 v64, v69, v64
	v_max_f32_e32 v64, 0, v64
	v_sqrt_f32_e32 v64, v64
	s_nop 0
	v_mul_f32_e32 v64, v65, v64
	v_mul_f32_e32 v70, v64, v90
	v_add_f32_e32 v64, v71, v31
	v_mul_f32_e32 v64, 0xbfb8aa3b, v64
	v_exp_f32_e32 v64, v64
	v_add_f32_e32 v65, v67, v35
	v_mul_f32_e32 v65, 0xbfb8aa3b, v65
	v_exp_f32_e32 v65, v65
	v_add_f32_e32 v64, 1.0, v64
	v_rcp_f32_e32 v64, v64
	v_add_f32_e32 v65, 1.0, v65
	v_rcp_f32_e32 v65, v65
	v_mul_f32_e32 v64, v64, v151
	v_mul_f32_e32 v64, 0x3fb8aa3b, v64
	v_exp_f32_e32 v64, v64
	s_nop 0
	v_sub_f32_e32 v67, 1.0, v64
	v_add_f32_e32 v64, 1.0, v64
	v_mul_f32_e32 v64, v67, v64
	v_max_f32_e32 v64, 0, v64
	v_sqrt_f32_e32 v64, v64
	s_nop 0
	v_mul_f32_e32 v64, v65, v64
	v_mul_f32_e32 v71, v64, v82
	v_cvt_pk_bf16_f32 v64, v85, v77
	v_cvt_pk_bf16_f32 v65, v78, v79
	v_cvt_pk_bf16_f32 v66, v76, v68
	v_cvt_pk_bf16_f32 v67, v69, v67
	v_lshl_add_u64 v[68:69], s[20:21], 0, v[80:81]
	global_store_dwordx4 v[68:69], v[64:67], off sc0 sc1
	s_nop 1
	v_cvt_pk_bf16_f32 v64, v72, v73
	v_cvt_pk_bf16_f32 v65, v74, v75
	v_cvt_pk_bf16_f32 v66, v83, v84
	v_cvt_pk_bf16_f32 v67, v70, v71
	v_lshl_add_u64 v[68:69], s[34:35], 0, v[80:81]
	global_store_dwordx4 v[68:69], v[64:67], off sc0 sc1
	s_nop 1
	v_lshl_add_u64 v[64:65], v[148:149], 0, s[8:9]
	v_lshl_add_u64 v[66:67], s[30:31], 0, v[64:65]
	global_load_dwordx4 v[66:69], v[66:67], off
	s_mov_b64 s[8:9], 0x50000
	s_waitcnt vmcnt(0)
	v_lshlrev_b32_e32 v70, 16, v66
	v_and_b32_e32 v71, 0xffff0000, v66
	v_lshlrev_b32_e32 v74, 16, v69
	v_and_b32_e32 v66, 0xffff0000, v69
	v_sub_f32_e32 v69, 1.0, v60
	v_add_f32_e32 v60, 1.0, v60
	v_mul_f32_e32 v60, v69, v60
	v_max_f32_e32 v60, 0, v60
	v_sqrt_f32_e32 v60, v60
	v_lshlrev_b32_e32 v72, 16, v67
	v_and_b32_e32 v67, 0xffff0000, v67
	v_lshlrev_b32_e32 v73, 16, v68
	v_mul_f32_e32 v56, v56, v60
	v_add_f32_e32 v60, v61, v41
	v_mul_f32_e32 v60, 0xbfb8aa3b, v60
	v_exp_f32_e32 v60, v60
	v_and_b32_e32 v68, 0xffff0000, v68
	v_mul_f32_e32 v56, v56, v70
	v_add_f32_e32 v60, 1.0, v60
	v_rcp_f32_e32 v60, v60
	s_nop 0
	v_mul_f32_e32 v60, v60, v190
	v_mul_f32_e32 v60, 0x3fb8aa3b, v60
	v_exp_f32_e32 v60, v60
	s_nop 0
	v_sub_f32_e32 v61, 1.0, v60
	v_add_f32_e32 v60, 1.0, v60
	v_mul_f32_e32 v60, v61, v60
	v_max_f32_e32 v60, 0, v60
	v_sqrt_f32_e32 v60, v60
	s_nop 0
	v_mul_f32_e32 v57, v57, v60
	v_add_f32_e32 v60, v62, v42
	v_mul_f32_e32 v60, 0xbfb8aa3b, v60
	v_exp_f32_e32 v60, v60
	v_mul_f32_e32 v57, v57, v71
	v_add_f32_e32 v60, 1.0, v60
	v_rcp_f32_e32 v60, v60
	s_nop 0
	v_mul_f32_e32 v60, v60, v191
	v_mul_f32_e32 v60, 0x3fb8aa3b, v60
	v_exp_f32_e32 v60, v60
	s_nop 0
	v_sub_f32_e32 v62, 1.0, v60
	v_add_f32_e32 v60, 1.0, v60
	v_mul_f32_e32 v60, v62, v60
	v_max_f32_e32 v60, 0, v60
	v_sqrt_f32_e32 v60, v60
	s_nop 0
	v_mul_f32_e32 v58, v58, v60
	v_add_f32_e32 v60, v63, v43
	v_mul_f32_e32 v60, 0xbfb8aa3b, v60
	v_exp_f32_e32 v60, v60
	v_mul_f32_e32 v58, v58, v72
	v_add_f32_e32 v60, 1.0, v60
	v_rcp_f32_e32 v60, v60
	s_nop 0
	v_mul_f32_e32 v60, v60, v192
	v_mul_f32_e32 v60, 0x3fb8aa3b, v60
	v_exp_f32_e32 v60, v60
	s_nop 0
	v_sub_f32_e32 v63, 1.0, v60
	v_add_f32_e32 v60, 1.0, v60
	v_mul_f32_e32 v60, v63, v60
	v_max_f32_e32 v60, 0, v60
	v_sqrt_f32_e32 v60, v60
	s_nop 0
	v_mul_f32_e32 v59, v59, v60
	v_sub_f32_e32 v60, 1.0, v52
	v_add_f32_e32 v52, 1.0, v52
	v_mul_f32_e32 v52, v60, v52
	v_max_f32_e32 v52, 0, v52
	v_sqrt_f32_e32 v52, v52
	v_mul_f32_e32 v59, v59, v67
	v_mul_f32_e32 v48, v48, v52
	v_mul_f32_e32 v67, v48, v73
	v_add_f32_e32 v48, v53, v29
	v_mul_f32_e32 v48, 0xbfb8aa3b, v48
	v_exp_f32_e32 v48, v48
	s_nop 0
	v_add_f32_e32 v48, 1.0, v48
	v_rcp_f32_e32 v48, v48
	s_nop 0
	v_mul_f32_e32 v48, v48, v189
	v_mul_f32_e32 v48, 0x3fb8aa3b, v48
	v_exp_f32_e32 v48, v48
	s_nop 0
	v_sub_f32_e32 v52, 1.0, v48
	v_add_f32_e32 v48, 1.0, v48
	v_mul_f32_e32 v48, v52, v48
	v_max_f32_e32 v48, 0, v48
	v_sqrt_f32_e32 v48, v48
	s_nop 0
	v_mul_f32_e32 v48, v49, v48
	v_mul_f32_e32 v68, v48, v68
	v_add_f32_e32 v48, v54, v30
	v_mul_f32_e32 v48, 0xbfb8aa3b, v48
	v_exp_f32_e32 v48, v48
	v_add_f32_e32 v49, v50, v34
	v_mul_f32_e32 v49, 0xbfb8aa3b, v49
	v_exp_f32_e32 v49, v49
	v_add_f32_e32 v48, 1.0, v48
	v_rcp_f32_e32 v48, v48
	v_add_f32_e32 v49, 1.0, v49
	v_rcp_f32_e32 v49, v49
	v_mul_f32_e32 v48, v48, v150
	v_mul_f32_e32 v48, 0x3fb8aa3b, v48
	v_exp_f32_e32 v48, v48
	s_nop 0
	v_sub_f32_e32 v53, 1.0, v48
	v_add_f32_e32 v48, 1.0, v48
	v_mul_f32_e32 v48, v53, v48
	v_max_f32_e32 v48, 0, v48
	v_sqrt_f32_e32 v48, v48
	s_nop 0
	v_mul_f32_e32 v48, v49, v48
	v_mul_f32_e32 v54, v48, v74
	v_add_f32_e32 v48, v55, v31
	v_mul_f32_e32 v48, 0xbfb8aa3b, v48
	v_exp_f32_e32 v48, v48
	v_add_f32_e32 v49, v51, v35
	v_mul_f32_e32 v49, 0xbfb8aa3b, v49
	v_exp_f32_e32 v49, v49
	v_add_f32_e32 v48, 1.0, v48
	v_rcp_f32_e32 v48, v48
	v_add_f32_e32 v49, 1.0, v49
	v_rcp_f32_e32 v49, v49
	v_mul_f32_e32 v48, v48, v151
	v_mul_f32_e32 v48, 0x3fb8aa3b, v48
	v_exp_f32_e32 v48, v48
	s_nop 0
	v_sub_f32_e32 v51, 1.0, v48
	v_add_f32_e32 v48, 1.0, v48
	v_mul_f32_e32 v48, v51, v48
	v_max_f32_e32 v48, 0, v48
	v_sqrt_f32_e32 v48, v48
	s_nop 0
	v_mul_f32_e32 v48, v49, v48
	v_mul_f32_e32 v55, v48, v66
	v_cvt_pk_bf16_f32 v48, v69, v61
	v_cvt_pk_bf16_f32 v49, v62, v63
	v_cvt_pk_bf16_f32 v50, v60, v52
	v_cvt_pk_bf16_f32 v51, v53, v51
	v_lshl_add_u64 v[52:53], s[20:21], 0, v[64:65]
	global_store_dwordx4 v[52:53], v[48:51], off sc0 sc1
	s_nop 1
	v_cvt_pk_bf16_f32 v48, v56, v57
	v_cvt_pk_bf16_f32 v49, v58, v59
	v_cvt_pk_bf16_f32 v50, v67, v68
	v_cvt_pk_bf16_f32 v51, v54, v55
	v_lshl_add_u64 v[52:53], s[34:35], 0, v[64:65]
	global_store_dwordx4 v[52:53], v[48:51], off sc0 sc1
	s_nop 1
	v_lshl_add_u64 v[48:49], v[148:149], 0, s[8:9]
	v_lshl_add_u64 v[50:51], s[30:31], 0, v[48:49]
	global_load_dwordx4 v[50:53], v[50:51], off
	s_mov_b64 s[8:9], 0x58000
	s_waitcnt vmcnt(0)
	v_lshlrev_b32_e32 v54, 16, v50
	v_and_b32_e32 v55, 0xffff0000, v50
	v_lshlrev_b32_e32 v58, 16, v53
	v_and_b32_e32 v50, 0xffff0000, v53
	v_sub_f32_e32 v53, 1.0, v36
	v_add_f32_e32 v36, 1.0, v36
	v_mul_f32_e32 v36, v53, v36
	v_max_f32_e32 v36, 0, v36
	v_sqrt_f32_e32 v36, v36
	v_lshlrev_b32_e32 v56, 16, v51
	v_and_b32_e32 v51, 0xffff0000, v51
	v_lshlrev_b32_e32 v57, 16, v52
	v_mul_f32_e32 v24, v24, v36
	v_add_f32_e32 v36, v37, v41
	v_mul_f32_e32 v36, 0xbfb8aa3b, v36
	v_exp_f32_e32 v36, v36
	v_and_b32_e32 v52, 0xffff0000, v52
	v_mul_f32_e32 v24, v24, v54
	v_add_f32_e32 v36, 1.0, v36
	v_rcp_f32_e32 v36, v36
	s_nop 0
	v_mul_f32_e32 v36, v36, v190
	v_mul_f32_e32 v36, 0x3fb8aa3b, v36
	v_exp_f32_e32 v36, v36
	s_nop 0
	v_sub_f32_e32 v37, 1.0, v36
	v_add_f32_e32 v36, 1.0, v36
	v_mul_f32_e32 v36, v37, v36
	v_max_f32_e32 v36, 0, v36
	v_sqrt_f32_e32 v36, v36
	s_nop 0
	v_mul_f32_e32 v25, v25, v36
	v_add_f32_e32 v36, v38, v42
	v_mul_f32_e32 v36, 0xbfb8aa3b, v36
	v_exp_f32_e32 v36, v36
	v_mul_f32_e32 v25, v25, v55
	v_add_f32_e32 v36, 1.0, v36
	v_rcp_f32_e32 v36, v36
	s_nop 0
	v_mul_f32_e32 v36, v36, v191
	v_mul_f32_e32 v36, 0x3fb8aa3b, v36
	v_exp_f32_e32 v36, v36
	s_nop 0
	v_sub_f32_e32 v38, 1.0, v36
	v_add_f32_e32 v36, 1.0, v36
	v_mul_f32_e32 v36, v38, v36
	v_max_f32_e32 v36, 0, v36
	v_sqrt_f32_e32 v36, v36
	s_nop 0
	v_mul_f32_e32 v26, v26, v36
	v_add_f32_e32 v36, v39, v43
	v_mul_f32_e32 v36, 0xbfb8aa3b, v36
	v_exp_f32_e32 v36, v36
	v_mul_f32_e32 v26, v26, v56
	v_add_f32_e32 v36, 1.0, v36
	v_rcp_f32_e32 v36, v36
	s_nop 0
	v_mul_f32_e32 v36, v36, v192
	v_mul_f32_e32 v36, 0x3fb8aa3b, v36
	v_exp_f32_e32 v36, v36
	s_nop 0
	v_sub_f32_e32 v39, 1.0, v36
	v_add_f32_e32 v36, 1.0, v36
	v_mul_f32_e32 v36, v39, v36
	v_max_f32_e32 v36, 0, v36
	v_sqrt_f32_e32 v36, v36
	s_nop 0
	v_mul_f32_e32 v27, v27, v36
	v_sub_f32_e32 v36, 1.0, v20
	v_add_f32_e32 v20, 1.0, v20
	v_mul_f32_e32 v20, v36, v20
	v_max_f32_e32 v20, 0, v20
	v_sqrt_f32_e32 v20, v20
	v_mul_f32_e32 v27, v27, v51
	v_mul_f32_e32 v16, v16, v20
	v_mul_f32_e32 v51, v16, v57
	v_add_f32_e32 v16, v21, v29
	v_mul_f32_e32 v16, 0xbfb8aa3b, v16
	v_exp_f32_e32 v16, v16
	s_nop 0
	v_add_f32_e32 v16, 1.0, v16
	v_rcp_f32_e32 v16, v16
	s_nop 0
	v_mul_f32_e32 v16, v16, v189
	v_mul_f32_e32 v16, 0x3fb8aa3b, v16
	v_exp_f32_e32 v16, v16
	s_nop 0
	v_sub_f32_e32 v20, 1.0, v16
	v_add_f32_e32 v16, 1.0, v16
	v_mul_f32_e32 v16, v20, v16
	v_max_f32_e32 v16, 0, v16
	v_sqrt_f32_e32 v16, v16
	s_nop 0
	v_mul_f32_e32 v16, v17, v16
	v_mul_f32_e32 v52, v16, v52
	v_add_f32_e32 v16, v22, v30
	v_mul_f32_e32 v16, 0xbfb8aa3b, v16
	v_exp_f32_e32 v16, v16
	v_add_f32_e32 v17, v18, v34
	v_mul_f32_e32 v17, 0xbfb8aa3b, v17
	v_exp_f32_e32 v17, v17
	v_add_f32_e32 v16, 1.0, v16
	v_rcp_f32_e32 v16, v16
	v_add_f32_e32 v17, 1.0, v17
	v_rcp_f32_e32 v17, v17
	v_mul_f32_e32 v16, v16, v150
	v_mul_f32_e32 v16, 0x3fb8aa3b, v16
	v_exp_f32_e32 v16, v16
	s_nop 0
	v_sub_f32_e32 v21, 1.0, v16
	v_add_f32_e32 v16, 1.0, v16
	v_mul_f32_e32 v16, v21, v16
	v_max_f32_e32 v16, 0, v16
	v_sqrt_f32_e32 v16, v16
	s_nop 0
	v_mul_f32_e32 v16, v17, v16
	v_mul_f32_e32 v22, v16, v58
	v_add_f32_e32 v16, v23, v31
	v_mul_f32_e32 v16, 0xbfb8aa3b, v16
	v_exp_f32_e32 v16, v16
	v_add_f32_e32 v17, v19, v35
	v_mul_f32_e32 v17, 0xbfb8aa3b, v17
	v_exp_f32_e32 v17, v17
	v_add_f32_e32 v16, 1.0, v16
	v_rcp_f32_e32 v16, v16
	v_add_f32_e32 v17, 1.0, v17
	v_rcp_f32_e32 v17, v17
	v_mul_f32_e32 v16, v16, v151
	v_mul_f32_e32 v16, 0x3fb8aa3b, v16
	v_exp_f32_e32 v16, v16
	s_nop 0
	v_sub_f32_e32 v19, 1.0, v16
	v_add_f32_e32 v16, 1.0, v16
	v_mul_f32_e32 v16, v19, v16
	v_max_f32_e32 v16, 0, v16
	v_sqrt_f32_e32 v16, v16
	s_nop 0
	v_mul_f32_e32 v16, v17, v16
	v_mul_f32_e32 v23, v16, v50
	v_cvt_pk_bf16_f32 v16, v53, v37
	v_cvt_pk_bf16_f32 v17, v38, v39
	v_cvt_pk_bf16_f32 v18, v36, v20
	v_cvt_pk_bf16_f32 v19, v21, v19
	v_lshl_add_u64 v[20:21], s[20:21], 0, v[48:49]
	global_store_dwordx4 v[20:21], v[16:19], off sc0 sc1
	s_nop 1
	v_cvt_pk_bf16_f32 v16, v24, v25
	v_cvt_pk_bf16_f32 v17, v26, v27
	v_cvt_pk_bf16_f32 v18, v51, v52
	v_cvt_pk_bf16_f32 v19, v22, v23
	v_lshl_add_u64 v[20:21], s[34:35], 0, v[48:49]
	global_store_dwordx4 v[20:21], v[16:19], off sc0 sc1
	s_nop 1
	v_lshl_add_u64 v[16:17], v[148:149], 0, s[8:9]
	v_lshl_add_u64 v[18:19], s[30:31], 0, v[16:17]
	global_load_dwordx4 v[18:21], v[18:19], off
	s_waitcnt vmcnt(0)
	v_lshlrev_b32_e32 v22, 16, v18
	v_and_b32_e32 v23, 0xffff0000, v18
	v_lshlrev_b32_e32 v26, 16, v21
	v_and_b32_e32 v18, 0xffff0000, v21
	v_sub_f32_e32 v21, 1.0, v12
	v_add_f32_e32 v12, 1.0, v12
	v_mul_f32_e32 v12, v21, v12
	v_max_f32_e32 v12, 0, v12
	v_sqrt_f32_e32 v12, v12
	v_lshlrev_b32_e32 v24, 16, v19
	v_and_b32_e32 v19, 0xffff0000, v19
	v_lshlrev_b32_e32 v25, 16, v20
	v_mul_f32_e32 v8, v8, v12
	v_add_f32_e32 v12, v13, v41
	v_mul_f32_e32 v12, 0xbfb8aa3b, v12
	v_exp_f32_e32 v12, v12
	v_and_b32_e32 v20, 0xffff0000, v20
	v_mul_f32_e32 v8, v8, v22
	v_add_f32_e32 v12, 1.0, v12
	v_rcp_f32_e32 v12, v12
	s_nop 0
	v_mul_f32_e32 v12, v12, v190
	v_mul_f32_e32 v12, 0x3fb8aa3b, v12
	v_exp_f32_e32 v12, v12
	s_nop 0
	v_sub_f32_e32 v13, 1.0, v12
	v_add_f32_e32 v12, 1.0, v12
	v_mul_f32_e32 v12, v13, v12
	v_max_f32_e32 v12, 0, v12
	v_sqrt_f32_e32 v12, v12
	s_nop 0
	v_mul_f32_e32 v9, v9, v12
	v_add_f32_e32 v12, v14, v42
	v_mul_f32_e32 v12, 0xbfb8aa3b, v12
	v_exp_f32_e32 v12, v12
	v_mul_f32_e32 v9, v9, v23
	v_add_f32_e32 v12, 1.0, v12
	v_rcp_f32_e32 v12, v12
	s_nop 0
	v_mul_f32_e32 v12, v12, v191
	v_mul_f32_e32 v12, 0x3fb8aa3b, v12
	v_exp_f32_e32 v12, v12
	s_nop 0
	v_sub_f32_e32 v14, 1.0, v12
	v_add_f32_e32 v12, 1.0, v12
	v_mul_f32_e32 v12, v14, v12
	v_max_f32_e32 v12, 0, v12
	v_sqrt_f32_e32 v12, v12
	s_nop 0
	v_mul_f32_e32 v10, v10, v12
	v_add_f32_e32 v12, v15, v43
	v_mul_f32_e32 v12, 0xbfb8aa3b, v12
	v_exp_f32_e32 v12, v12
	v_mul_f32_e32 v10, v10, v24
	v_add_f32_e32 v12, 1.0, v12
	v_rcp_f32_e32 v12, v12
	s_nop 0
	v_mul_f32_e32 v12, v12, v192
	v_mul_f32_e32 v12, 0x3fb8aa3b, v12
	v_exp_f32_e32 v12, v12
	s_nop 0
	v_sub_f32_e32 v15, 1.0, v12
	v_add_f32_e32 v12, 1.0, v12
	v_mul_f32_e32 v12, v15, v12
	v_max_f32_e32 v12, 0, v12
	v_sqrt_f32_e32 v12, v12
	s_nop 0
	v_mul_f32_e32 v11, v11, v12
	v_sub_f32_e32 v12, 1.0, v4
	v_add_f32_e32 v4, 1.0, v4
	v_mul_f32_e32 v4, v12, v4
	v_max_f32_e32 v4, 0, v4
	v_sqrt_f32_e32 v4, v4
	v_mul_f32_e32 v11, v11, v19
	v_mul_f32_e32 v0, v0, v4
	v_mul_f32_e32 v19, v0, v25
	v_add_f32_e32 v0, v5, v29
	v_mul_f32_e32 v0, 0xbfb8aa3b, v0
	v_exp_f32_e32 v0, v0
	s_nop 0
	v_add_f32_e32 v0, 1.0, v0
	v_rcp_f32_e32 v0, v0
	s_nop 0
	v_mul_f32_e32 v0, v0, v189
	v_mul_f32_e32 v0, 0x3fb8aa3b, v0
	v_exp_f32_e32 v0, v0
	s_nop 0
	v_sub_f32_e32 v4, 1.0, v0
	v_add_f32_e32 v0, 1.0, v0
	v_mul_f32_e32 v0, v4, v0
	v_max_f32_e32 v0, 0, v0
	v_sqrt_f32_e32 v0, v0
	s_nop 0
	v_mul_f32_e32 v0, v1, v0
	v_mul_f32_e32 v20, v0, v20
	v_add_f32_e32 v0, v6, v30
	v_mul_f32_e32 v0, 0xbfb8aa3b, v0
	v_exp_f32_e32 v0, v0
	v_add_f32_e32 v1, v2, v34
	v_mul_f32_e32 v1, 0xbfb8aa3b, v1
	v_exp_f32_e32 v1, v1
	v_add_f32_e32 v0, 1.0, v0
	v_rcp_f32_e32 v0, v0
	v_add_f32_e32 v1, 1.0, v1
	v_rcp_f32_e32 v1, v1
	v_mul_f32_e32 v0, v0, v150
	v_mul_f32_e32 v0, 0x3fb8aa3b, v0
	v_exp_f32_e32 v0, v0
	s_nop 0
	v_sub_f32_e32 v5, 1.0, v0
	v_add_f32_e32 v0, 1.0, v0
	v_mul_f32_e32 v0, v5, v0
	v_max_f32_e32 v0, 0, v0
	v_sqrt_f32_e32 v0, v0
	s_nop 0
	v_mul_f32_e32 v0, v1, v0
	v_mul_f32_e32 v6, v0, v26
	v_add_f32_e32 v0, v7, v31
	v_mul_f32_e32 v0, 0xbfb8aa3b, v0
	v_exp_f32_e32 v0, v0
	v_add_f32_e32 v1, v3, v35
	v_mul_f32_e32 v1, 0xbfb8aa3b, v1
	v_exp_f32_e32 v1, v1
	v_add_f32_e32 v0, 1.0, v0
	v_rcp_f32_e32 v0, v0
	v_add_f32_e32 v1, 1.0, v1
	v_rcp_f32_e32 v1, v1
	v_mul_f32_e32 v0, v0, v151
	v_mul_f32_e32 v0, 0x3fb8aa3b, v0
	v_exp_f32_e32 v0, v0
	s_nop 0
	v_sub_f32_e32 v3, 1.0, v0
	v_add_f32_e32 v0, 1.0, v0
	v_mul_f32_e32 v0, v3, v0
	v_max_f32_e32 v0, 0, v0
	v_sqrt_f32_e32 v0, v0
	s_nop 0
	v_mul_f32_e32 v0, v1, v0
	v_mul_f32_e32 v7, v0, v18
	v_cvt_pk_bf16_f32 v0, v21, v13
	v_cvt_pk_bf16_f32 v1, v14, v15
	v_cvt_pk_bf16_f32 v2, v12, v4
	v_cvt_pk_bf16_f32 v3, v5, v3
	v_lshl_add_u64 v[4:5], s[20:21], 0, v[16:17]
	global_store_dwordx4 v[4:5], v[0:3], off sc0 sc1
	s_nop 1
	v_cvt_pk_bf16_f32 v0, v8, v9
	v_cvt_pk_bf16_f32 v1, v10, v11
	v_cvt_pk_bf16_f32 v2, v19, v20
	v_cvt_pk_bf16_f32 v3, v6, v7
	v_lshl_add_u64 v[4:5], s[34:35], 0, v[16:17]
	global_store_dwordx4 v[4:5], v[0:3], off sc0 sc1
	s_nop 1
	s_nop 0
	s_mov_b64 s[36:37], exec
	v_readlane_b32 s8, v254, 0
	v_readlane_b32 s9, v254, 1
	s_and_b64 s[8:9], s[36:37], s[8:9]
	s_mov_b64 exec, s[8:9]
	s_cbranch_execz .LBB0_464
	s_mov_b64 s[38:39], exec
	v_mbcnt_lo_u32_b32 v0, s38, 0
	v_mbcnt_hi_u32_b32 v0, s39, v0
	v_cmp_eq_u32_e32 vcc, 0, v0
	s_and_b64 s[8:9], exec, vcc
	s_mov_b64 exec, s[8:9]
	s_cbranch_execz .LBB0_464
	s_lshl_b32 s0, s0, 6
	s_ashr_i32 s1, s0, 31
	s_lshl_b64 s[0:1], s[0:1], 2
	v_readlane_b32 s4, v254, 51
	v_readlane_b32 s5, v254, 52
	s_add_u32 s0, s4, s0
	s_addc_u32 s1, s5, s1
	s_bcnt1_i32_b64 s8, s[38:39]
	v_mov_b32_e32 v0, s8
	s_sub_u32 s98, s0, 1
	s_subb_u32 s99, s1, 0

.Ldp_1_x:
	v_readlane_b32 s92, v254, 55
	v_readlane_b32 s94, v254, 53
	v_readlane_b32 s10, v254, 51
	v_readlane_b32 s91, v254, 57
	v_readlane_b32 s93, v254, 56
	v_readlane_b32 s95, v254, 54
	v_readlane_b32 s11, v254, 52
	s_barrier

.LBB0_522:
	v_readlane_b32 s0, v254, 2
	v_readlane_b32 s1, v254, 3
	s_cmpk_gt_i32 s101, 0x427
	s_nop 0
	v_cndmask_b32_e64 v0, 0, 1, s[0:1]
	v_cmp_ne_u32_e64 s[4:5], 1, v0
	s_cbranch_scc1 .LBB0_572
	s_add_u32 s3, s24, 0x64000
	s_addc_u32 s16, s25, 0
	s_add_u32 s10, s24, 0x6a400
	s_addc_u32 s11, s25, 0
	s_mov_b32 s17, 0xfe03f81
	v_mov_b32_e32 v99, 0
	s_movk_i32 s27, 0x407f
	s_mov_b32 s28, 0x1fc07f
	s_add_i32 s29, 0, 0x8000
	s_movk_i32 s33, 0x80f
	s_mov_b64 s[42:43], 0x10ec000
	s_mov_b64 s[44:45], 0x1086000
	v_mov_b32_e32 v183, 0xc000
	v_mov_b32_e32 v184, 0x6c000
	s_mov_b32 s38, s101
	s_branch .LBB0_525

.LBB0_611:
	s_or_b32 s44, s86, 1
	v_add_u32_e32 v151, s50, v147
	s_lshl_b64 s[18:19], s[44:45], 7
	s_add_i32 s44, s86, 2
	ds_read_b128 v[142:145], v151
	ds_read_b128 v[154:157], v151 offset:1024
	ds_read_b128 v[158:161], v151 offset:2048
	ds_read_b128 v[162:165], v151 offset:3072
	v_add_u32_e32 v151, s51, v147
	s_lshl_b64 s[88:89], s[44:45], 7
	ds_read_b128 v[166:169], v151
	ds_read_b128 v[170:173], v151 offset:1024
	ds_read_b128 v[184:187], v151 offset:2048
	ds_read_b128 v[188:191], v151 offset:3072
	s_add_u32 s87, s80, s88
	s_addc_u32 s90, s81, s89
	s_and_b64 s[36:37], s[6:7], exec
	s_cselect_b32 s37, s15, s90
	s_cselect_b32 s36, s42, s87
	s_add_u32 s87, s82, s88
	s_addc_u32 s88, s83, s89
	s_and_b64 s[6:7], s[6:7], exec
	s_cselect_b32 s7, s43, s88
	s_cselect_b32 s6, s69, s87
	s_add_u32 s18, s71, s18
	s_addc_u32 s19, s73, s19
	v_lshl_add_u64 v[174:175], s[18:19], 0, v[128:129]
	s_add_i32 m0, s16, 0xc000
	ds_read_b128 v[192:195], v150
	ds_read_b128 v[196:199], v150 offset:1024
	ds_read_b128 v[200:203], v150 offset:2048
	ds_read_b128 v[204:207], v150 offset:3072
	ds_read_b128 v[208:211], v150 offset:4096
	ds_read_b128 v[212:215], v150 offset:5120
	ds_read_b128 v[216:219], v150 offset:6144
	ds_read_b128 v[220:223], v150 offset:7168
	global_load_lds_dwordx4 v[174:175], off
	v_lshl_add_u64 v[174:175], s[18:19], 0, v[132:133]
	s_add_i32 m0, s16, 0xe000
	s_nop 0
	global_load_lds_dwordx4 v[174:175], off
	s_cmp_eq_u32 s99, 0
	s_cbranch_scc1 .Ldpw_2_0a
	s_waitcnt vmcnt(16)
	s_branch .Ldpw_2_0b

.Ldpw_2_0b:
	s_waitcnt lgkmcnt(0)
	s_barrier
	s_setprio 1
	s_waitcnt lgkmcnt(0)
	v_mfma_f32_16x16x32_bf16 v[124:127], v[142:145], v[192:195], v[124:127]
	v_mfma_f32_16x16x32_bf16 v[120:123], v[158:161], v[192:195], v[120:123]
	v_mfma_f32_16x16x32_bf16 v[108:111], v[142:145], v[200:203], v[108:111]
	v_mfma_f32_16x16x32_bf16 v[104:107], v[158:161], v[200:203], v[104:107]
	v_mfma_f32_16x16x32_bf16 v[92:95], v[142:145], v[208:211], v[92:95]
	v_mfma_f32_16x16x32_bf16 v[88:91], v[158:161], v[208:211], v[88:91]
	v_mfma_f32_16x16x32_bf16 v[76:79], v[142:145], v[216:219], v[76:79]
	v_mfma_f32_16x16x32_bf16 v[72:75], v[158:161], v[216:219], v[72:75]
	v_mfma_f32_16x16x32_bf16 v[124:127], v[154:157], v[196:199], v[124:127]
	v_mfma_f32_16x16x32_bf16 v[120:123], v[162:165], v[196:199], v[120:123]
	v_mfma_f32_16x16x32_bf16 v[108:111], v[154:157], v[204:207], v[108:111]
	v_mfma_f32_16x16x32_bf16 v[104:107], v[162:165], v[204:207], v[104:107]
	v_mfma_f32_16x16x32_bf16 v[92:95], v[154:157], v[212:215], v[92:95]
	v_mfma_f32_16x16x32_bf16 v[88:91], v[162:165], v[212:215], v[88:91]
	v_mfma_f32_16x16x32_bf16 v[76:79], v[154:157], v[220:223], v[76:79]
	v_mfma_f32_16x16x32_bf16 v[72:75], v[162:165], v[220:223], v[72:75]
	s_setprio 0
	s_setprio 1
	v_mfma_f32_16x16x32_bf16 v[116:119], v[166:169], v[192:195], v[116:119]
	v_mfma_f32_16x16x32_bf16 v[112:115], v[184:187], v[192:195], v[112:115]
	v_mfma_f32_16x16x32_bf16 v[100:103], v[166:169], v[200:203], v[100:103]
	v_mfma_f32_16x16x32_bf16 v[96:99], v[184:187], v[200:203], v[96:99]
	v_mfma_f32_16x16x32_bf16 v[84:87], v[166:169], v[208:211], v[84:87]
	v_mfma_f32_16x16x32_bf16 v[80:83], v[184:187], v[208:211], v[80:83]
	v_mfma_f32_16x16x32_bf16 v[68:71], v[166:169], v[216:219], v[68:71]
	v_mfma_f32_16x16x32_bf16 v[64:67], v[184:187], v[216:219], v[64:67]
	v_mfma_f32_16x16x32_bf16 v[116:119], v[170:173], v[196:199], v[116:119]
	v_mfma_f32_16x16x32_bf16 v[112:115], v[188:191], v[196:199], v[112:115]
	v_mfma_f32_16x16x32_bf16 v[100:103], v[170:173], v[204:207], v[100:103]
	v_mfma_f32_16x16x32_bf16 v[96:99], v[188:191], v[204:207], v[96:99]
	v_mfma_f32_16x16x32_bf16 v[84:87], v[170:173], v[212:215], v[84:87]
	v_mfma_f32_16x16x32_bf16 v[80:83], v[188:191], v[212:215], v[80:83]
	v_mfma_f32_16x16x32_bf16 v[68:71], v[170:173], v[220:223], v[68:71]
	v_mfma_f32_16x16x32_bf16 v[64:67], v[188:191], v[220:223], v[64:67]
	s_setprio 0
	s_barrier
	s_add_i32 s18, s50, s11
	v_lshl_add_u64 v[174:175], s[6:7], 0, v[130:131]
	s_mov_b32 m0, s18
	ds_read_b128 v[192:195], v150 offset:16384
	ds_read_b128 v[196:199], v150 offset:17408
	ds_read_b128 v[200:203], v150 offset:18432
	ds_read_b128 v[204:207], v150 offset:19456
	ds_read_b128 v[208:211], v150 offset:20480
	ds_read_b128 v[212:215], v150 offset:21504
	ds_read_b128 v[216:219], v150 offset:22528
	ds_read_b128 v[220:223], v150 offset:23552
	global_load_lds_dwordx4 v[174:175], off
	s_add_i32 m0, s18, 0x2000
	s_add_u32 s18, s6, 0x40000
	v_lshl_add_u64 v[224:225], s[6:7], 0, v[134:135]
	s_addc_u32 s19, s7, 0
	s_add_i32 s87, s51, s11
	global_load_lds_dwordx4 v[224:225], off
	v_lshl_add_u64 v[226:227], s[18:19], 0, v[130:131]
	s_mov_b32 m0, s87
	v_lshl_add_u64 v[228:229], s[36:37], 0, v[132:133]
	global_load_lds_dwordx4 v[226:227], off
	v_lshl_add_u64 v[226:227], s[18:19], 0, v[134:135]
	s_add_i32 m0, s87, 0x2000
	s_nop 0
	global_load_lds_dwordx4 v[226:227], off
	v_lshl_add_u64 v[226:227], s[36:37], 0, v[128:129]
	s_mov_b32 m0, s16
	s_nop 0
	global_load_lds_dwordx4 v[226:227], off
	s_mov_b32 m0, s17
	s_nop 0
	global_load_lds_dwordx4 v[228:229], off
	s_cmp_eq_u32 s99, 0
	s_cbranch_scc1 .Ldpw_2_1a
	s_waitcnt vmcnt(16)
	s_branch .Ldpw_2_1b

.Ldpw_2_1b:
	s_waitcnt lgkmcnt(0)
	s_barrier
	s_setprio 1
	s_waitcnt lgkmcnt(0)
	v_mfma_f32_16x16x32_bf16 v[60:63], v[142:145], v[192:195], v[60:63]
	v_mfma_f32_16x16x32_bf16 v[56:59], v[158:161], v[192:195], v[56:59]
	v_mfma_f32_16x16x32_bf16 v[44:47], v[142:145], v[200:203], v[44:47]
	v_mfma_f32_16x16x32_bf16 v[40:43], v[158:161], v[200:203], v[40:43]
	v_mfma_f32_16x16x32_bf16 v[28:31], v[142:145], v[208:211], v[28:31]
	v_mfma_f32_16x16x32_bf16 v[24:27], v[158:161], v[208:211], v[24:27]
	v_mfma_f32_16x16x32_bf16 v[12:15], v[142:145], v[216:219], v[12:15]
	v_mfma_f32_16x16x32_bf16 v[8:11], v[158:161], v[216:219], v[8:11]
	v_mfma_f32_16x16x32_bf16 v[60:63], v[154:157], v[196:199], v[60:63]
	v_mfma_f32_16x16x32_bf16 v[56:59], v[162:165], v[196:199], v[56:59]
	v_mfma_f32_16x16x32_bf16 v[44:47], v[154:157], v[204:207], v[44:47]
	v_mfma_f32_16x16x32_bf16 v[40:43], v[162:165], v[204:207], v[40:43]
	v_mfma_f32_16x16x32_bf16 v[28:31], v[154:157], v[212:215], v[28:31]
	v_mfma_f32_16x16x32_bf16 v[24:27], v[162:165], v[212:215], v[24:27]
	v_mfma_f32_16x16x32_bf16 v[12:15], v[154:157], v[220:223], v[12:15]
	v_mfma_f32_16x16x32_bf16 v[8:11], v[162:165], v[220:223], v[8:11]
	s_setprio 0
	s_setprio 1
	v_mfma_f32_16x16x32_bf16 v[52:55], v[166:169], v[192:195], v[52:55]
	v_mfma_f32_16x16x32_bf16 v[48:51], v[184:187], v[192:195], v[48:51]
	v_mfma_f32_16x16x32_bf16 v[36:39], v[166:169], v[200:203], v[36:39]
	v_mfma_f32_16x16x32_bf16 v[32:35], v[184:187], v[200:203], v[32:35]
	v_mfma_f32_16x16x32_bf16 v[20:23], v[166:169], v[208:211], v[20:23]
	v_mfma_f32_16x16x32_bf16 v[16:19], v[184:187], v[208:211], v[16:19]
	v_mfma_f32_16x16x32_bf16 v[4:7], v[166:169], v[216:219], v[4:7]
	v_mfma_f32_16x16x32_bf16 v[0:3], v[184:187], v[216:219], v[0:3]
	v_mfma_f32_16x16x32_bf16 v[52:55], v[170:173], v[196:199], v[52:55]
	v_mfma_f32_16x16x32_bf16 v[48:51], v[188:191], v[196:199], v[48:51]
	v_mfma_f32_16x16x32_bf16 v[36:39], v[170:173], v[204:207], v[36:39]
	v_mfma_f32_16x16x32_bf16 v[32:35], v[188:191], v[204:207], v[32:35]
	v_mfma_f32_16x16x32_bf16 v[20:23], v[170:173], v[212:215], v[20:23]
	v_mfma_f32_16x16x32_bf16 v[16:19], v[188:191], v[212:215], v[16:19]
	v_mfma_f32_16x16x32_bf16 v[4:7], v[170:173], v[220:223], v[4:7]
	v_mfma_f32_16x16x32_bf16 v[0:3], v[188:191], v[220:223], v[0:3]
	s_setprio 0
	s_barrier
	s_add_i32 s87, 0, 0x18000
	v_add_u32_e32 v151, s87, v147
	s_add_i32 s88, 0, 0x1c000
	ds_read_b128 v[142:145], v151
	ds_read_b128 v[154:157], v151 offset:1024
	ds_read_b128 v[158:161], v151 offset:2048
	ds_read_b128 v[162:165], v151 offset:3072
	v_add_u32_e32 v151, s88, v147
	ds_read_b128 v[166:169], v151
	ds_read_b128 v[170:173], v151 offset:1024
	ds_read_b128 v[184:187], v151 offset:2048
	ds_read_b128 v[188:191], v151 offset:3072
	s_add_u32 s18, s36, 0x40000
	s_addc_u32 s19, s37, 0
	s_mov_b32 m0, s28
	v_lshl_add_u64 v[230:231], s[18:19], 0, v[128:129]
	ds_read_b128 v[192:195], v150 offset:32768
	ds_read_b128 v[196:199], v150 offset:33792
	ds_read_b128 v[200:203], v150 offset:34816
	ds_read_b128 v[204:207], v150 offset:35840
	ds_read_b128 v[208:211], v150 offset:36864
	ds_read_b128 v[212:215], v150 offset:37888
	ds_read_b128 v[216:219], v150 offset:38912
	ds_read_b128 v[220:223], v150 offset:39936
	global_load_lds_dwordx4 v[230:231], off
	v_lshl_add_u64 v[230:231], s[18:19], 0, v[132:133]
	s_mov_b32 m0, s29
	s_nop 0
	global_load_lds_dwordx4 v[230:231], off
	s_waitcnt vmcnt(8)
	s_cmp_eq_u32 s99, 0
	s_cbranch_scc1 .Ldp_2_l
	v_readlane_b32 s100, v0, 0
	s_mov_b64 exec, 1
	v_writelane_b32 v0, 1, 0
	s_nop 1
	global_atomic_add v0, v0, s[98:99]
	s_nop 1
	v_writelane_b32 v0, s100, 0
	s_mov_b64 exec, -1
	s_mov_b32 s99, 0
.Ldp_2_l:
	s_waitcnt lgkmcnt(0)
	s_barrier
	s_setprio 1
	s_waitcnt lgkmcnt(0)
	v_mfma_f32_16x16x32_bf16 v[124:127], v[142:145], v[192:195], v[124:127]
	v_mfma_f32_16x16x32_bf16 v[120:123], v[158:161], v[192:195], v[120:123]
	v_mfma_f32_16x16x32_bf16 v[108:111], v[142:145], v[200:203], v[108:111]
	v_mfma_f32_16x16x32_bf16 v[104:107], v[158:161], v[200:203], v[104:107]
	v_mfma_f32_16x16x32_bf16 v[92:95], v[142:145], v[208:211], v[92:95]
	v_mfma_f32_16x16x32_bf16 v[88:91], v[158:161], v[208:211], v[88:91]
	v_mfma_f32_16x16x32_bf16 v[76:79], v[142:145], v[216:219], v[76:79]
	v_mfma_f32_16x16x32_bf16 v[72:75], v[158:161], v[216:219], v[72:75]
	v_mfma_f32_16x16x32_bf16 v[124:127], v[154:157], v[196:199], v[124:127]
	v_mfma_f32_16x16x32_bf16 v[120:123], v[162:165], v[196:199], v[120:123]
	v_mfma_f32_16x16x32_bf16 v[108:111], v[154:157], v[204:207], v[108:111]
	v_mfma_f32_16x16x32_bf16 v[104:107], v[162:165], v[204:207], v[104:107]
	v_mfma_f32_16x16x32_bf16 v[92:95], v[154:157], v[212:215], v[92:95]
	v_mfma_f32_16x16x32_bf16 v[88:91], v[162:165], v[212:215], v[88:91]
	v_mfma_f32_16x16x32_bf16 v[76:79], v[154:157], v[220:223], v[76:79]
	v_mfma_f32_16x16x32_bf16 v[72:75], v[162:165], v[220:223], v[72:75]
	s_setprio 0
	s_setprio 1
	v_mfma_f32_16x16x32_bf16 v[116:119], v[166:169], v[192:195], v[116:119]
	v_mfma_f32_16x16x32_bf16 v[112:115], v[184:187], v[192:195], v[112:115]
	v_mfma_f32_16x16x32_bf16 v[100:103], v[166:169], v[200:203], v[100:103]
	v_mfma_f32_16x16x32_bf16 v[96:99], v[184:187], v[200:203], v[96:99]
	v_mfma_f32_16x16x32_bf16 v[84:87], v[166:169], v[208:211], v[84:87]
	v_mfma_f32_16x16x32_bf16 v[80:83], v[184:187], v[208:211], v[80:83]
	v_mfma_f32_16x16x32_bf16 v[68:71], v[166:169], v[216:219], v[68:71]
	v_mfma_f32_16x16x32_bf16 v[64:67], v[184:187], v[216:219], v[64:67]
	v_mfma_f32_16x16x32_bf16 v[116:119], v[170:173], v[196:199], v[116:119]
	v_mfma_f32_16x16x32_bf16 v[112:115], v[188:191], v[196:199], v[112:115]
	v_mfma_f32_16x16x32_bf16 v[100:103], v[170:173], v[204:207], v[100:103]
	v_mfma_f32_16x16x32_bf16 v[96:99], v[188:191], v[204:207], v[96:99]
	v_mfma_f32_16x16x32_bf16 v[84:87], v[170:173], v[212:215], v[84:87]
	v_mfma_f32_16x16x32_bf16 v[80:83], v[188:191], v[212:215], v[80:83]
	v_mfma_f32_16x16x32_bf16 v[68:71], v[170:173], v[220:223], v[68:71]
	v_mfma_f32_16x16x32_bf16 v[64:67], v[188:191], v[220:223], v[64:67]
	s_setprio 0
	s_barrier
	s_add_i32 s18, s87, s11
	v_lshl_add_u64 v[174:175], v[174:175], 0, s[48:49]
	s_mov_b32 m0, s18
	ds_read_b128 v[192:195], v150 offset:49152
	ds_read_b128 v[196:199], v150 offset:50176
	ds_read_b128 v[200:203], v150 offset:51200
	ds_read_b128 v[204:207], v150 offset:52224
	ds_read_b128 v[208:211], v150 offset:53248
	ds_read_b128 v[212:215], v150 offset:54272
	ds_read_b128 v[216:219], v150 offset:55296
	ds_read_b128 v[220:223], v150 offset:56320
	global_load_lds_dwordx4 v[174:175], off
	s_add_i32 m0, s18, 0x2000
	s_add_u32 s6, s6, 0x40080
	v_lshl_add_u64 v[174:175], v[224:225], 0, s[48:49]
	s_addc_u32 s7, s7, 0
	s_add_i32 s18, s88, s11
	global_load_lds_dwordx4 v[174:175], off
	v_lshl_add_u64 v[174:175], s[6:7], 0, v[130:131]
	s_mov_b32 m0, s18
	s_nop 0
	global_load_lds_dwordx4 v[174:175], off
	v_lshl_add_u64 v[174:175], s[6:7], 0, v[134:135]
	s_add_i32 m0, s18, 0x2000
	s_nop 0
	global_load_lds_dwordx4 v[174:175], off
	v_lshl_add_u64 v[174:175], v[226:227], 0, s[48:49]
	s_mov_b32 m0, s38
	s_nop 0
	global_load_lds_dwordx4 v[174:175], off
	v_lshl_add_u64 v[174:175], v[228:229], 0, s[48:49]
	s_mov_b32 m0, s39
	s_nop 0
	global_load_lds_dwordx4 v[174:175], off
	s_waitcnt vmcnt(8)
	s_waitcnt lgkmcnt(0)
	s_barrier
	s_setprio 1
	s_waitcnt lgkmcnt(0)
	v_mfma_f32_16x16x32_bf16 v[60:63], v[142:145], v[192:195], v[60:63]
	v_mfma_f32_16x16x32_bf16 v[56:59], v[158:161], v[192:195], v[56:59]
	v_mfma_f32_16x16x32_bf16 v[44:47], v[142:145], v[200:203], v[44:47]
	v_mfma_f32_16x16x32_bf16 v[40:43], v[158:161], v[200:203], v[40:43]
	v_mfma_f32_16x16x32_bf16 v[28:31], v[142:145], v[208:211], v[28:31]
	v_mfma_f32_16x16x32_bf16 v[24:27], v[158:161], v[208:211], v[24:27]
	v_mfma_f32_16x16x32_bf16 v[12:15], v[142:145], v[216:219], v[12:15]
	v_mfma_f32_16x16x32_bf16 v[8:11], v[158:161], v[216:219], v[8:11]
	v_mfma_f32_16x16x32_bf16 v[60:63], v[154:157], v[196:199], v[60:63]
	v_mfma_f32_16x16x32_bf16 v[56:59], v[162:165], v[196:199], v[56:59]
	v_mfma_f32_16x16x32_bf16 v[44:47], v[154:157], v[204:207], v[44:47]
	v_mfma_f32_16x16x32_bf16 v[40:43], v[162:165], v[204:207], v[40:43]
	v_mfma_f32_16x16x32_bf16 v[28:31], v[154:157], v[212:215], v[28:31]
	v_mfma_f32_16x16x32_bf16 v[24:27], v[162:165], v[212:215], v[24:27]
	v_mfma_f32_16x16x32_bf16 v[12:15], v[154:157], v[220:223], v[12:15]
	v_mfma_f32_16x16x32_bf16 v[8:11], v[162:165], v[220:223], v[8:11]
	s_setprio 0
	s_setprio 1
	v_mfma_f32_16x16x32_bf16 v[52:55], v[166:169], v[192:195], v[52:55]
	v_mfma_f32_16x16x32_bf16 v[48:51], v[184:187], v[192:195], v[48:51]
	v_mfma_f32_16x16x32_bf16 v[36:39], v[166:169], v[200:203], v[36:39]
	v_mfma_f32_16x16x32_bf16 v[32:35], v[184:187], v[200:203], v[32:35]
	v_mfma_f32_16x16x32_bf16 v[20:23], v[166:169], v[208:211], v[20:23]
	v_mfma_f32_16x16x32_bf16 v[16:19], v[184:187], v[208:211], v[16:19]
	v_mfma_f32_16x16x32_bf16 v[4:7], v[166:169], v[216:219], v[4:7]
	v_mfma_f32_16x16x32_bf16 v[0:3], v[184:187], v[216:219], v[0:3]
	v_mfma_f32_16x16x32_bf16 v[52:55], v[170:173], v[196:199], v[52:55]
	v_mfma_f32_16x16x32_bf16 v[48:51], v[188:191], v[196:199], v[48:51]
	v_mfma_f32_16x16x32_bf16 v[36:39], v[170:173], v[204:207], v[36:39]
	v_mfma_f32_16x16x32_bf16 v[32:35], v[188:191], v[204:207], v[32:35]
	v_mfma_f32_16x16x32_bf16 v[20:23], v[170:173], v[212:215], v[20:23]
	v_mfma_f32_16x16x32_bf16 v[16:19], v[188:191], v[212:215], v[16:19]
	v_mfma_f32_16x16x32_bf16 v[4:7], v[170:173], v[220:223], v[4:7]
	v_mfma_f32_16x16x32_bf16 v[0:3], v[188:191], v[220:223], v[0:3]
	s_setprio 0
	s_barrier
	s_cmp_gt_u32 s86, 13
	s_mov_b32 s86, s44
	s_cbranch_scc1 .LBB0_630

.LBB0_648:
	s_or_b64 exec, exec, s[6:7]
	s_nop 0
	s_mov_b64 s[6:7], exec
	v_readlane_b32 s14, v254, 0
	v_readlane_b32 s15, v254, 1
	s_and_b64 s[14:15], s[6:7], s[14:15]
	s_mov_b64 exec, s[14:15]
	s_cbranch_execz .LBB0_651
	s_mov_b64 s[14:15], exec
	v_mbcnt_lo_u32_b32 v0, s14, 0
	v_mbcnt_hi_u32_b32 v0, s15, v0
	v_cmp_eq_u32_e32 vcc, 0, v0
	s_and_b64 s[18:19], exec, vcc
	s_mov_b64 exec, s[18:19]
	s_cbranch_execz .LBB0_651
	s_lshl_b32 s18, s10, 6
	s_ashr_i32 s19, s18, 31
	s_lshl_b64 s[18:19], s[18:19], 2
	s_add_u32 s18, s56, s18
	s_addc_u32 s19, s57, s19
	s_bcnt1_i32_b64 s10, s[14:15]
	v_mov_b32_e32 v0, s10
	s_sub_u32 s98, s18, 1
	s_subb_u32 s99, s19, 0

.LBB0_655:
	s_movk_i32 s8, 0x100
	v_mov_b32_e32 v8, v153
	s_cmp_lt_i32 s101, 48
	s_cselect_b64 s[0:1], -1, 0
	s_cmp_gt_i32 s101, 47
	v_readfirstlane_b32 s9, v8
	s_cbranch_scc1 .LBB0_657
	s_ashr_i32 s6, s101, 31
	s_lshr_b32 s6, s6, 28
	s_add_i32 s6, s101, s6
	s_ashr_i32 s7, s6, 4
	s_and_b32 s6, s6, -16
	s_add_i32 s14, s7, 64
	s_sub_i32 s16, s101, s6

.LBB0_681:
	s_add_i32 s49, s49, 1
	s_mul_i32 s6, s49, s26
	s_add_i32 s6, s6, s101
	s_cmp_lt_i32 s6, 48
	s_cselect_b64 s[84:85], -1, 0
	s_cmp_gt_i32 s6, 47
	s_cbranch_scc1 .LBB0_683
	s_ashr_i32 s7, s6, 31
	s_lshr_b32 s7, s7, 28
	s_add_i32 s7, s6, s7
	s_ashr_i32 s8, s7, 4
	s_and_b32 s7, s7, -16
	s_add_i32 s72, s8, 64
	s_sub_i32 s50, s6, s7

.LBB0_691:
	v_add_u32_e32 v141, s41, v138
	s_or_b32 s44, s88, 1
	s_add_i32 s88, s88, 2
	s_mov_b32 s89, s45
	ds_read_b128 v[142:145], v141
	ds_read_b128 v[146:149], v141 offset:1024
	ds_read_b128 v[154:157], v141 offset:2048
	ds_read_b128 v[158:161], v141 offset:3072
	v_add_u32_e32 v141, s48, v138
	s_lshl_b64 s[18:19], s[44:45], 7
	s_lshl_b64 s[76:77], s[88:89], 7
	ds_read_b128 v[162:165], v141
	ds_read_b128 v[166:169], v141 offset:1024
	ds_read_b128 v[170:173], v141 offset:2048
	ds_read_b128 v[184:187], v141 offset:3072
	s_add_u32 s44, s80, s76
	s_addc_u32 s71, s81, s77
	s_and_b64 s[8:9], s[6:7], exec
	s_cselect_b32 s9, s75, s71
	s_cselect_b32 s8, s74, s44
	s_add_u32 s44, s82, s76
	s_addc_u32 s71, s83, s77
	s_and_b64 s[6:7], s[6:7], exec
	s_cselect_b32 s7, s79, s71
	s_cselect_b32 s6, s78, s44
	s_add_u32 s18, s42, s18
	s_addc_u32 s19, s43, s19
	v_lshl_add_u64 v[150:151], s[18:19], 0, v[128:129]
	s_add_i32 m0, s28, 0xc000
	ds_read_b128 v[188:191], v140
	ds_read_b128 v[192:195], v140 offset:1024
	ds_read_b128 v[196:199], v140 offset:2048
	ds_read_b128 v[200:203], v140 offset:3072
	ds_read_b128 v[204:207], v140 offset:4096
	ds_read_b128 v[208:211], v140 offset:5120
	ds_read_b128 v[212:215], v140 offset:6144
	ds_read_b128 v[216:219], v140 offset:7168
	global_load_lds_dwordx4 v[150:151], off
	v_lshl_add_u64 v[150:151], s[18:19], 0, v[132:133]
	s_add_i32 m0, s28, 0xe000
	s_nop 0
	global_load_lds_dwordx4 v[150:151], off
	s_cmp_eq_u32 s99, 0
	s_cbranch_scc1 .Ldpw_3_0a
	s_waitcnt vmcnt(16)
	s_branch .Ldpw_3_0b

.Ldpw_3_0b:
	s_waitcnt lgkmcnt(0)
	s_barrier
	s_setprio 1
	s_waitcnt lgkmcnt(0)
	v_mfma_f32_16x16x32_bf16 v[124:127], v[142:145], v[188:191], v[124:127]
	v_mfma_f32_16x16x32_bf16 v[120:123], v[154:157], v[188:191], v[120:123]
	v_mfma_f32_16x16x32_bf16 v[108:111], v[142:145], v[196:199], v[108:111]
	v_mfma_f32_16x16x32_bf16 v[104:107], v[154:157], v[196:199], v[104:107]
	v_mfma_f32_16x16x32_bf16 v[92:95], v[142:145], v[204:207], v[92:95]
	v_mfma_f32_16x16x32_bf16 v[88:91], v[154:157], v[204:207], v[88:91]
	v_mfma_f32_16x16x32_bf16 v[76:79], v[142:145], v[212:215], v[76:79]
	v_mfma_f32_16x16x32_bf16 v[72:75], v[154:157], v[212:215], v[72:75]
	v_mfma_f32_16x16x32_bf16 v[124:127], v[146:149], v[192:195], v[124:127]
	v_mfma_f32_16x16x32_bf16 v[120:123], v[158:161], v[192:195], v[120:123]
	v_mfma_f32_16x16x32_bf16 v[108:111], v[146:149], v[200:203], v[108:111]
	v_mfma_f32_16x16x32_bf16 v[104:107], v[158:161], v[200:203], v[104:107]
	v_mfma_f32_16x16x32_bf16 v[92:95], v[146:149], v[208:211], v[92:95]
	v_mfma_f32_16x16x32_bf16 v[88:91], v[158:161], v[208:211], v[88:91]
	v_mfma_f32_16x16x32_bf16 v[76:79], v[146:149], v[216:219], v[76:79]
	v_mfma_f32_16x16x32_bf16 v[72:75], v[158:161], v[216:219], v[72:75]
	s_setprio 0
	s_setprio 1
	v_mfma_f32_16x16x32_bf16 v[116:119], v[162:165], v[188:191], v[116:119]
	v_mfma_f32_16x16x32_bf16 v[112:115], v[170:173], v[188:191], v[112:115]
	v_mfma_f32_16x16x32_bf16 v[100:103], v[162:165], v[196:199], v[100:103]
	v_mfma_f32_16x16x32_bf16 v[96:99], v[170:173], v[196:199], v[96:99]
	v_mfma_f32_16x16x32_bf16 v[84:87], v[162:165], v[204:207], v[84:87]
	v_mfma_f32_16x16x32_bf16 v[80:83], v[170:173], v[204:207], v[80:83]
	v_mfma_f32_16x16x32_bf16 v[68:71], v[162:165], v[212:215], v[68:71]
	v_mfma_f32_16x16x32_bf16 v[64:67], v[170:173], v[212:215], v[64:67]
	v_mfma_f32_16x16x32_bf16 v[116:119], v[166:169], v[192:195], v[116:119]
	v_mfma_f32_16x16x32_bf16 v[112:115], v[184:187], v[192:195], v[112:115]
	v_mfma_f32_16x16x32_bf16 v[100:103], v[166:169], v[200:203], v[100:103]
	v_mfma_f32_16x16x32_bf16 v[96:99], v[184:187], v[200:203], v[96:99]
	v_mfma_f32_16x16x32_bf16 v[84:87], v[166:169], v[208:211], v[84:87]
	v_mfma_f32_16x16x32_bf16 v[80:83], v[184:187], v[208:211], v[80:83]
	v_mfma_f32_16x16x32_bf16 v[68:71], v[166:169], v[216:219], v[68:71]
	v_mfma_f32_16x16x32_bf16 v[64:67], v[184:187], v[216:219], v[64:67]
	s_setprio 0
	s_barrier
	s_add_i32 s18, s41, s17
	v_lshl_add_u64 v[150:151], s[6:7], 0, v[130:131]
	s_mov_b32 m0, s18
	ds_read_b128 v[188:191], v140 offset:16384
	ds_read_b128 v[192:195], v140 offset:17408
	ds_read_b128 v[196:199], v140 offset:18432
	ds_read_b128 v[200:203], v140 offset:19456
	ds_read_b128 v[204:207], v140 offset:20480
	ds_read_b128 v[208:211], v140 offset:21504
	ds_read_b128 v[212:215], v140 offset:22528
	ds_read_b128 v[216:219], v140 offset:23552
	global_load_lds_dwordx4 v[150:151], off
	s_add_i32 m0, s18, 0x2000
	s_add_u32 s18, s6, 0x40000
	v_lshl_add_u64 v[174:175], s[6:7], 0, v[134:135]
	s_addc_u32 s19, s7, 0
	s_add_i32 s44, s48, s17
	global_load_lds_dwordx4 v[174:175], off
	v_lshl_add_u64 v[220:221], s[18:19], 0, v[130:131]
	s_mov_b32 m0, s44
	v_lshl_add_u64 v[222:223], s[8:9], 0, v[132:133]
	global_load_lds_dwordx4 v[220:221], off
	v_lshl_add_u64 v[220:221], s[18:19], 0, v[134:135]
	s_add_i32 m0, s44, 0x2000
	s_nop 0
	global_load_lds_dwordx4 v[220:221], off
	v_lshl_add_u64 v[220:221], s[8:9], 0, v[128:129]
	s_mov_b32 m0, s28
	s_nop 0
	global_load_lds_dwordx4 v[220:221], off
	s_mov_b32 m0, s29
	s_nop 0
	global_load_lds_dwordx4 v[222:223], off
	s_cmp_eq_u32 s99, 0
	s_cbranch_scc1 .Ldpw_3_1a
	s_waitcnt vmcnt(16)
	s_branch .Ldpw_3_1b

.Ldpw_3_1b:
	s_waitcnt lgkmcnt(0)
	s_barrier
	s_setprio 1
	s_waitcnt lgkmcnt(0)
	v_mfma_f32_16x16x32_bf16 v[60:63], v[142:145], v[188:191], v[60:63]
	v_mfma_f32_16x16x32_bf16 v[56:59], v[154:157], v[188:191], v[56:59]
	v_mfma_f32_16x16x32_bf16 v[44:47], v[142:145], v[196:199], v[44:47]
	v_mfma_f32_16x16x32_bf16 v[40:43], v[154:157], v[196:199], v[40:43]
	v_mfma_f32_16x16x32_bf16 v[28:31], v[142:145], v[204:207], v[28:31]
	v_mfma_f32_16x16x32_bf16 v[24:27], v[154:157], v[204:207], v[24:27]
	v_mfma_f32_16x16x32_bf16 v[12:15], v[142:145], v[212:215], v[12:15]
	v_mfma_f32_16x16x32_bf16 v[8:11], v[154:157], v[212:215], v[8:11]
	v_mfma_f32_16x16x32_bf16 v[60:63], v[146:149], v[192:195], v[60:63]
	v_mfma_f32_16x16x32_bf16 v[56:59], v[158:161], v[192:195], v[56:59]
	v_mfma_f32_16x16x32_bf16 v[44:47], v[146:149], v[200:203], v[44:47]
	v_mfma_f32_16x16x32_bf16 v[40:43], v[158:161], v[200:203], v[40:43]
	v_mfma_f32_16x16x32_bf16 v[28:31], v[146:149], v[208:211], v[28:31]
	v_mfma_f32_16x16x32_bf16 v[24:27], v[158:161], v[208:211], v[24:27]
	v_mfma_f32_16x16x32_bf16 v[12:15], v[146:149], v[216:219], v[12:15]
	v_mfma_f32_16x16x32_bf16 v[8:11], v[158:161], v[216:219], v[8:11]
	s_setprio 0
	s_setprio 1
	v_mfma_f32_16x16x32_bf16 v[52:55], v[162:165], v[188:191], v[52:55]
	v_mfma_f32_16x16x32_bf16 v[48:51], v[170:173], v[188:191], v[48:51]
	v_mfma_f32_16x16x32_bf16 v[36:39], v[162:165], v[196:199], v[36:39]
	v_mfma_f32_16x16x32_bf16 v[32:35], v[170:173], v[196:199], v[32:35]
	v_mfma_f32_16x16x32_bf16 v[20:23], v[162:165], v[204:207], v[20:23]
	v_mfma_f32_16x16x32_bf16 v[16:19], v[170:173], v[204:207], v[16:19]
	v_mfma_f32_16x16x32_bf16 v[4:7], v[162:165], v[212:215], v[4:7]
	v_mfma_f32_16x16x32_bf16 v[0:3], v[170:173], v[212:215], v[0:3]
	v_mfma_f32_16x16x32_bf16 v[52:55], v[166:169], v[192:195], v[52:55]
	v_mfma_f32_16x16x32_bf16 v[48:51], v[184:187], v[192:195], v[48:51]
	v_mfma_f32_16x16x32_bf16 v[36:39], v[166:169], v[200:203], v[36:39]
	v_mfma_f32_16x16x32_bf16 v[32:35], v[184:187], v[200:203], v[32:35]
	v_mfma_f32_16x16x32_bf16 v[20:23], v[166:169], v[208:211], v[20:23]
	v_mfma_f32_16x16x32_bf16 v[16:19], v[184:187], v[208:211], v[16:19]
	v_mfma_f32_16x16x32_bf16 v[4:7], v[166:169], v[216:219], v[4:7]
	v_mfma_f32_16x16x32_bf16 v[0:3], v[184:187], v[216:219], v[0:3]
	s_setprio 0
	s_barrier
	s_add_i32 s18, 0, 0x18000
	v_add_u32_e32 v141, s18, v138
	s_add_i32 s19, 0, 0x1c000
	ds_read_b128 v[142:145], v141
	ds_read_b128 v[146:149], v141 offset:1024
	ds_read_b128 v[154:157], v141 offset:2048
	ds_read_b128 v[158:161], v141 offset:3072
	v_add_u32_e32 v141, s19, v138
	ds_read_b128 v[162:165], v141
	ds_read_b128 v[166:169], v141 offset:1024
	ds_read_b128 v[170:173], v141 offset:2048
	ds_read_b128 v[184:187], v141 offset:3072
	s_add_u32 s8, s8, 0x40000
	s_addc_u32 s9, s9, 0
	s_mov_b32 m0, s33
	v_lshl_add_u64 v[224:225], s[8:9], 0, v[128:129]
	ds_read_b128 v[188:191], v140 offset:32768
	ds_read_b128 v[192:195], v140 offset:33792
	ds_read_b128 v[196:199], v140 offset:34816
	ds_read_b128 v[200:203], v140 offset:35840
	ds_read_b128 v[204:207], v140 offset:36864
	ds_read_b128 v[208:211], v140 offset:37888
	ds_read_b128 v[212:215], v140 offset:38912
	ds_read_b128 v[216:219], v140 offset:39936
	global_load_lds_dwordx4 v[224:225], off
	v_lshl_add_u64 v[224:225], s[8:9], 0, v[132:133]
	s_mov_b32 m0, s36
	s_nop 0
	global_load_lds_dwordx4 v[224:225], off
	s_waitcnt vmcnt(8)
	s_cmp_eq_u32 s99, 0
	s_cbranch_scc1 .Ldp_3_l
	v_readlane_b32 s100, v0, 0
	s_mov_b64 exec, 1
	v_writelane_b32 v0, 1, 0
	s_nop 1
	global_atomic_add v0, v0, s[98:99]
	s_nop 1
	v_writelane_b32 v0, s100, 0
	s_mov_b64 exec, -1
	s_mov_b32 s99, 0
.Ldp_3_l:
	s_waitcnt lgkmcnt(0)
	s_barrier
	s_setprio 1
	s_waitcnt lgkmcnt(0)
	v_mfma_f32_16x16x32_bf16 v[124:127], v[142:145], v[188:191], v[124:127]
	v_mfma_f32_16x16x32_bf16 v[120:123], v[154:157], v[188:191], v[120:123]
	v_mfma_f32_16x16x32_bf16 v[108:111], v[142:145], v[196:199], v[108:111]
	v_mfma_f32_16x16x32_bf16 v[104:107], v[154:157], v[196:199], v[104:107]
	v_mfma_f32_16x16x32_bf16 v[92:95], v[142:145], v[204:207], v[92:95]
	v_mfma_f32_16x16x32_bf16 v[88:91], v[154:157], v[204:207], v[88:91]
	v_mfma_f32_16x16x32_bf16 v[76:79], v[142:145], v[212:215], v[76:79]
	v_mfma_f32_16x16x32_bf16 v[72:75], v[154:157], v[212:215], v[72:75]
	v_mfma_f32_16x16x32_bf16 v[124:127], v[146:149], v[192:195], v[124:127]
	v_mfma_f32_16x16x32_bf16 v[120:123], v[158:161], v[192:195], v[120:123]
	v_mfma_f32_16x16x32_bf16 v[108:111], v[146:149], v[200:203], v[108:111]
	v_mfma_f32_16x16x32_bf16 v[104:107], v[158:161], v[200:203], v[104:107]
	v_mfma_f32_16x16x32_bf16 v[92:95], v[146:149], v[208:211], v[92:95]
	v_mfma_f32_16x16x32_bf16 v[88:91], v[158:161], v[208:211], v[88:91]
	v_mfma_f32_16x16x32_bf16 v[76:79], v[146:149], v[216:219], v[76:79]
	v_mfma_f32_16x16x32_bf16 v[72:75], v[158:161], v[216:219], v[72:75]
	s_setprio 0
	s_setprio 1
	v_mfma_f32_16x16x32_bf16 v[116:119], v[162:165], v[188:191], v[116:119]
	v_mfma_f32_16x16x32_bf16 v[112:115], v[170:173], v[188:191], v[112:115]
	v_mfma_f32_16x16x32_bf16 v[100:103], v[162:165], v[196:199], v[100:103]
	v_mfma_f32_16x16x32_bf16 v[96:99], v[170:173], v[196:199], v[96:99]
	v_mfma_f32_16x16x32_bf16 v[84:87], v[162:165], v[204:207], v[84:87]
	v_mfma_f32_16x16x32_bf16 v[80:83], v[170:173], v[204:207], v[80:83]
	v_mfma_f32_16x16x32_bf16 v[68:71], v[162:165], v[212:215], v[68:71]
	v_mfma_f32_16x16x32_bf16 v[64:67], v[170:173], v[212:215], v[64:67]
	v_mfma_f32_16x16x32_bf16 v[116:119], v[166:169], v[192:195], v[116:119]
	v_mfma_f32_16x16x32_bf16 v[112:115], v[184:187], v[192:195], v[112:115]
	v_mfma_f32_16x16x32_bf16 v[100:103], v[166:169], v[200:203], v[100:103]
	v_mfma_f32_16x16x32_bf16 v[96:99], v[184:187], v[200:203], v[96:99]
	v_mfma_f32_16x16x32_bf16 v[84:87], v[166:169], v[208:211], v[84:87]
	v_mfma_f32_16x16x32_bf16 v[80:83], v[184:187], v[208:211], v[80:83]
	v_mfma_f32_16x16x32_bf16 v[68:71], v[166:169], v[216:219], v[68:71]
	v_mfma_f32_16x16x32_bf16 v[64:67], v[184:187], v[216:219], v[64:67]
	s_setprio 0
	s_barrier
	s_add_i32 s8, s18, s17
	v_lshl_add_u64 v[150:151], v[150:151], 0, s[58:59]
	s_mov_b32 m0, s8
	ds_read_b128 v[188:191], v140 offset:49152
	ds_read_b128 v[192:195], v140 offset:50176
	ds_read_b128 v[196:199], v140 offset:51200
	ds_read_b128 v[200:203], v140 offset:52224
	ds_read_b128 v[204:207], v140 offset:53248
	ds_read_b128 v[208:211], v140 offset:54272
	ds_read_b128 v[212:215], v140 offset:55296
	ds_read_b128 v[216:219], v140 offset:56320
	global_load_lds_dwordx4 v[150:151], off
	s_add_i32 m0, s8, 0x2000
	s_add_u32 s6, s6, 0x40080
	v_lshl_add_u64 v[150:151], v[174:175], 0, s[58:59]
	s_addc_u32 s7, s7, 0
	s_add_i32 s8, s19, s17
	global_load_lds_dwordx4 v[150:151], off
	v_lshl_add_u64 v[150:151], s[6:7], 0, v[130:131]
	s_mov_b32 m0, s8
	s_nop 0
	global_load_lds_dwordx4 v[150:151], off
	v_lshl_add_u64 v[150:151], s[6:7], 0, v[134:135]
	s_add_i32 m0, s8, 0x2000
	s_nop 0
	global_load_lds_dwordx4 v[150:151], off
	v_lshl_add_u64 v[150:151], v[220:221], 0, s[58:59]
	s_mov_b32 m0, s38
	s_nop 0
	global_load_lds_dwordx4 v[150:151], off
	v_lshl_add_u64 v[150:151], v[222:223], 0, s[58:59]
	s_mov_b32 m0, s39
	s_nop 0
	global_load_lds_dwordx4 v[150:151], off
	s_waitcnt vmcnt(8)
	s_waitcnt lgkmcnt(0)
	s_barrier
	s_setprio 1
	s_waitcnt lgkmcnt(0)
	v_mfma_f32_16x16x32_bf16 v[60:63], v[142:145], v[188:191], v[60:63]
	v_mfma_f32_16x16x32_bf16 v[56:59], v[154:157], v[188:191], v[56:59]
	v_mfma_f32_16x16x32_bf16 v[44:47], v[142:145], v[196:199], v[44:47]
	v_mfma_f32_16x16x32_bf16 v[40:43], v[154:157], v[196:199], v[40:43]
	v_mfma_f32_16x16x32_bf16 v[28:31], v[142:145], v[204:207], v[28:31]
	v_mfma_f32_16x16x32_bf16 v[24:27], v[154:157], v[204:207], v[24:27]
	v_mfma_f32_16x16x32_bf16 v[12:15], v[142:145], v[212:215], v[12:15]
	v_mfma_f32_16x16x32_bf16 v[8:11], v[154:157], v[212:215], v[8:11]
	v_mfma_f32_16x16x32_bf16 v[60:63], v[146:149], v[192:195], v[60:63]
	v_mfma_f32_16x16x32_bf16 v[56:59], v[158:161], v[192:195], v[56:59]
	v_mfma_f32_16x16x32_bf16 v[44:47], v[146:149], v[200:203], v[44:47]
	v_mfma_f32_16x16x32_bf16 v[40:43], v[158:161], v[200:203], v[40:43]
	v_mfma_f32_16x16x32_bf16 v[28:31], v[146:149], v[208:211], v[28:31]
	v_mfma_f32_16x16x32_bf16 v[24:27], v[158:161], v[208:211], v[24:27]
	v_mfma_f32_16x16x32_bf16 v[12:15], v[146:149], v[216:219], v[12:15]
	v_mfma_f32_16x16x32_bf16 v[8:11], v[158:161], v[216:219], v[8:11]
	s_setprio 0
	s_setprio 1
	v_mfma_f32_16x16x32_bf16 v[52:55], v[162:165], v[188:191], v[52:55]
	v_mfma_f32_16x16x32_bf16 v[48:51], v[170:173], v[188:191], v[48:51]
	v_mfma_f32_16x16x32_bf16 v[36:39], v[162:165], v[196:199], v[36:39]
	v_mfma_f32_16x16x32_bf16 v[32:35], v[170:173], v[196:199], v[32:35]
	v_mfma_f32_16x16x32_bf16 v[20:23], v[162:165], v[204:207], v[20:23]
	v_mfma_f32_16x16x32_bf16 v[16:19], v[170:173], v[204:207], v[16:19]
	v_mfma_f32_16x16x32_bf16 v[4:7], v[162:165], v[212:215], v[4:7]
	v_mfma_f32_16x16x32_bf16 v[0:3], v[170:173], v[212:215], v[0:3]
	v_mfma_f32_16x16x32_bf16 v[52:55], v[166:169], v[192:195], v[52:55]
	v_mfma_f32_16x16x32_bf16 v[48:51], v[184:187], v[192:195], v[48:51]
	v_mfma_f32_16x16x32_bf16 v[36:39], v[166:169], v[200:203], v[36:39]
	v_mfma_f32_16x16x32_bf16 v[32:35], v[184:187], v[200:203], v[32:35]
	v_mfma_f32_16x16x32_bf16 v[20:23], v[166:169], v[208:211], v[20:23]
	v_mfma_f32_16x16x32_bf16 v[16:19], v[184:187], v[208:211], v[16:19]
	v_mfma_f32_16x16x32_bf16 v[4:7], v[166:169], v[216:219], v[4:7]
	v_mfma_f32_16x16x32_bf16 v[0:3], v[184:187], v[216:219], v[0:3]
	s_setprio 0
	s_barrier
	s_cmp_ge_i32 s88, s37
	s_cbranch_scc1 .LBB0_710

.LBB0_712:
	s_ashr_i32 s6, s16, 31
	s_lshr_b32 s6, s6, 30
	s_add_i32 s8, s16, s6
	s_and_b32 s6, s8, 0xfffffc
	s_sub_i32 s6, s16, s6
	s_mulk_i32 s6, 0x300
	v_lshl_add_u32 v142, s14, 8, v139
	s_ashr_i32 s7, s6, 31
	v_ashrrev_i32_e32 v143, 31, v142
	v_lshl_add_u64 v[142:143], v[142:143], 0, s[6:7]
	v_readlane_b32 s6, v254, 51
	v_lshlrev_b64 v[142:143], 11, v[142:143]
	v_readlane_b32 s7, v254, 52
	s_mov_b32 s71, s45
	v_cvt_pk_bf16_f32 v124, v124, v125
	v_cvt_pk_bf16_f32 v125, v126, v127
	v_cvt_pk_bf16_f32 v126, v120, v121
	v_cvt_pk_bf16_f32 v127, v122, v123
	s_nop 0
	v_lshl_add_u64 v[142:143], s[6:7], 0, v[142:143]
	s_lshl_b32 s6, s8, 6
	s_and_b32 s6, s6, 0xffffff00
	s_ashr_i32 s7, s6, 31
	v_lshl_add_u64 v[142:143], s[6:7], 1, v[142:143]
	v_lshl_add_u64 v[142:143], v[142:143], 0, s[70:71]
	v_lshl_add_u64 v[142:143], v[142:143], 0, v[136:137]
	s_mov_b64 s[6:7], 0x100
	global_store_dwordx4 v[142:143], v[124:127], off sc0 sc1
	s_nop 1
	v_cvt_pk_bf16_f32 v116, v116, v117
	v_cvt_pk_bf16_f32 v117, v118, v119
	v_cvt_pk_bf16_f32 v118, v112, v113
	v_lshl_add_u64 v[112:113], v[142:143], 0, s[6:7]
	s_mov_b64 s[6:7], 0x8000
	v_cvt_pk_bf16_f32 v119, v114, v115
	s_nop 0
	global_store_dwordx4 v[112:113], v[116:119], off sc0 sc1
	s_nop 1
	v_lshl_add_u64 v[112:113], v[142:143], 0, s[6:7]
	s_mov_b64 s[6:7], 0x8100
	v_cvt_pk_bf16_f32 v108, v108, v109
	v_cvt_pk_bf16_f32 v109, v110, v111
	v_cvt_pk_bf16_f32 v110, v104, v105
	v_cvt_pk_bf16_f32 v111, v106, v107
	s_nop 0
	global_store_dwordx4 v[112:113], v[108:111], off sc0 sc1
	s_nop 1
	v_cvt_pk_bf16_f32 v100, v100, v101
	v_cvt_pk_bf16_f32 v101, v102, v103
	v_cvt_pk_bf16_f32 v102, v96, v97
	v_lshl_add_u64 v[96:97], v[142:143], 0, s[6:7]
	s_mov_b64 s[6:7], 0x10000
	v_cvt_pk_bf16_f32 v103, v98, v99
	s_nop 0
	global_store_dwordx4 v[96:97], v[100:103], off sc0 sc1
	s_nop 1
	v_lshl_add_u64 v[96:97], v[142:143], 0, s[6:7]
	s_mov_b64 s[6:7], 0x10100
	v_cvt_pk_bf16_f32 v92, v92, v93
	v_cvt_pk_bf16_f32 v93, v94, v95
	v_cvt_pk_bf16_f32 v94, v88, v89
	v_cvt_pk_bf16_f32 v95, v90, v91
	s_nop 0
	global_store_dwordx4 v[96:97], v[92:95], off sc0 sc1
	s_nop 1
	v_cvt_pk_bf16_f32 v84, v84, v85
	v_cvt_pk_bf16_f32 v85, v86, v87
	v_cvt_pk_bf16_f32 v86, v80, v81
	v_lshl_add_u64 v[80:81], v[142:143], 0, s[6:7]
	s_mov_b64 s[6:7], 0x18000
	v_cvt_pk_bf16_f32 v87, v82, v83
	s_nop 0
	global_store_dwordx4 v[80:81], v[84:87], off sc0 sc1
	s_nop 1
	v_lshl_add_u64 v[80:81], v[142:143], 0, s[6:7]
	s_mov_b64 s[6:7], 0x18100
	v_cvt_pk_bf16_f32 v76, v76, v77
	v_cvt_pk_bf16_f32 v77, v78, v79
	v_cvt_pk_bf16_f32 v78, v72, v73
	v_cvt_pk_bf16_f32 v79, v74, v75
	s_nop 0
	global_store_dwordx4 v[80:81], v[76:79], off sc0 sc1
	s_nop 1
	v_cvt_pk_bf16_f32 v68, v68, v69
	v_cvt_pk_bf16_f32 v69, v70, v71
	v_cvt_pk_bf16_f32 v70, v64, v65
	v_lshl_add_u64 v[64:65], v[142:143], 0, s[6:7]
	s_mov_b64 s[6:7], 0x40000
	v_cvt_pk_bf16_f32 v71, v66, v67
	s_nop 0
	global_store_dwordx4 v[64:65], v[68:71], off sc0 sc1
	s_nop 1
	v_lshl_add_u64 v[64:65], v[142:143], 0, s[6:7]
	s_mov_b64 s[6:7], 0x40100
	v_cvt_pk_bf16_f32 v60, v60, v61
	v_cvt_pk_bf16_f32 v61, v62, v63
	v_cvt_pk_bf16_f32 v62, v56, v57
	v_cvt_pk_bf16_f32 v63, v58, v59
	s_nop 0
	global_store_dwordx4 v[64:65], v[60:63], off sc0 sc1
	s_nop 1
	v_cvt_pk_bf16_f32 v52, v52, v53
	v_cvt_pk_bf16_f32 v53, v54, v55
	v_cvt_pk_bf16_f32 v54, v48, v49
	v_lshl_add_u64 v[48:49], v[142:143], 0, s[6:7]
	s_mov_b64 s[6:7], 0x48000
	v_cvt_pk_bf16_f32 v55, v50, v51
	s_nop 0
	global_store_dwordx4 v[48:49], v[52:55], off sc0 sc1
	s_nop 1
	v_lshl_add_u64 v[48:49], v[142:143], 0, s[6:7]
	s_mov_b64 s[6:7], 0x48100
	v_cvt_pk_bf16_f32 v44, v44, v45
	v_cvt_pk_bf16_f32 v45, v46, v47
	v_cvt_pk_bf16_f32 v46, v40, v41
	v_cvt_pk_bf16_f32 v47, v42, v43
	s_nop 0
	global_store_dwordx4 v[48:49], v[44:47], off sc0 sc1
	s_nop 1
	v_cvt_pk_bf16_f32 v36, v36, v37
	v_cvt_pk_bf16_f32 v37, v38, v39
	v_cvt_pk_bf16_f32 v38, v32, v33
	v_lshl_add_u64 v[32:33], v[142:143], 0, s[6:7]
	s_mov_b64 s[6:7], 0x50000
	v_cvt_pk_bf16_f32 v39, v34, v35
	s_nop 0
	global_store_dwordx4 v[32:33], v[36:39], off sc0 sc1
	s_nop 1
	v_lshl_add_u64 v[32:33], v[142:143], 0, s[6:7]
	s_mov_b64 s[6:7], 0x50100
	v_cvt_pk_bf16_f32 v28, v28, v29
	v_cvt_pk_bf16_f32 v29, v30, v31
	v_cvt_pk_bf16_f32 v30, v24, v25
	v_cvt_pk_bf16_f32 v31, v26, v27
	s_nop 0
	global_store_dwordx4 v[32:33], v[28:31], off sc0 sc1
	s_nop 1
	v_cvt_pk_bf16_f32 v20, v20, v21
	v_cvt_pk_bf16_f32 v21, v22, v23
	v_cvt_pk_bf16_f32 v22, v16, v17
	v_lshl_add_u64 v[16:17], v[142:143], 0, s[6:7]
	s_mov_b64 s[6:7], 0x58000
	v_cvt_pk_bf16_f32 v23, v18, v19
	s_nop 0
	global_store_dwordx4 v[16:17], v[20:23], off sc0 sc1
	s_nop 1
	v_lshl_add_u64 v[16:17], v[142:143], 0, s[6:7]
	s_mov_b64 s[6:7], 0x58100
	v_cvt_pk_bf16_f32 v12, v12, v13
	v_cvt_pk_bf16_f32 v13, v14, v15
	v_cvt_pk_bf16_f32 v14, v8, v9
	v_cvt_pk_bf16_f32 v15, v10, v11
	s_nop 0
	global_store_dwordx4 v[16:17], v[12:15], off sc0 sc1
	s_nop 1
	v_cvt_pk_bf16_f32 v4, v4, v5
	v_cvt_pk_bf16_f32 v5, v6, v7
	v_cvt_pk_bf16_f32 v6, v0, v1
	v_cvt_pk_bf16_f32 v7, v2, v3
	v_lshl_add_u64 v[0:1], v[142:143], 0, s[6:7]
	global_store_dwordx4 v[0:1], v[4:7], off sc0 sc1
	s_nop 1
	s_nop 0
	s_mov_b64 s[6:7], exec
	v_readlane_b32 s8, v254, 0
	v_readlane_b32 s9, v254, 1
	s_and_b64 s[8:9], s[6:7], s[8:9]
	s_mov_b64 exec, s[8:9]
	s_cbranch_execz .LBB0_715
	s_mov_b64 s[8:9], exec
	v_mbcnt_lo_u32_b32 v0, s8, 0
	v_mbcnt_hi_u32_b32 v0, s9, v0
	v_cmp_eq_u32_e32 vcc, 0, v0
	s_and_b64 s[18:19], exec, vcc
	s_mov_b64 exec, s[18:19]
	s_cbranch_execz .LBB0_715
	s_lshl_b32 s18, s14, 6
	s_ashr_i32 s19, s18, 31
	s_lshl_b64 s[18:19], s[18:19], 2
	s_add_u32 s18, s56, s18
	s_addc_u32 s19, s57, s19
	s_bcnt1_i32_b64 s8, s[8:9]
	v_mov_b32_e32 v0, s8
	s_sub_u32 s98, s18, 1
	s_subb_u32 s99, s19, 0

.Ldp_3_x:
	s_barrier
.LBB0_719:
	v_mov_b32_e32 v48, v152
	v_readlane_b32 s36, v254, 4
	v_ashrrev_i32_e32 v49, 31, v48
	v_lshlrev_b64 v[50:51], 4, v[48:49]
	v_lshl_add_u64 v[22:23], s[66:67], 0, v[50:51]
	s_waitcnt lgkmcnt(0)
	global_load_dwordx4 v[0:3], v[22:23], off
	v_readlane_b32 s37, v254, 5
	v_readlane_b32 s38, v254, 6
	v_readlane_b32 s39, v254, 7
	s_mov_b64 s[8:9], s[36:37]
	s_cmp_lg_u64 s[8:9], 0
	s_cselect_b64 s[0:1], -1, 0
	s_cmp_eq_u64 s[8:9], 0
	v_lshl_add_u64 v[32:33], s[8:9], 0, v[50:51]
	v_mov_b32_e32 v4, 0
	v_mov_b32_e32 v8, 0
	v_mov_b32_e32 v9, 0
	v_mov_b32_e32 v10, 0
	v_mov_b32_e32 v11, 0
	v_readlane_b32 s40, v254, 8
	v_readlane_b32 s41, v254, 9
	v_readlane_b32 s42, v254, 10
	v_readlane_b32 s43, v254, 11
	v_readlane_b32 s44, v254, 12
	v_readlane_b32 s45, v254, 13
	v_readlane_b32 s46, v254, 14
	v_readlane_b32 s47, v254, 15
	v_readlane_b32 s48, v254, 16
	v_readlane_b32 s49, v254, 17
	v_readlane_b32 s50, v254, 18
	v_readlane_b32 s51, v254, 19
	s_mov_b64 s[10:11], s[38:39]
	s_cbranch_scc1 .LBB0_721
	global_load_dwordx4 v[8:11], v[32:33], off

.LBB0_1116:
	s_or_b32 s52, s43, 1
	v_add_u32_e32 v142, s28, v145
	s_lshl_b64 s[10:11], s[52:53], 7
	s_add_i32 s52, s43, 2
	ds_read_b128 v[156:159], v142
	ds_read_b128 v[160:163], v142 offset:1024
	ds_read_b128 v[164:167], v142 offset:2048
	ds_read_b128 v[168:171], v142 offset:3072
	v_add_u32_e32 v142, s29, v145
	s_lshl_b64 s[6:7], s[52:53], 7
	ds_read_b128 v[172:175], v142
	ds_read_b128 v[176:179], v142 offset:1024
	ds_read_b128 v[180:183], v142 offset:2048
	ds_read_b128 v[184:187], v142 offset:3072
	s_add_u32 s18, s80, s6
	s_addc_u32 s19, s81, s7
	s_and_b64 s[8:9], s[86:87], exec
	s_cselect_b32 s9, s16, s19
	s_cselect_b32 s8, s17, s18
	s_add_u32 s18, s82, s6
	s_addc_u32 s19, s83, s7
	s_and_b64 s[6:7], s[86:87], exec
	s_cselect_b32 s7, s55, s19
	s_cselect_b32 s6, s63, s18
	s_add_u32 s10, s69, s10
	s_addc_u32 s11, s71, s11
	v_lshl_add_u64 v[142:143], s[10:11], 0, v[128:129]
	s_add_i32 m0, s40, 0xc000
	ds_read_b128 v[188:191], v146
	ds_read_b128 v[192:195], v146 offset:1024
	ds_read_b128 v[196:199], v146 offset:2048
	ds_read_b128 v[200:203], v146 offset:3072
	ds_read_b128 v[204:207], v146 offset:4096
	ds_read_b128 v[208:211], v146 offset:5120
	ds_read_b128 v[212:215], v146 offset:6144
	ds_read_b128 v[216:219], v146 offset:7168
	global_load_lds_dwordx4 v[142:143], off
	v_lshl_add_u64 v[142:143], s[10:11], 0, v[132:133]
	s_add_i32 m0, s40, 0xe000
	s_nop 0
	global_load_lds_dwordx4 v[142:143], off
	s_cmp_eq_u32 s99, 0
	s_cbranch_scc1 .Ldpw_4_0a
	s_waitcnt vmcnt(16)
	s_branch .Ldpw_4_0b

.Ldpw_4_0b:
	s_waitcnt lgkmcnt(0)
	s_barrier
	s_setprio 1
	s_waitcnt lgkmcnt(0)
	v_mfma_f32_16x16x32_bf16 v[124:127], v[156:159], v[188:191], v[124:127]
	v_mfma_f32_16x16x32_bf16 v[120:123], v[164:167], v[188:191], v[120:123]
	v_mfma_f32_16x16x32_bf16 v[108:111], v[156:159], v[196:199], v[108:111]
	v_mfma_f32_16x16x32_bf16 v[104:107], v[164:167], v[196:199], v[104:107]
	v_mfma_f32_16x16x32_bf16 v[92:95], v[156:159], v[204:207], v[92:95]
	v_mfma_f32_16x16x32_bf16 v[88:91], v[164:167], v[204:207], v[88:91]
	v_mfma_f32_16x16x32_bf16 v[76:79], v[156:159], v[212:215], v[76:79]
	v_mfma_f32_16x16x32_bf16 v[72:75], v[164:167], v[212:215], v[72:75]
	v_mfma_f32_16x16x32_bf16 v[124:127], v[160:163], v[192:195], v[124:127]
	v_mfma_f32_16x16x32_bf16 v[120:123], v[168:171], v[192:195], v[120:123]
	v_mfma_f32_16x16x32_bf16 v[108:111], v[160:163], v[200:203], v[108:111]
	v_mfma_f32_16x16x32_bf16 v[104:107], v[168:171], v[200:203], v[104:107]
	v_mfma_f32_16x16x32_bf16 v[92:95], v[160:163], v[208:211], v[92:95]
	v_mfma_f32_16x16x32_bf16 v[88:91], v[168:171], v[208:211], v[88:91]
	v_mfma_f32_16x16x32_bf16 v[76:79], v[160:163], v[216:219], v[76:79]
	v_mfma_f32_16x16x32_bf16 v[72:75], v[168:171], v[216:219], v[72:75]
	s_setprio 0
	s_setprio 1
	v_mfma_f32_16x16x32_bf16 v[116:119], v[172:175], v[188:191], v[116:119]
	v_mfma_f32_16x16x32_bf16 v[112:115], v[180:183], v[188:191], v[112:115]
	v_mfma_f32_16x16x32_bf16 v[100:103], v[172:175], v[196:199], v[100:103]
	v_mfma_f32_16x16x32_bf16 v[96:99], v[180:183], v[196:199], v[96:99]
	v_mfma_f32_16x16x32_bf16 v[84:87], v[172:175], v[204:207], v[84:87]
	v_mfma_f32_16x16x32_bf16 v[80:83], v[180:183], v[204:207], v[80:83]
	v_mfma_f32_16x16x32_bf16 v[68:71], v[172:175], v[212:215], v[68:71]
	v_mfma_f32_16x16x32_bf16 v[64:67], v[180:183], v[212:215], v[64:67]
	v_mfma_f32_16x16x32_bf16 v[116:119], v[176:179], v[192:195], v[116:119]
	v_mfma_f32_16x16x32_bf16 v[112:115], v[184:187], v[192:195], v[112:115]
	v_mfma_f32_16x16x32_bf16 v[100:103], v[176:179], v[200:203], v[100:103]
	v_mfma_f32_16x16x32_bf16 v[96:99], v[184:187], v[200:203], v[96:99]
	v_mfma_f32_16x16x32_bf16 v[84:87], v[176:179], v[208:211], v[84:87]
	v_mfma_f32_16x16x32_bf16 v[80:83], v[184:187], v[208:211], v[80:83]
	v_mfma_f32_16x16x32_bf16 v[68:71], v[176:179], v[216:219], v[68:71]
	v_mfma_f32_16x16x32_bf16 v[64:67], v[184:187], v[216:219], v[64:67]
	s_setprio 0
	s_barrier
	s_add_i32 s10, s28, s15
	v_lshl_add_u64 v[142:143], s[6:7], 0, v[130:131]
	s_mov_b32 m0, s10
	ds_read_b128 v[188:191], v146 offset:16384
	ds_read_b128 v[192:195], v146 offset:17408
	ds_read_b128 v[196:199], v146 offset:18432
	ds_read_b128 v[200:203], v146 offset:19456
	ds_read_b128 v[204:207], v146 offset:20480
	ds_read_b128 v[208:211], v146 offset:21504
	ds_read_b128 v[212:215], v146 offset:22528
	ds_read_b128 v[216:219], v146 offset:23552
	global_load_lds_dwordx4 v[142:143], off
	s_add_i32 m0, s10, 0x2000
	s_add_u32 s10, s6, 0x40000
	v_lshl_add_u64 v[220:221], s[6:7], 0, v[134:135]
	s_addc_u32 s11, s7, 0
	s_add_i32 s18, s29, s15
	global_load_lds_dwordx4 v[220:221], off
	v_lshl_add_u64 v[222:223], s[10:11], 0, v[130:131]
	s_mov_b32 m0, s18
	v_lshl_add_u64 v[224:225], s[8:9], 0, v[132:133]
	global_load_lds_dwordx4 v[222:223], off
	v_lshl_add_u64 v[222:223], s[10:11], 0, v[134:135]
	s_add_i32 m0, s18, 0x2000
	s_nop 0
	global_load_lds_dwordx4 v[222:223], off
	v_lshl_add_u64 v[222:223], s[8:9], 0, v[128:129]
	s_mov_b32 m0, s40
	s_nop 0
	global_load_lds_dwordx4 v[222:223], off
	s_mov_b32 m0, s41
	s_nop 0
	global_load_lds_dwordx4 v[224:225], off
	s_cmp_eq_u32 s99, 0
	s_cbranch_scc1 .Ldpw_4_1a
	s_waitcnt vmcnt(16)
	s_branch .Ldpw_4_1b

.Ldpw_4_1b:
	s_waitcnt lgkmcnt(0)
	s_barrier
	s_setprio 1
	s_waitcnt lgkmcnt(0)
	v_mfma_f32_16x16x32_bf16 v[60:63], v[156:159], v[188:191], v[60:63]
	v_mfma_f32_16x16x32_bf16 v[56:59], v[164:167], v[188:191], v[56:59]
	v_mfma_f32_16x16x32_bf16 v[44:47], v[156:159], v[196:199], v[44:47]
	v_mfma_f32_16x16x32_bf16 v[40:43], v[164:167], v[196:199], v[40:43]
	v_mfma_f32_16x16x32_bf16 v[28:31], v[156:159], v[204:207], v[28:31]
	v_mfma_f32_16x16x32_bf16 v[24:27], v[164:167], v[204:207], v[24:27]
	v_mfma_f32_16x16x32_bf16 v[12:15], v[156:159], v[212:215], v[12:15]
	v_mfma_f32_16x16x32_bf16 v[8:11], v[164:167], v[212:215], v[8:11]
	v_mfma_f32_16x16x32_bf16 v[60:63], v[160:163], v[192:195], v[60:63]
	v_mfma_f32_16x16x32_bf16 v[56:59], v[168:171], v[192:195], v[56:59]
	v_mfma_f32_16x16x32_bf16 v[44:47], v[160:163], v[200:203], v[44:47]
	v_mfma_f32_16x16x32_bf16 v[40:43], v[168:171], v[200:203], v[40:43]
	v_mfma_f32_16x16x32_bf16 v[28:31], v[160:163], v[208:211], v[28:31]
	v_mfma_f32_16x16x32_bf16 v[24:27], v[168:171], v[208:211], v[24:27]
	v_mfma_f32_16x16x32_bf16 v[12:15], v[160:163], v[216:219], v[12:15]
	v_mfma_f32_16x16x32_bf16 v[8:11], v[168:171], v[216:219], v[8:11]
	s_setprio 0
	s_setprio 1
	v_mfma_f32_16x16x32_bf16 v[52:55], v[172:175], v[188:191], v[52:55]
	v_mfma_f32_16x16x32_bf16 v[48:51], v[180:183], v[188:191], v[48:51]
	v_mfma_f32_16x16x32_bf16 v[36:39], v[172:175], v[196:199], v[36:39]
	v_mfma_f32_16x16x32_bf16 v[32:35], v[180:183], v[196:199], v[32:35]
	v_mfma_f32_16x16x32_bf16 v[20:23], v[172:175], v[204:207], v[20:23]
	v_mfma_f32_16x16x32_bf16 v[16:19], v[180:183], v[204:207], v[16:19]
	v_mfma_f32_16x16x32_bf16 v[4:7], v[172:175], v[212:215], v[4:7]
	v_mfma_f32_16x16x32_bf16 v[0:3], v[180:183], v[212:215], v[0:3]
	v_mfma_f32_16x16x32_bf16 v[52:55], v[176:179], v[192:195], v[52:55]
	v_mfma_f32_16x16x32_bf16 v[48:51], v[184:187], v[192:195], v[48:51]
	v_mfma_f32_16x16x32_bf16 v[36:39], v[176:179], v[200:203], v[36:39]
	v_mfma_f32_16x16x32_bf16 v[32:35], v[184:187], v[200:203], v[32:35]
	v_mfma_f32_16x16x32_bf16 v[20:23], v[176:179], v[208:211], v[20:23]
	v_mfma_f32_16x16x32_bf16 v[16:19], v[184:187], v[208:211], v[16:19]
	v_mfma_f32_16x16x32_bf16 v[4:7], v[176:179], v[216:219], v[4:7]
	v_mfma_f32_16x16x32_bf16 v[0:3], v[184:187], v[216:219], v[0:3]
	s_setprio 0
	s_barrier
	s_add_i32 s10, 0, 0x18000
	v_add_u32_e32 v147, s10, v145
	s_add_i32 s11, 0, 0x1c000
	ds_read_b128 v[156:159], v147
	ds_read_b128 v[160:163], v147 offset:1024
	ds_read_b128 v[164:167], v147 offset:2048
	ds_read_b128 v[168:171], v147 offset:3072
	v_add_u32_e32 v147, s11, v145
	ds_read_b128 v[172:175], v147
	ds_read_b128 v[176:179], v147 offset:1024
	ds_read_b128 v[180:183], v147 offset:2048
	ds_read_b128 v[184:187], v147 offset:3072
	s_add_u32 s8, s8, 0x40000
	s_addc_u32 s9, s9, 0
	s_mov_b32 m0, s48
	v_lshl_add_u64 v[226:227], s[8:9], 0, v[128:129]
	ds_read_b128 v[188:191], v146 offset:32768
	ds_read_b128 v[192:195], v146 offset:33792
	ds_read_b128 v[196:199], v146 offset:34816
	ds_read_b128 v[200:203], v146 offset:35840
	ds_read_b128 v[204:207], v146 offset:36864
	ds_read_b128 v[208:211], v146 offset:37888
	ds_read_b128 v[212:215], v146 offset:38912
	ds_read_b128 v[216:219], v146 offset:39936
	global_load_lds_dwordx4 v[226:227], off
	v_lshl_add_u64 v[226:227], s[8:9], 0, v[132:133]
	s_mov_b32 m0, s49
	s_nop 0
	global_load_lds_dwordx4 v[226:227], off
	s_waitcnt vmcnt(8)
	s_cmp_eq_u32 s99, 0
	s_cbranch_scc1 .Ldp_4_l
	v_readlane_b32 s100, v0, 0
	s_mov_b64 exec, 1
	v_writelane_b32 v0, 1, 0
	s_nop 1
	global_atomic_add v0, v0, s[98:99]
	s_nop 1
	v_writelane_b32 v0, s100, 0
	s_mov_b64 exec, -1
	s_mov_b32 s99, 0
.Ldp_4_l:
	s_waitcnt lgkmcnt(0)
	s_barrier
	s_setprio 1
	s_waitcnt lgkmcnt(0)
	v_mfma_f32_16x16x32_bf16 v[124:127], v[156:159], v[188:191], v[124:127]
	v_mfma_f32_16x16x32_bf16 v[120:123], v[164:167], v[188:191], v[120:123]
	v_mfma_f32_16x16x32_bf16 v[108:111], v[156:159], v[196:199], v[108:111]
	v_mfma_f32_16x16x32_bf16 v[104:107], v[164:167], v[196:199], v[104:107]
	v_mfma_f32_16x16x32_bf16 v[92:95], v[156:159], v[204:207], v[92:95]
	v_mfma_f32_16x16x32_bf16 v[88:91], v[164:167], v[204:207], v[88:91]
	v_mfma_f32_16x16x32_bf16 v[76:79], v[156:159], v[212:215], v[76:79]
	v_mfma_f32_16x16x32_bf16 v[72:75], v[164:167], v[212:215], v[72:75]
	v_mfma_f32_16x16x32_bf16 v[124:127], v[160:163], v[192:195], v[124:127]
	v_mfma_f32_16x16x32_bf16 v[120:123], v[168:171], v[192:195], v[120:123]
	v_mfma_f32_16x16x32_bf16 v[108:111], v[160:163], v[200:203], v[108:111]
	v_mfma_f32_16x16x32_bf16 v[104:107], v[168:171], v[200:203], v[104:107]
	v_mfma_f32_16x16x32_bf16 v[92:95], v[160:163], v[208:211], v[92:95]
	v_mfma_f32_16x16x32_bf16 v[88:91], v[168:171], v[208:211], v[88:91]
	v_mfma_f32_16x16x32_bf16 v[76:79], v[160:163], v[216:219], v[76:79]
	v_mfma_f32_16x16x32_bf16 v[72:75], v[168:171], v[216:219], v[72:75]
	s_setprio 0
	s_setprio 1
	v_mfma_f32_16x16x32_bf16 v[116:119], v[172:175], v[188:191], v[116:119]
	v_mfma_f32_16x16x32_bf16 v[112:115], v[180:183], v[188:191], v[112:115]
	v_mfma_f32_16x16x32_bf16 v[100:103], v[172:175], v[196:199], v[100:103]
	v_mfma_f32_16x16x32_bf16 v[96:99], v[180:183], v[196:199], v[96:99]
	v_mfma_f32_16x16x32_bf16 v[84:87], v[172:175], v[204:207], v[84:87]
	v_mfma_f32_16x16x32_bf16 v[80:83], v[180:183], v[204:207], v[80:83]
	v_mfma_f32_16x16x32_bf16 v[68:71], v[172:175], v[212:215], v[68:71]
	v_mfma_f32_16x16x32_bf16 v[64:67], v[180:183], v[212:215], v[64:67]
	v_mfma_f32_16x16x32_bf16 v[116:119], v[176:179], v[192:195], v[116:119]
	v_mfma_f32_16x16x32_bf16 v[112:115], v[184:187], v[192:195], v[112:115]
	v_mfma_f32_16x16x32_bf16 v[100:103], v[176:179], v[200:203], v[100:103]
	v_mfma_f32_16x16x32_bf16 v[96:99], v[184:187], v[200:203], v[96:99]
	v_mfma_f32_16x16x32_bf16 v[84:87], v[176:179], v[208:211], v[84:87]
	v_mfma_f32_16x16x32_bf16 v[80:83], v[184:187], v[208:211], v[80:83]
	v_mfma_f32_16x16x32_bf16 v[68:71], v[176:179], v[216:219], v[68:71]
	v_mfma_f32_16x16x32_bf16 v[64:67], v[184:187], v[216:219], v[64:67]
	s_setprio 0
	s_barrier
	s_add_i32 s8, s10, s15
	v_lshl_add_u64 v[142:143], v[142:143], 0, s[56:57]
	s_mov_b32 m0, s8
	ds_read_b128 v[188:191], v146 offset:49152
	ds_read_b128 v[192:195], v146 offset:50176
	ds_read_b128 v[196:199], v146 offset:51200
	ds_read_b128 v[200:203], v146 offset:52224
	ds_read_b128 v[204:207], v146 offset:53248
	ds_read_b128 v[208:211], v146 offset:54272
	ds_read_b128 v[212:215], v146 offset:55296
	ds_read_b128 v[216:219], v146 offset:56320
	global_load_lds_dwordx4 v[142:143], off
	s_add_i32 m0, s8, 0x2000
	s_add_u32 s6, s6, 0x40080
	v_lshl_add_u64 v[142:143], v[220:221], 0, s[56:57]
	s_addc_u32 s7, s7, 0
	s_add_i32 s8, s11, s15
	global_load_lds_dwordx4 v[142:143], off
	v_lshl_add_u64 v[142:143], s[6:7], 0, v[130:131]
	s_mov_b32 m0, s8
	s_nop 0
	global_load_lds_dwordx4 v[142:143], off
	v_lshl_add_u64 v[142:143], s[6:7], 0, v[134:135]
	s_add_i32 m0, s8, 0x2000
	s_nop 0
	global_load_lds_dwordx4 v[142:143], off
	v_lshl_add_u64 v[142:143], v[222:223], 0, s[56:57]
	s_mov_b32 m0, s79
	s_nop 0
	global_load_lds_dwordx4 v[142:143], off
	v_lshl_add_u64 v[142:143], v[224:225], 0, s[56:57]
	s_mov_b32 m0, s27
	s_nop 0
	global_load_lds_dwordx4 v[142:143], off
	s_waitcnt vmcnt(8)
	s_waitcnt lgkmcnt(0)
	s_barrier
	s_setprio 1
	s_waitcnt lgkmcnt(0)
	v_mfma_f32_16x16x32_bf16 v[60:63], v[156:159], v[188:191], v[60:63]
	v_mfma_f32_16x16x32_bf16 v[56:59], v[164:167], v[188:191], v[56:59]
	v_mfma_f32_16x16x32_bf16 v[44:47], v[156:159], v[196:199], v[44:47]
	v_mfma_f32_16x16x32_bf16 v[40:43], v[164:167], v[196:199], v[40:43]
	v_mfma_f32_16x16x32_bf16 v[28:31], v[156:159], v[204:207], v[28:31]
	v_mfma_f32_16x16x32_bf16 v[24:27], v[164:167], v[204:207], v[24:27]
	v_mfma_f32_16x16x32_bf16 v[12:15], v[156:159], v[212:215], v[12:15]
	v_mfma_f32_16x16x32_bf16 v[8:11], v[164:167], v[212:215], v[8:11]
	v_mfma_f32_16x16x32_bf16 v[60:63], v[160:163], v[192:195], v[60:63]
	v_mfma_f32_16x16x32_bf16 v[56:59], v[168:171], v[192:195], v[56:59]
	v_mfma_f32_16x16x32_bf16 v[44:47], v[160:163], v[200:203], v[44:47]
	v_mfma_f32_16x16x32_bf16 v[40:43], v[168:171], v[200:203], v[40:43]
	v_mfma_f32_16x16x32_bf16 v[28:31], v[160:163], v[208:211], v[28:31]
	v_mfma_f32_16x16x32_bf16 v[24:27], v[168:171], v[208:211], v[24:27]
	v_mfma_f32_16x16x32_bf16 v[12:15], v[160:163], v[216:219], v[12:15]
	v_mfma_f32_16x16x32_bf16 v[8:11], v[168:171], v[216:219], v[8:11]
	s_setprio 0
	s_setprio 1
	v_mfma_f32_16x16x32_bf16 v[52:55], v[172:175], v[188:191], v[52:55]
	v_mfma_f32_16x16x32_bf16 v[48:51], v[180:183], v[188:191], v[48:51]
	v_mfma_f32_16x16x32_bf16 v[36:39], v[172:175], v[196:199], v[36:39]
	v_mfma_f32_16x16x32_bf16 v[32:35], v[180:183], v[196:199], v[32:35]
	v_mfma_f32_16x16x32_bf16 v[20:23], v[172:175], v[204:207], v[20:23]
	v_mfma_f32_16x16x32_bf16 v[16:19], v[180:183], v[204:207], v[16:19]
	v_mfma_f32_16x16x32_bf16 v[4:7], v[172:175], v[212:215], v[4:7]
	v_mfma_f32_16x16x32_bf16 v[0:3], v[180:183], v[212:215], v[0:3]
	v_mfma_f32_16x16x32_bf16 v[52:55], v[176:179], v[192:195], v[52:55]
	v_mfma_f32_16x16x32_bf16 v[48:51], v[184:187], v[192:195], v[48:51]
	v_mfma_f32_16x16x32_bf16 v[36:39], v[176:179], v[200:203], v[36:39]
	v_mfma_f32_16x16x32_bf16 v[32:35], v[184:187], v[200:203], v[32:35]
	v_mfma_f32_16x16x32_bf16 v[20:23], v[176:179], v[208:211], v[20:23]
	v_mfma_f32_16x16x32_bf16 v[16:19], v[184:187], v[208:211], v[16:19]
	v_mfma_f32_16x16x32_bf16 v[4:7], v[176:179], v[216:219], v[4:7]
	v_mfma_f32_16x16x32_bf16 v[0:3], v[184:187], v[216:219], v[0:3]
	s_setprio 0
	s_barrier
	s_cmp_gt_u32 s43, 13
	s_mov_b32 s43, s52
	s_cbranch_scc1 .LBB0_1186

.LBB0_1188:
	v_readlane_b32 s6, v254, 37
	v_readlane_b32 s7, v254, 38
	v_lshl_add_u32 v147, s14, 8, v144
	s_mov_b32 s63, s53
	v_mov_b64_e32 v[142:143], s[6:7]
	s_movk_i32 s6, 0x1600
	v_mad_i64_i32 v[142:143], s[6:7], v147, s6, v[142:143]
	v_mul_f32_e32 v147, 0xbfb8aa3b, v124
	v_exp_f32_e32 v147, v147
	s_lshl_b32 s6, s78, 7
	s_ashr_i32 s7, s6, 31
	v_lshl_add_u64 v[142:143], s[6:7], 1, v[142:143]
	v_add_f32_e32 v147, 1.0, v147
	v_rcp_f32_e32 v156, v147
	v_mul_f32_e32 v147, 0xbfb8aa3b, v120
	v_exp_f32_e32 v147, v147
	v_lshl_add_u64 v[142:143], v[142:143], 0, s[62:63]
	v_lshl_add_u64 v[142:143], v[142:143], 0, v[136:137]
	s_mov_b64 s[6:7], 0x16000
	v_add_f32_e32 v147, 1.0, v147
	v_rcp_f32_e32 v158, v147
	v_mul_f32_e32 v147, 0xbfb8aa3b, v125
	v_exp_f32_e32 v147, v147
	s_nop 0
	v_add_f32_e32 v147, 1.0, v147
	v_rcp_f32_e32 v157, v147
	v_mul_f32_e32 v147, 0xbfb8aa3b, v121
	v_exp_f32_e32 v147, v147
	v_pk_mul_f32 v[124:125], v[124:125], v[156:157]
	s_nop 0
	v_pk_mul_f32 v[116:117], v[124:125], v[116:117]
	v_add_f32_e32 v147, 1.0, v147
	v_rcp_f32_e32 v159, v147
	v_mul_f32_e32 v147, 0xbfb8aa3b, v126
	v_exp_f32_e32 v147, v147
	v_pk_mul_f32 v[120:121], v[120:121], v[158:159]
	v_add_f32_e32 v147, 1.0, v147
	v_rcp_f32_e32 v160, v147
	v_mul_f32_e32 v147, 0xbfb8aa3b, v122
	v_exp_f32_e32 v147, v147
	s_nop 0
	v_add_f32_e32 v147, 1.0, v147
	v_rcp_f32_e32 v162, v147
	v_mul_f32_e32 v147, 0xbfb8aa3b, v127
	v_exp_f32_e32 v147, v147
	s_nop 0
	v_add_f32_e32 v147, 1.0, v147
	v_rcp_f32_e32 v161, v147
	v_mul_f32_e32 v147, 0xbfb8aa3b, v123
	v_exp_f32_e32 v147, v147
	v_pk_mul_f32 v[126:127], v[126:127], v[160:161]
	s_nop 0
	v_pk_mul_f32 v[118:119], v[126:127], v[118:119]
	v_add_f32_e32 v147, 1.0, v147
	v_rcp_f32_e32 v163, v147
	s_nop 0
	v_pk_mul_f32 v[122:123], v[122:123], v[162:163]
	s_nop 0
	v_pk_mul_f32 v[122:123], v[122:123], v[114:115]
	v_pk_mul_f32 v[114:115], v[120:121], v[112:113]
	v_cvt_pk_bf16_f32 v112, v116, v117
	v_cvt_pk_bf16_f32 v113, v118, v119
	v_mul_f32_e32 v117, 0xbfb8aa3b, v106
	v_cvt_pk_bf16_f32 v114, v114, v115
	v_cvt_pk_bf16_f32 v115, v122, v123
	v_exp_f32_e32 v117, v117
	global_store_dwordx4 v[142:143], v[112:115], off sc0 sc1
	s_nop 1
	v_mul_f32_e32 v113, 0xbfb8aa3b, v104
	v_exp_f32_e32 v113, v113
	v_mul_f32_e32 v112, 0xbfb8aa3b, v108
	v_exp_f32_e32 v112, v112
	v_add_f32_e32 v117, 1.0, v117
	v_add_f32_e32 v113, 1.0, v113
	v_rcp_f32_e32 v114, v113
	v_mul_f32_e32 v113, 0xbfb8aa3b, v109
	v_exp_f32_e32 v113, v113
	v_add_f32_e32 v112, 1.0, v112
	v_rcp_f32_e32 v112, v112
	v_mul_f32_e32 v115, 0xbfb8aa3b, v105
	v_add_f32_e32 v113, 1.0, v113
	v_rcp_f32_e32 v113, v113
	v_mul_f32_e32 v116, 0xbfb8aa3b, v110
	v_rcp_f32_e32 v118, v117
	v_mul_f32_e32 v117, 0xbfb8aa3b, v111
	v_pk_mul_f32 v[108:109], v[108:109], v[112:113]
	v_mul_f32_e32 v112, 0xbfb8aa3b, v107
	v_exp_f32_e32 v115, v115
	v_exp_f32_e32 v116, v116
	v_exp_f32_e32 v117, v117
	v_exp_f32_e32 v112, v112
	v_add_f32_e32 v115, 1.0, v115
	v_add_f32_e32 v116, 1.0, v116
	v_add_f32_e32 v117, 1.0, v117
	v_add_f32_e32 v112, 1.0, v112
	v_rcp_f32_e32 v115, v115
	v_rcp_f32_e32 v116, v116
	v_rcp_f32_e32 v117, v117
	v_rcp_f32_e32 v119, v112
	v_pk_mul_f32 v[104:105], v[104:105], v[114:115]
	v_pk_mul_f32 v[100:101], v[108:109], v[100:101]
	v_pk_mul_f32 v[110:111], v[110:111], v[116:117]
	v_pk_mul_f32 v[106:107], v[106:107], v[118:119]
	v_pk_mul_f32 v[102:103], v[110:111], v[102:103]
	v_pk_mul_f32 v[106:107], v[106:107], v[98:99]
	v_pk_mul_f32 v[98:99], v[104:105], v[96:97]
	v_cvt_pk_bf16_f32 v96, v100, v101
	v_cvt_pk_bf16_f32 v97, v102, v103
	v_lshl_add_u64 v[100:101], v[142:143], 0, s[6:7]
	v_cvt_pk_bf16_f32 v98, v98, v99
	v_cvt_pk_bf16_f32 v99, v106, v107
	s_mov_b64 s[6:7], 0x2c000
	global_store_dwordx4 v[100:101], v[96:99], off sc0 sc1
	s_nop 1
	v_mul_f32_e32 v97, 0xbfb8aa3b, v88
	v_exp_f32_e32 v97, v97
	v_mul_f32_e32 v96, 0xbfb8aa3b, v92
	v_exp_f32_e32 v96, v96
	v_mul_f32_e32 v101, 0xbfb8aa3b, v90
	v_add_f32_e32 v97, 1.0, v97
	v_rcp_f32_e32 v98, v97
	v_mul_f32_e32 v97, 0xbfb8aa3b, v93
	v_exp_f32_e32 v97, v97
	v_add_f32_e32 v96, 1.0, v96
	v_exp_f32_e32 v101, v101
	v_rcp_f32_e32 v96, v96
	v_add_f32_e32 v97, 1.0, v97
	v_rcp_f32_e32 v97, v97
	v_add_f32_e32 v101, 1.0, v101
	v_mul_f32_e32 v99, 0xbfb8aa3b, v89
	v_mul_f32_e32 v100, 0xbfb8aa3b, v94
	v_rcp_f32_e32 v102, v101
	v_mul_f32_e32 v101, 0xbfb8aa3b, v95
	v_pk_mul_f32 v[92:93], v[92:93], v[96:97]
	v_mul_f32_e32 v96, 0xbfb8aa3b, v91
	v_exp_f32_e32 v99, v99
	v_exp_f32_e32 v100, v100
	v_exp_f32_e32 v101, v101
	v_exp_f32_e32 v96, v96
	v_add_f32_e32 v99, 1.0, v99
	v_add_f32_e32 v100, 1.0, v100
	v_add_f32_e32 v101, 1.0, v101
	v_add_f32_e32 v96, 1.0, v96
	v_rcp_f32_e32 v99, v99
	v_rcp_f32_e32 v100, v100
	v_rcp_f32_e32 v101, v101
	v_rcp_f32_e32 v103, v96
	v_pk_mul_f32 v[88:89], v[88:89], v[98:99]
	v_pk_mul_f32 v[84:85], v[92:93], v[84:85]
	v_pk_mul_f32 v[94:95], v[94:95], v[100:101]
	v_pk_mul_f32 v[90:91], v[90:91], v[102:103]
	v_pk_mul_f32 v[86:87], v[94:95], v[86:87]
	v_pk_mul_f32 v[90:91], v[90:91], v[82:83]
	v_pk_mul_f32 v[82:83], v[88:89], v[80:81]
	v_cvt_pk_bf16_f32 v80, v84, v85
	v_cvt_pk_bf16_f32 v81, v86, v87
	v_lshl_add_u64 v[84:85], v[142:143], 0, s[6:7]
	v_cvt_pk_bf16_f32 v82, v82, v83
	v_cvt_pk_bf16_f32 v83, v90, v91
	s_mov_b64 s[6:7], 0x42000
	global_store_dwordx4 v[84:85], v[80:83], off sc0 sc1
	s_nop 1
	v_mul_f32_e32 v81, 0xbfb8aa3b, v72
	v_exp_f32_e32 v81, v81
	v_mul_f32_e32 v80, 0xbfb8aa3b, v76
	v_exp_f32_e32 v80, v80
	v_mul_f32_e32 v85, 0xbfb8aa3b, v74
	v_add_f32_e32 v81, 1.0, v81
	v_rcp_f32_e32 v82, v81
	v_mul_f32_e32 v81, 0xbfb8aa3b, v77
	v_exp_f32_e32 v81, v81
	v_add_f32_e32 v80, 1.0, v80
	v_exp_f32_e32 v85, v85
	v_rcp_f32_e32 v80, v80
	v_add_f32_e32 v81, 1.0, v81
	v_rcp_f32_e32 v81, v81
	v_add_f32_e32 v85, 1.0, v85
	v_mul_f32_e32 v83, 0xbfb8aa3b, v73
	v_mul_f32_e32 v84, 0xbfb8aa3b, v78
	v_rcp_f32_e32 v86, v85
	v_mul_f32_e32 v85, 0xbfb8aa3b, v79
	v_pk_mul_f32 v[76:77], v[76:77], v[80:81]
	v_mul_f32_e32 v80, 0xbfb8aa3b, v75
	v_exp_f32_e32 v83, v83
	v_exp_f32_e32 v84, v84
	v_exp_f32_e32 v85, v85
	v_exp_f32_e32 v80, v80
	v_add_f32_e32 v83, 1.0, v83
	v_add_f32_e32 v84, 1.0, v84
	v_add_f32_e32 v85, 1.0, v85
	v_add_f32_e32 v80, 1.0, v80
	v_rcp_f32_e32 v83, v83
	v_rcp_f32_e32 v84, v84
	v_rcp_f32_e32 v85, v85
	v_rcp_f32_e32 v87, v80
	v_pk_mul_f32 v[72:73], v[72:73], v[82:83]
	v_pk_mul_f32 v[68:69], v[76:77], v[68:69]
	v_pk_mul_f32 v[78:79], v[78:79], v[84:85]
	v_pk_mul_f32 v[74:75], v[74:75], v[86:87]
	v_pk_mul_f32 v[70:71], v[78:79], v[70:71]
	v_pk_mul_f32 v[74:75], v[74:75], v[66:67]
	v_pk_mul_f32 v[66:67], v[72:73], v[64:65]
	v_cvt_pk_bf16_f32 v64, v68, v69
	v_cvt_pk_bf16_f32 v65, v70, v71
	v_lshl_add_u64 v[68:69], v[142:143], 0, s[6:7]
	v_cvt_pk_bf16_f32 v66, v66, v67
	v_cvt_pk_bf16_f32 v67, v74, v75
	s_mov_b64 s[6:7], 0xb0000
	global_store_dwordx4 v[68:69], v[64:67], off sc0 sc1
	s_nop 1
	v_mul_f32_e32 v65, 0xbfb8aa3b, v56
	v_exp_f32_e32 v65, v65
	v_mul_f32_e32 v64, 0xbfb8aa3b, v60
	v_exp_f32_e32 v64, v64
	v_mul_f32_e32 v69, 0xbfb8aa3b, v58
	v_add_f32_e32 v65, 1.0, v65
	v_rcp_f32_e32 v66, v65
	v_mul_f32_e32 v65, 0xbfb8aa3b, v61
	v_exp_f32_e32 v65, v65
	v_add_f32_e32 v64, 1.0, v64
	v_exp_f32_e32 v69, v69
	v_rcp_f32_e32 v64, v64
	v_add_f32_e32 v65, 1.0, v65
	v_rcp_f32_e32 v65, v65
	v_add_f32_e32 v69, 1.0, v69
	v_mul_f32_e32 v67, 0xbfb8aa3b, v57
	v_mul_f32_e32 v68, 0xbfb8aa3b, v62
	v_rcp_f32_e32 v70, v69
	v_mul_f32_e32 v69, 0xbfb8aa3b, v63
	v_pk_mul_f32 v[60:61], v[60:61], v[64:65]
	v_mul_f32_e32 v64, 0xbfb8aa3b, v59
	v_exp_f32_e32 v67, v67
	v_exp_f32_e32 v68, v68
	v_exp_f32_e32 v69, v69
	v_exp_f32_e32 v64, v64
	v_add_f32_e32 v67, 1.0, v67
	v_add_f32_e32 v68, 1.0, v68
	v_add_f32_e32 v69, 1.0, v69
	v_add_f32_e32 v64, 1.0, v64
	v_rcp_f32_e32 v67, v67
	v_rcp_f32_e32 v68, v68
	v_rcp_f32_e32 v69, v69
	v_rcp_f32_e32 v71, v64
	v_pk_mul_f32 v[56:57], v[56:57], v[66:67]
	v_pk_mul_f32 v[52:53], v[60:61], v[52:53]
	v_pk_mul_f32 v[62:63], v[62:63], v[68:69]
	v_pk_mul_f32 v[58:59], v[58:59], v[70:71]
	v_pk_mul_f32 v[54:55], v[62:63], v[54:55]
	v_pk_mul_f32 v[58:59], v[58:59], v[50:51]
	v_pk_mul_f32 v[50:51], v[56:57], v[48:49]
	v_cvt_pk_bf16_f32 v48, v52, v53
	v_cvt_pk_bf16_f32 v49, v54, v55
	v_lshl_add_u64 v[52:53], v[142:143], 0, s[6:7]
	v_cvt_pk_bf16_f32 v50, v50, v51
	v_cvt_pk_bf16_f32 v51, v58, v59
	s_mov_b64 s[6:7], 0xc6000
	global_store_dwordx4 v[52:53], v[48:51], off sc0 sc1
	s_nop 1
	v_mul_f32_e32 v49, 0xbfb8aa3b, v40
	v_exp_f32_e32 v49, v49
	v_mul_f32_e32 v48, 0xbfb8aa3b, v44
	v_exp_f32_e32 v48, v48
	v_mul_f32_e32 v53, 0xbfb8aa3b, v42
	v_add_f32_e32 v49, 1.0, v49
	v_rcp_f32_e32 v50, v49
	v_mul_f32_e32 v49, 0xbfb8aa3b, v45
	v_exp_f32_e32 v49, v49
	v_add_f32_e32 v48, 1.0, v48
	v_exp_f32_e32 v53, v53
	v_rcp_f32_e32 v48, v48
	v_add_f32_e32 v49, 1.0, v49
	v_rcp_f32_e32 v49, v49
	v_add_f32_e32 v53, 1.0, v53
	v_mul_f32_e32 v51, 0xbfb8aa3b, v41
	v_mul_f32_e32 v52, 0xbfb8aa3b, v46
	v_rcp_f32_e32 v54, v53
	v_mul_f32_e32 v53, 0xbfb8aa3b, v47
	v_pk_mul_f32 v[44:45], v[44:45], v[48:49]
	v_mul_f32_e32 v48, 0xbfb8aa3b, v43
	v_exp_f32_e32 v51, v51
	v_exp_f32_e32 v52, v52
	v_exp_f32_e32 v53, v53
	v_exp_f32_e32 v48, v48
	v_add_f32_e32 v51, 1.0, v51
	v_add_f32_e32 v52, 1.0, v52
	v_add_f32_e32 v53, 1.0, v53
	v_add_f32_e32 v48, 1.0, v48
	v_rcp_f32_e32 v51, v51
	v_rcp_f32_e32 v52, v52
	v_rcp_f32_e32 v53, v53
	v_rcp_f32_e32 v55, v48
	v_pk_mul_f32 v[40:41], v[40:41], v[50:51]
	v_pk_mul_f32 v[36:37], v[44:45], v[36:37]
	v_pk_mul_f32 v[46:47], v[46:47], v[52:53]
	v_pk_mul_f32 v[42:43], v[42:43], v[54:55]
	v_pk_mul_f32 v[38:39], v[46:47], v[38:39]
	v_pk_mul_f32 v[42:43], v[42:43], v[34:35]
	v_pk_mul_f32 v[34:35], v[40:41], v[32:33]
	v_cvt_pk_bf16_f32 v32, v36, v37
	v_cvt_pk_bf16_f32 v33, v38, v39
	v_lshl_add_u64 v[36:37], v[142:143], 0, s[6:7]
	v_cvt_pk_bf16_f32 v34, v34, v35
	v_cvt_pk_bf16_f32 v35, v42, v43
	s_mov_b64 s[6:7], 0xdc000
	global_store_dwordx4 v[36:37], v[32:35], off sc0 sc1
	s_nop 1
	v_mul_f32_e32 v33, 0xbfb8aa3b, v24
	v_exp_f32_e32 v33, v33
	v_mul_f32_e32 v32, 0xbfb8aa3b, v28
	v_exp_f32_e32 v32, v32
	v_mul_f32_e32 v37, 0xbfb8aa3b, v26
	v_add_f32_e32 v33, 1.0, v33
	v_rcp_f32_e32 v34, v33
	v_mul_f32_e32 v33, 0xbfb8aa3b, v29
	v_exp_f32_e32 v33, v33
	v_add_f32_e32 v32, 1.0, v32
	v_exp_f32_e32 v37, v37
	v_rcp_f32_e32 v32, v32
	v_add_f32_e32 v33, 1.0, v33
	v_rcp_f32_e32 v33, v33
	v_add_f32_e32 v37, 1.0, v37
	v_mul_f32_e32 v35, 0xbfb8aa3b, v25
	v_mul_f32_e32 v36, 0xbfb8aa3b, v30
	v_rcp_f32_e32 v38, v37
	v_mul_f32_e32 v37, 0xbfb8aa3b, v31
	v_pk_mul_f32 v[28:29], v[28:29], v[32:33]
	v_mul_f32_e32 v32, 0xbfb8aa3b, v27
	v_exp_f32_e32 v35, v35
	v_exp_f32_e32 v36, v36
	v_exp_f32_e32 v37, v37
	v_exp_f32_e32 v32, v32
	v_add_f32_e32 v35, 1.0, v35
	v_add_f32_e32 v36, 1.0, v36
	v_add_f32_e32 v37, 1.0, v37
	v_add_f32_e32 v32, 1.0, v32
	v_rcp_f32_e32 v35, v35
	v_rcp_f32_e32 v36, v36
	v_rcp_f32_e32 v37, v37
	v_rcp_f32_e32 v39, v32
	v_pk_mul_f32 v[24:25], v[24:25], v[34:35]
	v_pk_mul_f32 v[20:21], v[28:29], v[20:21]
	v_pk_mul_f32 v[30:31], v[30:31], v[36:37]
	v_pk_mul_f32 v[26:27], v[26:27], v[38:39]
	v_pk_mul_f32 v[22:23], v[30:31], v[22:23]
	v_pk_mul_f32 v[26:27], v[26:27], v[18:19]
	v_pk_mul_f32 v[18:19], v[24:25], v[16:17]
	v_cvt_pk_bf16_f32 v16, v20, v21
	v_cvt_pk_bf16_f32 v17, v22, v23
	v_lshl_add_u64 v[20:21], v[142:143], 0, s[6:7]
	v_cvt_pk_bf16_f32 v18, v18, v19
	v_cvt_pk_bf16_f32 v19, v26, v27
	s_mov_b64 s[6:7], 0xf2000
	global_store_dwordx4 v[20:21], v[16:19], off sc0 sc1
	s_nop 1
	v_mul_f32_e32 v17, 0xbfb8aa3b, v8
	v_exp_f32_e32 v17, v17
	v_mul_f32_e32 v16, 0xbfb8aa3b, v12
	v_exp_f32_e32 v16, v16
	v_mul_f32_e32 v21, 0xbfb8aa3b, v10
	v_add_f32_e32 v17, 1.0, v17
	v_rcp_f32_e32 v18, v17
	v_mul_f32_e32 v17, 0xbfb8aa3b, v13
	v_exp_f32_e32 v17, v17
	v_add_f32_e32 v16, 1.0, v16
	v_rcp_f32_e32 v16, v16
	v_exp_f32_e32 v21, v21
	v_add_f32_e32 v17, 1.0, v17
	v_rcp_f32_e32 v17, v17
	v_mul_f32_e32 v19, 0xbfb8aa3b, v9
	v_add_f32_e32 v21, 1.0, v21
	v_exp_f32_e32 v19, v19
	v_pk_mul_f32 v[12:13], v[12:13], v[16:17]
	v_mul_f32_e32 v16, 0xbfb8aa3b, v11
	v_mul_f32_e32 v20, 0xbfb8aa3b, v14
	v_rcp_f32_e32 v22, v21
	v_mul_f32_e32 v21, 0xbfb8aa3b, v15
	v_exp_f32_e32 v16, v16
	v_exp_f32_e32 v20, v20
	v_exp_f32_e32 v21, v21
	v_add_f32_e32 v19, 1.0, v19
	v_add_f32_e32 v16, 1.0, v16
	v_rcp_f32_e32 v19, v19
	v_add_f32_e32 v20, 1.0, v20
	v_add_f32_e32 v21, 1.0, v21
	v_rcp_f32_e32 v23, v16
	v_rcp_f32_e32 v20, v20
	v_rcp_f32_e32 v21, v21
	v_pk_mul_f32 v[8:9], v[8:9], v[18:19]
	v_pk_mul_f32 v[10:11], v[10:11], v[22:23]
	v_pk_mul_f32 v[4:5], v[12:13], v[4:5]
	v_pk_mul_f32 v[14:15], v[14:15], v[20:21]
	v_pk_mul_f32 v[10:11], v[10:11], v[2:3]
	v_pk_mul_f32 v[2:3], v[8:9], v[0:1]
	v_pk_mul_f32 v[6:7], v[14:15], v[6:7]
	v_cvt_pk_bf16_f32 v0, v4, v5
	v_lshl_add_u64 v[4:5], v[142:143], 0, s[6:7]
	v_cvt_pk_bf16_f32 v1, v6, v7
	v_cvt_pk_bf16_f32 v2, v2, v3
	v_cvt_pk_bf16_f32 v3, v10, v11
	s_nop 0
	global_store_dwordx4 v[4:5], v[0:3], off sc0 sc1
	s_nop 1
	s_nop 0
	s_mov_b64 s[6:7], exec
	v_readlane_b32 s8, v254, 0
	v_readlane_b32 s9, v254, 1
	s_and_b64 s[8:9], s[6:7], s[8:9]
	s_mov_b64 exec, s[8:9]
	s_cbranch_execz .LBB0_1191
	s_mov_b64 s[8:9], exec
	v_mbcnt_lo_u32_b32 v0, s8, 0
	v_mbcnt_hi_u32_b32 v0, s9, v0
	v_cmp_eq_u32_e32 vcc, 0, v0
	s_and_b64 s[10:11], exec, vcc
	s_mov_b64 exec, s[10:11]
	s_cbranch_execz .LBB0_1191
	s_lshl_b32 s10, s14, 6
	s_ashr_i32 s11, s10, 31
	s_lshl_b64 s[10:11], s[10:11], 2
	v_readlane_b32 s14, v254, 20
	s_add_u32 s10, s14, s10
	v_readlane_b32 s14, v254, 2
	s_addc_u32 s11, s14, s11
	s_bcnt1_i32_b64 s8, s[8:9]
	v_mov_b32_e32 v0, s8
	s_sub_u32 s98, s10, 1
	s_subb_u32 s99, s11, 0

.Ldp_4_x:
	s_barrier
.LBB0_1195:
	v_readlane_b32 s0, v254, 62
	v_mov_b32_e32 v8, v153
	v_readlane_b32 s1, v254, 63
	s_and_b64 vcc, exec, s[0:1]
	v_readfirstlane_b32 s8, v8
	s_cbranch_vccnz .LBB0_1201
	s_ashr_i32 s0, s2, 31
	s_lshr_b32 s0, s0, 29
	s_add_i32 s3, s2, s0
	s_and_b32 s0, s3, -8
	s_sub_i32 s6, s2, s0
	s_cmp_gt_i32 s6, -1
	s_cbranch_scc0 .LBB0_1198
	s_lshl_b32 s7, s6, 5
	s_cbranch_execz .LBB0_1199
	s_branch .LBB0_1200

.LBB0_1238:
	s_or_b32 s56, s43, 1
	v_add_u32_e32 v157, s40, v147
	s_lshl_b64 s[18:19], s[56:57], 7
	s_add_i32 s56, s43, 2
	ds_read_b128 v[142:145], v157
	ds_read_b128 v[158:161], v157 offset:1024
	ds_read_b128 v[162:165], v157 offset:2048
	ds_read_b128 v[166:169], v157 offset:3072
	v_add_u32_e32 v157, s41, v147
	s_lshl_b64 s[76:77], s[56:57], 7
	ds_read_b128 v[170:173], v157
	ds_read_b128 v[174:177], v157 offset:1024
	ds_read_b128 v[178:181], v157 offset:2048
	ds_read_b128 v[182:185], v157 offset:3072
	s_add_u32 s51, s78, s76
	s_addc_u32 s71, s79, s77
	s_and_b64 s[8:9], s[6:7], exec
	s_cselect_b32 s9, s73, s71
	s_cselect_b32 s8, s72, s51
	s_add_u32 s51, s80, s76
	s_addc_u32 s71, s81, s77
	s_and_b64 s[6:7], s[6:7], exec
	s_cselect_b32 s7, s75, s71
	s_cselect_b32 s6, s74, s51
	s_add_u32 s18, s11, s18
	s_addc_u32 s19, s42, s19
	v_lshl_add_u64 v[218:219], s[18:19], 0, v[128:129]
	s_add_i32 m0, s17, 0xc000
	ds_read_b128 v[186:189], v156
	ds_read_b128 v[190:193], v156 offset:1024
	ds_read_b128 v[194:197], v156 offset:2048
	ds_read_b128 v[198:201], v156 offset:3072
	ds_read_b128 v[202:205], v156 offset:4096
	ds_read_b128 v[206:209], v156 offset:5120
	ds_read_b128 v[210:213], v156 offset:6144
	ds_read_b128 v[214:217], v156 offset:7168
	global_load_lds_dwordx4 v[218:219], off
	v_lshl_add_u64 v[218:219], s[18:19], 0, v[132:133]
	s_add_i32 m0, s17, 0xe000
	s_nop 0
	global_load_lds_dwordx4 v[218:219], off
	s_cmp_eq_u32 s99, 0
	s_cbranch_scc1 .Ldpw_5_0a
	s_waitcnt vmcnt(16)
	s_branch .Ldpw_5_0b

.Ldpw_5_0b:
	s_waitcnt lgkmcnt(0)
	s_barrier
	s_setprio 1
	s_waitcnt lgkmcnt(0)
	v_mfma_f32_16x16x32_bf16 v[124:127], v[142:145], v[186:189], v[124:127]
	v_mfma_f32_16x16x32_bf16 v[120:123], v[162:165], v[186:189], v[120:123]
	v_mfma_f32_16x16x32_bf16 v[108:111], v[142:145], v[194:197], v[108:111]
	v_mfma_f32_16x16x32_bf16 v[104:107], v[162:165], v[194:197], v[104:107]
	v_mfma_f32_16x16x32_bf16 v[92:95], v[142:145], v[202:205], v[92:95]
	v_mfma_f32_16x16x32_bf16 v[88:91], v[162:165], v[202:205], v[88:91]
	v_mfma_f32_16x16x32_bf16 v[76:79], v[142:145], v[210:213], v[76:79]
	v_mfma_f32_16x16x32_bf16 v[72:75], v[162:165], v[210:213], v[72:75]
	v_mfma_f32_16x16x32_bf16 v[124:127], v[158:161], v[190:193], v[124:127]
	v_mfma_f32_16x16x32_bf16 v[120:123], v[166:169], v[190:193], v[120:123]
	v_mfma_f32_16x16x32_bf16 v[108:111], v[158:161], v[198:201], v[108:111]
	v_mfma_f32_16x16x32_bf16 v[104:107], v[166:169], v[198:201], v[104:107]
	v_mfma_f32_16x16x32_bf16 v[92:95], v[158:161], v[206:209], v[92:95]
	v_mfma_f32_16x16x32_bf16 v[88:91], v[166:169], v[206:209], v[88:91]
	v_mfma_f32_16x16x32_bf16 v[76:79], v[158:161], v[214:217], v[76:79]
	v_mfma_f32_16x16x32_bf16 v[72:75], v[166:169], v[214:217], v[72:75]
	s_setprio 0
	s_setprio 1
	v_mfma_f32_16x16x32_bf16 v[116:119], v[170:173], v[186:189], v[116:119]
	v_mfma_f32_16x16x32_bf16 v[112:115], v[178:181], v[186:189], v[112:115]
	v_mfma_f32_16x16x32_bf16 v[100:103], v[170:173], v[194:197], v[100:103]
	v_mfma_f32_16x16x32_bf16 v[96:99], v[178:181], v[194:197], v[96:99]
	v_mfma_f32_16x16x32_bf16 v[84:87], v[170:173], v[202:205], v[84:87]
	v_mfma_f32_16x16x32_bf16 v[80:83], v[178:181], v[202:205], v[80:83]
	v_mfma_f32_16x16x32_bf16 v[68:71], v[170:173], v[210:213], v[68:71]
	v_mfma_f32_16x16x32_bf16 v[64:67], v[178:181], v[210:213], v[64:67]
	v_mfma_f32_16x16x32_bf16 v[116:119], v[174:177], v[190:193], v[116:119]
	v_mfma_f32_16x16x32_bf16 v[112:115], v[182:185], v[190:193], v[112:115]
	v_mfma_f32_16x16x32_bf16 v[100:103], v[174:177], v[198:201], v[100:103]
	v_mfma_f32_16x16x32_bf16 v[96:99], v[182:185], v[198:201], v[96:99]
	v_mfma_f32_16x16x32_bf16 v[84:87], v[174:177], v[206:209], v[84:87]
	v_mfma_f32_16x16x32_bf16 v[80:83], v[182:185], v[206:209], v[80:83]
	v_mfma_f32_16x16x32_bf16 v[68:71], v[174:177], v[214:217], v[68:71]
	v_mfma_f32_16x16x32_bf16 v[64:67], v[182:185], v[214:217], v[64:67]
	s_setprio 0
	s_barrier
	s_add_i32 s18, s40, s16
	v_lshl_add_u64 v[218:219], s[6:7], 0, v[130:131]
	s_mov_b32 m0, s18
	ds_read_b128 v[186:189], v156 offset:16384
	ds_read_b128 v[190:193], v156 offset:17408
	ds_read_b128 v[194:197], v156 offset:18432
	ds_read_b128 v[198:201], v156 offset:19456
	ds_read_b128 v[202:205], v156 offset:20480
	ds_read_b128 v[206:209], v156 offset:21504
	ds_read_b128 v[210:213], v156 offset:22528
	ds_read_b128 v[214:217], v156 offset:23552
	global_load_lds_dwordx4 v[218:219], off
	s_add_i32 m0, s18, 0x2000
	s_add_u32 s18, s6, 0xb0000
	v_lshl_add_u64 v[220:221], s[6:7], 0, v[134:135]
	s_addc_u32 s19, s7, 0
	s_add_i32 s51, s41, s16
	global_load_lds_dwordx4 v[220:221], off
	v_lshl_add_u64 v[222:223], s[18:19], 0, v[130:131]
	s_mov_b32 m0, s51
	v_lshl_add_u64 v[224:225], s[8:9], 0, v[132:133]
	global_load_lds_dwordx4 v[222:223], off
	v_lshl_add_u64 v[222:223], s[18:19], 0, v[134:135]
	s_add_i32 m0, s51, 0x2000
	s_nop 0
	global_load_lds_dwordx4 v[222:223], off
	v_lshl_add_u64 v[222:223], s[8:9], 0, v[128:129]
	s_mov_b32 m0, s17
	s_nop 0
	global_load_lds_dwordx4 v[222:223], off
	s_mov_b32 m0, s27
	s_nop 0
	global_load_lds_dwordx4 v[224:225], off
	s_cmp_eq_u32 s99, 0
	s_cbranch_scc1 .Ldpw_5_1a
	s_waitcnt vmcnt(16)
	s_branch .Ldpw_5_1b

.Ldpw_5_1b:
	s_waitcnt lgkmcnt(0)
	s_barrier
	s_setprio 1
	s_waitcnt lgkmcnt(0)
	v_mfma_f32_16x16x32_bf16 v[60:63], v[142:145], v[186:189], v[60:63]
	v_mfma_f32_16x16x32_bf16 v[56:59], v[162:165], v[186:189], v[56:59]
	v_mfma_f32_16x16x32_bf16 v[44:47], v[142:145], v[194:197], v[44:47]
	v_mfma_f32_16x16x32_bf16 v[40:43], v[162:165], v[194:197], v[40:43]
	v_mfma_f32_16x16x32_bf16 v[28:31], v[142:145], v[202:205], v[28:31]
	v_mfma_f32_16x16x32_bf16 v[24:27], v[162:165], v[202:205], v[24:27]
	v_mfma_f32_16x16x32_bf16 v[12:15], v[142:145], v[210:213], v[12:15]
	v_mfma_f32_16x16x32_bf16 v[8:11], v[162:165], v[210:213], v[8:11]
	v_mfma_f32_16x16x32_bf16 v[60:63], v[158:161], v[190:193], v[60:63]
	v_mfma_f32_16x16x32_bf16 v[56:59], v[166:169], v[190:193], v[56:59]
	v_mfma_f32_16x16x32_bf16 v[44:47], v[158:161], v[198:201], v[44:47]
	v_mfma_f32_16x16x32_bf16 v[40:43], v[166:169], v[198:201], v[40:43]
	v_mfma_f32_16x16x32_bf16 v[28:31], v[158:161], v[206:209], v[28:31]
	v_mfma_f32_16x16x32_bf16 v[24:27], v[166:169], v[206:209], v[24:27]
	v_mfma_f32_16x16x32_bf16 v[12:15], v[158:161], v[214:217], v[12:15]
	v_mfma_f32_16x16x32_bf16 v[8:11], v[166:169], v[214:217], v[8:11]
	s_setprio 0
	s_setprio 1
	v_mfma_f32_16x16x32_bf16 v[52:55], v[170:173], v[186:189], v[52:55]
	v_mfma_f32_16x16x32_bf16 v[48:51], v[178:181], v[186:189], v[48:51]
	v_mfma_f32_16x16x32_bf16 v[36:39], v[170:173], v[194:197], v[36:39]
	v_mfma_f32_16x16x32_bf16 v[32:35], v[178:181], v[194:197], v[32:35]
	v_mfma_f32_16x16x32_bf16 v[20:23], v[170:173], v[202:205], v[20:23]
	v_mfma_f32_16x16x32_bf16 v[16:19], v[178:181], v[202:205], v[16:19]
	v_mfma_f32_16x16x32_bf16 v[4:7], v[170:173], v[210:213], v[4:7]
	v_mfma_f32_16x16x32_bf16 v[0:3], v[178:181], v[210:213], v[0:3]
	v_mfma_f32_16x16x32_bf16 v[52:55], v[174:177], v[190:193], v[52:55]
	v_mfma_f32_16x16x32_bf16 v[48:51], v[182:185], v[190:193], v[48:51]
	v_mfma_f32_16x16x32_bf16 v[36:39], v[174:177], v[198:201], v[36:39]
	v_mfma_f32_16x16x32_bf16 v[32:35], v[182:185], v[198:201], v[32:35]
	v_mfma_f32_16x16x32_bf16 v[20:23], v[174:177], v[206:209], v[20:23]
	v_mfma_f32_16x16x32_bf16 v[16:19], v[182:185], v[206:209], v[16:19]
	v_mfma_f32_16x16x32_bf16 v[4:7], v[174:177], v[214:217], v[4:7]
	v_mfma_f32_16x16x32_bf16 v[0:3], v[182:185], v[214:217], v[0:3]
	s_setprio 0
	s_barrier
	s_add_i32 s18, 0, 0x18000
	v_add_u32_e32 v157, s18, v147
	s_add_i32 s19, 0, 0x1c000
	ds_read_b128 v[142:145], v157
	ds_read_b128 v[158:161], v157 offset:1024
	ds_read_b128 v[162:165], v157 offset:2048
	ds_read_b128 v[166:169], v157 offset:3072
	v_add_u32_e32 v157, s19, v147
	ds_read_b128 v[170:173], v157
	ds_read_b128 v[174:177], v157 offset:1024
	ds_read_b128 v[178:181], v157 offset:2048
	ds_read_b128 v[182:185], v157 offset:3072
	s_add_u32 s8, s8, 0xb0000
	s_addc_u32 s9, s9, 0
	s_mov_b32 m0, s28
	v_lshl_add_u64 v[226:227], s[8:9], 0, v[128:129]
	ds_read_b128 v[186:189], v156 offset:32768
	ds_read_b128 v[190:193], v156 offset:33792
	ds_read_b128 v[194:197], v156 offset:34816
	ds_read_b128 v[198:201], v156 offset:35840
	ds_read_b128 v[202:205], v156 offset:36864
	ds_read_b128 v[206:209], v156 offset:37888
	ds_read_b128 v[210:213], v156 offset:38912
	ds_read_b128 v[214:217], v156 offset:39936
	global_load_lds_dwordx4 v[226:227], off
	v_lshl_add_u64 v[226:227], s[8:9], 0, v[132:133]
	s_mov_b32 m0, s29
	s_nop 0
	global_load_lds_dwordx4 v[226:227], off
	s_waitcnt vmcnt(8)
	s_cmp_eq_u32 s99, 0
	s_cbranch_scc1 .Ldp_5_l
	v_readlane_b32 s100, v0, 0
	s_mov_b64 exec, 1
	v_writelane_b32 v0, 1, 0
	s_nop 1
	global_atomic_add v0, v0, s[98:99]
	s_nop 1
	v_writelane_b32 v0, s100, 0
	s_mov_b64 exec, -1
	s_mov_b32 s99, 0
.Ldp_5_l:
	s_waitcnt lgkmcnt(0)
	s_barrier
	s_setprio 1
	s_waitcnt lgkmcnt(0)
	v_mfma_f32_16x16x32_bf16 v[124:127], v[142:145], v[186:189], v[124:127]
	v_mfma_f32_16x16x32_bf16 v[120:123], v[162:165], v[186:189], v[120:123]
	v_mfma_f32_16x16x32_bf16 v[108:111], v[142:145], v[194:197], v[108:111]
	v_mfma_f32_16x16x32_bf16 v[104:107], v[162:165], v[194:197], v[104:107]
	v_mfma_f32_16x16x32_bf16 v[92:95], v[142:145], v[202:205], v[92:95]
	v_mfma_f32_16x16x32_bf16 v[88:91], v[162:165], v[202:205], v[88:91]
	v_mfma_f32_16x16x32_bf16 v[76:79], v[142:145], v[210:213], v[76:79]
	v_mfma_f32_16x16x32_bf16 v[72:75], v[162:165], v[210:213], v[72:75]
	v_mfma_f32_16x16x32_bf16 v[124:127], v[158:161], v[190:193], v[124:127]
	v_mfma_f32_16x16x32_bf16 v[120:123], v[166:169], v[190:193], v[120:123]
	v_mfma_f32_16x16x32_bf16 v[108:111], v[158:161], v[198:201], v[108:111]
	v_mfma_f32_16x16x32_bf16 v[104:107], v[166:169], v[198:201], v[104:107]
	v_mfma_f32_16x16x32_bf16 v[92:95], v[158:161], v[206:209], v[92:95]
	v_mfma_f32_16x16x32_bf16 v[88:91], v[166:169], v[206:209], v[88:91]
	v_mfma_f32_16x16x32_bf16 v[76:79], v[158:161], v[214:217], v[76:79]
	v_mfma_f32_16x16x32_bf16 v[72:75], v[166:169], v[214:217], v[72:75]
	s_setprio 0
	s_setprio 1
	v_mfma_f32_16x16x32_bf16 v[116:119], v[170:173], v[186:189], v[116:119]
	v_mfma_f32_16x16x32_bf16 v[112:115], v[178:181], v[186:189], v[112:115]
	v_mfma_f32_16x16x32_bf16 v[100:103], v[170:173], v[194:197], v[100:103]
	v_mfma_f32_16x16x32_bf16 v[96:99], v[178:181], v[194:197], v[96:99]
	v_mfma_f32_16x16x32_bf16 v[84:87], v[170:173], v[202:205], v[84:87]
	v_mfma_f32_16x16x32_bf16 v[80:83], v[178:181], v[202:205], v[80:83]
	v_mfma_f32_16x16x32_bf16 v[68:71], v[170:173], v[210:213], v[68:71]
	v_mfma_f32_16x16x32_bf16 v[64:67], v[178:181], v[210:213], v[64:67]
	v_mfma_f32_16x16x32_bf16 v[116:119], v[174:177], v[190:193], v[116:119]
	v_mfma_f32_16x16x32_bf16 v[112:115], v[182:185], v[190:193], v[112:115]
	v_mfma_f32_16x16x32_bf16 v[100:103], v[174:177], v[198:201], v[100:103]
	v_mfma_f32_16x16x32_bf16 v[96:99], v[182:185], v[198:201], v[96:99]
	v_mfma_f32_16x16x32_bf16 v[84:87], v[174:177], v[206:209], v[84:87]
	v_mfma_f32_16x16x32_bf16 v[80:83], v[182:185], v[206:209], v[80:83]
	v_mfma_f32_16x16x32_bf16 v[68:71], v[174:177], v[214:217], v[68:71]
	v_mfma_f32_16x16x32_bf16 v[64:67], v[182:185], v[214:217], v[64:67]
	s_setprio 0
	s_barrier
	s_add_i32 s8, s18, s16
	v_lshl_add_u64 v[218:219], v[218:219], 0, s[62:63]
	s_mov_b32 m0, s8
	ds_read_b128 v[186:189], v156 offset:49152
	ds_read_b128 v[190:193], v156 offset:50176
	ds_read_b128 v[194:197], v156 offset:51200
	ds_read_b128 v[198:201], v156 offset:52224
	ds_read_b128 v[202:205], v156 offset:53248
	ds_read_b128 v[206:209], v156 offset:54272
	ds_read_b128 v[210:213], v156 offset:55296
	ds_read_b128 v[214:217], v156 offset:56320
	global_load_lds_dwordx4 v[218:219], off
	s_add_i32 m0, s8, 0x2000
	s_add_u32 s6, s6, 0xb0080
	v_lshl_add_u64 v[218:219], v[220:221], 0, s[62:63]
	s_addc_u32 s7, s7, 0
	s_add_i32 s8, s19, s16
	global_load_lds_dwordx4 v[218:219], off
	v_lshl_add_u64 v[218:219], s[6:7], 0, v[130:131]
	s_mov_b32 m0, s8
	s_nop 0
	global_load_lds_dwordx4 v[218:219], off
	v_lshl_add_u64 v[218:219], s[6:7], 0, v[134:135]
	s_add_i32 m0, s8, 0x2000
	s_nop 0
	global_load_lds_dwordx4 v[218:219], off
	v_lshl_add_u64 v[218:219], v[222:223], 0, s[62:63]
	s_mov_b32 m0, s36
	s_nop 0
	global_load_lds_dwordx4 v[218:219], off
	v_lshl_add_u64 v[218:219], v[224:225], 0, s[62:63]
	s_mov_b32 m0, s37
	s_nop 0
	global_load_lds_dwordx4 v[218:219], off
	s_waitcnt vmcnt(8)
	s_waitcnt lgkmcnt(0)
	s_barrier
	s_setprio 1
	s_waitcnt lgkmcnt(0)
	v_mfma_f32_16x16x32_bf16 v[60:63], v[142:145], v[186:189], v[60:63]
	v_mfma_f32_16x16x32_bf16 v[56:59], v[162:165], v[186:189], v[56:59]
	v_mfma_f32_16x16x32_bf16 v[44:47], v[142:145], v[194:197], v[44:47]
	v_mfma_f32_16x16x32_bf16 v[40:43], v[162:165], v[194:197], v[40:43]
	v_mfma_f32_16x16x32_bf16 v[28:31], v[142:145], v[202:205], v[28:31]
	v_mfma_f32_16x16x32_bf16 v[24:27], v[162:165], v[202:205], v[24:27]
	v_mfma_f32_16x16x32_bf16 v[12:15], v[142:145], v[210:213], v[12:15]
	v_mfma_f32_16x16x32_bf16 v[8:11], v[162:165], v[210:213], v[8:11]
	v_mfma_f32_16x16x32_bf16 v[60:63], v[158:161], v[190:193], v[60:63]
	v_mfma_f32_16x16x32_bf16 v[56:59], v[166:169], v[190:193], v[56:59]
	v_mfma_f32_16x16x32_bf16 v[44:47], v[158:161], v[198:201], v[44:47]
	v_mfma_f32_16x16x32_bf16 v[40:43], v[166:169], v[198:201], v[40:43]
	v_mfma_f32_16x16x32_bf16 v[28:31], v[158:161], v[206:209], v[28:31]
	v_mfma_f32_16x16x32_bf16 v[24:27], v[166:169], v[206:209], v[24:27]
	v_mfma_f32_16x16x32_bf16 v[12:15], v[158:161], v[214:217], v[12:15]
	v_mfma_f32_16x16x32_bf16 v[8:11], v[166:169], v[214:217], v[8:11]
	s_setprio 0
	s_setprio 1
	v_mfma_f32_16x16x32_bf16 v[52:55], v[170:173], v[186:189], v[52:55]
	v_mfma_f32_16x16x32_bf16 v[48:51], v[178:181], v[186:189], v[48:51]
	v_mfma_f32_16x16x32_bf16 v[36:39], v[170:173], v[194:197], v[36:39]
	v_mfma_f32_16x16x32_bf16 v[32:35], v[178:181], v[194:197], v[32:35]
	v_mfma_f32_16x16x32_bf16 v[20:23], v[170:173], v[202:205], v[20:23]
	v_mfma_f32_16x16x32_bf16 v[16:19], v[178:181], v[202:205], v[16:19]
	v_mfma_f32_16x16x32_bf16 v[4:7], v[170:173], v[210:213], v[4:7]
	v_mfma_f32_16x16x32_bf16 v[0:3], v[178:181], v[210:213], v[0:3]
	v_mfma_f32_16x16x32_bf16 v[52:55], v[174:177], v[190:193], v[52:55]
	v_mfma_f32_16x16x32_bf16 v[48:51], v[182:185], v[190:193], v[48:51]
	v_mfma_f32_16x16x32_bf16 v[36:39], v[174:177], v[198:201], v[36:39]
	v_mfma_f32_16x16x32_bf16 v[32:35], v[182:185], v[198:201], v[32:35]
	v_mfma_f32_16x16x32_bf16 v[20:23], v[174:177], v[206:209], v[20:23]
	v_mfma_f32_16x16x32_bf16 v[16:19], v[182:185], v[206:209], v[16:19]
	v_mfma_f32_16x16x32_bf16 v[4:7], v[174:177], v[214:217], v[4:7]
	v_mfma_f32_16x16x32_bf16 v[0:3], v[182:185], v[214:217], v[0:3]
	s_setprio 0
	s_barrier
	s_cmp_gt_u32 s43, 41
	s_mov_b32 s43, s56
	s_cbranch_scc1 .LBB0_1257

.LBB0_1275:
	s_or_b64 exec, exec, s[6:7]
	s_nop 0
	s_mov_b64 s[6:7], exec
	v_readlane_b32 s8, v254, 0
	v_readlane_b32 s9, v254, 1
	s_and_b64 s[8:9], s[6:7], s[8:9]
	s_mov_b64 exec, s[8:9]
	s_cbranch_execz .LBB0_1280
	s_mov_b64 s[10:11], exec
	v_mbcnt_lo_u32_b32 v0, s10, 0
	v_mbcnt_hi_u32_b32 v0, s11, v0
	v_cmp_eq_u32_e32 vcc, 0, v0
	s_and_saveexec_b64 s[8:9], vcc
	s_cbranch_execz .LBB0_1278
	s_lshl_b32 s14, s3, 6
	s_ashr_i32 s15, s14, 31
	s_lshl_b64 s[14:15], s[14:15], 2
	s_add_u32 s14, s54, s14
	s_addc_u32 s15, s55, s15
	s_bcnt1_i32_b64 s3, s[10:11]
	v_mov_b32_e32 v0, s3
	s_sub_u32 s98, s14, 1
	s_subb_u32 s99, s15, 0

.Ldp_5_x:
	s_barrier
.LBB0_1284:
	s_movk_i32 s8, 0x100
	v_mov_b32_e32 v8, v153
	s_cmpk_lt_i32 s2, 0x84
	s_cselect_b64 s[0:1], -1, 0
	v_readfirstlane_b32 s9, v8
	s_cmpk_gt_i32 s2, 0x83
	s_mul_hi_i32 s6, s2, 0x2e8ba2e9
	s_cbranch_scc1 .LBB0_1286
	s_lshr_b32 s3, s6, 31
	s_ashr_i32 s6, s6, 3
	s_add_i32 s6, s6, s3
	s_add_i32 s3, s6, 64
	s_mul_i32 s6, s6, 44
	s_sub_i32 s10, s2, s6

.LBB0_1320:
	v_add_u32_e32 v141, s38, v138
	s_or_b32 s14, s86, 1
	s_add_i32 s86, s86, 2
	s_mov_b32 s87, s15
	ds_read_b128 v[142:145], v141
	ds_read_b128 v[156:159], v141 offset:1024
	ds_read_b128 v[160:163], v141 offset:2048
	ds_read_b128 v[164:167], v141 offset:3072
	v_add_u32_e32 v141, s39, v138
	s_lshl_b64 s[18:19], s[14:15], 7
	s_lshl_b64 s[50:51], s[86:87], 7
	ds_read_b128 v[168:171], v141
	ds_read_b128 v[172:175], v141 offset:1024
	ds_read_b128 v[176:179], v141 offset:2048
	ds_read_b128 v[180:183], v141 offset:3072
	s_add_u32 s14, s78, s50
	s_addc_u32 s43, s79, s51
	s_and_b64 s[8:9], s[6:7], exec
	s_cselect_b32 s9, s73, s43
	s_cselect_b32 s8, s72, s14
	s_add_u32 s14, s80, s50
	s_addc_u32 s43, s81, s51
	s_and_b64 s[6:7], s[6:7], exec
	s_cselect_b32 s7, s75, s43
	s_cselect_b32 s6, s74, s14
	s_add_u32 s18, s11, s18
	s_addc_u32 s19, s42, s19
	v_lshl_add_u64 v[146:147], s[18:19], 0, v[128:129]
	s_add_i32 m0, s16, 0xc000
	ds_read_b128 v[184:187], v140
	ds_read_b128 v[188:191], v140 offset:1024
	ds_read_b128 v[192:195], v140 offset:2048
	ds_read_b128 v[196:199], v140 offset:3072
	ds_read_b128 v[200:203], v140 offset:4096
	ds_read_b128 v[204:207], v140 offset:5120
	ds_read_b128 v[208:211], v140 offset:6144
	ds_read_b128 v[212:215], v140 offset:7168
	global_load_lds_dwordx4 v[146:147], off
	v_lshl_add_u64 v[146:147], s[18:19], 0, v[132:133]
	s_add_i32 m0, s16, 0xe000
	s_nop 0
	global_load_lds_dwordx4 v[146:147], off
	s_cmp_eq_u32 s99, 0
	s_cbranch_scc1 .Ldpw_6_0a
	s_waitcnt vmcnt(16)
	s_branch .Ldpw_6_0b

.Ldpw_6_0b:
	s_waitcnt lgkmcnt(0)
	s_barrier
	s_setprio 1
	s_waitcnt lgkmcnt(0)
	v_mfma_f32_16x16x32_bf16 v[120:123], v[142:145], v[184:187], v[120:123]
	v_mfma_f32_16x16x32_bf16 v[124:127], v[160:163], v[184:187], v[124:127]
	v_mfma_f32_16x16x32_bf16 v[108:111], v[142:145], v[192:195], v[108:111]
	v_mfma_f32_16x16x32_bf16 v[104:107], v[160:163], v[192:195], v[104:107]
	v_mfma_f32_16x16x32_bf16 v[92:95], v[142:145], v[200:203], v[92:95]
	v_mfma_f32_16x16x32_bf16 v[88:91], v[160:163], v[200:203], v[88:91]
	v_mfma_f32_16x16x32_bf16 v[76:79], v[142:145], v[208:211], v[76:79]
	v_mfma_f32_16x16x32_bf16 v[72:75], v[160:163], v[208:211], v[72:75]
	v_mfma_f32_16x16x32_bf16 v[120:123], v[156:159], v[188:191], v[120:123]
	v_mfma_f32_16x16x32_bf16 v[124:127], v[164:167], v[188:191], v[124:127]
	v_mfma_f32_16x16x32_bf16 v[108:111], v[156:159], v[196:199], v[108:111]
	v_mfma_f32_16x16x32_bf16 v[104:107], v[164:167], v[196:199], v[104:107]
	v_mfma_f32_16x16x32_bf16 v[92:95], v[156:159], v[204:207], v[92:95]
	v_mfma_f32_16x16x32_bf16 v[88:91], v[164:167], v[204:207], v[88:91]
	v_mfma_f32_16x16x32_bf16 v[76:79], v[156:159], v[212:215], v[76:79]
	v_mfma_f32_16x16x32_bf16 v[72:75], v[164:167], v[212:215], v[72:75]
	s_setprio 0
	s_setprio 1
	v_mfma_f32_16x16x32_bf16 v[116:119], v[168:171], v[184:187], v[116:119]
	v_mfma_f32_16x16x32_bf16 v[112:115], v[176:179], v[184:187], v[112:115]
	v_mfma_f32_16x16x32_bf16 v[100:103], v[168:171], v[192:195], v[100:103]
	v_mfma_f32_16x16x32_bf16 v[96:99], v[176:179], v[192:195], v[96:99]
	v_mfma_f32_16x16x32_bf16 v[84:87], v[168:171], v[200:203], v[84:87]
	v_mfma_f32_16x16x32_bf16 v[80:83], v[176:179], v[200:203], v[80:83]
	v_mfma_f32_16x16x32_bf16 v[68:71], v[168:171], v[208:211], v[68:71]
	v_mfma_f32_16x16x32_bf16 v[64:67], v[176:179], v[208:211], v[64:67]
	v_mfma_f32_16x16x32_bf16 v[116:119], v[172:175], v[188:191], v[116:119]
	v_mfma_f32_16x16x32_bf16 v[112:115], v[180:183], v[188:191], v[112:115]
	v_mfma_f32_16x16x32_bf16 v[100:103], v[172:175], v[196:199], v[100:103]
	v_mfma_f32_16x16x32_bf16 v[96:99], v[180:183], v[196:199], v[96:99]
	v_mfma_f32_16x16x32_bf16 v[84:87], v[172:175], v[204:207], v[84:87]
	v_mfma_f32_16x16x32_bf16 v[80:83], v[180:183], v[204:207], v[80:83]
	v_mfma_f32_16x16x32_bf16 v[68:71], v[172:175], v[212:215], v[68:71]
	v_mfma_f32_16x16x32_bf16 v[64:67], v[180:183], v[212:215], v[64:67]
	s_setprio 0
	s_barrier
	s_add_i32 s14, s38, s13
	v_lshl_add_u64 v[146:147], s[6:7], 0, v[130:131]
	s_mov_b32 m0, s14
	ds_read_b128 v[184:187], v140 offset:16384
	ds_read_b128 v[188:191], v140 offset:17408
	ds_read_b128 v[192:195], v140 offset:18432
	ds_read_b128 v[196:199], v140 offset:19456
	ds_read_b128 v[200:203], v140 offset:20480
	ds_read_b128 v[204:207], v140 offset:21504
	ds_read_b128 v[208:211], v140 offset:22528
	ds_read_b128 v[212:215], v140 offset:23552
	global_load_lds_dwordx4 v[146:147], off
	s_add_i32 m0, s14, 0x2000
	s_add_u32 s18, s6, 0xb0000
	v_lshl_add_u64 v[216:217], s[6:7], 0, v[134:135]
	s_addc_u32 s19, s7, 0
	s_add_i32 s14, s39, s13
	global_load_lds_dwordx4 v[216:217], off
	v_lshl_add_u64 v[218:219], s[18:19], 0, v[130:131]
	s_mov_b32 m0, s14
	v_lshl_add_u64 v[220:221], s[8:9], 0, v[132:133]
	global_load_lds_dwordx4 v[218:219], off
	v_lshl_add_u64 v[218:219], s[18:19], 0, v[134:135]
	s_add_i32 m0, s14, 0x2000
	s_nop 0
	global_load_lds_dwordx4 v[218:219], off
	v_lshl_add_u64 v[218:219], s[8:9], 0, v[128:129]
	s_mov_b32 m0, s16
	s_nop 0
	global_load_lds_dwordx4 v[218:219], off
	s_mov_b32 m0, s17
	s_nop 0
	global_load_lds_dwordx4 v[220:221], off
	s_cmp_eq_u32 s99, 0
	s_cbranch_scc1 .Ldpw_6_1a
	s_waitcnt vmcnt(16)
	s_branch .Ldpw_6_1b

.Ldpw_6_1b:
	s_waitcnt lgkmcnt(0)
	s_barrier
	s_setprio 1
	s_waitcnt lgkmcnt(0)
	v_mfma_f32_16x16x32_bf16 v[60:63], v[142:145], v[184:187], v[60:63]
	v_mfma_f32_16x16x32_bf16 v[56:59], v[160:163], v[184:187], v[56:59]
	v_mfma_f32_16x16x32_bf16 v[44:47], v[142:145], v[192:195], v[44:47]
	v_mfma_f32_16x16x32_bf16 v[40:43], v[160:163], v[192:195], v[40:43]
	v_mfma_f32_16x16x32_bf16 v[28:31], v[142:145], v[200:203], v[28:31]
	v_mfma_f32_16x16x32_bf16 v[24:27], v[160:163], v[200:203], v[24:27]
	v_mfma_f32_16x16x32_bf16 v[12:15], v[142:145], v[208:211], v[12:15]
	v_mfma_f32_16x16x32_bf16 v[8:11], v[160:163], v[208:211], v[8:11]
	v_mfma_f32_16x16x32_bf16 v[60:63], v[156:159], v[188:191], v[60:63]
	v_mfma_f32_16x16x32_bf16 v[56:59], v[164:167], v[188:191], v[56:59]
	v_mfma_f32_16x16x32_bf16 v[44:47], v[156:159], v[196:199], v[44:47]
	v_mfma_f32_16x16x32_bf16 v[40:43], v[164:167], v[196:199], v[40:43]
	v_mfma_f32_16x16x32_bf16 v[28:31], v[156:159], v[204:207], v[28:31]
	v_mfma_f32_16x16x32_bf16 v[24:27], v[164:167], v[204:207], v[24:27]
	v_mfma_f32_16x16x32_bf16 v[12:15], v[156:159], v[212:215], v[12:15]
	v_mfma_f32_16x16x32_bf16 v[8:11], v[164:167], v[212:215], v[8:11]
	s_setprio 0
	s_setprio 1
	v_mfma_f32_16x16x32_bf16 v[52:55], v[168:171], v[184:187], v[52:55]
	v_mfma_f32_16x16x32_bf16 v[48:51], v[176:179], v[184:187], v[48:51]
	v_mfma_f32_16x16x32_bf16 v[36:39], v[168:171], v[192:195], v[36:39]
	v_mfma_f32_16x16x32_bf16 v[32:35], v[176:179], v[192:195], v[32:35]
	v_mfma_f32_16x16x32_bf16 v[20:23], v[168:171], v[200:203], v[20:23]
	v_mfma_f32_16x16x32_bf16 v[16:19], v[176:179], v[200:203], v[16:19]
	v_mfma_f32_16x16x32_bf16 v[4:7], v[168:171], v[208:211], v[4:7]
	v_mfma_f32_16x16x32_bf16 v[0:3], v[176:179], v[208:211], v[0:3]
	v_mfma_f32_16x16x32_bf16 v[52:55], v[172:175], v[188:191], v[52:55]
	v_mfma_f32_16x16x32_bf16 v[48:51], v[180:183], v[188:191], v[48:51]
	v_mfma_f32_16x16x32_bf16 v[36:39], v[172:175], v[196:199], v[36:39]
	v_mfma_f32_16x16x32_bf16 v[32:35], v[180:183], v[196:199], v[32:35]
	v_mfma_f32_16x16x32_bf16 v[20:23], v[172:175], v[204:207], v[20:23]
	v_mfma_f32_16x16x32_bf16 v[16:19], v[180:183], v[204:207], v[16:19]
	v_mfma_f32_16x16x32_bf16 v[4:7], v[172:175], v[212:215], v[4:7]
	v_mfma_f32_16x16x32_bf16 v[0:3], v[180:183], v[212:215], v[0:3]
	s_setprio 0
	s_barrier
	s_add_i32 s14, 0, 0x18000
	v_add_u32_e32 v141, s14, v138
	s_add_i32 s18, 0, 0x1c000
	ds_read_b128 v[142:145], v141
	ds_read_b128 v[156:159], v141 offset:1024
	ds_read_b128 v[160:163], v141 offset:2048
	ds_read_b128 v[164:167], v141 offset:3072
	v_add_u32_e32 v141, s18, v138
	ds_read_b128 v[168:171], v141
	ds_read_b128 v[172:175], v141 offset:1024
	ds_read_b128 v[176:179], v141 offset:2048
	ds_read_b128 v[180:183], v141 offset:3072
	s_add_u32 s8, s8, 0xb0000
	s_addc_u32 s9, s9, 0
	s_mov_b32 m0, s27
	v_lshl_add_u64 v[222:223], s[8:9], 0, v[128:129]
	ds_read_b128 v[184:187], v140 offset:32768
	ds_read_b128 v[188:191], v140 offset:33792
	ds_read_b128 v[192:195], v140 offset:34816
	ds_read_b128 v[196:199], v140 offset:35840
	ds_read_b128 v[200:203], v140 offset:36864
	ds_read_b128 v[204:207], v140 offset:37888
	ds_read_b128 v[208:211], v140 offset:38912
	ds_read_b128 v[212:215], v140 offset:39936
	global_load_lds_dwordx4 v[222:223], off
	v_lshl_add_u64 v[222:223], s[8:9], 0, v[132:133]
	s_mov_b32 m0, s28
	s_nop 0
	global_load_lds_dwordx4 v[222:223], off
	s_waitcnt vmcnt(8)
	s_cmp_eq_u32 s99, 0
	s_cbranch_scc1 .Ldp_6_l
	v_readlane_b32 s100, v0, 0
	s_mov_b64 exec, 1
	v_writelane_b32 v0, 1, 0
	s_nop 1
	global_atomic_add v0, v0, s[98:99]
	s_nop 1
	v_writelane_b32 v0, s100, 0
	s_mov_b64 exec, -1
	s_mov_b32 s99, 0
.Ldp_6_l:
	s_waitcnt lgkmcnt(0)
	s_barrier
	s_setprio 1
	s_waitcnt lgkmcnt(0)
	v_mfma_f32_16x16x32_bf16 v[120:123], v[142:145], v[184:187], v[120:123]
	v_mfma_f32_16x16x32_bf16 v[124:127], v[160:163], v[184:187], v[124:127]
	v_mfma_f32_16x16x32_bf16 v[108:111], v[142:145], v[192:195], v[108:111]
	v_mfma_f32_16x16x32_bf16 v[104:107], v[160:163], v[192:195], v[104:107]
	v_mfma_f32_16x16x32_bf16 v[92:95], v[142:145], v[200:203], v[92:95]
	v_mfma_f32_16x16x32_bf16 v[88:91], v[160:163], v[200:203], v[88:91]
	v_mfma_f32_16x16x32_bf16 v[76:79], v[142:145], v[208:211], v[76:79]
	v_mfma_f32_16x16x32_bf16 v[72:75], v[160:163], v[208:211], v[72:75]
	v_mfma_f32_16x16x32_bf16 v[120:123], v[156:159], v[188:191], v[120:123]
	v_mfma_f32_16x16x32_bf16 v[124:127], v[164:167], v[188:191], v[124:127]
	v_mfma_f32_16x16x32_bf16 v[108:111], v[156:159], v[196:199], v[108:111]
	v_mfma_f32_16x16x32_bf16 v[104:107], v[164:167], v[196:199], v[104:107]
	v_mfma_f32_16x16x32_bf16 v[92:95], v[156:159], v[204:207], v[92:95]
	v_mfma_f32_16x16x32_bf16 v[88:91], v[164:167], v[204:207], v[88:91]
	v_mfma_f32_16x16x32_bf16 v[76:79], v[156:159], v[212:215], v[76:79]
	v_mfma_f32_16x16x32_bf16 v[72:75], v[164:167], v[212:215], v[72:75]
	s_setprio 0
	s_setprio 1
	v_mfma_f32_16x16x32_bf16 v[116:119], v[168:171], v[184:187], v[116:119]
	v_mfma_f32_16x16x32_bf16 v[112:115], v[176:179], v[184:187], v[112:115]
	v_mfma_f32_16x16x32_bf16 v[100:103], v[168:171], v[192:195], v[100:103]
	v_mfma_f32_16x16x32_bf16 v[96:99], v[176:179], v[192:195], v[96:99]
	v_mfma_f32_16x16x32_bf16 v[84:87], v[168:171], v[200:203], v[84:87]
	v_mfma_f32_16x16x32_bf16 v[80:83], v[176:179], v[200:203], v[80:83]
	v_mfma_f32_16x16x32_bf16 v[68:71], v[168:171], v[208:211], v[68:71]
	v_mfma_f32_16x16x32_bf16 v[64:67], v[176:179], v[208:211], v[64:67]
	v_mfma_f32_16x16x32_bf16 v[116:119], v[172:175], v[188:191], v[116:119]
	v_mfma_f32_16x16x32_bf16 v[112:115], v[180:183], v[188:191], v[112:115]
	v_mfma_f32_16x16x32_bf16 v[100:103], v[172:175], v[196:199], v[100:103]
	v_mfma_f32_16x16x32_bf16 v[96:99], v[180:183], v[196:199], v[96:99]
	v_mfma_f32_16x16x32_bf16 v[84:87], v[172:175], v[204:207], v[84:87]
	v_mfma_f32_16x16x32_bf16 v[80:83], v[180:183], v[204:207], v[80:83]
	v_mfma_f32_16x16x32_bf16 v[68:71], v[172:175], v[212:215], v[68:71]
	v_mfma_f32_16x16x32_bf16 v[64:67], v[180:183], v[212:215], v[64:67]
	s_setprio 0
	s_barrier
	s_add_i32 s8, s14, s13
	v_lshl_add_u64 v[146:147], v[146:147], 0, s[58:59]
	s_mov_b32 m0, s8
	ds_read_b128 v[184:187], v140 offset:49152
	ds_read_b128 v[188:191], v140 offset:50176
	ds_read_b128 v[192:195], v140 offset:51200
	ds_read_b128 v[196:199], v140 offset:52224
	ds_read_b128 v[200:203], v140 offset:53248
	ds_read_b128 v[204:207], v140 offset:54272
	ds_read_b128 v[208:211], v140 offset:55296
	ds_read_b128 v[212:215], v140 offset:56320
	global_load_lds_dwordx4 v[146:147], off
	s_add_i32 m0, s8, 0x2000
	s_add_u32 s6, s6, 0xb0080
	v_lshl_add_u64 v[146:147], v[216:217], 0, s[58:59]
	s_addc_u32 s7, s7, 0
	s_add_i32 s8, s18, s13
	global_load_lds_dwordx4 v[146:147], off
	v_lshl_add_u64 v[146:147], s[6:7], 0, v[130:131]
	s_mov_b32 m0, s8
	s_nop 0
	global_load_lds_dwordx4 v[146:147], off
	v_lshl_add_u64 v[146:147], s[6:7], 0, v[134:135]
	s_add_i32 m0, s8, 0x2000
	s_nop 0
	global_load_lds_dwordx4 v[146:147], off
	v_lshl_add_u64 v[146:147], v[218:219], 0, s[58:59]
	s_mov_b32 m0, s33
	s_nop 0
	global_load_lds_dwordx4 v[146:147], off
	v_lshl_add_u64 v[146:147], v[220:221], 0, s[58:59]
	s_mov_b32 m0, s36
	s_nop 0
	global_load_lds_dwordx4 v[146:147], off
	s_waitcnt vmcnt(8)
	s_waitcnt lgkmcnt(0)
	s_barrier
	s_setprio 1
	s_waitcnt lgkmcnt(0)
	v_mfma_f32_16x16x32_bf16 v[60:63], v[142:145], v[184:187], v[60:63]
	v_mfma_f32_16x16x32_bf16 v[56:59], v[160:163], v[184:187], v[56:59]
	v_mfma_f32_16x16x32_bf16 v[44:47], v[142:145], v[192:195], v[44:47]
	v_mfma_f32_16x16x32_bf16 v[40:43], v[160:163], v[192:195], v[40:43]
	v_mfma_f32_16x16x32_bf16 v[28:31], v[142:145], v[200:203], v[28:31]
	v_mfma_f32_16x16x32_bf16 v[24:27], v[160:163], v[200:203], v[24:27]
	v_mfma_f32_16x16x32_bf16 v[12:15], v[142:145], v[208:211], v[12:15]
	v_mfma_f32_16x16x32_bf16 v[8:11], v[160:163], v[208:211], v[8:11]
	v_mfma_f32_16x16x32_bf16 v[60:63], v[156:159], v[188:191], v[60:63]
	v_mfma_f32_16x16x32_bf16 v[56:59], v[164:167], v[188:191], v[56:59]
	v_mfma_f32_16x16x32_bf16 v[44:47], v[156:159], v[196:199], v[44:47]
	v_mfma_f32_16x16x32_bf16 v[40:43], v[164:167], v[196:199], v[40:43]
	v_mfma_f32_16x16x32_bf16 v[28:31], v[156:159], v[204:207], v[28:31]
	v_mfma_f32_16x16x32_bf16 v[24:27], v[164:167], v[204:207], v[24:27]
	v_mfma_f32_16x16x32_bf16 v[12:15], v[156:159], v[212:215], v[12:15]
	v_mfma_f32_16x16x32_bf16 v[8:11], v[164:167], v[212:215], v[8:11]
	s_setprio 0
	s_setprio 1
	v_mfma_f32_16x16x32_bf16 v[52:55], v[168:171], v[184:187], v[52:55]
	v_mfma_f32_16x16x32_bf16 v[48:51], v[176:179], v[184:187], v[48:51]
	v_mfma_f32_16x16x32_bf16 v[36:39], v[168:171], v[192:195], v[36:39]
	v_mfma_f32_16x16x32_bf16 v[32:35], v[176:179], v[192:195], v[32:35]
	v_mfma_f32_16x16x32_bf16 v[20:23], v[168:171], v[200:203], v[20:23]
	v_mfma_f32_16x16x32_bf16 v[16:19], v[176:179], v[200:203], v[16:19]
	v_mfma_f32_16x16x32_bf16 v[4:7], v[168:171], v[208:211], v[4:7]
	v_mfma_f32_16x16x32_bf16 v[0:3], v[176:179], v[208:211], v[0:3]
	v_mfma_f32_16x16x32_bf16 v[52:55], v[172:175], v[188:191], v[52:55]
	v_mfma_f32_16x16x32_bf16 v[48:51], v[180:183], v[188:191], v[48:51]
	v_mfma_f32_16x16x32_bf16 v[36:39], v[172:175], v[196:199], v[36:39]
	v_mfma_f32_16x16x32_bf16 v[32:35], v[180:183], v[196:199], v[32:35]
	v_mfma_f32_16x16x32_bf16 v[20:23], v[172:175], v[204:207], v[20:23]
	v_mfma_f32_16x16x32_bf16 v[16:19], v[180:183], v[204:207], v[16:19]
	v_mfma_f32_16x16x32_bf16 v[4:7], v[172:175], v[212:215], v[4:7]
	v_mfma_f32_16x16x32_bf16 v[0:3], v[180:183], v[212:215], v[0:3]
	s_setprio 0
	s_barrier
	s_cmp_ge_i32 s86, s29
	s_cbranch_scc1 .LBB0_1339

.LBB0_1341:
	s_mul_hi_i32 s6, s10, 0x2e8ba2e9
	s_lshr_b32 s7, s6, 31
	s_ashr_i32 s6, s6, 1
	s_add_i32 s8, s6, s7
	s_mul_i32 s6, s8, 11
	s_sub_i32 s6, s10, s6
	s_mulk_i32 s6, 0x300
	v_lshl_add_u32 v142, s3, 8, v139
	s_ashr_i32 s7, s6, 31
	v_ashrrev_i32_e32 v143, 31, v142
	v_lshl_add_u64 v[142:143], v[142:143], 0, s[6:7]
	v_readlane_b32 s6, v254, 51
	v_lshlrev_b64 v[142:143], 11, v[142:143]
	v_readlane_b32 s7, v254, 52
	s_mov_b32 s71, s15
	v_cvt_pk_bf16_f32 v120, v120, v121
	v_cvt_pk_bf16_f32 v121, v122, v123
	v_cvt_pk_bf16_f32 v122, v124, v125
	v_cvt_pk_bf16_f32 v123, v126, v127
	s_nop 0
	v_lshl_add_u64 v[142:143], s[6:7], 0, v[142:143]
	s_lshl_b32 s6, s8, 8
	s_ashr_i32 s7, s6, 31
	v_lshl_add_u64 v[142:143], s[6:7], 1, v[142:143]
	v_lshl_add_u64 v[142:143], v[142:143], 0, s[70:71]
	v_lshl_add_u64 v[142:143], v[142:143], 0, v[136:137]
	s_mov_b64 s[6:7], 0x100
	global_store_dwordx4 v[142:143], v[120:123], off sc0 sc1
	s_nop 1
	v_cvt_pk_bf16_f32 v116, v116, v117
	v_cvt_pk_bf16_f32 v117, v118, v119
	v_cvt_pk_bf16_f32 v118, v112, v113
	v_lshl_add_u64 v[112:113], v[142:143], 0, s[6:7]
	s_mov_b64 s[6:7], 0x8000
	v_cvt_pk_bf16_f32 v119, v114, v115
	s_nop 0
	global_store_dwordx4 v[112:113], v[116:119], off sc0 sc1
	s_nop 1
	v_lshl_add_u64 v[112:113], v[142:143], 0, s[6:7]
	s_mov_b64 s[6:7], 0x8100
	v_cvt_pk_bf16_f32 v108, v108, v109
	v_cvt_pk_bf16_f32 v109, v110, v111
	v_cvt_pk_bf16_f32 v110, v104, v105
	v_cvt_pk_bf16_f32 v111, v106, v107
	s_nop 0
	global_store_dwordx4 v[112:113], v[108:111], off sc0 sc1
	s_nop 1
	v_cvt_pk_bf16_f32 v100, v100, v101
	v_cvt_pk_bf16_f32 v101, v102, v103
	v_cvt_pk_bf16_f32 v102, v96, v97
	v_lshl_add_u64 v[96:97], v[142:143], 0, s[6:7]
	s_mov_b64 s[6:7], 0x10000
	v_cvt_pk_bf16_f32 v103, v98, v99
	s_nop 0
	global_store_dwordx4 v[96:97], v[100:103], off sc0 sc1
	s_nop 1
	v_lshl_add_u64 v[96:97], v[142:143], 0, s[6:7]
	s_mov_b64 s[6:7], 0x10100
	v_cvt_pk_bf16_f32 v92, v92, v93
	v_cvt_pk_bf16_f32 v93, v94, v95
	v_cvt_pk_bf16_f32 v94, v88, v89
	v_cvt_pk_bf16_f32 v95, v90, v91
	s_nop 0
	global_store_dwordx4 v[96:97], v[92:95], off sc0 sc1
	s_nop 1
	v_cvt_pk_bf16_f32 v84, v84, v85
	v_cvt_pk_bf16_f32 v85, v86, v87
	v_cvt_pk_bf16_f32 v86, v80, v81
	v_lshl_add_u64 v[80:81], v[142:143], 0, s[6:7]
	s_mov_b64 s[6:7], 0x18000
	v_cvt_pk_bf16_f32 v87, v82, v83
	s_nop 0
	global_store_dwordx4 v[80:81], v[84:87], off sc0 sc1
	s_nop 1
	v_lshl_add_u64 v[80:81], v[142:143], 0, s[6:7]
	s_mov_b64 s[6:7], 0x18100
	v_cvt_pk_bf16_f32 v76, v76, v77
	v_cvt_pk_bf16_f32 v77, v78, v79
	v_cvt_pk_bf16_f32 v78, v72, v73
	v_cvt_pk_bf16_f32 v79, v74, v75
	s_nop 0
	global_store_dwordx4 v[80:81], v[76:79], off sc0 sc1
	s_nop 1
	v_cvt_pk_bf16_f32 v68, v68, v69
	v_cvt_pk_bf16_f32 v69, v70, v71
	v_cvt_pk_bf16_f32 v70, v64, v65
	v_lshl_add_u64 v[64:65], v[142:143], 0, s[6:7]
	s_mov_b64 s[6:7], 0x40000
	v_cvt_pk_bf16_f32 v71, v66, v67
	s_nop 0
	global_store_dwordx4 v[64:65], v[68:71], off sc0 sc1
	s_nop 1
	v_lshl_add_u64 v[64:65], v[142:143], 0, s[6:7]
	s_mov_b64 s[6:7], 0x40100
	v_cvt_pk_bf16_f32 v60, v60, v61
	v_cvt_pk_bf16_f32 v61, v62, v63
	v_cvt_pk_bf16_f32 v62, v56, v57
	v_cvt_pk_bf16_f32 v63, v58, v59
	s_nop 0
	global_store_dwordx4 v[64:65], v[60:63], off sc0 sc1
	s_nop 1
	v_cvt_pk_bf16_f32 v52, v52, v53
	v_cvt_pk_bf16_f32 v53, v54, v55
	v_cvt_pk_bf16_f32 v54, v48, v49
	v_lshl_add_u64 v[48:49], v[142:143], 0, s[6:7]
	s_mov_b64 s[6:7], 0x48000
	v_cvt_pk_bf16_f32 v55, v50, v51
	s_nop 0
	global_store_dwordx4 v[48:49], v[52:55], off sc0 sc1
	s_nop 1
	v_lshl_add_u64 v[48:49], v[142:143], 0, s[6:7]
	s_mov_b64 s[6:7], 0x48100
	v_cvt_pk_bf16_f32 v44, v44, v45
	v_cvt_pk_bf16_f32 v45, v46, v47
	v_cvt_pk_bf16_f32 v46, v40, v41
	v_cvt_pk_bf16_f32 v47, v42, v43
	s_nop 0
	global_store_dwordx4 v[48:49], v[44:47], off sc0 sc1
	s_nop 1
	v_cvt_pk_bf16_f32 v36, v36, v37
	v_cvt_pk_bf16_f32 v37, v38, v39
	v_cvt_pk_bf16_f32 v38, v32, v33
	v_lshl_add_u64 v[32:33], v[142:143], 0, s[6:7]
	s_mov_b64 s[6:7], 0x50000
	v_cvt_pk_bf16_f32 v39, v34, v35
	s_nop 0
	global_store_dwordx4 v[32:33], v[36:39], off sc0 sc1
	s_nop 1
	v_lshl_add_u64 v[32:33], v[142:143], 0, s[6:7]
	s_mov_b64 s[6:7], 0x50100
	v_cvt_pk_bf16_f32 v28, v28, v29
	v_cvt_pk_bf16_f32 v29, v30, v31
	v_cvt_pk_bf16_f32 v30, v24, v25
	v_cvt_pk_bf16_f32 v31, v26, v27
	s_nop 0
	global_store_dwordx4 v[32:33], v[28:31], off sc0 sc1
	s_nop 1
	v_cvt_pk_bf16_f32 v20, v20, v21
	v_cvt_pk_bf16_f32 v21, v22, v23
	v_cvt_pk_bf16_f32 v22, v16, v17
	v_lshl_add_u64 v[16:17], v[142:143], 0, s[6:7]
	s_mov_b64 s[6:7], 0x58000
	v_cvt_pk_bf16_f32 v23, v18, v19
	s_nop 0
	global_store_dwordx4 v[16:17], v[20:23], off sc0 sc1
	s_nop 1
	v_lshl_add_u64 v[16:17], v[142:143], 0, s[6:7]
	s_mov_b64 s[6:7], 0x58100
	v_cvt_pk_bf16_f32 v12, v12, v13
	v_cvt_pk_bf16_f32 v13, v14, v15
	v_cvt_pk_bf16_f32 v14, v8, v9
	v_cvt_pk_bf16_f32 v15, v10, v11
	s_nop 0
	global_store_dwordx4 v[16:17], v[12:15], off sc0 sc1
	s_nop 1
	v_cvt_pk_bf16_f32 v4, v4, v5
	v_cvt_pk_bf16_f32 v5, v6, v7
	v_cvt_pk_bf16_f32 v6, v0, v1
	v_cvt_pk_bf16_f32 v7, v2, v3
	v_lshl_add_u64 v[0:1], v[142:143], 0, s[6:7]
	global_store_dwordx4 v[0:1], v[4:7], off sc0 sc1
	s_nop 1
	s_nop 0
	s_mov_b64 s[6:7], exec
	v_readlane_b32 s8, v254, 0
	v_readlane_b32 s9, v254, 1
	s_and_b64 s[8:9], s[6:7], s[8:9]
	s_mov_b64 exec, s[8:9]
	s_cbranch_execz .LBB0_1346
	s_mov_b64 s[10:11], exec
	v_mbcnt_lo_u32_b32 v0, s10, 0
	v_mbcnt_hi_u32_b32 v0, s11, v0
	v_cmp_eq_u32_e32 vcc, 0, v0
	s_and_saveexec_b64 s[8:9], vcc
	s_cbranch_execz .LBB0_1344
	s_lshl_b32 s18, s3, 6
	s_ashr_i32 s19, s18, 31
	s_lshl_b64 s[18:19], s[18:19], 2
	s_add_u32 s18, s54, s18
	s_addc_u32 s19, s55, s19
	s_bcnt1_i32_b64 s3, s[10:11]
	v_mov_b32_e32 v0, s3
	s_sub_u32 s98, s18, 1
	s_subb_u32 s99, s19, 0

.Ldp_6_x:
	s_barrier
.LBB0_1350:
	v_mov_b32_e32 v32, v152
	v_readlane_b32 s68, v254, 4
	v_ashrrev_i32_e32 v33, 31, v32
	s_waitcnt lgkmcnt(0)
	v_lshlrev_b64 v[0:1], 4, v[32:33]
	v_readlane_b32 s70, v254, 6
	v_readlane_b32 s71, v254, 7
	s_mov_b64 s[0:1], 0x1000
	v_readlane_b32 s69, v254, 5
	v_lshl_add_u64 v[20:21], s[70:71], 0, v[0:1]
	v_lshl_add_u64 v[0:1], s[64:65], 0, v[0:1]
	v_add_co_u32_e32 v24, vcc, 0x1000, v0
	v_lshl_add_u64 v[28:29], v[0:1], 0, s[0:1]
	s_nop 0
	v_addc_co_u32_e32 v25, vcc, 0, v1, vcc
	global_load_dwordx4 v[0:3], v[20:21], off
	global_load_dwordx4 v[4:7], v[20:21], off offset:1024
	global_load_dwordx4 v[8:11], v[28:29], off offset:1024
	global_load_dwordx4 v[12:15], v[28:29], off offset:2048
	global_load_dwordx4 v[16:19], v[20:21], off offset:2048
	s_nop 0
	global_load_dwordx4 v[20:23], v[20:21], off offset:3072
	s_nop 0
	global_load_dwordx4 v[24:27], v[24:25], off
	s_nop 0
	global_load_dwordx4 v[28:31], v[28:29], off offset:3072
	s_add_u32 s0, s24, 0x5c000
	v_writelane_b32 v255, s0, 2
	s_addc_u32 s0, s25, 0
	v_writelane_b32 v255, s0, 3
	v_readlane_b32 s0, v254, 60
	v_readlane_b32 s72, v254, 8
	v_readlane_b32 s73, v254, 9
	v_readlane_b32 s74, v254, 10
	v_readlane_b32 s75, v254, 11
	v_readlane_b32 s78, v254, 14
	v_readlane_b32 s79, v254, 15
	s_add_u32 s58, s24, 0x74300
	v_readlane_b32 s1, v254, 61
	v_lshlrev_b64 v[40:41], 3, v[32:33]
	s_mov_b32 s57, 0
	s_addc_u32 s59, s25, 0
	v_cmp_gt_i32_e64 s[14:15], 16, v32
	v_lshl_add_u64 v[34:35], v[32:33], 2, s[0:1]
	v_lshl_add_u64 v[36:37], s[30:31], 0, v[40:41]
	v_lshl_add_u64 v[38:39], s[20:21], 0, v[40:41]
	v_lshl_add_u64 v[40:41], s[24:25], 0, v[40:41]
	s_mov_b32 s3, -1
	v_mov_b32_e32 v43, 0
	s_add_i32 s96, 0, 0x20080
	s_mov_b64 s[62:63], 0x800
	s_mov_b64 s[64:65], 0xa00
	s_mov_b64 s[68:69], 0xc00
	s_mov_b64 s[70:71], 0xe00
	v_mov_b32_e32 v146, 0x358637bd
	s_mov_b32 s97, 0x800000
	v_mov_b32_e32 v147, 0x160
	s_mov_b64 s[72:73], 0x200
	s_mov_b64 s[74:75], 0x400
	s_mov_b64 s[78:79], 0x600
	v_readlane_b32 s76, v254, 12
	v_readlane_b32 s77, v254, 13
	v_readlane_b32 s80, v254, 16
	v_readlane_b32 s81, v254, 17
	v_readlane_b32 s82, v254, 18
	v_readlane_b32 s83, v254, 19
	s_branch .LBB0_1354

.LBB0_1448:
	v_mov_b32_e32 v8, v153
	s_cmpk_lt_i32 s101, 0x324
	s_cselect_b64 s[0:1], -1, 0
	s_cmpk_gt_i32 s101, 0x323
	v_readfirstlane_b32 s3, v8
	s_cbranch_scc1 .LBB0_1454
	s_ashr_i32 s6, s101, 31
	s_lshr_b32 s6, s6, 29
	s_add_i32 s8, s101, s6
	s_and_b32 s6, s8, -8
	s_sub_i32 s9, s101, s6
	s_cmp_gt_i32 s9, 3
	s_cbranch_scc0 .LBB0_1451
	s_mul_i32 s6, s9, 0x64
	s_add_i32 s10, s6, 4
	s_cbranch_execz .LBB0_1452
	s_branch .LBB0_1453

.LBB0_1536:
	s_mov_b64 s[64:65], 0x80
	s_and_b32 s0, s0, 3
	s_add_i32 m0, s28, 0x18000
	v_lshl_add_u64 v[4:5], v[4:5], 0, s[64:65]
	s_lshl_b32 s8, s1, 13
	s_lshl_b32 s16, s0, 5
	s_lshl_b32 s0, s0, 12
	s_waitcnt vmcnt(2)
	s_barrier
	global_load_lds_dwordx4 v[4:5], off
	v_lshl_add_u64 v[2:3], v[2:3], 0, s[64:65]
	s_add_i32 m0, s28, 0x1a000
	s_add_i32 s17, s28, 0x8000
	s_add_i32 s40, s28, 0xa000
	global_load_lds_dwordx4 v[2:3], off
	v_lshl_add_u64 v[0:1], v[0:1], 0, s[64:65]
	s_mov_b32 m0, s17
	s_add_u32 s6, s82, 0x40080
	global_load_lds_dwordx4 v[0:1], off
	v_lshl_add_u64 v[0:1], v[6:7], 0, s[64:65]
	s_mov_b32 m0, s40
	s_addc_u32 s7, s83, 0
	global_load_lds_dwordx4 v[0:1], off
	s_add_i32 m0, s28, 0x1c000
	v_lshl_add_u64 v[0:1], s[6:7], 0, v[130:131]
	global_load_lds_dwordx4 v[0:1], off
	v_lshl_add_u64 v[0:1], s[6:7], 0, v[134:135]
	s_add_i32 m0, s28, 0x1e000
	s_cmpk_lt_u32 s3, 0x100
	global_load_lds_dwordx4 v[0:1], off
	v_bfe_u32 v0, v8, 4, 2
	v_and_b32_e32 v1, 15, v8
	v_lshlrev_b32_e32 v138, 3, v0
	v_lshlrev_b32_e32 v0, 4, v0
	v_lshl_or_b32 v139, s1, 6, v1
	v_lshl_or_b32 v0, v1, 6, v0
	v_lshlrev_b32_e32 v1, 2, v8
	v_and_b32_e32 v1, 32, v1
	s_waitcnt vmcnt(6)
	v_bitop3_b32 v2, v0, s8, v1 bitop3:0xde
	v_bitop3_b32 v156, v0, s0, v1 bitop3:0xde
	s_cselect_b64 s[68:69], -1, 0
	s_ashr_i32 s41, s26, 31
	s_ashr_i32 s48, s101, 31
	v_mov_b64_e32 v[140:141], 0x324
	v_mov_b64_e32 v[142:143], 0x323
	s_add_i32 s49, 0, 0x10000
	s_add_i32 s55, 0, 0x14000
	v_add_u32_e32 v157, 0, v2
	s_mov_b32 s57, 0
	s_barrier
	s_branch .LBB0_1539

.LBB0_1539:
	s_add_i32 s57, s57, 1
	s_mul_i32 s0, s57, s41
	s_mul_hi_u32 s1, s57, s26
	s_add_i32 s1, s1, s0
	s_mul_i32 s0, s57, s26
	s_add_u32 s6, s0, s101
	s_addc_u32 s7, s1, s48
	v_cmp_gt_i64_e32 vcc, s[6:7], v[142:143]
	v_cmp_lt_i64_e64 s[0:1], s[6:7], v[140:141]
	s_cbranch_vccnz .LBB0_1545
	s_ashr_i32 s3, s6, 31
	s_lshr_b32 s3, s3, 29
	s_add_i32 s3, s6, s3
	s_and_b32 s7, s3, -8
	s_sub_i32 s8, s6, s7
	s_cmp_gt_i32 s8, 3
	s_mov_b64 s[6:7], -1
	s_cbranch_scc0 .LBB0_1542
	s_mul_i32 s6, s8, 0x64
	s_add_i32 s9, s6, 4
	s_mov_b64 s[6:7], 0

.LBB0_1548:
	s_or_b32 s58, s43, 1
	v_add_u32_e32 v136, s49, v156
	s_lshl_b64 s[10:11], s[58:59], 7
	s_add_i32 s58, s43, 2
	ds_read_b128 v[144:147], v136
	ds_read_b128 v[158:161], v136 offset:1024
	ds_read_b128 v[162:165], v136 offset:2048
	ds_read_b128 v[166:169], v136 offset:3072
	v_add_u32_e32 v136, s55, v156
	s_lshl_b64 s[6:7], s[58:59], 7
	ds_read_b128 v[170:173], v136
	ds_read_b128 v[174:177], v136 offset:1024
	ds_read_b128 v[178:181], v136 offset:2048
	ds_read_b128 v[182:185], v136 offset:3072
	s_add_u32 s18, s80, s6
	s_addc_u32 s19, s81, s7
	s_and_b64 s[8:9], s[86:87], exec
	s_cselect_b32 s9, s73, s19
	s_cselect_b32 s8, s3, s18
	s_add_u32 s18, s82, s6
	s_addc_u32 s19, s83, s7
	s_and_b64 s[6:7], s[86:87], exec
	s_cselect_b32 s7, s71, s19
	s_cselect_b32 s6, s33, s18
	s_add_u32 s10, s62, s10
	s_addc_u32 s11, s63, s11
	v_lshl_add_u64 v[218:219], s[10:11], 0, v[128:129]
	s_add_i32 m0, s28, 0xc000
	ds_read_b128 v[186:189], v157
	ds_read_b128 v[190:193], v157 offset:1024
	ds_read_b128 v[194:197], v157 offset:2048
	ds_read_b128 v[198:201], v157 offset:3072
	ds_read_b128 v[202:205], v157 offset:4096
	ds_read_b128 v[206:209], v157 offset:5120
	ds_read_b128 v[210:213], v157 offset:6144
	ds_read_b128 v[214:217], v157 offset:7168
	global_load_lds_dwordx4 v[218:219], off
	v_lshl_add_u64 v[218:219], s[10:11], 0, v[132:133]
	s_add_i32 m0, s28, 0xe000
	s_nop 0
	global_load_lds_dwordx4 v[218:219], off
	s_cmp_eq_u32 s99, 0
	s_cbranch_scc1 .Ldpw_7_0a
	s_waitcnt vmcnt(16)
	s_branch .Ldpw_7_0b

.Ldpw_7_0b:
	s_waitcnt lgkmcnt(0)
	s_barrier
	s_setprio 1
	s_waitcnt lgkmcnt(0)
	v_mfma_f32_16x16x32_bf16 v[124:127], v[144:147], v[186:189], v[124:127]
	v_mfma_f32_16x16x32_bf16 v[120:123], v[162:165], v[186:189], v[120:123]
	v_mfma_f32_16x16x32_bf16 v[112:115], v[144:147], v[194:197], v[112:115]
	v_mfma_f32_16x16x32_bf16 v[104:107], v[162:165], v[194:197], v[104:107]
	v_mfma_f32_16x16x32_bf16 v[96:99], v[144:147], v[202:205], v[96:99]
	v_mfma_f32_16x16x32_bf16 v[88:91], v[162:165], v[202:205], v[88:91]
	v_mfma_f32_16x16x32_bf16 v[80:83], v[144:147], v[210:213], v[80:83]
	v_mfma_f32_16x16x32_bf16 v[72:75], v[162:165], v[210:213], v[72:75]
	v_mfma_f32_16x16x32_bf16 v[124:127], v[158:161], v[190:193], v[124:127]
	v_mfma_f32_16x16x32_bf16 v[120:123], v[166:169], v[190:193], v[120:123]
	v_mfma_f32_16x16x32_bf16 v[112:115], v[158:161], v[198:201], v[112:115]
	v_mfma_f32_16x16x32_bf16 v[104:107], v[166:169], v[198:201], v[104:107]
	v_mfma_f32_16x16x32_bf16 v[96:99], v[158:161], v[206:209], v[96:99]
	v_mfma_f32_16x16x32_bf16 v[88:91], v[166:169], v[206:209], v[88:91]
	v_mfma_f32_16x16x32_bf16 v[80:83], v[158:161], v[214:217], v[80:83]
	v_mfma_f32_16x16x32_bf16 v[72:75], v[166:169], v[214:217], v[72:75]
	s_setprio 0
	s_setprio 1
	v_mfma_f32_16x16x32_bf16 v[116:119], v[170:173], v[186:189], v[116:119]
	v_mfma_f32_16x16x32_bf16 v[108:111], v[178:181], v[186:189], v[108:111]
	v_mfma_f32_16x16x32_bf16 v[100:103], v[170:173], v[194:197], v[100:103]
	v_mfma_f32_16x16x32_bf16 v[92:95], v[178:181], v[194:197], v[92:95]
	v_mfma_f32_16x16x32_bf16 v[84:87], v[170:173], v[202:205], v[84:87]
	v_mfma_f32_16x16x32_bf16 v[76:79], v[178:181], v[202:205], v[76:79]
	v_mfma_f32_16x16x32_bf16 v[68:71], v[170:173], v[210:213], v[68:71]
	v_mfma_f32_16x16x32_bf16 v[64:67], v[178:181], v[210:213], v[64:67]
	v_mfma_f32_16x16x32_bf16 v[116:119], v[174:177], v[190:193], v[116:119]
	v_mfma_f32_16x16x32_bf16 v[108:111], v[182:185], v[190:193], v[108:111]
	v_mfma_f32_16x16x32_bf16 v[100:103], v[174:177], v[198:201], v[100:103]
	v_mfma_f32_16x16x32_bf16 v[92:95], v[182:185], v[198:201], v[92:95]
	v_mfma_f32_16x16x32_bf16 v[84:87], v[174:177], v[206:209], v[84:87]
	v_mfma_f32_16x16x32_bf16 v[76:79], v[182:185], v[206:209], v[76:79]
	v_mfma_f32_16x16x32_bf16 v[68:71], v[174:177], v[214:217], v[68:71]
	v_mfma_f32_16x16x32_bf16 v[64:67], v[182:185], v[214:217], v[64:67]
	s_setprio 0
	s_barrier
	s_add_i32 s10, s49, s27
	v_lshl_add_u64 v[218:219], s[6:7], 0, v[130:131]
	s_mov_b32 m0, s10
	ds_read_b128 v[186:189], v157 offset:16384
	ds_read_b128 v[190:193], v157 offset:17408
	ds_read_b128 v[194:197], v157 offset:18432
	ds_read_b128 v[198:201], v157 offset:19456
	ds_read_b128 v[202:205], v157 offset:20480
	ds_read_b128 v[206:209], v157 offset:21504
	ds_read_b128 v[210:213], v157 offset:22528
	ds_read_b128 v[214:217], v157 offset:23552
	global_load_lds_dwordx4 v[218:219], off
	s_add_i32 m0, s10, 0x2000
	s_add_u32 s10, s6, 0x40000
	v_lshl_add_u64 v[220:221], s[6:7], 0, v[134:135]
	s_addc_u32 s11, s7, 0
	s_add_i32 s18, s55, s27
	global_load_lds_dwordx4 v[220:221], off
	v_lshl_add_u64 v[222:223], s[10:11], 0, v[130:131]
	s_mov_b32 m0, s18
	v_lshl_add_u64 v[224:225], s[8:9], 0, v[132:133]
	global_load_lds_dwordx4 v[222:223], off
	v_lshl_add_u64 v[222:223], s[10:11], 0, v[134:135]
	s_add_i32 m0, s18, 0x2000
	s_nop 0
	global_load_lds_dwordx4 v[222:223], off
	v_lshl_add_u64 v[222:223], s[8:9], 0, v[128:129]
	s_mov_b32 m0, s28
	s_nop 0
	global_load_lds_dwordx4 v[222:223], off
	s_mov_b32 m0, s29
	s_nop 0
	global_load_lds_dwordx4 v[224:225], off
	s_cmp_eq_u32 s99, 0
	s_cbranch_scc1 .Ldpw_7_1a
	s_waitcnt vmcnt(16)
	s_branch .Ldpw_7_1b

.Ldpw_7_1b:
	s_waitcnt lgkmcnt(0)
	s_barrier
	s_setprio 1
	s_waitcnt lgkmcnt(0)
	v_mfma_f32_16x16x32_bf16 v[60:63], v[144:147], v[186:189], v[60:63]
	v_mfma_f32_16x16x32_bf16 v[56:59], v[162:165], v[186:189], v[56:59]
	v_mfma_f32_16x16x32_bf16 v[48:51], v[144:147], v[194:197], v[48:51]
	v_mfma_f32_16x16x32_bf16 v[40:43], v[162:165], v[194:197], v[40:43]
	v_mfma_f32_16x16x32_bf16 v[32:35], v[144:147], v[202:205], v[32:35]
	v_mfma_f32_16x16x32_bf16 v[24:27], v[162:165], v[202:205], v[24:27]
	v_mfma_f32_16x16x32_bf16 v[16:19], v[144:147], v[210:213], v[16:19]
	v_mfma_f32_16x16x32_bf16 v[8:11], v[162:165], v[210:213], v[8:11]
	v_mfma_f32_16x16x32_bf16 v[60:63], v[158:161], v[190:193], v[60:63]
	v_mfma_f32_16x16x32_bf16 v[56:59], v[166:169], v[190:193], v[56:59]
	v_mfma_f32_16x16x32_bf16 v[48:51], v[158:161], v[198:201], v[48:51]
	v_mfma_f32_16x16x32_bf16 v[40:43], v[166:169], v[198:201], v[40:43]
	v_mfma_f32_16x16x32_bf16 v[32:35], v[158:161], v[206:209], v[32:35]
	v_mfma_f32_16x16x32_bf16 v[24:27], v[166:169], v[206:209], v[24:27]
	v_mfma_f32_16x16x32_bf16 v[16:19], v[158:161], v[214:217], v[16:19]
	v_mfma_f32_16x16x32_bf16 v[8:11], v[166:169], v[214:217], v[8:11]
	s_setprio 0
	s_setprio 1
	v_mfma_f32_16x16x32_bf16 v[52:55], v[170:173], v[186:189], v[52:55]
	v_mfma_f32_16x16x32_bf16 v[44:47], v[178:181], v[186:189], v[44:47]
	v_mfma_f32_16x16x32_bf16 v[36:39], v[170:173], v[194:197], v[36:39]
	v_mfma_f32_16x16x32_bf16 v[28:31], v[178:181], v[194:197], v[28:31]
	v_mfma_f32_16x16x32_bf16 v[20:23], v[170:173], v[202:205], v[20:23]
	v_mfma_f32_16x16x32_bf16 v[12:15], v[178:181], v[202:205], v[12:15]
	v_mfma_f32_16x16x32_bf16 v[4:7], v[170:173], v[210:213], v[4:7]
	v_mfma_f32_16x16x32_bf16 v[0:3], v[178:181], v[210:213], v[0:3]
	v_mfma_f32_16x16x32_bf16 v[52:55], v[174:177], v[190:193], v[52:55]
	v_mfma_f32_16x16x32_bf16 v[44:47], v[182:185], v[190:193], v[44:47]
	v_mfma_f32_16x16x32_bf16 v[36:39], v[174:177], v[198:201], v[36:39]
	v_mfma_f32_16x16x32_bf16 v[28:31], v[182:185], v[198:201], v[28:31]
	v_mfma_f32_16x16x32_bf16 v[20:23], v[174:177], v[206:209], v[20:23]
	v_mfma_f32_16x16x32_bf16 v[12:15], v[182:185], v[206:209], v[12:15]
	v_mfma_f32_16x16x32_bf16 v[4:7], v[174:177], v[214:217], v[4:7]
	v_mfma_f32_16x16x32_bf16 v[0:3], v[182:185], v[214:217], v[0:3]
	s_setprio 0
	s_barrier
	s_add_i32 s10, 0, 0x18000
	v_add_u32_e32 v136, s10, v156
	s_add_i32 s11, 0, 0x1c000
	ds_read_b128 v[144:147], v136
	ds_read_b128 v[158:161], v136 offset:1024
	ds_read_b128 v[162:165], v136 offset:2048
	ds_read_b128 v[166:169], v136 offset:3072
	v_add_u32_e32 v136, s11, v156
	ds_read_b128 v[170:173], v136
	ds_read_b128 v[174:177], v136 offset:1024
	ds_read_b128 v[178:181], v136 offset:2048
	ds_read_b128 v[182:185], v136 offset:3072
	s_add_u32 s8, s8, 0x40000
	s_addc_u32 s9, s9, 0
	s_mov_b32 m0, s12
	v_lshl_add_u64 v[226:227], s[8:9], 0, v[128:129]
	ds_read_b128 v[186:189], v157 offset:32768
	ds_read_b128 v[190:193], v157 offset:33792
	ds_read_b128 v[194:197], v157 offset:34816
	ds_read_b128 v[198:201], v157 offset:35840
	ds_read_b128 v[202:205], v157 offset:36864
	ds_read_b128 v[206:209], v157 offset:37888
	ds_read_b128 v[210:213], v157 offset:38912
	ds_read_b128 v[214:217], v157 offset:39936
	global_load_lds_dwordx4 v[226:227], off
	v_lshl_add_u64 v[226:227], s[8:9], 0, v[132:133]
	s_mov_b32 m0, s13
	s_nop 0
	global_load_lds_dwordx4 v[226:227], off
	s_waitcnt vmcnt(8)
	s_cmp_eq_u32 s99, 0
	s_cbranch_scc1 .Ldp_7_l
	v_readlane_b32 s100, v0, 0
	s_mov_b64 exec, 1
	v_writelane_b32 v0, 1, 0
	s_nop 1
	global_atomic_add v0, v0, s[98:99]
	s_nop 1
	v_writelane_b32 v0, s100, 0
	s_mov_b64 exec, -1
	s_mov_b32 s99, 0
.Ldp_7_l:
	s_waitcnt lgkmcnt(0)
	s_barrier
	s_setprio 1
	s_waitcnt lgkmcnt(0)
	v_mfma_f32_16x16x32_bf16 v[124:127], v[144:147], v[186:189], v[124:127]
	v_mfma_f32_16x16x32_bf16 v[120:123], v[162:165], v[186:189], v[120:123]
	v_mfma_f32_16x16x32_bf16 v[112:115], v[144:147], v[194:197], v[112:115]
	v_mfma_f32_16x16x32_bf16 v[104:107], v[162:165], v[194:197], v[104:107]
	v_mfma_f32_16x16x32_bf16 v[96:99], v[144:147], v[202:205], v[96:99]
	v_mfma_f32_16x16x32_bf16 v[88:91], v[162:165], v[202:205], v[88:91]
	v_mfma_f32_16x16x32_bf16 v[80:83], v[144:147], v[210:213], v[80:83]
	v_mfma_f32_16x16x32_bf16 v[72:75], v[162:165], v[210:213], v[72:75]
	v_mfma_f32_16x16x32_bf16 v[124:127], v[158:161], v[190:193], v[124:127]
	v_mfma_f32_16x16x32_bf16 v[120:123], v[166:169], v[190:193], v[120:123]
	v_mfma_f32_16x16x32_bf16 v[112:115], v[158:161], v[198:201], v[112:115]
	v_mfma_f32_16x16x32_bf16 v[104:107], v[166:169], v[198:201], v[104:107]
	v_mfma_f32_16x16x32_bf16 v[96:99], v[158:161], v[206:209], v[96:99]
	v_mfma_f32_16x16x32_bf16 v[88:91], v[166:169], v[206:209], v[88:91]
	v_mfma_f32_16x16x32_bf16 v[80:83], v[158:161], v[214:217], v[80:83]
	v_mfma_f32_16x16x32_bf16 v[72:75], v[166:169], v[214:217], v[72:75]
	s_setprio 0
	s_setprio 1
	v_mfma_f32_16x16x32_bf16 v[116:119], v[170:173], v[186:189], v[116:119]
	v_mfma_f32_16x16x32_bf16 v[108:111], v[178:181], v[186:189], v[108:111]
	v_mfma_f32_16x16x32_bf16 v[100:103], v[170:173], v[194:197], v[100:103]
	v_mfma_f32_16x16x32_bf16 v[92:95], v[178:181], v[194:197], v[92:95]
	v_mfma_f32_16x16x32_bf16 v[84:87], v[170:173], v[202:205], v[84:87]
	v_mfma_f32_16x16x32_bf16 v[76:79], v[178:181], v[202:205], v[76:79]
	v_mfma_f32_16x16x32_bf16 v[68:71], v[170:173], v[210:213], v[68:71]
	v_mfma_f32_16x16x32_bf16 v[64:67], v[178:181], v[210:213], v[64:67]
	v_mfma_f32_16x16x32_bf16 v[116:119], v[174:177], v[190:193], v[116:119]
	v_mfma_f32_16x16x32_bf16 v[108:111], v[182:185], v[190:193], v[108:111]
	v_mfma_f32_16x16x32_bf16 v[100:103], v[174:177], v[198:201], v[100:103]
	v_mfma_f32_16x16x32_bf16 v[92:95], v[182:185], v[198:201], v[92:95]
	v_mfma_f32_16x16x32_bf16 v[84:87], v[174:177], v[206:209], v[84:87]
	v_mfma_f32_16x16x32_bf16 v[76:79], v[182:185], v[206:209], v[76:79]
	v_mfma_f32_16x16x32_bf16 v[68:71], v[174:177], v[214:217], v[68:71]
	v_mfma_f32_16x16x32_bf16 v[64:67], v[182:185], v[214:217], v[64:67]
	s_setprio 0
	s_barrier
	s_add_i32 s8, s10, s27
	v_lshl_add_u64 v[218:219], v[218:219], 0, s[64:65]
	s_mov_b32 m0, s8
	ds_read_b128 v[186:189], v157 offset:49152
	ds_read_b128 v[190:193], v157 offset:50176
	ds_read_b128 v[194:197], v157 offset:51200
	ds_read_b128 v[198:201], v157 offset:52224
	ds_read_b128 v[202:205], v157 offset:53248
	ds_read_b128 v[206:209], v157 offset:54272
	ds_read_b128 v[210:213], v157 offset:55296
	ds_read_b128 v[214:217], v157 offset:56320
	global_load_lds_dwordx4 v[218:219], off
	s_add_i32 m0, s8, 0x2000
	s_add_u32 s6, s6, 0x40080
	v_lshl_add_u64 v[218:219], v[220:221], 0, s[64:65]
	s_addc_u32 s7, s7, 0
	s_add_i32 s8, s11, s27
	global_load_lds_dwordx4 v[218:219], off
	v_lshl_add_u64 v[218:219], s[6:7], 0, v[130:131]
	s_mov_b32 m0, s8
	s_nop 0
	global_load_lds_dwordx4 v[218:219], off
	v_lshl_add_u64 v[218:219], s[6:7], 0, v[134:135]
	s_add_i32 m0, s8, 0x2000
	s_nop 0
	global_load_lds_dwordx4 v[218:219], off
	v_lshl_add_u64 v[218:219], v[222:223], 0, s[64:65]
	s_mov_b32 m0, s17
	s_nop 0
	global_load_lds_dwordx4 v[218:219], off
	v_lshl_add_u64 v[218:219], v[224:225], 0, s[64:65]
	s_mov_b32 m0, s40
	s_nop 0
	global_load_lds_dwordx4 v[218:219], off
	s_waitcnt vmcnt(8)
	s_waitcnt lgkmcnt(0)
	s_barrier
	s_setprio 1
	s_waitcnt lgkmcnt(0)
	v_mfma_f32_16x16x32_bf16 v[60:63], v[144:147], v[186:189], v[60:63]
	v_mfma_f32_16x16x32_bf16 v[56:59], v[162:165], v[186:189], v[56:59]
	v_mfma_f32_16x16x32_bf16 v[48:51], v[144:147], v[194:197], v[48:51]
	v_mfma_f32_16x16x32_bf16 v[40:43], v[162:165], v[194:197], v[40:43]
	v_mfma_f32_16x16x32_bf16 v[32:35], v[144:147], v[202:205], v[32:35]
	v_mfma_f32_16x16x32_bf16 v[24:27], v[162:165], v[202:205], v[24:27]
	v_mfma_f32_16x16x32_bf16 v[16:19], v[144:147], v[210:213], v[16:19]
	v_mfma_f32_16x16x32_bf16 v[8:11], v[162:165], v[210:213], v[8:11]
	v_mfma_f32_16x16x32_bf16 v[60:63], v[158:161], v[190:193], v[60:63]
	v_mfma_f32_16x16x32_bf16 v[56:59], v[166:169], v[190:193], v[56:59]
	v_mfma_f32_16x16x32_bf16 v[48:51], v[158:161], v[198:201], v[48:51]
	v_mfma_f32_16x16x32_bf16 v[40:43], v[166:169], v[198:201], v[40:43]
	v_mfma_f32_16x16x32_bf16 v[32:35], v[158:161], v[206:209], v[32:35]
	v_mfma_f32_16x16x32_bf16 v[24:27], v[166:169], v[206:209], v[24:27]
	v_mfma_f32_16x16x32_bf16 v[16:19], v[158:161], v[214:217], v[16:19]
	v_mfma_f32_16x16x32_bf16 v[8:11], v[166:169], v[214:217], v[8:11]
	s_setprio 0
	s_setprio 1
	v_mfma_f32_16x16x32_bf16 v[52:55], v[170:173], v[186:189], v[52:55]
	v_mfma_f32_16x16x32_bf16 v[44:47], v[178:181], v[186:189], v[44:47]
	v_mfma_f32_16x16x32_bf16 v[36:39], v[170:173], v[194:197], v[36:39]
	v_mfma_f32_16x16x32_bf16 v[28:31], v[178:181], v[194:197], v[28:31]
	v_mfma_f32_16x16x32_bf16 v[20:23], v[170:173], v[202:205], v[20:23]
	v_mfma_f32_16x16x32_bf16 v[12:15], v[178:181], v[202:205], v[12:15]
	v_mfma_f32_16x16x32_bf16 v[4:7], v[170:173], v[210:213], v[4:7]
	v_mfma_f32_16x16x32_bf16 v[0:3], v[178:181], v[210:213], v[0:3]
	v_mfma_f32_16x16x32_bf16 v[52:55], v[174:177], v[190:193], v[52:55]
	v_mfma_f32_16x16x32_bf16 v[44:47], v[182:185], v[190:193], v[44:47]
	v_mfma_f32_16x16x32_bf16 v[36:39], v[174:177], v[198:201], v[36:39]
	v_mfma_f32_16x16x32_bf16 v[28:31], v[182:185], v[198:201], v[28:31]
	v_mfma_f32_16x16x32_bf16 v[20:23], v[174:177], v[206:209], v[20:23]
	v_mfma_f32_16x16x32_bf16 v[12:15], v[182:185], v[206:209], v[12:15]
	v_mfma_f32_16x16x32_bf16 v[4:7], v[174:177], v[214:217], v[4:7]
	v_mfma_f32_16x16x32_bf16 v[0:3], v[182:185], v[214:217], v[0:3]
	s_setprio 0
	s_barrier
	s_cmp_gt_u32 s43, 13
	s_mov_b32 s43, s58
	s_cbranch_scc1 .LBB0_1618

.LBB0_1624:
	s_nop 0
	s_mov_b64 s[6:7], exec
	v_readlane_b32 s8, v254, 0
	v_readlane_b32 s9, v254, 1
	s_and_b64 s[8:9], s[6:7], s[8:9]
	s_mov_b64 exec, s[8:9]
	s_cbranch_execz .LBB0_1627
	s_mov_b64 s[8:9], exec
	v_mbcnt_lo_u32_b32 v0, s8, 0
	v_mbcnt_hi_u32_b32 v0, s9, v0
	v_cmp_eq_u32_e32 vcc, 0, v0
	s_and_b64 s[10:11], exec, vcc
	s_mov_b64 exec, s[10:11]
	s_cbranch_execz .LBB0_1627
	s_lshl_b32 s10, s54, 6
	s_ashr_i32 s11, s10, 31
	s_lshl_b64 s[10:11], s[10:11], 2
	s_add_u32 s10, s14, s10
	s_addc_u32 s11, s15, s11
	s_bcnt1_i32_b64 s3, s[8:9]
	v_mov_b32_e32 v0, s3
	s_sub_u32 s98, s10, 1
	s_subb_u32 s99, s11, 0

.Ldp_7_x:
	s_barrier
.LBB0_1631:
	v_mov_b32_e32 v26, v153
	v_readlane_b32 s68, v254, 21
	v_lshlrev_b32_e32 v0, 3, v26
	v_and_b32_e32 v104, 0x3f8, v0
	v_readlane_b32 s76, v254, 29
	v_readlane_b32 s77, v254, 30
	v_mov_b32_e32 v107, 0
	v_lshlrev_b32_e32 v106, 2, v104
	s_mov_b64 s[8:9], s[76:77]
	v_lshl_add_u64 v[8:9], s[8:9], 0, v[106:107]
	s_mov_b64 s[0:1], 0x1000
	v_lshl_add_u64 v[16:17], v[8:9], 0, s[0:1]
	s_movk_i32 s0, 0x2000
	v_add_co_u32_e32 v12, vcc, s0, v8
	s_mov_b64 s[0:1], 0x2000
	s_nop 0
	v_addc_co_u32_e32 v13, vcc, 0, v9, vcc
	v_lshl_add_u64 v[20:21], v[8:9], 0, s[0:1]
	global_load_dwordx4 v[0:3], v106, s[76:77]
	global_load_dwordx4 v[4:7], v106, s[76:77] offset:16
	global_load_dwordx4 v[8:11], v[12:13], off offset:-4096
	s_nop 0
	global_load_dwordx4 v[12:15], v[12:13], off
	s_nop 0
	global_load_dwordx4 v[16:19], v[16:17], off offset:16
	s_nop 0
	global_load_dwordx4 v[20:23], v[20:21], off offset:16
	s_add_u32 s50, s24, 0x5a400
	s_addc_u32 s51, s25, 0
	v_readlane_b32 s0, v254, 37
	s_add_u32 s3, s24, 0x54000
	v_lshlrev_b32_e32 v24, 1, v104
	v_mov_b32_e32 v25, v107
	v_readlane_b32 s1, v254, 38
	s_addc_u32 s33, s25, 0
	v_lshl_add_u64 v[110:111], s[34:35], 0, v[24:25]
	v_lshl_add_u64 v[112:113], s[0:1], 0, v[24:25]
	v_lshl_add_u64 v[114:115], s[30:31], 0, v[24:25]
	v_ashrrev_i32_e32 v24, 4, v26
	v_readlane_b32 s80, v254, 33
	v_readlane_b32 s81, v254, 34
	v_readlane_b32 s82, v254, 35
	v_readlane_b32 s83, v254, 36
	s_add_u32 s54, s24, 0x74400
	v_ashrrev_i32_e32 v105, 7, v26
	v_and_b32_e32 v133, -8, v24
	v_lshl_add_u64 v[24:25], s[22:23], 0, v[106:107]
	s_mov_b64 s[0:1], 0x4220000
	s_mov_b32 s53, 0
	s_addc_u32 s55, s25, 0
	v_lshl_add_u64 v[108:109], s[60:61], 0, v[106:107]
	v_and_b32_e32 v132, 3, v105
	v_lshl_add_u64 v[116:117], v[24:25], 0, s[0:1]
	s_mov_b32 s10, -1
	s_movk_i32 s80, 0x60
	s_add_i32 s81, 0, 0x20080
	s_movk_i32 s82, 0x407f
	s_movk_i32 s83, 0x4080
	s_mov_b32 s84, 0xfe03f81
	s_movk_i32 s85, 0xf7f0
	s_movk_i32 s86, 0x80d
	v_mov_b32_e32 v134, 0xfffff7f2
	v_readlane_b32 s69, v254, 22
	v_readlane_b32 s70, v254, 23
	v_readlane_b32 s71, v254, 24
	v_readlane_b32 s72, v254, 25
	v_readlane_b32 s73, v254, 26
	v_readlane_b32 s74, v254, 27
	v_readlane_b32 s75, v254, 28
	v_readlane_b32 s78, v254, 31
	v_readlane_b32 s79, v254, 32
	s_branch .LBB0_1635

.LBB0_1855:
	s_or_b32 s56, s55, 1
	v_add_u32_e32 v157, s37, v147
	s_lshl_b64 s[18:19], s[56:57], 7
	s_add_i32 s56, s55, 2
	ds_read_b128 v[142:145], v157
	ds_read_b128 v[158:161], v157 offset:1024
	ds_read_b128 v[162:165], v157 offset:2048
	ds_read_b128 v[166:169], v157 offset:3072
	v_add_u32_e32 v157, s38, v147
	s_lshl_b64 s[82:83], s[56:57], 7
	ds_read_b128 v[170:173], v157
	ds_read_b128 v[174:177], v157 offset:1024
	ds_read_b128 v[178:181], v157 offset:2048
	ds_read_b128 v[182:185], v157 offset:3072
	s_add_u32 s65, s76, s82
	s_addc_u32 s69, s77, s83
	s_and_b64 s[8:9], s[6:7], exec
	s_cselect_b32 s9, s40, s69
	s_cselect_b32 s8, s41, s65
	s_add_u32 s65, s78, s82
	s_addc_u32 s69, s79, s83
	s_and_b64 s[6:7], s[6:7], exec
	s_cselect_b32 s7, s42, s69
	s_cselect_b32 s6, s43, s65
	s_add_u32 s18, s48, s18
	s_addc_u32 s19, s49, s19
	v_lshl_add_u64 v[218:219], s[18:19], 0, v[128:129]
	s_add_i32 m0, s11, 0xc000
	ds_read_b128 v[186:189], v156
	ds_read_b128 v[190:193], v156 offset:1024
	ds_read_b128 v[194:197], v156 offset:2048
	ds_read_b128 v[198:201], v156 offset:3072
	ds_read_b128 v[202:205], v156 offset:4096
	ds_read_b128 v[206:209], v156 offset:5120
	ds_read_b128 v[210:213], v156 offset:6144
	ds_read_b128 v[214:217], v156 offset:7168
	global_load_lds_dwordx4 v[218:219], off
	v_lshl_add_u64 v[218:219], s[18:19], 0, v[132:133]
	s_add_i32 m0, s11, 0xe000
	s_nop 0
	global_load_lds_dwordx4 v[218:219], off
	s_cmp_eq_u32 s99, 0
	s_cbranch_scc1 .Ldpw_8_0a
	s_waitcnt vmcnt(16)
	s_branch .Ldpw_8_0b

.Ldpw_8_0b:
	s_waitcnt lgkmcnt(0)
	s_barrier
	s_setprio 1
	s_waitcnt lgkmcnt(0)
	v_mfma_f32_16x16x32_bf16 v[124:127], v[142:145], v[186:189], v[124:127]
	v_mfma_f32_16x16x32_bf16 v[120:123], v[162:165], v[186:189], v[120:123]
	v_mfma_f32_16x16x32_bf16 v[108:111], v[142:145], v[194:197], v[108:111]
	v_mfma_f32_16x16x32_bf16 v[104:107], v[162:165], v[194:197], v[104:107]
	v_mfma_f32_16x16x32_bf16 v[92:95], v[142:145], v[202:205], v[92:95]
	v_mfma_f32_16x16x32_bf16 v[88:91], v[162:165], v[202:205], v[88:91]
	v_mfma_f32_16x16x32_bf16 v[76:79], v[142:145], v[210:213], v[76:79]
	v_mfma_f32_16x16x32_bf16 v[72:75], v[162:165], v[210:213], v[72:75]
	v_mfma_f32_16x16x32_bf16 v[124:127], v[158:161], v[190:193], v[124:127]
	v_mfma_f32_16x16x32_bf16 v[120:123], v[166:169], v[190:193], v[120:123]
	v_mfma_f32_16x16x32_bf16 v[108:111], v[158:161], v[198:201], v[108:111]
	v_mfma_f32_16x16x32_bf16 v[104:107], v[166:169], v[198:201], v[104:107]
	v_mfma_f32_16x16x32_bf16 v[92:95], v[158:161], v[206:209], v[92:95]
	v_mfma_f32_16x16x32_bf16 v[88:91], v[166:169], v[206:209], v[88:91]
	v_mfma_f32_16x16x32_bf16 v[76:79], v[158:161], v[214:217], v[76:79]
	v_mfma_f32_16x16x32_bf16 v[72:75], v[166:169], v[214:217], v[72:75]
	s_setprio 0
	s_setprio 1
	v_mfma_f32_16x16x32_bf16 v[116:119], v[170:173], v[186:189], v[116:119]
	v_mfma_f32_16x16x32_bf16 v[112:115], v[178:181], v[186:189], v[112:115]
	v_mfma_f32_16x16x32_bf16 v[100:103], v[170:173], v[194:197], v[100:103]
	v_mfma_f32_16x16x32_bf16 v[96:99], v[178:181], v[194:197], v[96:99]
	v_mfma_f32_16x16x32_bf16 v[84:87], v[170:173], v[202:205], v[84:87]
	v_mfma_f32_16x16x32_bf16 v[80:83], v[178:181], v[202:205], v[80:83]
	v_mfma_f32_16x16x32_bf16 v[68:71], v[170:173], v[210:213], v[68:71]
	v_mfma_f32_16x16x32_bf16 v[64:67], v[178:181], v[210:213], v[64:67]
	v_mfma_f32_16x16x32_bf16 v[116:119], v[174:177], v[190:193], v[116:119]
	v_mfma_f32_16x16x32_bf16 v[112:115], v[182:185], v[190:193], v[112:115]
	v_mfma_f32_16x16x32_bf16 v[100:103], v[174:177], v[198:201], v[100:103]
	v_mfma_f32_16x16x32_bf16 v[96:99], v[182:185], v[198:201], v[96:99]
	v_mfma_f32_16x16x32_bf16 v[84:87], v[174:177], v[206:209], v[84:87]
	v_mfma_f32_16x16x32_bf16 v[80:83], v[182:185], v[206:209], v[80:83]
	v_mfma_f32_16x16x32_bf16 v[68:71], v[174:177], v[214:217], v[68:71]
	v_mfma_f32_16x16x32_bf16 v[64:67], v[182:185], v[214:217], v[64:67]
	s_setprio 0
	s_barrier
	s_add_i32 s18, s37, s10
	v_lshl_add_u64 v[218:219], s[6:7], 0, v[130:131]
	s_mov_b32 m0, s18
	ds_read_b128 v[186:189], v156 offset:16384
	ds_read_b128 v[190:193], v156 offset:17408
	ds_read_b128 v[194:197], v156 offset:18432
	ds_read_b128 v[198:201], v156 offset:19456
	ds_read_b128 v[202:205], v156 offset:20480
	ds_read_b128 v[206:209], v156 offset:21504
	ds_read_b128 v[210:213], v156 offset:22528
	ds_read_b128 v[214:217], v156 offset:23552
	global_load_lds_dwordx4 v[218:219], off
	s_add_i32 m0, s18, 0x2000
	s_add_u32 s18, s6, 0x40000
	v_lshl_add_u64 v[220:221], s[6:7], 0, v[134:135]
	s_addc_u32 s19, s7, 0
	s_add_i32 s65, s38, s10
	global_load_lds_dwordx4 v[220:221], off
	v_lshl_add_u64 v[222:223], s[18:19], 0, v[130:131]
	s_mov_b32 m0, s65
	v_lshl_add_u64 v[224:225], s[8:9], 0, v[132:133]
	global_load_lds_dwordx4 v[222:223], off
	v_lshl_add_u64 v[222:223], s[18:19], 0, v[134:135]
	s_add_i32 m0, s65, 0x2000
	s_nop 0
	global_load_lds_dwordx4 v[222:223], off
	v_lshl_add_u64 v[222:223], s[8:9], 0, v[128:129]
	s_mov_b32 m0, s11
	s_nop 0
	global_load_lds_dwordx4 v[222:223], off
	s_mov_b32 m0, s12
	s_nop 0
	global_load_lds_dwordx4 v[224:225], off
	s_cmp_eq_u32 s99, 0
	s_cbranch_scc1 .Ldpw_8_1a
	s_waitcnt vmcnt(16)
	s_branch .Ldpw_8_1b

.Ldpw_8_1b:
	s_waitcnt lgkmcnt(0)
	s_barrier
	s_setprio 1
	s_waitcnt lgkmcnt(0)
	v_mfma_f32_16x16x32_bf16 v[60:63], v[142:145], v[186:189], v[60:63]
	v_mfma_f32_16x16x32_bf16 v[56:59], v[162:165], v[186:189], v[56:59]
	v_mfma_f32_16x16x32_bf16 v[44:47], v[142:145], v[194:197], v[44:47]
	v_mfma_f32_16x16x32_bf16 v[40:43], v[162:165], v[194:197], v[40:43]
	v_mfma_f32_16x16x32_bf16 v[28:31], v[142:145], v[202:205], v[28:31]
	v_mfma_f32_16x16x32_bf16 v[24:27], v[162:165], v[202:205], v[24:27]
	v_mfma_f32_16x16x32_bf16 v[12:15], v[142:145], v[210:213], v[12:15]
	v_mfma_f32_16x16x32_bf16 v[8:11], v[162:165], v[210:213], v[8:11]
	v_mfma_f32_16x16x32_bf16 v[60:63], v[158:161], v[190:193], v[60:63]
	v_mfma_f32_16x16x32_bf16 v[56:59], v[166:169], v[190:193], v[56:59]
	v_mfma_f32_16x16x32_bf16 v[44:47], v[158:161], v[198:201], v[44:47]
	v_mfma_f32_16x16x32_bf16 v[40:43], v[166:169], v[198:201], v[40:43]
	v_mfma_f32_16x16x32_bf16 v[28:31], v[158:161], v[206:209], v[28:31]
	v_mfma_f32_16x16x32_bf16 v[24:27], v[166:169], v[206:209], v[24:27]
	v_mfma_f32_16x16x32_bf16 v[12:15], v[158:161], v[214:217], v[12:15]
	v_mfma_f32_16x16x32_bf16 v[8:11], v[166:169], v[214:217], v[8:11]
	s_setprio 0
	s_setprio 1
	v_mfma_f32_16x16x32_bf16 v[52:55], v[170:173], v[186:189], v[52:55]
	v_mfma_f32_16x16x32_bf16 v[48:51], v[178:181], v[186:189], v[48:51]
	v_mfma_f32_16x16x32_bf16 v[36:39], v[170:173], v[194:197], v[36:39]
	v_mfma_f32_16x16x32_bf16 v[32:35], v[178:181], v[194:197], v[32:35]
	v_mfma_f32_16x16x32_bf16 v[20:23], v[170:173], v[202:205], v[20:23]
	v_mfma_f32_16x16x32_bf16 v[16:19], v[178:181], v[202:205], v[16:19]
	v_mfma_f32_16x16x32_bf16 v[4:7], v[170:173], v[210:213], v[4:7]
	v_mfma_f32_16x16x32_bf16 v[0:3], v[178:181], v[210:213], v[0:3]
	v_mfma_f32_16x16x32_bf16 v[52:55], v[174:177], v[190:193], v[52:55]
	v_mfma_f32_16x16x32_bf16 v[48:51], v[182:185], v[190:193], v[48:51]
	v_mfma_f32_16x16x32_bf16 v[36:39], v[174:177], v[198:201], v[36:39]
	v_mfma_f32_16x16x32_bf16 v[32:35], v[182:185], v[198:201], v[32:35]
	v_mfma_f32_16x16x32_bf16 v[20:23], v[174:177], v[206:209], v[20:23]
	v_mfma_f32_16x16x32_bf16 v[16:19], v[182:185], v[206:209], v[16:19]
	v_mfma_f32_16x16x32_bf16 v[4:7], v[174:177], v[214:217], v[4:7]
	v_mfma_f32_16x16x32_bf16 v[0:3], v[182:185], v[214:217], v[0:3]
	s_setprio 0
	s_barrier
	s_add_i32 s18, 0, 0x18000
	v_add_u32_e32 v157, s18, v147
	s_add_i32 s19, 0, 0x1c000
	ds_read_b128 v[142:145], v157
	ds_read_b128 v[158:161], v157 offset:1024
	ds_read_b128 v[162:165], v157 offset:2048
	ds_read_b128 v[166:169], v157 offset:3072
	v_add_u32_e32 v157, s19, v147
	ds_read_b128 v[170:173], v157
	ds_read_b128 v[174:177], v157 offset:1024
	ds_read_b128 v[178:181], v157 offset:2048
	ds_read_b128 v[182:185], v157 offset:3072
	s_add_u32 s8, s8, 0x40000
	s_addc_u32 s9, s9, 0
	s_mov_b32 m0, s13
	v_lshl_add_u64 v[226:227], s[8:9], 0, v[128:129]
	ds_read_b128 v[186:189], v156 offset:32768
	ds_read_b128 v[190:193], v156 offset:33792
	ds_read_b128 v[194:197], v156 offset:34816
	ds_read_b128 v[198:201], v156 offset:35840
	ds_read_b128 v[202:205], v156 offset:36864
	ds_read_b128 v[206:209], v156 offset:37888
	ds_read_b128 v[210:213], v156 offset:38912
	ds_read_b128 v[214:217], v156 offset:39936
	global_load_lds_dwordx4 v[226:227], off
	v_lshl_add_u64 v[226:227], s[8:9], 0, v[132:133]
	s_mov_b32 m0, s16
	s_nop 0
	global_load_lds_dwordx4 v[226:227], off
	s_waitcnt vmcnt(8)
	s_cmp_eq_u32 s99, 0
	s_cbranch_scc1 .Ldp_8_l
	v_readlane_b32 s100, v0, 0
	s_mov_b64 exec, 1
	v_writelane_b32 v0, 1, 0
	s_nop 1
	global_atomic_add v0, v0, s[98:99]
	s_nop 1
	v_writelane_b32 v0, s100, 0
	s_mov_b64 exec, -1
	s_mov_b32 s99, 0
.Ldp_8_l:
	s_waitcnt lgkmcnt(0)
	s_barrier
	s_setprio 1
	s_waitcnt lgkmcnt(0)
	v_mfma_f32_16x16x32_bf16 v[124:127], v[142:145], v[186:189], v[124:127]
	v_mfma_f32_16x16x32_bf16 v[120:123], v[162:165], v[186:189], v[120:123]
	v_mfma_f32_16x16x32_bf16 v[108:111], v[142:145], v[194:197], v[108:111]
	v_mfma_f32_16x16x32_bf16 v[104:107], v[162:165], v[194:197], v[104:107]
	v_mfma_f32_16x16x32_bf16 v[92:95], v[142:145], v[202:205], v[92:95]
	v_mfma_f32_16x16x32_bf16 v[88:91], v[162:165], v[202:205], v[88:91]
	v_mfma_f32_16x16x32_bf16 v[76:79], v[142:145], v[210:213], v[76:79]
	v_mfma_f32_16x16x32_bf16 v[72:75], v[162:165], v[210:213], v[72:75]
	v_mfma_f32_16x16x32_bf16 v[124:127], v[158:161], v[190:193], v[124:127]
	v_mfma_f32_16x16x32_bf16 v[120:123], v[166:169], v[190:193], v[120:123]
	v_mfma_f32_16x16x32_bf16 v[108:111], v[158:161], v[198:201], v[108:111]
	v_mfma_f32_16x16x32_bf16 v[104:107], v[166:169], v[198:201], v[104:107]
	v_mfma_f32_16x16x32_bf16 v[92:95], v[158:161], v[206:209], v[92:95]
	v_mfma_f32_16x16x32_bf16 v[88:91], v[166:169], v[206:209], v[88:91]
	v_mfma_f32_16x16x32_bf16 v[76:79], v[158:161], v[214:217], v[76:79]
	v_mfma_f32_16x16x32_bf16 v[72:75], v[166:169], v[214:217], v[72:75]
	s_setprio 0
	s_setprio 1
	v_mfma_f32_16x16x32_bf16 v[116:119], v[170:173], v[186:189], v[116:119]
	v_mfma_f32_16x16x32_bf16 v[112:115], v[178:181], v[186:189], v[112:115]
	v_mfma_f32_16x16x32_bf16 v[100:103], v[170:173], v[194:197], v[100:103]
	v_mfma_f32_16x16x32_bf16 v[96:99], v[178:181], v[194:197], v[96:99]
	v_mfma_f32_16x16x32_bf16 v[84:87], v[170:173], v[202:205], v[84:87]
	v_mfma_f32_16x16x32_bf16 v[80:83], v[178:181], v[202:205], v[80:83]
	v_mfma_f32_16x16x32_bf16 v[68:71], v[170:173], v[210:213], v[68:71]
	v_mfma_f32_16x16x32_bf16 v[64:67], v[178:181], v[210:213], v[64:67]
	v_mfma_f32_16x16x32_bf16 v[116:119], v[174:177], v[190:193], v[116:119]
	v_mfma_f32_16x16x32_bf16 v[112:115], v[182:185], v[190:193], v[112:115]
	v_mfma_f32_16x16x32_bf16 v[100:103], v[174:177], v[198:201], v[100:103]
	v_mfma_f32_16x16x32_bf16 v[96:99], v[182:185], v[198:201], v[96:99]
	v_mfma_f32_16x16x32_bf16 v[84:87], v[174:177], v[206:209], v[84:87]
	v_mfma_f32_16x16x32_bf16 v[80:83], v[182:185], v[206:209], v[80:83]
	v_mfma_f32_16x16x32_bf16 v[68:71], v[174:177], v[214:217], v[68:71]
	v_mfma_f32_16x16x32_bf16 v[64:67], v[182:185], v[214:217], v[64:67]
	s_setprio 0
	s_barrier
	s_add_i32 s8, s18, s10
	v_lshl_add_u64 v[218:219], v[218:219], 0, s[60:61]
	s_mov_b32 m0, s8
	ds_read_b128 v[186:189], v156 offset:49152
	ds_read_b128 v[190:193], v156 offset:50176
	ds_read_b128 v[194:197], v156 offset:51200
	ds_read_b128 v[198:201], v156 offset:52224
	ds_read_b128 v[202:205], v156 offset:53248
	ds_read_b128 v[206:209], v156 offset:54272
	ds_read_b128 v[210:213], v156 offset:55296
	ds_read_b128 v[214:217], v156 offset:56320
	global_load_lds_dwordx4 v[218:219], off
	s_add_i32 m0, s8, 0x2000
	s_add_u32 s6, s6, 0x40080
	v_lshl_add_u64 v[218:219], v[220:221], 0, s[60:61]
	s_addc_u32 s7, s7, 0
	s_add_i32 s8, s19, s10
	global_load_lds_dwordx4 v[218:219], off
	v_lshl_add_u64 v[218:219], s[6:7], 0, v[130:131]
	s_mov_b32 m0, s8
	s_nop 0
	global_load_lds_dwordx4 v[218:219], off
	v_lshl_add_u64 v[218:219], s[6:7], 0, v[134:135]
	s_add_i32 m0, s8, 0x2000
	s_nop 0
	global_load_lds_dwordx4 v[218:219], off
	v_lshl_add_u64 v[218:219], v[222:223], 0, s[60:61]
	s_mov_b32 m0, s27
	s_nop 0
	global_load_lds_dwordx4 v[218:219], off
	v_lshl_add_u64 v[218:219], v[224:225], 0, s[60:61]
	s_mov_b32 m0, s28
	s_nop 0
	global_load_lds_dwordx4 v[218:219], off
	s_waitcnt vmcnt(8)
	s_waitcnt lgkmcnt(0)
	s_barrier
	s_setprio 1
	s_waitcnt lgkmcnt(0)
	v_mfma_f32_16x16x32_bf16 v[60:63], v[142:145], v[186:189], v[60:63]
	v_mfma_f32_16x16x32_bf16 v[56:59], v[162:165], v[186:189], v[56:59]
	v_mfma_f32_16x16x32_bf16 v[44:47], v[142:145], v[194:197], v[44:47]
	v_mfma_f32_16x16x32_bf16 v[40:43], v[162:165], v[194:197], v[40:43]
	v_mfma_f32_16x16x32_bf16 v[28:31], v[142:145], v[202:205], v[28:31]
	v_mfma_f32_16x16x32_bf16 v[24:27], v[162:165], v[202:205], v[24:27]
	v_mfma_f32_16x16x32_bf16 v[12:15], v[142:145], v[210:213], v[12:15]
	v_mfma_f32_16x16x32_bf16 v[8:11], v[162:165], v[210:213], v[8:11]
	v_mfma_f32_16x16x32_bf16 v[60:63], v[158:161], v[190:193], v[60:63]
	v_mfma_f32_16x16x32_bf16 v[56:59], v[166:169], v[190:193], v[56:59]
	v_mfma_f32_16x16x32_bf16 v[44:47], v[158:161], v[198:201], v[44:47]
	v_mfma_f32_16x16x32_bf16 v[40:43], v[166:169], v[198:201], v[40:43]
	v_mfma_f32_16x16x32_bf16 v[28:31], v[158:161], v[206:209], v[28:31]
	v_mfma_f32_16x16x32_bf16 v[24:27], v[166:169], v[206:209], v[24:27]
	v_mfma_f32_16x16x32_bf16 v[12:15], v[158:161], v[214:217], v[12:15]
	v_mfma_f32_16x16x32_bf16 v[8:11], v[166:169], v[214:217], v[8:11]
	s_setprio 0
	s_setprio 1
	v_mfma_f32_16x16x32_bf16 v[52:55], v[170:173], v[186:189], v[52:55]
	v_mfma_f32_16x16x32_bf16 v[48:51], v[178:181], v[186:189], v[48:51]
	v_mfma_f32_16x16x32_bf16 v[36:39], v[170:173], v[194:197], v[36:39]
	v_mfma_f32_16x16x32_bf16 v[32:35], v[178:181], v[194:197], v[32:35]
	v_mfma_f32_16x16x32_bf16 v[20:23], v[170:173], v[202:205], v[20:23]
	v_mfma_f32_16x16x32_bf16 v[16:19], v[178:181], v[202:205], v[16:19]
	v_mfma_f32_16x16x32_bf16 v[4:7], v[170:173], v[210:213], v[4:7]
	v_mfma_f32_16x16x32_bf16 v[0:3], v[178:181], v[210:213], v[0:3]
	v_mfma_f32_16x16x32_bf16 v[52:55], v[174:177], v[190:193], v[52:55]
	v_mfma_f32_16x16x32_bf16 v[48:51], v[182:185], v[190:193], v[48:51]
	v_mfma_f32_16x16x32_bf16 v[36:39], v[174:177], v[198:201], v[36:39]
	v_mfma_f32_16x16x32_bf16 v[32:35], v[182:185], v[198:201], v[32:35]
	v_mfma_f32_16x16x32_bf16 v[20:23], v[174:177], v[206:209], v[20:23]
	v_mfma_f32_16x16x32_bf16 v[16:19], v[182:185], v[206:209], v[16:19]
	v_mfma_f32_16x16x32_bf16 v[4:7], v[174:177], v[214:217], v[4:7]
	v_mfma_f32_16x16x32_bf16 v[0:3], v[182:185], v[214:217], v[0:3]
	s_setprio 0
	s_barrier
	s_cmp_gt_u32 s55, 13
	s_mov_b32 s55, s56
	s_cbranch_scc1 .LBB0_1874

.LBB0_1892:
	s_or_b64 exec, exec, s[6:7]
	s_nop 0
	s_mov_b64 s[6:7], exec
	v_readlane_b32 s8, v254, 0
	v_readlane_b32 s9, v254, 1
	s_and_b64 s[8:9], s[6:7], s[8:9]
	s_mov_b64 exec, s[8:9]
	s_cbranch_execz .LBB0_1895
	s_mov_b64 s[8:9], exec
	v_mbcnt_lo_u32_b32 v0, s8, 0
	v_mbcnt_hi_u32_b32 v0, s9, v0
	v_cmp_eq_u32_e32 vcc, 0, v0
	s_and_b64 s[18:19], exec, vcc
	s_mov_b64 exec, s[18:19]
	s_cbranch_execz .LBB0_1895
	s_lshl_b32 s18, s52, 6
	s_ashr_i32 s19, s18, 31
	s_lshl_b64 s[18:19], s[18:19], 2
	s_add_u32 s18, s34, s18
	s_addc_u32 s19, s35, s19
	s_bcnt1_i32_b64 s8, s[8:9]
	v_mov_b32_e32 v0, s8
	s_sub_u32 s98, s18, 1
	s_subb_u32 s99, s19, 0

.LBB0_1899:
	v_readlane_b32 s6, v255, 0
	s_movk_i32 s8, 0x100
	v_mov_b32_e32 v8, v153
	v_readlane_b32 s7, v255, 1
	s_and_b64 vcc, exec, s[6:7]
	v_readfirstlane_b32 s9, v8
	s_cbranch_vccnz .LBB0_1901
	s_ashr_i32 s0, s101, 31
	s_lshr_b32 s0, s0, 28
	s_add_i32 s0, s101, s0
	s_ashr_i32 s1, s0, 4
	s_and_b32 s0, s0, -16
	s_add_i32 s14, s1, 64
	s_sub_i32 s12, s101, s0

.LBB0_1925:
	s_add_i32 s41, s41, 1
	s_mul_i32 s6, s41, s26
	s_add_i32 s6, s6, s101
	s_cmp_lt_i32 s6, 48
	s_cselect_b64 s[74:75], -1, 0
	s_cmp_gt_i32 s6, 47
	s_cbranch_scc1 .LBB0_1927
	s_ashr_i32 s7, s6, 31
	s_lshr_b32 s7, s7, 28
	s_add_i32 s7, s6, s7
	s_ashr_i32 s8, s7, 4
	s_and_b32 s7, s7, -16
	s_add_i32 s62, s8, 64
	s_sub_i32 s48, s6, s7

.LBB0_1935:
	v_add_u32_e32 v141, s39, v138
	s_or_b32 s52, s78, 1
	s_add_i32 s78, s78, 2
	s_mov_b32 s79, s53
	ds_read_b128 v[142:145], v141
	ds_read_b128 v[156:159], v141 offset:1024
	ds_read_b128 v[160:163], v141 offset:2048
	ds_read_b128 v[164:167], v141 offset:3072
	v_add_u32_e32 v141, s40, v138
	s_lshl_b64 s[18:19], s[52:53], 7
	s_lshl_b64 s[80:81], s[78:79], 7
	ds_read_b128 v[168:171], v141
	ds_read_b128 v[172:175], v141 offset:1024
	ds_read_b128 v[176:179], v141 offset:2048
	ds_read_b128 v[180:183], v141 offset:3072
	s_add_u32 s52, s70, s80
	s_addc_u32 s61, s71, s81
	s_and_b64 s[10:11], s[6:7], exec
	s_cselect_b32 s11, s65, s61
	s_cselect_b32 s10, s64, s52
	s_add_u32 s52, s72, s80
	s_addc_u32 s61, s73, s81
	s_and_b64 s[6:7], s[6:7], exec
	s_cselect_b32 s7, s69, s61
	s_cselect_b32 s6, s68, s52
	s_add_u32 s18, s42, s18
	s_addc_u32 s19, s43, s19
	v_lshl_add_u64 v[146:147], s[18:19], 0, v[128:129]
	s_add_i32 m0, s16, 0xc000
	ds_read_b128 v[184:187], v140
	ds_read_b128 v[188:191], v140 offset:1024
	ds_read_b128 v[192:195], v140 offset:2048
	ds_read_b128 v[196:199], v140 offset:3072
	ds_read_b128 v[200:203], v140 offset:4096
	ds_read_b128 v[204:207], v140 offset:5120
	ds_read_b128 v[208:211], v140 offset:6144
	ds_read_b128 v[212:215], v140 offset:7168
	global_load_lds_dwordx4 v[146:147], off
	v_lshl_add_u64 v[146:147], s[18:19], 0, v[132:133]
	s_add_i32 m0, s16, 0xe000
	s_nop 0
	global_load_lds_dwordx4 v[146:147], off
	s_cmp_eq_u32 s99, 0
	s_cbranch_scc1 .Ldpw_9_0a
	s_waitcnt vmcnt(16)
	s_branch .Ldpw_9_0b

.Ldpw_9_0b:
	s_waitcnt lgkmcnt(0)
	s_barrier
	s_setprio 1
	s_waitcnt lgkmcnt(0)
	v_mfma_f32_16x16x32_bf16 v[124:127], v[142:145], v[184:187], v[124:127]
	v_mfma_f32_16x16x32_bf16 v[120:123], v[160:163], v[184:187], v[120:123]
	v_mfma_f32_16x16x32_bf16 v[108:111], v[142:145], v[192:195], v[108:111]
	v_mfma_f32_16x16x32_bf16 v[104:107], v[160:163], v[192:195], v[104:107]
	v_mfma_f32_16x16x32_bf16 v[92:95], v[142:145], v[200:203], v[92:95]
	v_mfma_f32_16x16x32_bf16 v[88:91], v[160:163], v[200:203], v[88:91]
	v_mfma_f32_16x16x32_bf16 v[76:79], v[142:145], v[208:211], v[76:79]
	v_mfma_f32_16x16x32_bf16 v[72:75], v[160:163], v[208:211], v[72:75]
	v_mfma_f32_16x16x32_bf16 v[124:127], v[156:159], v[188:191], v[124:127]
	v_mfma_f32_16x16x32_bf16 v[120:123], v[164:167], v[188:191], v[120:123]
	v_mfma_f32_16x16x32_bf16 v[108:111], v[156:159], v[196:199], v[108:111]
	v_mfma_f32_16x16x32_bf16 v[104:107], v[164:167], v[196:199], v[104:107]
	v_mfma_f32_16x16x32_bf16 v[92:95], v[156:159], v[204:207], v[92:95]
	v_mfma_f32_16x16x32_bf16 v[88:91], v[164:167], v[204:207], v[88:91]
	v_mfma_f32_16x16x32_bf16 v[76:79], v[156:159], v[212:215], v[76:79]
	v_mfma_f32_16x16x32_bf16 v[72:75], v[164:167], v[212:215], v[72:75]
	s_setprio 0
	s_setprio 1
	v_mfma_f32_16x16x32_bf16 v[116:119], v[168:171], v[184:187], v[116:119]
	v_mfma_f32_16x16x32_bf16 v[112:115], v[176:179], v[184:187], v[112:115]
	v_mfma_f32_16x16x32_bf16 v[100:103], v[168:171], v[192:195], v[100:103]
	v_mfma_f32_16x16x32_bf16 v[96:99], v[176:179], v[192:195], v[96:99]
	v_mfma_f32_16x16x32_bf16 v[84:87], v[168:171], v[200:203], v[84:87]
	v_mfma_f32_16x16x32_bf16 v[80:83], v[176:179], v[200:203], v[80:83]
	v_mfma_f32_16x16x32_bf16 v[68:71], v[168:171], v[208:211], v[68:71]
	v_mfma_f32_16x16x32_bf16 v[64:67], v[176:179], v[208:211], v[64:67]
	v_mfma_f32_16x16x32_bf16 v[116:119], v[172:175], v[188:191], v[116:119]
	v_mfma_f32_16x16x32_bf16 v[112:115], v[180:183], v[188:191], v[112:115]
	v_mfma_f32_16x16x32_bf16 v[100:103], v[172:175], v[196:199], v[100:103]
	v_mfma_f32_16x16x32_bf16 v[96:99], v[180:183], v[196:199], v[96:99]
	v_mfma_f32_16x16x32_bf16 v[84:87], v[172:175], v[204:207], v[84:87]
	v_mfma_f32_16x16x32_bf16 v[80:83], v[180:183], v[204:207], v[80:83]
	v_mfma_f32_16x16x32_bf16 v[68:71], v[172:175], v[212:215], v[68:71]
	v_mfma_f32_16x16x32_bf16 v[64:67], v[180:183], v[212:215], v[64:67]
	s_setprio 0
	s_barrier
	s_add_i32 s18, s39, s15
	v_lshl_add_u64 v[146:147], s[6:7], 0, v[130:131]
	s_mov_b32 m0, s18
	ds_read_b128 v[184:187], v140 offset:16384
	ds_read_b128 v[188:191], v140 offset:17408
	ds_read_b128 v[192:195], v140 offset:18432
	ds_read_b128 v[196:199], v140 offset:19456
	ds_read_b128 v[200:203], v140 offset:20480
	ds_read_b128 v[204:207], v140 offset:21504
	ds_read_b128 v[208:211], v140 offset:22528
	ds_read_b128 v[212:215], v140 offset:23552
	global_load_lds_dwordx4 v[146:147], off
	s_add_i32 m0, s18, 0x2000
	s_add_u32 s18, s6, 0x40000
	v_lshl_add_u64 v[216:217], s[6:7], 0, v[134:135]
	s_addc_u32 s19, s7, 0
	s_add_i32 s52, s40, s15
	global_load_lds_dwordx4 v[216:217], off
	v_lshl_add_u64 v[218:219], s[18:19], 0, v[130:131]
	s_mov_b32 m0, s52
	v_lshl_add_u64 v[220:221], s[10:11], 0, v[132:133]
	global_load_lds_dwordx4 v[218:219], off
	v_lshl_add_u64 v[218:219], s[18:19], 0, v[134:135]
	s_add_i32 m0, s52, 0x2000
	s_nop 0
	global_load_lds_dwordx4 v[218:219], off
	v_lshl_add_u64 v[218:219], s[10:11], 0, v[128:129]
	s_mov_b32 m0, s16
	s_nop 0
	global_load_lds_dwordx4 v[218:219], off
	s_mov_b32 m0, s17
	s_nop 0
	global_load_lds_dwordx4 v[220:221], off
	s_cmp_eq_u32 s99, 0
	s_cbranch_scc1 .Ldpw_9_1a
	s_waitcnt vmcnt(16)
	s_branch .Ldpw_9_1b

.Ldpw_9_1b:
	s_waitcnt lgkmcnt(0)
	s_barrier
	s_setprio 1
	s_waitcnt lgkmcnt(0)
	v_mfma_f32_16x16x32_bf16 v[60:63], v[142:145], v[184:187], v[60:63]
	v_mfma_f32_16x16x32_bf16 v[56:59], v[160:163], v[184:187], v[56:59]
	v_mfma_f32_16x16x32_bf16 v[44:47], v[142:145], v[192:195], v[44:47]
	v_mfma_f32_16x16x32_bf16 v[40:43], v[160:163], v[192:195], v[40:43]
	v_mfma_f32_16x16x32_bf16 v[28:31], v[142:145], v[200:203], v[28:31]
	v_mfma_f32_16x16x32_bf16 v[24:27], v[160:163], v[200:203], v[24:27]
	v_mfma_f32_16x16x32_bf16 v[12:15], v[142:145], v[208:211], v[12:15]
	v_mfma_f32_16x16x32_bf16 v[8:11], v[160:163], v[208:211], v[8:11]
	v_mfma_f32_16x16x32_bf16 v[60:63], v[156:159], v[188:191], v[60:63]
	v_mfma_f32_16x16x32_bf16 v[56:59], v[164:167], v[188:191], v[56:59]
	v_mfma_f32_16x16x32_bf16 v[44:47], v[156:159], v[196:199], v[44:47]
	v_mfma_f32_16x16x32_bf16 v[40:43], v[164:167], v[196:199], v[40:43]
	v_mfma_f32_16x16x32_bf16 v[28:31], v[156:159], v[204:207], v[28:31]
	v_mfma_f32_16x16x32_bf16 v[24:27], v[164:167], v[204:207], v[24:27]
	v_mfma_f32_16x16x32_bf16 v[12:15], v[156:159], v[212:215], v[12:15]
	v_mfma_f32_16x16x32_bf16 v[8:11], v[164:167], v[212:215], v[8:11]
	s_setprio 0
	s_setprio 1
	v_mfma_f32_16x16x32_bf16 v[52:55], v[168:171], v[184:187], v[52:55]
	v_mfma_f32_16x16x32_bf16 v[48:51], v[176:179], v[184:187], v[48:51]
	v_mfma_f32_16x16x32_bf16 v[36:39], v[168:171], v[192:195], v[36:39]
	v_mfma_f32_16x16x32_bf16 v[32:35], v[176:179], v[192:195], v[32:35]
	v_mfma_f32_16x16x32_bf16 v[20:23], v[168:171], v[200:203], v[20:23]
	v_mfma_f32_16x16x32_bf16 v[16:19], v[176:179], v[200:203], v[16:19]
	v_mfma_f32_16x16x32_bf16 v[4:7], v[168:171], v[208:211], v[4:7]
	v_mfma_f32_16x16x32_bf16 v[0:3], v[176:179], v[208:211], v[0:3]
	v_mfma_f32_16x16x32_bf16 v[52:55], v[172:175], v[188:191], v[52:55]
	v_mfma_f32_16x16x32_bf16 v[48:51], v[180:183], v[188:191], v[48:51]
	v_mfma_f32_16x16x32_bf16 v[36:39], v[172:175], v[196:199], v[36:39]
	v_mfma_f32_16x16x32_bf16 v[32:35], v[180:183], v[196:199], v[32:35]
	v_mfma_f32_16x16x32_bf16 v[20:23], v[172:175], v[204:207], v[20:23]
	v_mfma_f32_16x16x32_bf16 v[16:19], v[180:183], v[204:207], v[16:19]
	v_mfma_f32_16x16x32_bf16 v[4:7], v[172:175], v[212:215], v[4:7]
	v_mfma_f32_16x16x32_bf16 v[0:3], v[180:183], v[212:215], v[0:3]
	s_setprio 0
	s_barrier
	s_add_i32 s18, 0, 0x18000
	v_add_u32_e32 v141, s18, v138
	s_add_i32 s19, 0, 0x1c000
	ds_read_b128 v[142:145], v141
	ds_read_b128 v[156:159], v141 offset:1024
	ds_read_b128 v[160:163], v141 offset:2048
	ds_read_b128 v[164:167], v141 offset:3072
	v_add_u32_e32 v141, s19, v138
	ds_read_b128 v[168:171], v141
	ds_read_b128 v[172:175], v141 offset:1024
	ds_read_b128 v[176:179], v141 offset:2048
	ds_read_b128 v[180:183], v141 offset:3072
	s_add_u32 s10, s10, 0x40000
	s_addc_u32 s11, s11, 0
	s_mov_b32 m0, s27
	v_lshl_add_u64 v[222:223], s[10:11], 0, v[128:129]
	ds_read_b128 v[184:187], v140 offset:32768
	ds_read_b128 v[188:191], v140 offset:33792
	ds_read_b128 v[192:195], v140 offset:34816
	ds_read_b128 v[196:199], v140 offset:35840
	ds_read_b128 v[200:203], v140 offset:36864
	ds_read_b128 v[204:207], v140 offset:37888
	ds_read_b128 v[208:211], v140 offset:38912
	ds_read_b128 v[212:215], v140 offset:39936
	global_load_lds_dwordx4 v[222:223], off
	v_lshl_add_u64 v[222:223], s[10:11], 0, v[132:133]
	s_mov_b32 m0, s28
	s_nop 0
	global_load_lds_dwordx4 v[222:223], off
	s_waitcnt vmcnt(8)
	s_cmp_eq_u32 s99, 0
	s_cbranch_scc1 .Ldp_9_l
	v_readlane_b32 s100, v0, 0
	s_mov_b64 exec, 1
	v_writelane_b32 v0, 1, 0
	s_nop 1
	global_atomic_add v0, v0, s[98:99]
	s_nop 1
	v_writelane_b32 v0, s100, 0
	s_mov_b64 exec, -1
	s_mov_b32 s99, 0
.Ldp_9_l:
	s_waitcnt lgkmcnt(0)
	s_barrier
	s_setprio 1
	s_waitcnt lgkmcnt(0)
	v_mfma_f32_16x16x32_bf16 v[124:127], v[142:145], v[184:187], v[124:127]
	v_mfma_f32_16x16x32_bf16 v[120:123], v[160:163], v[184:187], v[120:123]
	v_mfma_f32_16x16x32_bf16 v[108:111], v[142:145], v[192:195], v[108:111]
	v_mfma_f32_16x16x32_bf16 v[104:107], v[160:163], v[192:195], v[104:107]
	v_mfma_f32_16x16x32_bf16 v[92:95], v[142:145], v[200:203], v[92:95]
	v_mfma_f32_16x16x32_bf16 v[88:91], v[160:163], v[200:203], v[88:91]
	v_mfma_f32_16x16x32_bf16 v[76:79], v[142:145], v[208:211], v[76:79]
	v_mfma_f32_16x16x32_bf16 v[72:75], v[160:163], v[208:211], v[72:75]
	v_mfma_f32_16x16x32_bf16 v[124:127], v[156:159], v[188:191], v[124:127]
	v_mfma_f32_16x16x32_bf16 v[120:123], v[164:167], v[188:191], v[120:123]
	v_mfma_f32_16x16x32_bf16 v[108:111], v[156:159], v[196:199], v[108:111]
	v_mfma_f32_16x16x32_bf16 v[104:107], v[164:167], v[196:199], v[104:107]
	v_mfma_f32_16x16x32_bf16 v[92:95], v[156:159], v[204:207], v[92:95]
	v_mfma_f32_16x16x32_bf16 v[88:91], v[164:167], v[204:207], v[88:91]
	v_mfma_f32_16x16x32_bf16 v[76:79], v[156:159], v[212:215], v[76:79]
	v_mfma_f32_16x16x32_bf16 v[72:75], v[164:167], v[212:215], v[72:75]
	s_setprio 0
	s_setprio 1
	v_mfma_f32_16x16x32_bf16 v[116:119], v[168:171], v[184:187], v[116:119]
	v_mfma_f32_16x16x32_bf16 v[112:115], v[176:179], v[184:187], v[112:115]
	v_mfma_f32_16x16x32_bf16 v[100:103], v[168:171], v[192:195], v[100:103]
	v_mfma_f32_16x16x32_bf16 v[96:99], v[176:179], v[192:195], v[96:99]
	v_mfma_f32_16x16x32_bf16 v[84:87], v[168:171], v[200:203], v[84:87]
	v_mfma_f32_16x16x32_bf16 v[80:83], v[176:179], v[200:203], v[80:83]
	v_mfma_f32_16x16x32_bf16 v[68:71], v[168:171], v[208:211], v[68:71]
	v_mfma_f32_16x16x32_bf16 v[64:67], v[176:179], v[208:211], v[64:67]
	v_mfma_f32_16x16x32_bf16 v[116:119], v[172:175], v[188:191], v[116:119]
	v_mfma_f32_16x16x32_bf16 v[112:115], v[180:183], v[188:191], v[112:115]
	v_mfma_f32_16x16x32_bf16 v[100:103], v[172:175], v[196:199], v[100:103]
	v_mfma_f32_16x16x32_bf16 v[96:99], v[180:183], v[196:199], v[96:99]
	v_mfma_f32_16x16x32_bf16 v[84:87], v[172:175], v[204:207], v[84:87]
	v_mfma_f32_16x16x32_bf16 v[80:83], v[180:183], v[204:207], v[80:83]
	v_mfma_f32_16x16x32_bf16 v[68:71], v[172:175], v[212:215], v[68:71]
	v_mfma_f32_16x16x32_bf16 v[64:67], v[180:183], v[212:215], v[64:67]
	s_setprio 0
	s_barrier
	s_add_i32 s10, s18, s15
	v_lshl_add_u64 v[146:147], v[146:147], 0, s[56:57]
	s_mov_b32 m0, s10
	ds_read_b128 v[184:187], v140 offset:49152
	ds_read_b128 v[188:191], v140 offset:50176
	ds_read_b128 v[192:195], v140 offset:51200
	ds_read_b128 v[196:199], v140 offset:52224
	ds_read_b128 v[200:203], v140 offset:53248
	ds_read_b128 v[204:207], v140 offset:54272
	ds_read_b128 v[208:211], v140 offset:55296
	ds_read_b128 v[212:215], v140 offset:56320
	global_load_lds_dwordx4 v[146:147], off
	s_add_i32 m0, s10, 0x2000
	s_add_u32 s6, s6, 0x40080
	v_lshl_add_u64 v[146:147], v[216:217], 0, s[56:57]
	s_addc_u32 s7, s7, 0
	s_add_i32 s10, s19, s15
	global_load_lds_dwordx4 v[146:147], off
	v_lshl_add_u64 v[146:147], s[6:7], 0, v[130:131]
	s_mov_b32 m0, s10
	s_nop 0
	global_load_lds_dwordx4 v[146:147], off
	v_lshl_add_u64 v[146:147], s[6:7], 0, v[134:135]
	s_add_i32 m0, s10, 0x2000
	s_nop 0
	global_load_lds_dwordx4 v[146:147], off
	v_lshl_add_u64 v[146:147], v[218:219], 0, s[56:57]
	s_mov_b32 m0, s36
	s_nop 0
	global_load_lds_dwordx4 v[146:147], off
	v_lshl_add_u64 v[146:147], v[220:221], 0, s[56:57]
	s_mov_b32 m0, s37
	s_nop 0
	global_load_lds_dwordx4 v[146:147], off
	s_waitcnt vmcnt(8)
	s_waitcnt lgkmcnt(0)
	s_barrier
	s_setprio 1
	s_waitcnt lgkmcnt(0)
	v_mfma_f32_16x16x32_bf16 v[60:63], v[142:145], v[184:187], v[60:63]
	v_mfma_f32_16x16x32_bf16 v[56:59], v[160:163], v[184:187], v[56:59]
	v_mfma_f32_16x16x32_bf16 v[44:47], v[142:145], v[192:195], v[44:47]
	v_mfma_f32_16x16x32_bf16 v[40:43], v[160:163], v[192:195], v[40:43]
	v_mfma_f32_16x16x32_bf16 v[28:31], v[142:145], v[200:203], v[28:31]
	v_mfma_f32_16x16x32_bf16 v[24:27], v[160:163], v[200:203], v[24:27]
	v_mfma_f32_16x16x32_bf16 v[12:15], v[142:145], v[208:211], v[12:15]
	v_mfma_f32_16x16x32_bf16 v[8:11], v[160:163], v[208:211], v[8:11]
	v_mfma_f32_16x16x32_bf16 v[60:63], v[156:159], v[188:191], v[60:63]
	v_mfma_f32_16x16x32_bf16 v[56:59], v[164:167], v[188:191], v[56:59]
	v_mfma_f32_16x16x32_bf16 v[44:47], v[156:159], v[196:199], v[44:47]
	v_mfma_f32_16x16x32_bf16 v[40:43], v[164:167], v[196:199], v[40:43]
	v_mfma_f32_16x16x32_bf16 v[28:31], v[156:159], v[204:207], v[28:31]
	v_mfma_f32_16x16x32_bf16 v[24:27], v[164:167], v[204:207], v[24:27]
	v_mfma_f32_16x16x32_bf16 v[12:15], v[156:159], v[212:215], v[12:15]
	v_mfma_f32_16x16x32_bf16 v[8:11], v[164:167], v[212:215], v[8:11]
	s_setprio 0
	s_setprio 1
	v_mfma_f32_16x16x32_bf16 v[52:55], v[168:171], v[184:187], v[52:55]
	v_mfma_f32_16x16x32_bf16 v[48:51], v[176:179], v[184:187], v[48:51]
	v_mfma_f32_16x16x32_bf16 v[36:39], v[168:171], v[192:195], v[36:39]
	v_mfma_f32_16x16x32_bf16 v[32:35], v[176:179], v[192:195], v[32:35]
	v_mfma_f32_16x16x32_bf16 v[20:23], v[168:171], v[200:203], v[20:23]
	v_mfma_f32_16x16x32_bf16 v[16:19], v[176:179], v[200:203], v[16:19]
	v_mfma_f32_16x16x32_bf16 v[4:7], v[168:171], v[208:211], v[4:7]
	v_mfma_f32_16x16x32_bf16 v[0:3], v[176:179], v[208:211], v[0:3]
	v_mfma_f32_16x16x32_bf16 v[52:55], v[172:175], v[188:191], v[52:55]
	v_mfma_f32_16x16x32_bf16 v[48:51], v[180:183], v[188:191], v[48:51]
	v_mfma_f32_16x16x32_bf16 v[36:39], v[172:175], v[196:199], v[36:39]
	v_mfma_f32_16x16x32_bf16 v[32:35], v[180:183], v[196:199], v[32:35]
	v_mfma_f32_16x16x32_bf16 v[20:23], v[172:175], v[204:207], v[20:23]
	v_mfma_f32_16x16x32_bf16 v[16:19], v[180:183], v[204:207], v[16:19]
	v_mfma_f32_16x16x32_bf16 v[4:7], v[172:175], v[212:215], v[4:7]
	v_mfma_f32_16x16x32_bf16 v[0:3], v[180:183], v[212:215], v[0:3]
	s_setprio 0
	s_barrier
	s_cmp_ge_i32 s78, s29
	s_cbranch_scc1 .LBB0_1954

.LBB0_1956:
	s_ashr_i32 s6, s12, 31
	s_lshr_b32 s6, s6, 30
	s_add_i32 s10, s12, s6
	s_and_b32 s6, s10, 0xfffffc
	s_sub_i32 s6, s12, s6
	s_mulk_i32 s6, 0x300
	v_lshl_add_u32 v142, s14, 8, v139
	s_ashr_i32 s7, s6, 31
	v_ashrrev_i32_e32 v143, 31, v142
	v_lshl_add_u64 v[142:143], v[142:143], 0, s[6:7]
	v_readlane_b32 s6, v254, 51
	v_lshlrev_b64 v[142:143], 11, v[142:143]
	v_readlane_b32 s7, v254, 52
	s_mov_b32 s61, s53
	v_cvt_pk_bf16_f32 v124, v124, v125
	v_cvt_pk_bf16_f32 v125, v126, v127
	v_cvt_pk_bf16_f32 v126, v120, v121
	v_cvt_pk_bf16_f32 v127, v122, v123
	s_nop 0
	v_lshl_add_u64 v[142:143], s[6:7], 0, v[142:143]
	s_lshl_b32 s6, s10, 6
	s_and_b32 s6, s6, 0xffffff00
	s_ashr_i32 s7, s6, 31
	v_lshl_add_u64 v[142:143], s[6:7], 1, v[142:143]
	v_lshl_add_u64 v[142:143], v[142:143], 0, s[60:61]
	v_lshl_add_u64 v[142:143], v[142:143], 0, v[136:137]
	s_mov_b64 s[6:7], 0x100
	global_store_dwordx4 v[142:143], v[124:127], off sc0 sc1
	s_nop 1
	v_cvt_pk_bf16_f32 v116, v116, v117
	v_cvt_pk_bf16_f32 v117, v118, v119
	v_cvt_pk_bf16_f32 v118, v112, v113
	v_lshl_add_u64 v[112:113], v[142:143], 0, s[6:7]
	s_mov_b64 s[6:7], 0x8000
	v_cvt_pk_bf16_f32 v119, v114, v115
	s_nop 0
	global_store_dwordx4 v[112:113], v[116:119], off sc0 sc1
	s_nop 1
	v_lshl_add_u64 v[112:113], v[142:143], 0, s[6:7]
	s_mov_b64 s[6:7], 0x8100
	v_cvt_pk_bf16_f32 v108, v108, v109
	v_cvt_pk_bf16_f32 v109, v110, v111
	v_cvt_pk_bf16_f32 v110, v104, v105
	v_cvt_pk_bf16_f32 v111, v106, v107
	s_nop 0
	global_store_dwordx4 v[112:113], v[108:111], off sc0 sc1
	s_nop 1
	v_cvt_pk_bf16_f32 v100, v100, v101
	v_cvt_pk_bf16_f32 v101, v102, v103
	v_cvt_pk_bf16_f32 v102, v96, v97
	v_lshl_add_u64 v[96:97], v[142:143], 0, s[6:7]
	s_mov_b64 s[6:7], 0x10000
	v_cvt_pk_bf16_f32 v103, v98, v99
	s_nop 0
	global_store_dwordx4 v[96:97], v[100:103], off sc0 sc1
	s_nop 1
	v_lshl_add_u64 v[96:97], v[142:143], 0, s[6:7]
	s_mov_b64 s[6:7], 0x10100
	v_cvt_pk_bf16_f32 v92, v92, v93
	v_cvt_pk_bf16_f32 v93, v94, v95
	v_cvt_pk_bf16_f32 v94, v88, v89
	v_cvt_pk_bf16_f32 v95, v90, v91
	s_nop 0
	global_store_dwordx4 v[96:97], v[92:95], off sc0 sc1
	s_nop 1
	v_cvt_pk_bf16_f32 v84, v84, v85
	v_cvt_pk_bf16_f32 v85, v86, v87
	v_cvt_pk_bf16_f32 v86, v80, v81
	v_lshl_add_u64 v[80:81], v[142:143], 0, s[6:7]
	s_mov_b64 s[6:7], 0x18000
	v_cvt_pk_bf16_f32 v87, v82, v83
	s_nop 0
	global_store_dwordx4 v[80:81], v[84:87], off sc0 sc1
	s_nop 1
	v_lshl_add_u64 v[80:81], v[142:143], 0, s[6:7]
	s_mov_b64 s[6:7], 0x18100
	v_cvt_pk_bf16_f32 v76, v76, v77
	v_cvt_pk_bf16_f32 v77, v78, v79
	v_cvt_pk_bf16_f32 v78, v72, v73
	v_cvt_pk_bf16_f32 v79, v74, v75
	s_nop 0
	global_store_dwordx4 v[80:81], v[76:79], off sc0 sc1
	s_nop 1
	v_cvt_pk_bf16_f32 v68, v68, v69
	v_cvt_pk_bf16_f32 v69, v70, v71
	v_cvt_pk_bf16_f32 v70, v64, v65
	v_lshl_add_u64 v[64:65], v[142:143], 0, s[6:7]
	s_mov_b64 s[6:7], 0x40000
	v_cvt_pk_bf16_f32 v71, v66, v67
	s_nop 0
	global_store_dwordx4 v[64:65], v[68:71], off sc0 sc1
	s_nop 1
	v_lshl_add_u64 v[64:65], v[142:143], 0, s[6:7]
	s_mov_b64 s[6:7], 0x40100
	v_cvt_pk_bf16_f32 v60, v60, v61
	v_cvt_pk_bf16_f32 v61, v62, v63
	v_cvt_pk_bf16_f32 v62, v56, v57
	v_cvt_pk_bf16_f32 v63, v58, v59
	s_nop 0
	global_store_dwordx4 v[64:65], v[60:63], off sc0 sc1
	s_nop 1
	v_cvt_pk_bf16_f32 v52, v52, v53
	v_cvt_pk_bf16_f32 v53, v54, v55
	v_cvt_pk_bf16_f32 v54, v48, v49
	v_lshl_add_u64 v[48:49], v[142:143], 0, s[6:7]
	s_mov_b64 s[6:7], 0x48000
	v_cvt_pk_bf16_f32 v55, v50, v51
	s_nop 0
	global_store_dwordx4 v[48:49], v[52:55], off sc0 sc1
	s_nop 1
	v_lshl_add_u64 v[48:49], v[142:143], 0, s[6:7]
	s_mov_b64 s[6:7], 0x48100
	v_cvt_pk_bf16_f32 v44, v44, v45
	v_cvt_pk_bf16_f32 v45, v46, v47
	v_cvt_pk_bf16_f32 v46, v40, v41
	v_cvt_pk_bf16_f32 v47, v42, v43
	s_nop 0
	global_store_dwordx4 v[48:49], v[44:47], off sc0 sc1
	s_nop 1
	v_cvt_pk_bf16_f32 v36, v36, v37
	v_cvt_pk_bf16_f32 v37, v38, v39
	v_cvt_pk_bf16_f32 v38, v32, v33
	v_lshl_add_u64 v[32:33], v[142:143], 0, s[6:7]
	s_mov_b64 s[6:7], 0x50000
	v_cvt_pk_bf16_f32 v39, v34, v35
	s_nop 0
	global_store_dwordx4 v[32:33], v[36:39], off sc0 sc1
	s_nop 1
	v_lshl_add_u64 v[32:33], v[142:143], 0, s[6:7]
	s_mov_b64 s[6:7], 0x50100
	v_cvt_pk_bf16_f32 v28, v28, v29
	v_cvt_pk_bf16_f32 v29, v30, v31
	v_cvt_pk_bf16_f32 v30, v24, v25
	v_cvt_pk_bf16_f32 v31, v26, v27
	s_nop 0
	global_store_dwordx4 v[32:33], v[28:31], off sc0 sc1
	s_nop 1
	v_cvt_pk_bf16_f32 v20, v20, v21
	v_cvt_pk_bf16_f32 v21, v22, v23
	v_cvt_pk_bf16_f32 v22, v16, v17
	v_lshl_add_u64 v[16:17], v[142:143], 0, s[6:7]
	s_mov_b64 s[6:7], 0x58000
	v_cvt_pk_bf16_f32 v23, v18, v19
	s_nop 0
	global_store_dwordx4 v[16:17], v[20:23], off sc0 sc1
	s_nop 1
	v_lshl_add_u64 v[16:17], v[142:143], 0, s[6:7]
	s_mov_b64 s[6:7], 0x58100
	v_cvt_pk_bf16_f32 v12, v12, v13
	v_cvt_pk_bf16_f32 v13, v14, v15
	v_cvt_pk_bf16_f32 v14, v8, v9
	v_cvt_pk_bf16_f32 v15, v10, v11
	s_nop 0
	global_store_dwordx4 v[16:17], v[12:15], off sc0 sc1
	s_nop 1
	v_cvt_pk_bf16_f32 v4, v4, v5
	v_cvt_pk_bf16_f32 v5, v6, v7
	v_cvt_pk_bf16_f32 v6, v0, v1
	v_cvt_pk_bf16_f32 v7, v2, v3
	v_lshl_add_u64 v[0:1], v[142:143], 0, s[6:7]
	global_store_dwordx4 v[0:1], v[4:7], off sc0 sc1
	s_nop 1
	s_nop 0
	s_mov_b64 s[6:7], exec
	v_readlane_b32 s10, v254, 0
	v_readlane_b32 s11, v254, 1
	s_and_b64 s[10:11], s[6:7], s[10:11]
	s_mov_b64 exec, s[10:11]
	s_cbranch_execz .LBB0_1959
	s_mov_b64 s[10:11], exec
	v_mbcnt_lo_u32_b32 v0, s10, 0
	v_mbcnt_hi_u32_b32 v0, s11, v0
	v_cmp_eq_u32_e32 vcc, 0, v0
	s_and_b64 s[18:19], exec, vcc
	s_mov_b64 exec, s[18:19]
	s_cbranch_execz .LBB0_1959
	s_lshl_b32 s18, s14, 6
	s_ashr_i32 s19, s18, 31
	s_lshl_b64 s[18:19], s[18:19], 2
	s_add_u32 s18, s34, s18
	s_addc_u32 s19, s35, s19
	s_bcnt1_i32_b64 s10, s[10:11]
	v_mov_b32_e32 v0, s10
	s_sub_u32 s98, s18, 1
	s_subb_u32 s99, s19, 0

.Ldp_9_x:
	s_barrier
.LBB0_1963:
	v_mov_b32_e32 v32, v152
	s_mov_b64 s[0:1], 0x1000
	v_ashrrev_i32_e32 v33, 31, v32
	s_waitcnt lgkmcnt(0)
	v_lshlrev_b64 v[0:1], 4, v[32:33]
	v_lshl_add_u64 v[2:3], s[66:67], 0, v[0:1]
	v_readlane_b32 s52, v254, 4
	v_readlane_b32 s53, v254, 5
	v_lshl_add_u64 v[34:35], v[2:3], 0, s[0:1]
	v_readlane_b32 s54, v254, 6
	v_lshl_add_u64 v[4:5], s[52:53], 0, v[0:1]
	v_add_co_u32_e32 v0, vcc, 0x1000, v2
	v_lshl_add_u64 v[36:37], v[4:5], 0, s[0:1]
	s_nop 0
	v_addc_co_u32_e32 v1, vcc, 0, v3, vcc
	v_add_co_u32_e32 v4, vcc, 0x1000, v4
	global_load_dwordx4 v[0:3], v[0:1], off
	s_nop 0
	v_addc_co_u32_e32 v5, vcc, 0, v5, vcc
	global_load_dwordx4 v[4:7], v[4:5], off
	s_nop 0
	global_load_dwordx4 v[8:11], v[34:35], off offset:1024
	global_load_dwordx4 v[12:15], v[34:35], off offset:2048
	global_load_dwordx4 v[16:19], v[36:37], off offset:1024
	global_load_dwordx4 v[20:23], v[36:37], off offset:2048
	global_load_dwordx4 v[24:27], v[34:35], off offset:3072
	global_load_dwordx4 v[28:31], v[36:37], off offset:3072
	s_add_u32 s0, s24, 0x4c000
	v_readlane_b32 s55, v254, 7
	v_readlane_b32 s56, v254, 8
	v_readlane_b32 s57, v254, 9
	v_readlane_b32 s58, v254, 10
	v_readlane_b32 s59, v254, 11
	v_readlane_b32 s60, v254, 12
	v_readlane_b32 s61, v254, 13
	v_readlane_b32 s62, v254, 14
	v_readlane_b32 s63, v254, 15
	v_readlane_b32 s64, v254, 16
	v_readlane_b32 s65, v254, 17
	v_readlane_b32 s66, v254, 18
	v_readlane_b32 s67, v254, 19
	v_writelane_b32 v254, s0, 47
	s_addc_u32 s0, s25, 0
	v_writelane_b32 v255, s0, 2
	v_readlane_b32 s0, v254, 60
	s_add_u32 s36, s24, 0x74500
	v_readlane_b32 s1, v254, 61
	v_lshlrev_b64 v[40:41], 3, v[32:33]
	s_mov_b32 s15, 0
	s_addc_u32 s37, s25, 0
	v_cmp_gt_i32_e64 s[8:9], 16, v32
	v_lshl_add_u64 v[34:35], v[32:33], 2, s[0:1]
	v_lshl_add_u64 v[36:37], s[30:31], 0, v[40:41]
	v_lshl_add_u64 v[38:39], s[20:21], 0, v[40:41]
	v_lshl_add_u64 v[40:41], s[24:25], 0, v[40:41]
	s_mov_b32 s3, -1
	v_mov_b32_e32 v43, 0
	s_add_i32 s90, 0, 0x20080
	s_mov_b64 s[40:41], 0x800
	s_mov_b64 s[52:53], 0xa00
	s_mov_b64 s[54:55], 0xc00
	s_mov_b64 s[56:57], 0xe00
	v_mov_b32_e32 v90, 0x358637bd
	s_mov_b32 s91, 0x800000
	s_mov_b64 s[58:59], 0x200
	s_mov_b64 s[60:61], 0x400
	s_mov_b64 s[62:63], 0x600
	v_mov_b32_e32 v91, 0x80
	s_branch .LBB0_1967

.LBB0_2161:
	s_or_b32 s10, s43, 1
	v_add_u32_e32 v142, s16, v145
	s_lshl_b64 s[18:19], s[10:11], 7
	s_add_i32 s10, s43, 2
	ds_read_b128 v[156:159], v142
	ds_read_b128 v[160:163], v142 offset:1024
	ds_read_b128 v[164:167], v142 offset:2048
	ds_read_b128 v[168:171], v142 offset:3072
	v_add_u32_e32 v142, s17, v145
	s_lshl_b64 s[6:7], s[10:11], 7
	ds_read_b128 v[172:175], v142
	ds_read_b128 v[176:179], v142 offset:1024
	ds_read_b128 v[180:183], v142 offset:2048
	ds_read_b128 v[184:187], v142 offset:3072
	s_add_u32 s48, s62, s6
	s_addc_u32 s49, s63, s7
	s_and_b64 s[38:39], s[68:69], exec
	s_cselect_b32 s39, s1, s49
	s_cselect_b32 s38, s15, s48
	s_add_u32 s48, s64, s6
	s_addc_u32 s49, s65, s7
	s_and_b64 s[6:7], s[68:69], exec
	s_cselect_b32 s7, s53, s49
	s_cselect_b32 s6, s55, s48
	s_add_u32 s18, s57, s18
	s_addc_u32 s19, s33, s19
	v_lshl_add_u64 v[142:143], s[18:19], 0, v[128:129]
	s_add_i32 m0, s92, 0xc000
	ds_read_b128 v[188:191], v146
	ds_read_b128 v[192:195], v146 offset:1024
	ds_read_b128 v[196:199], v146 offset:2048
	ds_read_b128 v[200:203], v146 offset:3072
	ds_read_b128 v[204:207], v146 offset:4096
	ds_read_b128 v[208:211], v146 offset:5120
	ds_read_b128 v[212:215], v146 offset:6144
	ds_read_b128 v[216:219], v146 offset:7168
	global_load_lds_dwordx4 v[142:143], off
	v_lshl_add_u64 v[142:143], s[18:19], 0, v[132:133]
	s_add_i32 m0, s92, 0xe000
	s_nop 0
	global_load_lds_dwordx4 v[142:143], off
	s_cmp_eq_u32 s99, 0
	s_cbranch_scc1 .Ldpw_10_0a
	s_waitcnt vmcnt(16)
	s_branch .Ldpw_10_0b

.Ldpw_10_0b:
	s_waitcnt lgkmcnt(0)
	s_barrier
	s_setprio 1
	s_waitcnt lgkmcnt(0)
	v_mfma_f32_16x16x32_bf16 v[124:127], v[156:159], v[188:191], v[124:127]
	v_mfma_f32_16x16x32_bf16 v[120:123], v[164:167], v[188:191], v[120:123]
	v_mfma_f32_16x16x32_bf16 v[108:111], v[156:159], v[196:199], v[108:111]
	v_mfma_f32_16x16x32_bf16 v[104:107], v[164:167], v[196:199], v[104:107]
	v_mfma_f32_16x16x32_bf16 v[92:95], v[156:159], v[204:207], v[92:95]
	v_mfma_f32_16x16x32_bf16 v[88:91], v[164:167], v[204:207], v[88:91]
	v_mfma_f32_16x16x32_bf16 v[76:79], v[156:159], v[212:215], v[76:79]
	v_mfma_f32_16x16x32_bf16 v[72:75], v[164:167], v[212:215], v[72:75]
	v_mfma_f32_16x16x32_bf16 v[124:127], v[160:163], v[192:195], v[124:127]
	v_mfma_f32_16x16x32_bf16 v[120:123], v[168:171], v[192:195], v[120:123]
	v_mfma_f32_16x16x32_bf16 v[108:111], v[160:163], v[200:203], v[108:111]
	v_mfma_f32_16x16x32_bf16 v[104:107], v[168:171], v[200:203], v[104:107]
	v_mfma_f32_16x16x32_bf16 v[92:95], v[160:163], v[208:211], v[92:95]
	v_mfma_f32_16x16x32_bf16 v[88:91], v[168:171], v[208:211], v[88:91]
	v_mfma_f32_16x16x32_bf16 v[76:79], v[160:163], v[216:219], v[76:79]
	v_mfma_f32_16x16x32_bf16 v[72:75], v[168:171], v[216:219], v[72:75]
	s_setprio 0
	s_setprio 1
	v_mfma_f32_16x16x32_bf16 v[116:119], v[172:175], v[188:191], v[116:119]
	v_mfma_f32_16x16x32_bf16 v[112:115], v[180:183], v[188:191], v[112:115]
	v_mfma_f32_16x16x32_bf16 v[100:103], v[172:175], v[196:199], v[100:103]
	v_mfma_f32_16x16x32_bf16 v[96:99], v[180:183], v[196:199], v[96:99]
	v_mfma_f32_16x16x32_bf16 v[84:87], v[172:175], v[204:207], v[84:87]
	v_mfma_f32_16x16x32_bf16 v[80:83], v[180:183], v[204:207], v[80:83]
	v_mfma_f32_16x16x32_bf16 v[68:71], v[172:175], v[212:215], v[68:71]
	v_mfma_f32_16x16x32_bf16 v[64:67], v[180:183], v[212:215], v[64:67]
	v_mfma_f32_16x16x32_bf16 v[116:119], v[176:179], v[192:195], v[116:119]
	v_mfma_f32_16x16x32_bf16 v[112:115], v[184:187], v[192:195], v[112:115]
	v_mfma_f32_16x16x32_bf16 v[100:103], v[176:179], v[200:203], v[100:103]
	v_mfma_f32_16x16x32_bf16 v[96:99], v[184:187], v[200:203], v[96:99]
	v_mfma_f32_16x16x32_bf16 v[84:87], v[176:179], v[208:211], v[84:87]
	v_mfma_f32_16x16x32_bf16 v[80:83], v[184:187], v[208:211], v[80:83]
	v_mfma_f32_16x16x32_bf16 v[68:71], v[176:179], v[216:219], v[68:71]
	v_mfma_f32_16x16x32_bf16 v[64:67], v[184:187], v[216:219], v[64:67]
	s_setprio 0
	s_barrier
	s_add_i32 s18, s16, s29
	v_lshl_add_u64 v[142:143], s[6:7], 0, v[130:131]
	s_mov_b32 m0, s18
	ds_read_b128 v[188:191], v146 offset:16384
	ds_read_b128 v[192:195], v146 offset:17408
	ds_read_b128 v[196:199], v146 offset:18432
	ds_read_b128 v[200:203], v146 offset:19456
	ds_read_b128 v[204:207], v146 offset:20480
	ds_read_b128 v[208:211], v146 offset:21504
	ds_read_b128 v[212:215], v146 offset:22528
	ds_read_b128 v[216:219], v146 offset:23552
	global_load_lds_dwordx4 v[142:143], off
	s_add_i32 m0, s18, 0x2000
	s_add_u32 s18, s6, 0x40000
	v_lshl_add_u64 v[220:221], s[6:7], 0, v[134:135]
	s_addc_u32 s19, s7, 0
	s_add_i32 s48, s17, s29
	global_load_lds_dwordx4 v[220:221], off
	v_lshl_add_u64 v[222:223], s[18:19], 0, v[130:131]
	s_mov_b32 m0, s48
	v_lshl_add_u64 v[224:225], s[38:39], 0, v[132:133]
	global_load_lds_dwordx4 v[222:223], off
	v_lshl_add_u64 v[222:223], s[18:19], 0, v[134:135]
	s_add_i32 m0, s48, 0x2000
	s_nop 0
	global_load_lds_dwordx4 v[222:223], off
	v_lshl_add_u64 v[222:223], s[38:39], 0, v[128:129]
	s_mov_b32 m0, s92
	s_nop 0
	global_load_lds_dwordx4 v[222:223], off
	s_mov_b32 m0, s93
	s_nop 0
	global_load_lds_dwordx4 v[224:225], off
	s_cmp_eq_u32 s99, 0
	s_cbranch_scc1 .Ldpw_10_1a
	s_waitcnt vmcnt(16)
	s_branch .Ldpw_10_1b

.Ldpw_10_1b:
	s_waitcnt lgkmcnt(0)
	s_barrier
	s_setprio 1
	s_waitcnt lgkmcnt(0)
	v_mfma_f32_16x16x32_bf16 v[60:63], v[156:159], v[188:191], v[60:63]
	v_mfma_f32_16x16x32_bf16 v[56:59], v[164:167], v[188:191], v[56:59]
	v_mfma_f32_16x16x32_bf16 v[44:47], v[156:159], v[196:199], v[44:47]
	v_mfma_f32_16x16x32_bf16 v[40:43], v[164:167], v[196:199], v[40:43]
	v_mfma_f32_16x16x32_bf16 v[28:31], v[156:159], v[204:207], v[28:31]
	v_mfma_f32_16x16x32_bf16 v[24:27], v[164:167], v[204:207], v[24:27]
	v_mfma_f32_16x16x32_bf16 v[12:15], v[156:159], v[212:215], v[12:15]
	v_mfma_f32_16x16x32_bf16 v[8:11], v[164:167], v[212:215], v[8:11]
	v_mfma_f32_16x16x32_bf16 v[60:63], v[160:163], v[192:195], v[60:63]
	v_mfma_f32_16x16x32_bf16 v[56:59], v[168:171], v[192:195], v[56:59]
	v_mfma_f32_16x16x32_bf16 v[44:47], v[160:163], v[200:203], v[44:47]
	v_mfma_f32_16x16x32_bf16 v[40:43], v[168:171], v[200:203], v[40:43]
	v_mfma_f32_16x16x32_bf16 v[28:31], v[160:163], v[208:211], v[28:31]
	v_mfma_f32_16x16x32_bf16 v[24:27], v[168:171], v[208:211], v[24:27]
	v_mfma_f32_16x16x32_bf16 v[12:15], v[160:163], v[216:219], v[12:15]
	v_mfma_f32_16x16x32_bf16 v[8:11], v[168:171], v[216:219], v[8:11]
	s_setprio 0
	s_setprio 1
	v_mfma_f32_16x16x32_bf16 v[52:55], v[172:175], v[188:191], v[52:55]
	v_mfma_f32_16x16x32_bf16 v[48:51], v[180:183], v[188:191], v[48:51]
	v_mfma_f32_16x16x32_bf16 v[36:39], v[172:175], v[196:199], v[36:39]
	v_mfma_f32_16x16x32_bf16 v[32:35], v[180:183], v[196:199], v[32:35]
	v_mfma_f32_16x16x32_bf16 v[20:23], v[172:175], v[204:207], v[20:23]
	v_mfma_f32_16x16x32_bf16 v[16:19], v[180:183], v[204:207], v[16:19]
	v_mfma_f32_16x16x32_bf16 v[4:7], v[172:175], v[212:215], v[4:7]
	v_mfma_f32_16x16x32_bf16 v[0:3], v[180:183], v[212:215], v[0:3]
	v_mfma_f32_16x16x32_bf16 v[52:55], v[176:179], v[192:195], v[52:55]
	v_mfma_f32_16x16x32_bf16 v[48:51], v[184:187], v[192:195], v[48:51]
	v_mfma_f32_16x16x32_bf16 v[36:39], v[176:179], v[200:203], v[36:39]
	v_mfma_f32_16x16x32_bf16 v[32:35], v[184:187], v[200:203], v[32:35]
	v_mfma_f32_16x16x32_bf16 v[20:23], v[176:179], v[208:211], v[20:23]
	v_mfma_f32_16x16x32_bf16 v[16:19], v[184:187], v[208:211], v[16:19]
	v_mfma_f32_16x16x32_bf16 v[4:7], v[176:179], v[216:219], v[4:7]
	v_mfma_f32_16x16x32_bf16 v[0:3], v[184:187], v[216:219], v[0:3]
	s_setprio 0
	s_barrier
	s_add_i32 s48, 0, 0x18000
	v_add_u32_e32 v147, s48, v145
	s_add_i32 s49, 0, 0x1c000
	ds_read_b128 v[156:159], v147
	ds_read_b128 v[160:163], v147 offset:1024
	ds_read_b128 v[164:167], v147 offset:2048
	ds_read_b128 v[168:171], v147 offset:3072
	v_add_u32_e32 v147, s49, v145
	ds_read_b128 v[172:175], v147
	ds_read_b128 v[176:179], v147 offset:1024
	ds_read_b128 v[180:183], v147 offset:2048
	ds_read_b128 v[184:187], v147 offset:3072
	s_add_u32 s18, s38, 0x40000
	s_addc_u32 s19, s39, 0
	s_mov_b32 m0, s94
	v_lshl_add_u64 v[226:227], s[18:19], 0, v[128:129]
	ds_read_b128 v[188:191], v146 offset:32768
	ds_read_b128 v[192:195], v146 offset:33792
	ds_read_b128 v[196:199], v146 offset:34816
	ds_read_b128 v[200:203], v146 offset:35840
	ds_read_b128 v[204:207], v146 offset:36864
	ds_read_b128 v[208:211], v146 offset:37888
	ds_read_b128 v[212:215], v146 offset:38912
	ds_read_b128 v[216:219], v146 offset:39936
	global_load_lds_dwordx4 v[226:227], off
	v_lshl_add_u64 v[226:227], s[18:19], 0, v[132:133]
	s_mov_b32 m0, s95
	s_nop 0
	global_load_lds_dwordx4 v[226:227], off
	s_waitcnt vmcnt(8)
	s_cmp_eq_u32 s99, 0
	s_cbranch_scc1 .Ldp_10_l
	v_readlane_b32 s100, v0, 0
	s_mov_b64 exec, 1
	v_writelane_b32 v0, 1, 0
	s_nop 1
	global_atomic_add v0, v0, s[98:99]
	s_nop 1
	v_writelane_b32 v0, s100, 0
	s_mov_b64 exec, -1
	s_mov_b32 s99, 0
.Ldp_10_l:
	s_waitcnt lgkmcnt(0)
	s_barrier
	s_setprio 1
	s_waitcnt lgkmcnt(0)
	v_mfma_f32_16x16x32_bf16 v[124:127], v[156:159], v[188:191], v[124:127]
	v_mfma_f32_16x16x32_bf16 v[120:123], v[164:167], v[188:191], v[120:123]
	v_mfma_f32_16x16x32_bf16 v[108:111], v[156:159], v[196:199], v[108:111]
	v_mfma_f32_16x16x32_bf16 v[104:107], v[164:167], v[196:199], v[104:107]
	v_mfma_f32_16x16x32_bf16 v[92:95], v[156:159], v[204:207], v[92:95]
	v_mfma_f32_16x16x32_bf16 v[88:91], v[164:167], v[204:207], v[88:91]
	v_mfma_f32_16x16x32_bf16 v[76:79], v[156:159], v[212:215], v[76:79]
	v_mfma_f32_16x16x32_bf16 v[72:75], v[164:167], v[212:215], v[72:75]
	v_mfma_f32_16x16x32_bf16 v[124:127], v[160:163], v[192:195], v[124:127]
	v_mfma_f32_16x16x32_bf16 v[120:123], v[168:171], v[192:195], v[120:123]
	v_mfma_f32_16x16x32_bf16 v[108:111], v[160:163], v[200:203], v[108:111]
	v_mfma_f32_16x16x32_bf16 v[104:107], v[168:171], v[200:203], v[104:107]
	v_mfma_f32_16x16x32_bf16 v[92:95], v[160:163], v[208:211], v[92:95]
	v_mfma_f32_16x16x32_bf16 v[88:91], v[168:171], v[208:211], v[88:91]
	v_mfma_f32_16x16x32_bf16 v[76:79], v[160:163], v[216:219], v[76:79]
	v_mfma_f32_16x16x32_bf16 v[72:75], v[168:171], v[216:219], v[72:75]
	s_setprio 0
	s_setprio 1
	v_mfma_f32_16x16x32_bf16 v[116:119], v[172:175], v[188:191], v[116:119]
	v_mfma_f32_16x16x32_bf16 v[112:115], v[180:183], v[188:191], v[112:115]
	v_mfma_f32_16x16x32_bf16 v[100:103], v[172:175], v[196:199], v[100:103]
	v_mfma_f32_16x16x32_bf16 v[96:99], v[180:183], v[196:199], v[96:99]
	v_mfma_f32_16x16x32_bf16 v[84:87], v[172:175], v[204:207], v[84:87]
	v_mfma_f32_16x16x32_bf16 v[80:83], v[180:183], v[204:207], v[80:83]
	v_mfma_f32_16x16x32_bf16 v[68:71], v[172:175], v[212:215], v[68:71]
	v_mfma_f32_16x16x32_bf16 v[64:67], v[180:183], v[212:215], v[64:67]
	v_mfma_f32_16x16x32_bf16 v[116:119], v[176:179], v[192:195], v[116:119]
	v_mfma_f32_16x16x32_bf16 v[112:115], v[184:187], v[192:195], v[112:115]
	v_mfma_f32_16x16x32_bf16 v[100:103], v[176:179], v[200:203], v[100:103]
	v_mfma_f32_16x16x32_bf16 v[96:99], v[184:187], v[200:203], v[96:99]
	v_mfma_f32_16x16x32_bf16 v[84:87], v[176:179], v[208:211], v[84:87]
	v_mfma_f32_16x16x32_bf16 v[80:83], v[184:187], v[208:211], v[80:83]
	v_mfma_f32_16x16x32_bf16 v[68:71], v[176:179], v[216:219], v[68:71]
	v_mfma_f32_16x16x32_bf16 v[64:67], v[184:187], v[216:219], v[64:67]
	s_setprio 0
	s_barrier
	s_add_i32 s18, s48, s29
	v_lshl_add_u64 v[142:143], v[142:143], 0, s[36:37]
	s_mov_b32 m0, s18
	ds_read_b128 v[188:191], v146 offset:49152
	ds_read_b128 v[192:195], v146 offset:50176
	ds_read_b128 v[196:199], v146 offset:51200
	ds_read_b128 v[200:203], v146 offset:52224
	ds_read_b128 v[204:207], v146 offset:53248
	ds_read_b128 v[208:211], v146 offset:54272
	ds_read_b128 v[212:215], v146 offset:55296
	ds_read_b128 v[216:219], v146 offset:56320
	global_load_lds_dwordx4 v[142:143], off
	s_add_i32 m0, s18, 0x2000
	s_add_u32 s6, s6, 0x40080
	v_lshl_add_u64 v[142:143], v[220:221], 0, s[36:37]
	s_addc_u32 s7, s7, 0
	s_add_i32 s18, s49, s29
	global_load_lds_dwordx4 v[142:143], off
	v_lshl_add_u64 v[142:143], s[6:7], 0, v[130:131]
	s_mov_b32 m0, s18
	s_nop 0
	global_load_lds_dwordx4 v[142:143], off
	v_lshl_add_u64 v[142:143], s[6:7], 0, v[134:135]
	s_add_i32 m0, s18, 0x2000
	s_nop 0
	global_load_lds_dwordx4 v[142:143], off
	v_lshl_add_u64 v[142:143], v[222:223], 0, s[36:37]
	s_mov_b32 m0, s96
	s_nop 0
	global_load_lds_dwordx4 v[142:143], off
	v_lshl_add_u64 v[142:143], v[224:225], 0, s[36:37]
	s_mov_b32 m0, s97
	s_nop 0
	global_load_lds_dwordx4 v[142:143], off
	s_waitcnt vmcnt(8)
	s_waitcnt lgkmcnt(0)
	s_barrier
	s_setprio 1
	s_waitcnt lgkmcnt(0)
	v_mfma_f32_16x16x32_bf16 v[60:63], v[156:159], v[188:191], v[60:63]
	v_mfma_f32_16x16x32_bf16 v[56:59], v[164:167], v[188:191], v[56:59]
	v_mfma_f32_16x16x32_bf16 v[44:47], v[156:159], v[196:199], v[44:47]
	v_mfma_f32_16x16x32_bf16 v[40:43], v[164:167], v[196:199], v[40:43]
	v_mfma_f32_16x16x32_bf16 v[28:31], v[156:159], v[204:207], v[28:31]
	v_mfma_f32_16x16x32_bf16 v[24:27], v[164:167], v[204:207], v[24:27]
	v_mfma_f32_16x16x32_bf16 v[12:15], v[156:159], v[212:215], v[12:15]
	v_mfma_f32_16x16x32_bf16 v[8:11], v[164:167], v[212:215], v[8:11]
	v_mfma_f32_16x16x32_bf16 v[60:63], v[160:163], v[192:195], v[60:63]
	v_mfma_f32_16x16x32_bf16 v[56:59], v[168:171], v[192:195], v[56:59]
	v_mfma_f32_16x16x32_bf16 v[44:47], v[160:163], v[200:203], v[44:47]
	v_mfma_f32_16x16x32_bf16 v[40:43], v[168:171], v[200:203], v[40:43]
	v_mfma_f32_16x16x32_bf16 v[28:31], v[160:163], v[208:211], v[28:31]
	v_mfma_f32_16x16x32_bf16 v[24:27], v[168:171], v[208:211], v[24:27]
	v_mfma_f32_16x16x32_bf16 v[12:15], v[160:163], v[216:219], v[12:15]
	v_mfma_f32_16x16x32_bf16 v[8:11], v[168:171], v[216:219], v[8:11]
	s_setprio 0
	s_setprio 1
	v_mfma_f32_16x16x32_bf16 v[52:55], v[172:175], v[188:191], v[52:55]
	v_mfma_f32_16x16x32_bf16 v[48:51], v[180:183], v[188:191], v[48:51]
	v_mfma_f32_16x16x32_bf16 v[36:39], v[172:175], v[196:199], v[36:39]
	v_mfma_f32_16x16x32_bf16 v[32:35], v[180:183], v[196:199], v[32:35]
	v_mfma_f32_16x16x32_bf16 v[20:23], v[172:175], v[204:207], v[20:23]
	v_mfma_f32_16x16x32_bf16 v[16:19], v[180:183], v[204:207], v[16:19]
	v_mfma_f32_16x16x32_bf16 v[4:7], v[172:175], v[212:215], v[4:7]
	v_mfma_f32_16x16x32_bf16 v[0:3], v[180:183], v[212:215], v[0:3]
	v_mfma_f32_16x16x32_bf16 v[52:55], v[176:179], v[192:195], v[52:55]
	v_mfma_f32_16x16x32_bf16 v[48:51], v[184:187], v[192:195], v[48:51]
	v_mfma_f32_16x16x32_bf16 v[36:39], v[176:179], v[200:203], v[36:39]
	v_mfma_f32_16x16x32_bf16 v[32:35], v[184:187], v[200:203], v[32:35]
	v_mfma_f32_16x16x32_bf16 v[20:23], v[176:179], v[208:211], v[20:23]
	v_mfma_f32_16x16x32_bf16 v[16:19], v[184:187], v[208:211], v[16:19]
	v_mfma_f32_16x16x32_bf16 v[4:7], v[176:179], v[216:219], v[4:7]
	v_mfma_f32_16x16x32_bf16 v[0:3], v[184:187], v[216:219], v[0:3]
	s_setprio 0
	s_barrier
	s_cmp_gt_u32 s43, 13
	s_mov_b32 s43, s10
	s_cbranch_scc1 .LBB0_2231

.LBB0_2233:
	v_readlane_b32 s6, v254, 37
	v_readlane_b32 s7, v254, 38
	v_lshl_add_u32 v147, s0, 8, v144
	s_movk_i32 s1, 0x1600
	v_mov_b64_e32 v[142:143], s[6:7]
	v_mad_i64_i32 v[142:143], s[6:7], v147, s1, v[142:143]
	v_mul_f32_e32 v147, 0xbfb8aa3b, v124
	v_exp_f32_e32 v147, v147
	v_mul_f32_e32 v156, 0xbfb8aa3b, v120
	v_exp_f32_e32 v157, v156
	v_mul_f32_e32 v158, 0xbfb8aa3b, v121
	v_add_f32_e32 v147, 1.0, v147
	v_rcp_f32_e32 v156, v147
	v_add_f32_e32 v147, 1.0, v157
	v_mul_f32_e32 v157, 0xbfb8aa3b, v125
	v_exp_f32_e32 v157, v157
	v_exp_f32_e32 v159, v158
	v_rcp_f32_e32 v158, v147
	v_mul_f32_e32 v162, 0xbfb8aa3b, v123
	v_add_f32_e32 v147, 1.0, v157
	v_rcp_f32_e32 v157, v147
	v_add_f32_e32 v147, 1.0, v159
	v_mul_f32_e32 v159, 0xbfb8aa3b, v126
	v_exp_f32_e32 v160, v159
	v_mul_f32_e32 v159, 0xbfb8aa3b, v122
	v_exp_f32_e32 v161, v159
	v_rcp_f32_e32 v159, v147
	v_add_f32_e32 v147, 1.0, v160
	v_rcp_f32_e32 v160, v147
	v_add_f32_e32 v147, 1.0, v161
	v_mul_f32_e32 v161, 0xbfb8aa3b, v127
	v_exp_f32_e32 v161, v161
	v_exp_f32_e32 v163, v162
	v_rcp_f32_e32 v162, v147
	v_pk_mul_f32 v[124:125], v[124:125], v[156:157]
	v_add_f32_e32 v147, 1.0, v161
	v_rcp_f32_e32 v161, v147
	v_add_f32_e32 v147, 1.0, v163
	v_rcp_f32_e32 v163, v147
	s_lshl_b32 s6, s14, 7
	v_pk_mul_f32 v[120:121], v[120:121], v[158:159]
	v_pk_mul_f32 v[116:117], v[124:125], v[116:117]
	v_pk_mul_f32 v[122:123], v[122:123], v[162:163]
	s_ashr_i32 s7, s6, 31
	v_pk_mul_f32 v[122:123], v[122:123], v[114:115]
	v_pk_mul_f32 v[114:115], v[120:121], v[112:113]
	v_cvt_pk_bf16_f32 v112, v116, v117
	v_mul_f32_e32 v116, 0xbfb8aa3b, v108
	v_lshl_add_u64 v[142:143], s[6:7], 1, v[142:143]
	s_mov_b32 s53, s11
	v_pk_mul_f32 v[126:127], v[126:127], v[160:161]
	v_exp_f32_e32 v116, v116
	v_lshl_add_u64 v[142:143], v[142:143], 0, s[52:53]
	v_pk_mul_f32 v[118:119], v[126:127], v[118:119]
	v_mul_f32_e32 v117, 0xbfb8aa3b, v104
	v_cvt_pk_bf16_f32 v113, v118, v119
	v_cvt_pk_bf16_f32 v114, v114, v115
	v_lshl_add_u64 v[142:143], v[142:143], 0, v[136:137]
	v_cvt_pk_bf16_f32 v115, v122, v123
	v_exp_f32_e32 v117, v117
	global_store_dwordx4 v[142:143], v[112:115], off sc0 sc1
	s_nop 1
	v_mul_f32_e32 v114, 0xbfb8aa3b, v109
	v_exp_f32_e32 v115, v114
	v_mul_f32_e32 v114, 0xbfb8aa3b, v105
	v_add_f32_e32 v112, 1.0, v116
	v_exp_f32_e32 v116, v114
	v_add_f32_e32 v113, 1.0, v117
	v_mul_f32_e32 v117, 0xbfb8aa3b, v106
	v_mul_f32_e32 v118, 0xbfb8aa3b, v111
	v_exp_f32_e32 v117, v117
	v_exp_f32_e32 v119, v118
	v_mul_f32_e32 v118, 0xbfb8aa3b, v107
	v_rcp_f32_e32 v114, v113
	v_add_f32_e32 v113, 1.0, v115
	v_add_f32_e32 v115, 1.0, v116
	v_mul_f32_e32 v116, 0xbfb8aa3b, v110
	v_exp_f32_e32 v120, v118
	v_exp_f32_e32 v116, v116
	v_add_f32_e32 v117, 1.0, v117
	v_rcp_f32_e32 v118, v117
	v_add_f32_e32 v117, 1.0, v119
	v_add_f32_e32 v119, 1.0, v120
	v_rcp_f32_e32 v115, v115
	v_add_f32_e32 v116, 1.0, v116
	v_rcp_f32_e32 v119, v119
	v_rcp_f32_e32 v112, v112
	v_rcp_f32_e32 v113, v113
	v_rcp_f32_e32 v116, v116
	v_rcp_f32_e32 v117, v117
	v_pk_mul_f32 v[104:105], v[104:105], v[114:115]
	v_pk_mul_f32 v[106:107], v[106:107], v[118:119]
	v_pk_mul_f32 v[108:109], v[108:109], v[112:113]
	v_pk_mul_f32 v[110:111], v[110:111], v[116:117]
	v_pk_mul_f32 v[106:107], v[106:107], v[98:99]
	v_pk_mul_f32 v[98:99], v[104:105], v[96:97]
	v_pk_mul_f32 v[102:103], v[110:111], v[102:103]
	v_pk_mul_f32 v[100:101], v[108:109], v[100:101]
	s_mov_b64 s[6:7], 0x16000
	v_cvt_pk_bf16_f32 v96, v100, v101
	v_cvt_pk_bf16_f32 v97, v102, v103
	v_cvt_pk_bf16_f32 v98, v98, v99
	v_cvt_pk_bf16_f32 v99, v106, v107
	v_lshl_add_u64 v[100:101], v[142:143], 0, s[6:7]
	v_mul_f32_e32 v102, 0xbfb8aa3b, v92
	v_mul_f32_e32 v103, 0xbfb8aa3b, v88
	global_store_dwordx4 v[100:101], v[96:99], off sc0 sc1
	s_nop 1
	v_mul_f32_e32 v98, 0xbfb8aa3b, v93
	v_exp_f32_e32 v102, v102
	v_exp_f32_e32 v103, v103
	v_exp_f32_e32 v99, v98
	v_mul_f32_e32 v98, 0xbfb8aa3b, v89
	v_exp_f32_e32 v100, v98
	v_add_f32_e32 v96, 1.0, v102
	v_add_f32_e32 v97, 1.0, v103
	v_mul_f32_e32 v101, 0xbfb8aa3b, v90
	v_mul_f32_e32 v102, 0xbfb8aa3b, v95
	v_rcp_f32_e32 v98, v97
	v_add_f32_e32 v97, 1.0, v99
	v_add_f32_e32 v99, 1.0, v100
	v_mul_f32_e32 v100, 0xbfb8aa3b, v94
	v_exp_f32_e32 v101, v101
	v_exp_f32_e32 v103, v102
	v_mul_f32_e32 v102, 0xbfb8aa3b, v91
	v_exp_f32_e32 v100, v100
	v_exp_f32_e32 v104, v102
	v_add_f32_e32 v101, 1.0, v101
	v_rcp_f32_e32 v102, v101
	v_add_f32_e32 v100, 1.0, v100
	v_add_f32_e32 v101, 1.0, v103
	v_add_f32_e32 v103, 1.0, v104
	v_rcp_f32_e32 v99, v99
	v_rcp_f32_e32 v100, v100
	v_rcp_f32_e32 v101, v101
	v_rcp_f32_e32 v103, v103
	v_rcp_f32_e32 v96, v96
	v_rcp_f32_e32 v97, v97
	v_pk_mul_f32 v[94:95], v[94:95], v[100:101]
	v_pk_mul_f32 v[88:89], v[88:89], v[98:99]
	v_pk_mul_f32 v[90:91], v[90:91], v[102:103]
	v_pk_mul_f32 v[92:93], v[92:93], v[96:97]
	v_pk_mul_f32 v[86:87], v[94:95], v[86:87]
	v_pk_mul_f32 v[90:91], v[90:91], v[82:83]
	v_pk_mul_f32 v[82:83], v[88:89], v[80:81]
	v_pk_mul_f32 v[84:85], v[92:93], v[84:85]
	s_mov_b64 s[6:7], 0x2c000
	v_cvt_pk_bf16_f32 v80, v84, v85
	v_cvt_pk_bf16_f32 v81, v86, v87
	v_cvt_pk_bf16_f32 v82, v82, v83
	v_mul_f32_e32 v86, 0xbfb8aa3b, v76
	v_cvt_pk_bf16_f32 v83, v90, v91
	v_lshl_add_u64 v[84:85], v[142:143], 0, s[6:7]
	v_exp_f32_e32 v86, v86
	v_mul_f32_e32 v87, 0xbfb8aa3b, v72
	global_store_dwordx4 v[84:85], v[80:83], off sc0 sc1
	s_nop 1
	v_mul_f32_e32 v82, 0xbfb8aa3b, v77
	v_exp_f32_e32 v87, v87
	v_exp_f32_e32 v83, v82
	v_mul_f32_e32 v82, 0xbfb8aa3b, v73
	v_exp_f32_e32 v84, v82
	v_add_f32_e32 v80, 1.0, v86
	v_mul_f32_e32 v85, 0xbfb8aa3b, v74
	v_mul_f32_e32 v86, 0xbfb8aa3b, v79
	v_add_f32_e32 v81, 1.0, v87
	v_exp_f32_e32 v85, v85
	v_exp_f32_e32 v87, v86
	v_mul_f32_e32 v86, 0xbfb8aa3b, v75
	v_rcp_f32_e32 v82, v81
	v_add_f32_e32 v81, 1.0, v83
	v_add_f32_e32 v83, 1.0, v84
	v_mul_f32_e32 v84, 0xbfb8aa3b, v78
	v_exp_f32_e32 v88, v86
	v_exp_f32_e32 v84, v84
	v_add_f32_e32 v85, 1.0, v85
	v_rcp_f32_e32 v86, v85
	v_add_f32_e32 v85, 1.0, v87
	v_add_f32_e32 v87, 1.0, v88
	v_rcp_f32_e32 v83, v83
	v_add_f32_e32 v84, 1.0, v84
	v_rcp_f32_e32 v87, v87
	v_rcp_f32_e32 v80, v80
	v_rcp_f32_e32 v81, v81
	v_rcp_f32_e32 v84, v84
	v_rcp_f32_e32 v85, v85
	v_pk_mul_f32 v[72:73], v[72:73], v[82:83]
	v_pk_mul_f32 v[74:75], v[74:75], v[86:87]
	v_pk_mul_f32 v[76:77], v[76:77], v[80:81]
	v_pk_mul_f32 v[78:79], v[78:79], v[84:85]
	v_pk_mul_f32 v[74:75], v[74:75], v[66:67]
	v_pk_mul_f32 v[66:67], v[72:73], v[64:65]
	v_pk_mul_f32 v[70:71], v[78:79], v[70:71]
	v_pk_mul_f32 v[68:69], v[76:77], v[68:69]
	s_mov_b64 s[6:7], 0x42000
	v_cvt_pk_bf16_f32 v64, v68, v69
	v_cvt_pk_bf16_f32 v65, v70, v71
	v_cvt_pk_bf16_f32 v66, v66, v67
	v_cvt_pk_bf16_f32 v67, v74, v75
	v_lshl_add_u64 v[68:69], v[142:143], 0, s[6:7]
	v_mul_f32_e32 v70, 0xbfb8aa3b, v60
	v_mul_f32_e32 v71, 0xbfb8aa3b, v56
	global_store_dwordx4 v[68:69], v[64:67], off sc0 sc1
	s_nop 1
	v_mul_f32_e32 v66, 0xbfb8aa3b, v61
	v_exp_f32_e32 v70, v70
	v_exp_f32_e32 v71, v71
	v_exp_f32_e32 v67, v66
	v_mul_f32_e32 v66, 0xbfb8aa3b, v57
	v_exp_f32_e32 v68, v66
	v_add_f32_e32 v64, 1.0, v70
	v_add_f32_e32 v65, 1.0, v71
	v_mul_f32_e32 v69, 0xbfb8aa3b, v58
	v_mul_f32_e32 v70, 0xbfb8aa3b, v63
	v_rcp_f32_e32 v66, v65
	v_add_f32_e32 v65, 1.0, v67
	v_add_f32_e32 v67, 1.0, v68
	v_mul_f32_e32 v68, 0xbfb8aa3b, v62
	v_exp_f32_e32 v69, v69
	v_exp_f32_e32 v71, v70
	v_mul_f32_e32 v70, 0xbfb8aa3b, v59
	v_exp_f32_e32 v68, v68
	v_exp_f32_e32 v72, v70
	v_add_f32_e32 v69, 1.0, v69
	v_rcp_f32_e32 v70, v69
	v_add_f32_e32 v68, 1.0, v68
	v_add_f32_e32 v69, 1.0, v71
	v_add_f32_e32 v71, 1.0, v72
	v_rcp_f32_e32 v67, v67
	v_rcp_f32_e32 v68, v68
	v_rcp_f32_e32 v69, v69
	v_rcp_f32_e32 v71, v71
	v_rcp_f32_e32 v64, v64
	v_rcp_f32_e32 v65, v65
	v_pk_mul_f32 v[62:63], v[62:63], v[68:69]
	v_pk_mul_f32 v[56:57], v[56:57], v[66:67]
	v_pk_mul_f32 v[58:59], v[58:59], v[70:71]
	v_pk_mul_f32 v[60:61], v[60:61], v[64:65]
	v_pk_mul_f32 v[54:55], v[62:63], v[54:55]
	v_pk_mul_f32 v[58:59], v[58:59], v[50:51]
	v_pk_mul_f32 v[50:51], v[56:57], v[48:49]
	v_pk_mul_f32 v[52:53], v[60:61], v[52:53]
	s_mov_b64 s[6:7], 0xb0000
	v_cvt_pk_bf16_f32 v48, v52, v53
	v_cvt_pk_bf16_f32 v49, v54, v55
	v_cvt_pk_bf16_f32 v50, v50, v51
	v_mul_f32_e32 v54, 0xbfb8aa3b, v44
	v_cvt_pk_bf16_f32 v51, v58, v59
	v_lshl_add_u64 v[52:53], v[142:143], 0, s[6:7]
	v_exp_f32_e32 v54, v54
	v_mul_f32_e32 v55, 0xbfb8aa3b, v40
	global_store_dwordx4 v[52:53], v[48:51], off sc0 sc1
	s_nop 1
	v_mul_f32_e32 v50, 0xbfb8aa3b, v45
	v_exp_f32_e32 v55, v55
	v_exp_f32_e32 v51, v50
	v_mul_f32_e32 v50, 0xbfb8aa3b, v41
	v_exp_f32_e32 v52, v50
	v_add_f32_e32 v48, 1.0, v54
	v_mul_f32_e32 v53, 0xbfb8aa3b, v42
	v_mul_f32_e32 v54, 0xbfb8aa3b, v47
	v_add_f32_e32 v49, 1.0, v55
	v_exp_f32_e32 v53, v53
	v_exp_f32_e32 v55, v54
	v_mul_f32_e32 v54, 0xbfb8aa3b, v43
	v_rcp_f32_e32 v50, v49
	v_add_f32_e32 v49, 1.0, v51
	v_add_f32_e32 v51, 1.0, v52
	v_mul_f32_e32 v52, 0xbfb8aa3b, v46
	v_exp_f32_e32 v56, v54
	v_exp_f32_e32 v52, v52
	v_add_f32_e32 v53, 1.0, v53
	v_rcp_f32_e32 v54, v53
	v_add_f32_e32 v53, 1.0, v55
	v_add_f32_e32 v55, 1.0, v56
	v_rcp_f32_e32 v51, v51
	v_add_f32_e32 v52, 1.0, v52
	v_rcp_f32_e32 v55, v55
	v_rcp_f32_e32 v48, v48
	v_rcp_f32_e32 v49, v49
	v_rcp_f32_e32 v52, v52
	v_rcp_f32_e32 v53, v53
	v_pk_mul_f32 v[40:41], v[40:41], v[50:51]
	v_pk_mul_f32 v[42:43], v[42:43], v[54:55]
	v_pk_mul_f32 v[44:45], v[44:45], v[48:49]
	v_pk_mul_f32 v[46:47], v[46:47], v[52:53]
	v_pk_mul_f32 v[42:43], v[42:43], v[34:35]
	v_pk_mul_f32 v[34:35], v[40:41], v[32:33]
	v_pk_mul_f32 v[38:39], v[46:47], v[38:39]
	v_pk_mul_f32 v[36:37], v[44:45], v[36:37]
	s_mov_b64 s[6:7], 0xc6000
	v_cvt_pk_bf16_f32 v32, v36, v37
	v_cvt_pk_bf16_f32 v33, v38, v39
	v_cvt_pk_bf16_f32 v34, v34, v35
	v_cvt_pk_bf16_f32 v35, v42, v43
	v_lshl_add_u64 v[36:37], v[142:143], 0, s[6:7]
	v_mul_f32_e32 v38, 0xbfb8aa3b, v28
	v_mul_f32_e32 v39, 0xbfb8aa3b, v24
	global_store_dwordx4 v[36:37], v[32:35], off sc0 sc1
	s_nop 1
	v_mul_f32_e32 v34, 0xbfb8aa3b, v29
	v_exp_f32_e32 v38, v38
	v_exp_f32_e32 v39, v39
	v_exp_f32_e32 v35, v34
	v_mul_f32_e32 v34, 0xbfb8aa3b, v25
	v_exp_f32_e32 v36, v34
	v_add_f32_e32 v32, 1.0, v38
	v_add_f32_e32 v33, 1.0, v39
	v_mul_f32_e32 v37, 0xbfb8aa3b, v26
	v_mul_f32_e32 v38, 0xbfb8aa3b, v31
	v_rcp_f32_e32 v34, v33
	v_add_f32_e32 v33, 1.0, v35
	v_add_f32_e32 v35, 1.0, v36
	v_mul_f32_e32 v36, 0xbfb8aa3b, v30
	v_exp_f32_e32 v37, v37
	v_exp_f32_e32 v39, v38
	v_mul_f32_e32 v38, 0xbfb8aa3b, v27
	v_exp_f32_e32 v36, v36
	v_exp_f32_e32 v40, v38
	v_add_f32_e32 v37, 1.0, v37
	v_rcp_f32_e32 v38, v37
	v_add_f32_e32 v36, 1.0, v36
	v_add_f32_e32 v37, 1.0, v39
	v_add_f32_e32 v39, 1.0, v40
	v_rcp_f32_e32 v35, v35
	v_rcp_f32_e32 v36, v36
	v_rcp_f32_e32 v37, v37
	v_rcp_f32_e32 v39, v39
	v_rcp_f32_e32 v32, v32
	v_rcp_f32_e32 v33, v33
	v_pk_mul_f32 v[30:31], v[30:31], v[36:37]
	v_pk_mul_f32 v[24:25], v[24:25], v[34:35]
	v_pk_mul_f32 v[26:27], v[26:27], v[38:39]
	v_pk_mul_f32 v[28:29], v[28:29], v[32:33]
	v_pk_mul_f32 v[22:23], v[30:31], v[22:23]
	v_pk_mul_f32 v[26:27], v[26:27], v[18:19]
	v_pk_mul_f32 v[18:19], v[24:25], v[16:17]
	v_pk_mul_f32 v[20:21], v[28:29], v[20:21]
	s_mov_b64 s[6:7], 0xdc000
	v_cvt_pk_bf16_f32 v16, v20, v21
	v_cvt_pk_bf16_f32 v17, v22, v23
	v_cvt_pk_bf16_f32 v18, v18, v19
	v_mul_f32_e32 v22, 0xbfb8aa3b, v12
	v_cvt_pk_bf16_f32 v19, v26, v27
	v_lshl_add_u64 v[20:21], v[142:143], 0, s[6:7]
	v_exp_f32_e32 v22, v22
	v_mul_f32_e32 v23, 0xbfb8aa3b, v8
	global_store_dwordx4 v[20:21], v[16:19], off sc0 sc1
	s_nop 1
	v_mul_f32_e32 v18, 0xbfb8aa3b, v13
	v_exp_f32_e32 v23, v23
	v_exp_f32_e32 v19, v18
	v_mul_f32_e32 v18, 0xbfb8aa3b, v9
	v_exp_f32_e32 v20, v18
	v_add_f32_e32 v16, 1.0, v22
	v_mul_f32_e32 v21, 0xbfb8aa3b, v10
	v_mul_f32_e32 v22, 0xbfb8aa3b, v15
	v_add_f32_e32 v17, 1.0, v23
	v_exp_f32_e32 v21, v21
	v_exp_f32_e32 v23, v22
	v_mul_f32_e32 v22, 0xbfb8aa3b, v11
	v_rcp_f32_e32 v18, v17
	v_add_f32_e32 v17, 1.0, v19
	v_add_f32_e32 v19, 1.0, v20
	v_mul_f32_e32 v20, 0xbfb8aa3b, v14
	v_exp_f32_e32 v24, v22
	v_exp_f32_e32 v20, v20
	v_add_f32_e32 v21, 1.0, v21
	v_rcp_f32_e32 v22, v21
	v_add_f32_e32 v21, 1.0, v23
	v_add_f32_e32 v23, 1.0, v24
	v_rcp_f32_e32 v16, v16
	v_rcp_f32_e32 v17, v17
	v_rcp_f32_e32 v19, v19
	v_add_f32_e32 v20, 1.0, v20
	v_rcp_f32_e32 v23, v23
	v_rcp_f32_e32 v20, v20
	v_rcp_f32_e32 v21, v21
	v_pk_mul_f32 v[12:13], v[12:13], v[16:17]
	v_pk_mul_f32 v[8:9], v[8:9], v[18:19]
	v_pk_mul_f32 v[10:11], v[10:11], v[22:23]
	v_pk_mul_f32 v[14:15], v[14:15], v[20:21]
	v_pk_mul_f32 v[4:5], v[12:13], v[4:5]
	v_pk_mul_f32 v[10:11], v[10:11], v[2:3]
	v_pk_mul_f32 v[2:3], v[8:9], v[0:1]
	s_mov_b64 s[6:7], 0xf2000
	v_pk_mul_f32 v[6:7], v[14:15], v[6:7]
	v_cvt_pk_bf16_f32 v0, v4, v5
	v_lshl_add_u64 v[4:5], v[142:143], 0, s[6:7]
	v_cvt_pk_bf16_f32 v1, v6, v7
	v_cvt_pk_bf16_f32 v2, v2, v3
	v_cvt_pk_bf16_f32 v3, v10, v11
	s_nop 0
	global_store_dwordx4 v[4:5], v[0:3], off sc0 sc1
	s_nop 1
	s_nop 0
	s_mov_b64 s[6:7], exec
	v_readlane_b32 s14, v254, 0
	v_readlane_b32 s15, v254, 1
	s_and_b64 s[14:15], s[6:7], s[14:15]
	s_mov_b64 exec, s[14:15]
	s_cbranch_execz .LBB0_2236
	s_mov_b64 s[14:15], exec
	v_mbcnt_lo_u32_b32 v0, s14, 0
	v_mbcnt_hi_u32_b32 v0, s15, v0
	v_cmp_eq_u32_e32 vcc, 0, v0
	s_and_b64 s[18:19], exec, vcc
	s_mov_b64 exec, s[18:19]
	s_cbranch_execz .LBB0_2236
	s_lshl_b32 s0, s0, 6
	s_ashr_i32 s1, s0, 31
	s_lshl_b64 s[0:1], s[0:1], 2
	v_readlane_b32 s10, v254, 20
	s_add_u32 s0, s10, s0
	v_readlane_b32 s10, v254, 2
	s_addc_u32 s1, s10, s1
	s_bcnt1_i32_b64 s10, s[14:15]
	v_mov_b32_e32 v0, s10
	s_sub_u32 s98, s0, 1
	s_subb_u32 s99, s1, 0

.Ldp_10_x:
	s_barrier
.LBB0_2240:
	v_readlane_b32 s0, v254, 62
	v_mov_b32_e32 v8, v153
	v_readlane_b32 s1, v254, 63
	s_and_b64 vcc, exec, s[0:1]
	v_readfirstlane_b32 s8, v8
	s_cbranch_vccnz .LBB0_2246
	s_ashr_i32 s0, s2, 31
	s_lshr_b32 s0, s0, 29
	s_add_i32 s7, s2, s0
	s_and_b32 s0, s7, -8
	s_sub_i32 s3, s2, s0
	s_cmp_gt_i32 s3, -1
	s_cbranch_scc0 .LBB0_2243
	s_lshl_b32 s6, s3, 5
	s_ashr_i32 s0, s7, 3
	s_cbranch_execz .LBB0_2244
	s_branch .LBB0_2245

.LBB0_2283:
	s_or_b32 s14, s43, 1
	v_add_u32_e32 v157, s71, v147
	s_lshl_b64 s[18:19], s[14:15], 7
	s_add_i32 s14, s43, 2
	ds_read_b128 v[142:145], v157
	ds_read_b128 v[158:161], v157 offset:1024
	ds_read_b128 v[162:165], v157 offset:2048
	ds_read_b128 v[166:169], v157 offset:3072
	v_add_u32_e32 v157, s72, v147
	s_lshl_b64 s[76:77], s[14:15], 7
	ds_read_b128 v[170:173], v157
	ds_read_b128 v[174:177], v157 offset:1024
	ds_read_b128 v[178:181], v157 offset:2048
	ds_read_b128 v[182:185], v157 offset:3072
	s_add_u32 s78, s60, s76
	s_addc_u32 s79, s61, s77
	s_and_b64 s[66:67], s[38:39], exec
	s_cselect_b32 s67, s57, s79
	s_cselect_b32 s66, s56, s78
	s_add_u32 s76, s62, s76
	s_addc_u32 s77, s63, s77
	s_and_b64 s[38:39], s[38:39], exec
	s_cselect_b32 s39, s59, s77
	s_cselect_b32 s38, s58, s76
	s_add_u32 s18, s41, s18
	s_addc_u32 s19, s42, s19
	v_lshl_add_u64 v[218:219], s[18:19], 0, v[128:129]
	s_add_i32 m0, s17, 0xc000
	ds_read_b128 v[186:189], v156
	ds_read_b128 v[190:193], v156 offset:1024
	ds_read_b128 v[194:197], v156 offset:2048
	ds_read_b128 v[198:201], v156 offset:3072
	ds_read_b128 v[202:205], v156 offset:4096
	ds_read_b128 v[206:209], v156 offset:5120
	ds_read_b128 v[210:213], v156 offset:6144
	ds_read_b128 v[214:217], v156 offset:7168
	global_load_lds_dwordx4 v[218:219], off
	v_lshl_add_u64 v[218:219], s[18:19], 0, v[132:133]
	s_add_i32 m0, s17, 0xe000
	s_nop 0
	global_load_lds_dwordx4 v[218:219], off
	s_cmp_eq_u32 s99, 0
	s_cbranch_scc1 .Ldpw_11_0a
	s_waitcnt vmcnt(16)
	s_branch .Ldpw_11_0b

.Ldpw_11_0b:
	s_waitcnt lgkmcnt(0)
	s_barrier
	s_setprio 1
	s_waitcnt lgkmcnt(0)
	v_mfma_f32_16x16x32_bf16 v[124:127], v[142:145], v[186:189], v[124:127]
	v_mfma_f32_16x16x32_bf16 v[120:123], v[162:165], v[186:189], v[120:123]
	v_mfma_f32_16x16x32_bf16 v[108:111], v[142:145], v[194:197], v[108:111]
	v_mfma_f32_16x16x32_bf16 v[104:107], v[162:165], v[194:197], v[104:107]
	v_mfma_f32_16x16x32_bf16 v[92:95], v[142:145], v[202:205], v[92:95]
	v_mfma_f32_16x16x32_bf16 v[88:91], v[162:165], v[202:205], v[88:91]
	v_mfma_f32_16x16x32_bf16 v[76:79], v[142:145], v[210:213], v[76:79]
	v_mfma_f32_16x16x32_bf16 v[72:75], v[162:165], v[210:213], v[72:75]
	v_mfma_f32_16x16x32_bf16 v[124:127], v[158:161], v[190:193], v[124:127]
	v_mfma_f32_16x16x32_bf16 v[120:123], v[166:169], v[190:193], v[120:123]
	v_mfma_f32_16x16x32_bf16 v[108:111], v[158:161], v[198:201], v[108:111]
	v_mfma_f32_16x16x32_bf16 v[104:107], v[166:169], v[198:201], v[104:107]
	v_mfma_f32_16x16x32_bf16 v[92:95], v[158:161], v[206:209], v[92:95]
	v_mfma_f32_16x16x32_bf16 v[88:91], v[166:169], v[206:209], v[88:91]
	v_mfma_f32_16x16x32_bf16 v[76:79], v[158:161], v[214:217], v[76:79]
	v_mfma_f32_16x16x32_bf16 v[72:75], v[166:169], v[214:217], v[72:75]
	s_setprio 0
	s_setprio 1
	v_mfma_f32_16x16x32_bf16 v[116:119], v[170:173], v[186:189], v[116:119]
	v_mfma_f32_16x16x32_bf16 v[112:115], v[178:181], v[186:189], v[112:115]
	v_mfma_f32_16x16x32_bf16 v[100:103], v[170:173], v[194:197], v[100:103]
	v_mfma_f32_16x16x32_bf16 v[96:99], v[178:181], v[194:197], v[96:99]
	v_mfma_f32_16x16x32_bf16 v[84:87], v[170:173], v[202:205], v[84:87]
	v_mfma_f32_16x16x32_bf16 v[80:83], v[178:181], v[202:205], v[80:83]
	v_mfma_f32_16x16x32_bf16 v[68:71], v[170:173], v[210:213], v[68:71]
	v_mfma_f32_16x16x32_bf16 v[64:67], v[178:181], v[210:213], v[64:67]
	v_mfma_f32_16x16x32_bf16 v[116:119], v[174:177], v[190:193], v[116:119]
	v_mfma_f32_16x16x32_bf16 v[112:115], v[182:185], v[190:193], v[112:115]
	v_mfma_f32_16x16x32_bf16 v[100:103], v[174:177], v[198:201], v[100:103]
	v_mfma_f32_16x16x32_bf16 v[96:99], v[182:185], v[198:201], v[96:99]
	v_mfma_f32_16x16x32_bf16 v[84:87], v[174:177], v[206:209], v[84:87]
	v_mfma_f32_16x16x32_bf16 v[80:83], v[182:185], v[206:209], v[80:83]
	v_mfma_f32_16x16x32_bf16 v[68:71], v[174:177], v[214:217], v[68:71]
	v_mfma_f32_16x16x32_bf16 v[64:67], v[182:185], v[214:217], v[64:67]
	s_setprio 0
	s_barrier
	s_add_i32 s18, s71, s16
	v_lshl_add_u64 v[218:219], s[38:39], 0, v[130:131]
	s_mov_b32 m0, s18
	ds_read_b128 v[186:189], v156 offset:16384
	ds_read_b128 v[190:193], v156 offset:17408
	ds_read_b128 v[194:197], v156 offset:18432
	ds_read_b128 v[198:201], v156 offset:19456
	ds_read_b128 v[202:205], v156 offset:20480
	ds_read_b128 v[206:209], v156 offset:21504
	ds_read_b128 v[210:213], v156 offset:22528
	ds_read_b128 v[214:217], v156 offset:23552
	global_load_lds_dwordx4 v[218:219], off
	s_add_i32 m0, s18, 0x2000
	s_add_u32 s18, s38, 0xb0000
	v_lshl_add_u64 v[220:221], s[38:39], 0, v[134:135]
	s_addc_u32 s19, s39, 0
	s_add_i32 s76, s72, s16
	global_load_lds_dwordx4 v[220:221], off
	v_lshl_add_u64 v[222:223], s[18:19], 0, v[130:131]
	s_mov_b32 m0, s76
	v_lshl_add_u64 v[224:225], s[66:67], 0, v[132:133]
	global_load_lds_dwordx4 v[222:223], off
	v_lshl_add_u64 v[222:223], s[18:19], 0, v[134:135]
	s_add_i32 m0, s76, 0x2000
	s_nop 0
	global_load_lds_dwordx4 v[222:223], off
	v_lshl_add_u64 v[222:223], s[66:67], 0, v[128:129]
	s_mov_b32 m0, s17
	s_nop 0
	global_load_lds_dwordx4 v[222:223], off
	s_mov_b32 m0, s27
	s_nop 0
	global_load_lds_dwordx4 v[224:225], off
	s_cmp_eq_u32 s99, 0
	s_cbranch_scc1 .Ldpw_11_1a
	s_waitcnt vmcnt(16)
	s_branch .Ldpw_11_1b

.Ldpw_11_1b:
	s_waitcnt lgkmcnt(0)
	s_barrier
	s_setprio 1
	s_waitcnt lgkmcnt(0)
	v_mfma_f32_16x16x32_bf16 v[60:63], v[142:145], v[186:189], v[60:63]
	v_mfma_f32_16x16x32_bf16 v[56:59], v[162:165], v[186:189], v[56:59]
	v_mfma_f32_16x16x32_bf16 v[44:47], v[142:145], v[194:197], v[44:47]
	v_mfma_f32_16x16x32_bf16 v[40:43], v[162:165], v[194:197], v[40:43]
	v_mfma_f32_16x16x32_bf16 v[28:31], v[142:145], v[202:205], v[28:31]
	v_mfma_f32_16x16x32_bf16 v[24:27], v[162:165], v[202:205], v[24:27]
	v_mfma_f32_16x16x32_bf16 v[12:15], v[142:145], v[210:213], v[12:15]
	v_mfma_f32_16x16x32_bf16 v[8:11], v[162:165], v[210:213], v[8:11]
	v_mfma_f32_16x16x32_bf16 v[60:63], v[158:161], v[190:193], v[60:63]
	v_mfma_f32_16x16x32_bf16 v[56:59], v[166:169], v[190:193], v[56:59]
	v_mfma_f32_16x16x32_bf16 v[44:47], v[158:161], v[198:201], v[44:47]
	v_mfma_f32_16x16x32_bf16 v[40:43], v[166:169], v[198:201], v[40:43]
	v_mfma_f32_16x16x32_bf16 v[28:31], v[158:161], v[206:209], v[28:31]
	v_mfma_f32_16x16x32_bf16 v[24:27], v[166:169], v[206:209], v[24:27]
	v_mfma_f32_16x16x32_bf16 v[12:15], v[158:161], v[214:217], v[12:15]
	v_mfma_f32_16x16x32_bf16 v[8:11], v[166:169], v[214:217], v[8:11]
	s_setprio 0
	s_setprio 1
	v_mfma_f32_16x16x32_bf16 v[52:55], v[170:173], v[186:189], v[52:55]
	v_mfma_f32_16x16x32_bf16 v[48:51], v[178:181], v[186:189], v[48:51]
	v_mfma_f32_16x16x32_bf16 v[36:39], v[170:173], v[194:197], v[36:39]
	v_mfma_f32_16x16x32_bf16 v[32:35], v[178:181], v[194:197], v[32:35]
	v_mfma_f32_16x16x32_bf16 v[20:23], v[170:173], v[202:205], v[20:23]
	v_mfma_f32_16x16x32_bf16 v[16:19], v[178:181], v[202:205], v[16:19]
	v_mfma_f32_16x16x32_bf16 v[4:7], v[170:173], v[210:213], v[4:7]
	v_mfma_f32_16x16x32_bf16 v[0:3], v[178:181], v[210:213], v[0:3]
	v_mfma_f32_16x16x32_bf16 v[52:55], v[174:177], v[190:193], v[52:55]
	v_mfma_f32_16x16x32_bf16 v[48:51], v[182:185], v[190:193], v[48:51]
	v_mfma_f32_16x16x32_bf16 v[36:39], v[174:177], v[198:201], v[36:39]
	v_mfma_f32_16x16x32_bf16 v[32:35], v[182:185], v[198:201], v[32:35]
	v_mfma_f32_16x16x32_bf16 v[20:23], v[174:177], v[206:209], v[20:23]
	v_mfma_f32_16x16x32_bf16 v[16:19], v[182:185], v[206:209], v[16:19]
	v_mfma_f32_16x16x32_bf16 v[4:7], v[174:177], v[214:217], v[4:7]
	v_mfma_f32_16x16x32_bf16 v[0:3], v[182:185], v[214:217], v[0:3]
	s_setprio 0
	s_barrier
	s_add_i32 s76, 0, 0x18000
	v_add_u32_e32 v157, s76, v147
	s_add_i32 s77, 0, 0x1c000
	ds_read_b128 v[142:145], v157
	ds_read_b128 v[158:161], v157 offset:1024
	ds_read_b128 v[162:165], v157 offset:2048
	ds_read_b128 v[166:169], v157 offset:3072
	v_add_u32_e32 v157, s77, v147
	ds_read_b128 v[170:173], v157
	ds_read_b128 v[174:177], v157 offset:1024
	ds_read_b128 v[178:181], v157 offset:2048
	ds_read_b128 v[182:185], v157 offset:3072
	s_add_u32 s18, s66, 0xb0000
	s_addc_u32 s19, s67, 0
	s_mov_b32 m0, s28
	v_lshl_add_u64 v[226:227], s[18:19], 0, v[128:129]
	ds_read_b128 v[186:189], v156 offset:32768
	ds_read_b128 v[190:193], v156 offset:33792
	ds_read_b128 v[194:197], v156 offset:34816
	ds_read_b128 v[198:201], v156 offset:35840
	ds_read_b128 v[202:205], v156 offset:36864
	ds_read_b128 v[206:209], v156 offset:37888
	ds_read_b128 v[210:213], v156 offset:38912
	ds_read_b128 v[214:217], v156 offset:39936
	global_load_lds_dwordx4 v[226:227], off
	v_lshl_add_u64 v[226:227], s[18:19], 0, v[132:133]
	s_mov_b32 m0, s29
	s_nop 0
	global_load_lds_dwordx4 v[226:227], off
	s_waitcnt vmcnt(8)
	s_cmp_eq_u32 s99, 0
	s_cbranch_scc1 .Ldp_11_l
	v_readlane_b32 s100, v0, 0
	s_mov_b64 exec, 1
	v_writelane_b32 v0, 1, 0
	s_nop 1
	global_atomic_add v0, v0, s[98:99]
	s_nop 1
	v_writelane_b32 v0, s100, 0
	s_mov_b64 exec, -1
	s_mov_b32 s99, 0
.Ldp_11_l:
	s_waitcnt lgkmcnt(0)
	s_barrier
	s_setprio 1
	s_waitcnt lgkmcnt(0)
	v_mfma_f32_16x16x32_bf16 v[124:127], v[142:145], v[186:189], v[124:127]
	v_mfma_f32_16x16x32_bf16 v[120:123], v[162:165], v[186:189], v[120:123]
	v_mfma_f32_16x16x32_bf16 v[108:111], v[142:145], v[194:197], v[108:111]
	v_mfma_f32_16x16x32_bf16 v[104:107], v[162:165], v[194:197], v[104:107]
	v_mfma_f32_16x16x32_bf16 v[92:95], v[142:145], v[202:205], v[92:95]
	v_mfma_f32_16x16x32_bf16 v[88:91], v[162:165], v[202:205], v[88:91]
	v_mfma_f32_16x16x32_bf16 v[76:79], v[142:145], v[210:213], v[76:79]
	v_mfma_f32_16x16x32_bf16 v[72:75], v[162:165], v[210:213], v[72:75]
	v_mfma_f32_16x16x32_bf16 v[124:127], v[158:161], v[190:193], v[124:127]
	v_mfma_f32_16x16x32_bf16 v[120:123], v[166:169], v[190:193], v[120:123]
	v_mfma_f32_16x16x32_bf16 v[108:111], v[158:161], v[198:201], v[108:111]
	v_mfma_f32_16x16x32_bf16 v[104:107], v[166:169], v[198:201], v[104:107]
	v_mfma_f32_16x16x32_bf16 v[92:95], v[158:161], v[206:209], v[92:95]
	v_mfma_f32_16x16x32_bf16 v[88:91], v[166:169], v[206:209], v[88:91]
	v_mfma_f32_16x16x32_bf16 v[76:79], v[158:161], v[214:217], v[76:79]
	v_mfma_f32_16x16x32_bf16 v[72:75], v[166:169], v[214:217], v[72:75]
	s_setprio 0
	s_setprio 1
	v_mfma_f32_16x16x32_bf16 v[116:119], v[170:173], v[186:189], v[116:119]
	v_mfma_f32_16x16x32_bf16 v[112:115], v[178:181], v[186:189], v[112:115]
	v_mfma_f32_16x16x32_bf16 v[100:103], v[170:173], v[194:197], v[100:103]
	v_mfma_f32_16x16x32_bf16 v[96:99], v[178:181], v[194:197], v[96:99]
	v_mfma_f32_16x16x32_bf16 v[84:87], v[170:173], v[202:205], v[84:87]
	v_mfma_f32_16x16x32_bf16 v[80:83], v[178:181], v[202:205], v[80:83]
	v_mfma_f32_16x16x32_bf16 v[68:71], v[170:173], v[210:213], v[68:71]
	v_mfma_f32_16x16x32_bf16 v[64:67], v[178:181], v[210:213], v[64:67]
	v_mfma_f32_16x16x32_bf16 v[116:119], v[174:177], v[190:193], v[116:119]
	v_mfma_f32_16x16x32_bf16 v[112:115], v[182:185], v[190:193], v[112:115]
	v_mfma_f32_16x16x32_bf16 v[100:103], v[174:177], v[198:201], v[100:103]
	v_mfma_f32_16x16x32_bf16 v[96:99], v[182:185], v[198:201], v[96:99]
	v_mfma_f32_16x16x32_bf16 v[84:87], v[174:177], v[206:209], v[84:87]
	v_mfma_f32_16x16x32_bf16 v[80:83], v[182:185], v[206:209], v[80:83]
	v_mfma_f32_16x16x32_bf16 v[68:71], v[174:177], v[214:217], v[68:71]
	v_mfma_f32_16x16x32_bf16 v[64:67], v[182:185], v[214:217], v[64:67]
	s_setprio 0
	s_barrier
	s_add_i32 s18, s76, s16
	v_lshl_add_u64 v[218:219], v[218:219], 0, s[34:35]
	s_mov_b32 m0, s18
	ds_read_b128 v[186:189], v156 offset:49152
	ds_read_b128 v[190:193], v156 offset:50176
	ds_read_b128 v[194:197], v156 offset:51200
	ds_read_b128 v[198:201], v156 offset:52224
	ds_read_b128 v[202:205], v156 offset:53248
	ds_read_b128 v[206:209], v156 offset:54272
	ds_read_b128 v[210:213], v156 offset:55296
	ds_read_b128 v[214:217], v156 offset:56320
	global_load_lds_dwordx4 v[218:219], off
	s_add_i32 m0, s18, 0x2000
	s_add_u32 s18, s38, 0xb0080
	v_lshl_add_u64 v[218:219], v[220:221], 0, s[34:35]
	s_addc_u32 s19, s39, 0
	s_add_i32 s38, s77, s16
	global_load_lds_dwordx4 v[218:219], off
	v_lshl_add_u64 v[218:219], s[18:19], 0, v[130:131]
	s_mov_b32 m0, s38
	s_nop 0
	global_load_lds_dwordx4 v[218:219], off
	v_lshl_add_u64 v[218:219], s[18:19], 0, v[134:135]
	s_add_i32 m0, s38, 0x2000
	s_nop 0
	global_load_lds_dwordx4 v[218:219], off
	v_lshl_add_u64 v[218:219], v[222:223], 0, s[34:35]
	s_mov_b32 m0, s49
	s_nop 0
	global_load_lds_dwordx4 v[218:219], off
	v_lshl_add_u64 v[218:219], v[224:225], 0, s[34:35]
	s_mov_b32 m0, s68
	s_nop 0
	global_load_lds_dwordx4 v[218:219], off
	s_waitcnt vmcnt(8)
	s_waitcnt lgkmcnt(0)
	s_barrier
	s_setprio 1
	s_waitcnt lgkmcnt(0)
	v_mfma_f32_16x16x32_bf16 v[60:63], v[142:145], v[186:189], v[60:63]
	v_mfma_f32_16x16x32_bf16 v[56:59], v[162:165], v[186:189], v[56:59]
	v_mfma_f32_16x16x32_bf16 v[44:47], v[142:145], v[194:197], v[44:47]
	v_mfma_f32_16x16x32_bf16 v[40:43], v[162:165], v[194:197], v[40:43]
	v_mfma_f32_16x16x32_bf16 v[28:31], v[142:145], v[202:205], v[28:31]
	v_mfma_f32_16x16x32_bf16 v[24:27], v[162:165], v[202:205], v[24:27]
	v_mfma_f32_16x16x32_bf16 v[12:15], v[142:145], v[210:213], v[12:15]
	v_mfma_f32_16x16x32_bf16 v[8:11], v[162:165], v[210:213], v[8:11]
	v_mfma_f32_16x16x32_bf16 v[60:63], v[158:161], v[190:193], v[60:63]
	v_mfma_f32_16x16x32_bf16 v[56:59], v[166:169], v[190:193], v[56:59]
	v_mfma_f32_16x16x32_bf16 v[44:47], v[158:161], v[198:201], v[44:47]
	v_mfma_f32_16x16x32_bf16 v[40:43], v[166:169], v[198:201], v[40:43]
	v_mfma_f32_16x16x32_bf16 v[28:31], v[158:161], v[206:209], v[28:31]
	v_mfma_f32_16x16x32_bf16 v[24:27], v[166:169], v[206:209], v[24:27]
	v_mfma_f32_16x16x32_bf16 v[12:15], v[158:161], v[214:217], v[12:15]
	v_mfma_f32_16x16x32_bf16 v[8:11], v[166:169], v[214:217], v[8:11]
	s_setprio 0
	s_setprio 1
	v_mfma_f32_16x16x32_bf16 v[52:55], v[170:173], v[186:189], v[52:55]
	v_mfma_f32_16x16x32_bf16 v[48:51], v[178:181], v[186:189], v[48:51]
	v_mfma_f32_16x16x32_bf16 v[36:39], v[170:173], v[194:197], v[36:39]
	v_mfma_f32_16x16x32_bf16 v[32:35], v[178:181], v[194:197], v[32:35]
	v_mfma_f32_16x16x32_bf16 v[20:23], v[170:173], v[202:205], v[20:23]
	v_mfma_f32_16x16x32_bf16 v[16:19], v[178:181], v[202:205], v[16:19]
	v_mfma_f32_16x16x32_bf16 v[4:7], v[170:173], v[210:213], v[4:7]
	v_mfma_f32_16x16x32_bf16 v[0:3], v[178:181], v[210:213], v[0:3]
	v_mfma_f32_16x16x32_bf16 v[52:55], v[174:177], v[190:193], v[52:55]
	v_mfma_f32_16x16x32_bf16 v[48:51], v[182:185], v[190:193], v[48:51]
	v_mfma_f32_16x16x32_bf16 v[36:39], v[174:177], v[198:201], v[36:39]
	v_mfma_f32_16x16x32_bf16 v[32:35], v[182:185], v[198:201], v[32:35]
	v_mfma_f32_16x16x32_bf16 v[20:23], v[174:177], v[206:209], v[20:23]
	v_mfma_f32_16x16x32_bf16 v[16:19], v[182:185], v[206:209], v[16:19]
	v_mfma_f32_16x16x32_bf16 v[4:7], v[174:177], v[214:217], v[4:7]
	v_mfma_f32_16x16x32_bf16 v[0:3], v[182:185], v[214:217], v[0:3]
	s_setprio 0
	s_barrier
	s_cmp_gt_u32 s43, 41
	s_mov_b32 s43, s14
	s_cbranch_scc1 .LBB0_2302

.LBB0_2320:
	s_or_b64 exec, exec, s[8:9]
	s_nop 0
	s_mov_b64 s[8:9], exec
	v_readlane_b32 s18, v254, 0
	v_readlane_b32 s19, v254, 1
	s_and_b64 s[18:19], s[8:9], s[18:19]
	s_mov_b64 exec, s[18:19]
	s_cbranch_execz .LBB0_2323
	s_mov_b64 s[38:39], exec
	v_mbcnt_lo_u32_b32 v0, s38, 0
	v_mbcnt_hi_u32_b32 v0, s39, v0
	v_cmp_eq_u32_e32 vcc, 0, v0
	s_and_b64 s[18:19], exec, vcc
	s_mov_b64 exec, s[18:19]
	s_cbranch_execz .LBB0_2323
	s_lshl_b32 s12, s12, 6
	s_ashr_i32 s13, s12, 31
	s_lshl_b64 s[12:13], s[12:13], 2
	s_add_u32 s12, s10, s12
	s_addc_u32 s13, s11, s13
	s_bcnt1_i32_b64 s14, s[38:39]
	v_mov_b32_e32 v0, s14
	s_sub_u32 s98, s12, 1
	s_subb_u32 s99, s13, 0

.Ldp_11_x:
	s_barrier
.LBB0_2327:
	v_readlane_b32 s6, v254, 44
	s_movk_i32 s14, 0x100
	v_readlane_b32 s7, v254, 45
	s_and_b64 vcc, exec, s[6:7]
	v_readfirstlane_b32 s30, v153
	s_cbranch_vccnz .LBB0_2329
	s_mul_hi_i32 s1, s2, 0x2e8ba2e9
	s_lshr_b32 s0, s1, 31
	s_ashr_i32 s1, s1, 3
	s_add_i32 s0, s1, s0
	s_add_i32 s16, s0, 64
	s_mul_i32 s0, s0, 44
	s_sub_i32 s17, s2, s0

.LBB0_2363:
	v_add_u32_e32 v141, s81, v138
	s_or_b32 s6, s70, 1
	s_add_i32 s70, s70, 2
	s_mov_b32 s71, s7
	ds_read_b128 v[142:145], v141
	ds_read_b128 v[156:159], v141 offset:1024
	ds_read_b128 v[160:163], v141 offset:2048
	ds_read_b128 v[164:167], v141 offset:3072
	v_add_u32_e32 v141, s82, v138
	s_lshl_b64 s[18:19], s[6:7], 7
	s_lshl_b64 s[48:49], s[70:71], 7
	ds_read_b128 v[168:171], v141
	ds_read_b128 v[172:175], v141 offset:1024
	ds_read_b128 v[176:179], v141 offset:2048
	ds_read_b128 v[180:183], v141 offset:3072
	s_add_u32 s6, s62, s48
	s_addc_u32 s43, s63, s49
	s_and_b64 s[72:73], s[38:39], exec
	s_cselect_b32 s73, s59, s43
	s_cselect_b32 s72, s58, s6
	s_add_u32 s6, s64, s48
	s_addc_u32 s43, s65, s49
	s_and_b64 s[38:39], s[38:39], exec
	s_cselect_b32 s39, s61, s43
	s_cselect_b32 s38, s60, s6
	s_add_u32 s18, s35, s18
	s_addc_u32 s19, s42, s19
	v_lshl_add_u64 v[146:147], s[18:19], 0, v[128:129]
	s_add_i32 m0, s29, 0xc000
	ds_read_b128 v[184:187], v140
	ds_read_b128 v[188:191], v140 offset:1024
	ds_read_b128 v[192:195], v140 offset:2048
	ds_read_b128 v[196:199], v140 offset:3072
	ds_read_b128 v[200:203], v140 offset:4096
	ds_read_b128 v[204:207], v140 offset:5120
	ds_read_b128 v[208:211], v140 offset:6144
	ds_read_b128 v[212:215], v140 offset:7168
	global_load_lds_dwordx4 v[146:147], off
	v_lshl_add_u64 v[146:147], s[18:19], 0, v[132:133]
	s_add_i32 m0, s29, 0xe000
	s_nop 0
	global_load_lds_dwordx4 v[146:147], off
	s_cmp_eq_u32 s99, 0
	s_cbranch_scc1 .Ldpw_12_0a
	s_waitcnt vmcnt(16)
	s_branch .Ldpw_12_0b

.Ldpw_12_0b:
	s_waitcnt lgkmcnt(0)
	s_barrier
	s_setprio 1
	s_waitcnt lgkmcnt(0)
	v_mfma_f32_16x16x32_bf16 v[120:123], v[142:145], v[184:187], v[120:123]
	v_mfma_f32_16x16x32_bf16 v[124:127], v[160:163], v[184:187], v[124:127]
	v_mfma_f32_16x16x32_bf16 v[108:111], v[142:145], v[192:195], v[108:111]
	v_mfma_f32_16x16x32_bf16 v[104:107], v[160:163], v[192:195], v[104:107]
	v_mfma_f32_16x16x32_bf16 v[92:95], v[142:145], v[200:203], v[92:95]
	v_mfma_f32_16x16x32_bf16 v[88:91], v[160:163], v[200:203], v[88:91]
	v_mfma_f32_16x16x32_bf16 v[76:79], v[142:145], v[208:211], v[76:79]
	v_mfma_f32_16x16x32_bf16 v[72:75], v[160:163], v[208:211], v[72:75]
	v_mfma_f32_16x16x32_bf16 v[120:123], v[156:159], v[188:191], v[120:123]
	v_mfma_f32_16x16x32_bf16 v[124:127], v[164:167], v[188:191], v[124:127]
	v_mfma_f32_16x16x32_bf16 v[108:111], v[156:159], v[196:199], v[108:111]
	v_mfma_f32_16x16x32_bf16 v[104:107], v[164:167], v[196:199], v[104:107]
	v_mfma_f32_16x16x32_bf16 v[92:95], v[156:159], v[204:207], v[92:95]
	v_mfma_f32_16x16x32_bf16 v[88:91], v[164:167], v[204:207], v[88:91]
	v_mfma_f32_16x16x32_bf16 v[76:79], v[156:159], v[212:215], v[76:79]
	v_mfma_f32_16x16x32_bf16 v[72:75], v[164:167], v[212:215], v[72:75]
	s_setprio 0
	s_setprio 1
	v_mfma_f32_16x16x32_bf16 v[116:119], v[168:171], v[184:187], v[116:119]
	v_mfma_f32_16x16x32_bf16 v[112:115], v[176:179], v[184:187], v[112:115]
	v_mfma_f32_16x16x32_bf16 v[100:103], v[168:171], v[192:195], v[100:103]
	v_mfma_f32_16x16x32_bf16 v[96:99], v[176:179], v[192:195], v[96:99]
	v_mfma_f32_16x16x32_bf16 v[84:87], v[168:171], v[200:203], v[84:87]
	v_mfma_f32_16x16x32_bf16 v[80:83], v[176:179], v[200:203], v[80:83]
	v_mfma_f32_16x16x32_bf16 v[68:71], v[168:171], v[208:211], v[68:71]
	v_mfma_f32_16x16x32_bf16 v[64:67], v[176:179], v[208:211], v[64:67]
	v_mfma_f32_16x16x32_bf16 v[116:119], v[172:175], v[188:191], v[116:119]
	v_mfma_f32_16x16x32_bf16 v[112:115], v[180:183], v[188:191], v[112:115]
	v_mfma_f32_16x16x32_bf16 v[100:103], v[172:175], v[196:199], v[100:103]
	v_mfma_f32_16x16x32_bf16 v[96:99], v[180:183], v[196:199], v[96:99]
	v_mfma_f32_16x16x32_bf16 v[84:87], v[172:175], v[204:207], v[84:87]
	v_mfma_f32_16x16x32_bf16 v[80:83], v[180:183], v[204:207], v[80:83]
	v_mfma_f32_16x16x32_bf16 v[68:71], v[172:175], v[212:215], v[68:71]
	v_mfma_f32_16x16x32_bf16 v[64:67], v[180:183], v[212:215], v[64:67]
	s_setprio 0
	s_barrier
	s_add_i32 s6, s81, s28
	v_lshl_add_u64 v[146:147], s[38:39], 0, v[130:131]
	s_mov_b32 m0, s6
	ds_read_b128 v[184:187], v140 offset:16384
	ds_read_b128 v[188:191], v140 offset:17408
	ds_read_b128 v[192:195], v140 offset:18432
	ds_read_b128 v[196:199], v140 offset:19456
	ds_read_b128 v[200:203], v140 offset:20480
	ds_read_b128 v[204:207], v140 offset:21504
	ds_read_b128 v[208:211], v140 offset:22528
	ds_read_b128 v[212:215], v140 offset:23552
	global_load_lds_dwordx4 v[146:147], off
	s_add_i32 m0, s6, 0x2000
	s_add_u32 s18, s38, 0xb0000
	v_lshl_add_u64 v[216:217], s[38:39], 0, v[134:135]
	s_addc_u32 s19, s39, 0
	s_add_i32 s6, s82, s28
	global_load_lds_dwordx4 v[216:217], off
	v_lshl_add_u64 v[218:219], s[18:19], 0, v[130:131]
	s_mov_b32 m0, s6
	v_lshl_add_u64 v[220:221], s[72:73], 0, v[132:133]
	global_load_lds_dwordx4 v[218:219], off
	v_lshl_add_u64 v[218:219], s[18:19], 0, v[134:135]
	s_add_i32 m0, s6, 0x2000
	s_nop 0
	global_load_lds_dwordx4 v[218:219], off
	v_lshl_add_u64 v[218:219], s[72:73], 0, v[128:129]
	s_mov_b32 m0, s29
	s_nop 0
	global_load_lds_dwordx4 v[218:219], off
	s_mov_b32 m0, s74
	s_nop 0
	global_load_lds_dwordx4 v[220:221], off
	s_cmp_eq_u32 s99, 0
	s_cbranch_scc1 .Ldpw_12_1a
	s_waitcnt vmcnt(16)
	s_branch .Ldpw_12_1b

.Ldpw_12_1b:
	s_waitcnt lgkmcnt(0)
	s_barrier
	s_setprio 1
	s_waitcnt lgkmcnt(0)
	v_mfma_f32_16x16x32_bf16 v[60:63], v[142:145], v[184:187], v[60:63]
	v_mfma_f32_16x16x32_bf16 v[56:59], v[160:163], v[184:187], v[56:59]
	v_mfma_f32_16x16x32_bf16 v[44:47], v[142:145], v[192:195], v[44:47]
	v_mfma_f32_16x16x32_bf16 v[40:43], v[160:163], v[192:195], v[40:43]
	v_mfma_f32_16x16x32_bf16 v[28:31], v[142:145], v[200:203], v[28:31]
	v_mfma_f32_16x16x32_bf16 v[24:27], v[160:163], v[200:203], v[24:27]
	v_mfma_f32_16x16x32_bf16 v[12:15], v[142:145], v[208:211], v[12:15]
	v_mfma_f32_16x16x32_bf16 v[8:11], v[160:163], v[208:211], v[8:11]
	v_mfma_f32_16x16x32_bf16 v[60:63], v[156:159], v[188:191], v[60:63]
	v_mfma_f32_16x16x32_bf16 v[56:59], v[164:167], v[188:191], v[56:59]
	v_mfma_f32_16x16x32_bf16 v[44:47], v[156:159], v[196:199], v[44:47]
	v_mfma_f32_16x16x32_bf16 v[40:43], v[164:167], v[196:199], v[40:43]
	v_mfma_f32_16x16x32_bf16 v[28:31], v[156:159], v[204:207], v[28:31]
	v_mfma_f32_16x16x32_bf16 v[24:27], v[164:167], v[204:207], v[24:27]
	v_mfma_f32_16x16x32_bf16 v[12:15], v[156:159], v[212:215], v[12:15]
	v_mfma_f32_16x16x32_bf16 v[8:11], v[164:167], v[212:215], v[8:11]
	s_setprio 0
	s_setprio 1
	v_mfma_f32_16x16x32_bf16 v[52:55], v[168:171], v[184:187], v[52:55]
	v_mfma_f32_16x16x32_bf16 v[48:51], v[176:179], v[184:187], v[48:51]
	v_mfma_f32_16x16x32_bf16 v[36:39], v[168:171], v[192:195], v[36:39]
	v_mfma_f32_16x16x32_bf16 v[32:35], v[176:179], v[192:195], v[32:35]
	v_mfma_f32_16x16x32_bf16 v[20:23], v[168:171], v[200:203], v[20:23]
	v_mfma_f32_16x16x32_bf16 v[16:19], v[176:179], v[200:203], v[16:19]
	v_mfma_f32_16x16x32_bf16 v[4:7], v[168:171], v[208:211], v[4:7]
	v_mfma_f32_16x16x32_bf16 v[0:3], v[176:179], v[208:211], v[0:3]
	v_mfma_f32_16x16x32_bf16 v[52:55], v[172:175], v[188:191], v[52:55]
	v_mfma_f32_16x16x32_bf16 v[48:51], v[180:183], v[188:191], v[48:51]
	v_mfma_f32_16x16x32_bf16 v[36:39], v[172:175], v[196:199], v[36:39]
	v_mfma_f32_16x16x32_bf16 v[32:35], v[180:183], v[196:199], v[32:35]
	v_mfma_f32_16x16x32_bf16 v[20:23], v[172:175], v[204:207], v[20:23]
	v_mfma_f32_16x16x32_bf16 v[16:19], v[180:183], v[204:207], v[16:19]
	v_mfma_f32_16x16x32_bf16 v[4:7], v[172:175], v[212:215], v[4:7]
	v_mfma_f32_16x16x32_bf16 v[0:3], v[180:183], v[212:215], v[0:3]
	s_setprio 0
	s_barrier
	s_add_i32 s6, 0, 0x18000
	v_add_u32_e32 v141, s6, v138
	s_add_i32 s43, 0, 0x1c000
	ds_read_b128 v[142:145], v141
	ds_read_b128 v[156:159], v141 offset:1024
	ds_read_b128 v[160:163], v141 offset:2048
	ds_read_b128 v[164:167], v141 offset:3072
	v_add_u32_e32 v141, s43, v138
	ds_read_b128 v[168:171], v141
	ds_read_b128 v[172:175], v141 offset:1024
	ds_read_b128 v[176:179], v141 offset:2048
	ds_read_b128 v[180:183], v141 offset:3072
	s_add_u32 s18, s72, 0xb0000
	s_addc_u32 s19, s73, 0
	s_mov_b32 m0, s75
	v_lshl_add_u64 v[222:223], s[18:19], 0, v[128:129]
	ds_read_b128 v[184:187], v140 offset:32768
	ds_read_b128 v[188:191], v140 offset:33792
	ds_read_b128 v[192:195], v140 offset:34816
	ds_read_b128 v[196:199], v140 offset:35840
	ds_read_b128 v[200:203], v140 offset:36864
	ds_read_b128 v[204:207], v140 offset:37888
	ds_read_b128 v[208:211], v140 offset:38912
	ds_read_b128 v[212:215], v140 offset:39936
	global_load_lds_dwordx4 v[222:223], off
	v_lshl_add_u64 v[222:223], s[18:19], 0, v[132:133]
	s_mov_b32 m0, s76
	s_nop 0
	global_load_lds_dwordx4 v[222:223], off
	s_waitcnt vmcnt(8)
	s_cmp_eq_u32 s99, 0
	s_cbranch_scc1 .Ldp_12_l
	v_readlane_b32 s100, v0, 0
	s_mov_b64 exec, 1
	v_writelane_b32 v0, 1, 0
	s_nop 1
	global_atomic_add v0, v0, s[98:99]
	s_nop 1
	v_writelane_b32 v0, s100, 0
	s_mov_b64 exec, -1
	s_mov_b32 s99, 0
.Ldp_12_l:
	s_waitcnt lgkmcnt(0)
	s_barrier
	s_setprio 1
	s_waitcnt lgkmcnt(0)
	v_mfma_f32_16x16x32_bf16 v[120:123], v[142:145], v[184:187], v[120:123]
	v_mfma_f32_16x16x32_bf16 v[124:127], v[160:163], v[184:187], v[124:127]
	v_mfma_f32_16x16x32_bf16 v[108:111], v[142:145], v[192:195], v[108:111]
	v_mfma_f32_16x16x32_bf16 v[104:107], v[160:163], v[192:195], v[104:107]
	v_mfma_f32_16x16x32_bf16 v[92:95], v[142:145], v[200:203], v[92:95]
	v_mfma_f32_16x16x32_bf16 v[88:91], v[160:163], v[200:203], v[88:91]
	v_mfma_f32_16x16x32_bf16 v[76:79], v[142:145], v[208:211], v[76:79]
	v_mfma_f32_16x16x32_bf16 v[72:75], v[160:163], v[208:211], v[72:75]
	v_mfma_f32_16x16x32_bf16 v[120:123], v[156:159], v[188:191], v[120:123]
	v_mfma_f32_16x16x32_bf16 v[124:127], v[164:167], v[188:191], v[124:127]
	v_mfma_f32_16x16x32_bf16 v[108:111], v[156:159], v[196:199], v[108:111]
	v_mfma_f32_16x16x32_bf16 v[104:107], v[164:167], v[196:199], v[104:107]
	v_mfma_f32_16x16x32_bf16 v[92:95], v[156:159], v[204:207], v[92:95]
	v_mfma_f32_16x16x32_bf16 v[88:91], v[164:167], v[204:207], v[88:91]
	v_mfma_f32_16x16x32_bf16 v[76:79], v[156:159], v[212:215], v[76:79]
	v_mfma_f32_16x16x32_bf16 v[72:75], v[164:167], v[212:215], v[72:75]
	s_setprio 0
	s_setprio 1
	v_mfma_f32_16x16x32_bf16 v[116:119], v[168:171], v[184:187], v[116:119]
	v_mfma_f32_16x16x32_bf16 v[112:115], v[176:179], v[184:187], v[112:115]
	v_mfma_f32_16x16x32_bf16 v[100:103], v[168:171], v[192:195], v[100:103]
	v_mfma_f32_16x16x32_bf16 v[96:99], v[176:179], v[192:195], v[96:99]
	v_mfma_f32_16x16x32_bf16 v[84:87], v[168:171], v[200:203], v[84:87]
	v_mfma_f32_16x16x32_bf16 v[80:83], v[176:179], v[200:203], v[80:83]
	v_mfma_f32_16x16x32_bf16 v[68:71], v[168:171], v[208:211], v[68:71]
	v_mfma_f32_16x16x32_bf16 v[64:67], v[176:179], v[208:211], v[64:67]
	v_mfma_f32_16x16x32_bf16 v[116:119], v[172:175], v[188:191], v[116:119]
	v_mfma_f32_16x16x32_bf16 v[112:115], v[180:183], v[188:191], v[112:115]
	v_mfma_f32_16x16x32_bf16 v[100:103], v[172:175], v[196:199], v[100:103]
	v_mfma_f32_16x16x32_bf16 v[96:99], v[180:183], v[196:199], v[96:99]
	v_mfma_f32_16x16x32_bf16 v[84:87], v[172:175], v[204:207], v[84:87]
	v_mfma_f32_16x16x32_bf16 v[80:83], v[180:183], v[204:207], v[80:83]
	v_mfma_f32_16x16x32_bf16 v[68:71], v[172:175], v[212:215], v[68:71]
	v_mfma_f32_16x16x32_bf16 v[64:67], v[180:183], v[212:215], v[64:67]
	s_setprio 0
	s_barrier
	s_add_i32 s6, s6, s28
	v_lshl_add_u64 v[146:147], v[146:147], 0, s[12:13]
	s_mov_b32 m0, s6
	ds_read_b128 v[184:187], v140 offset:49152
	ds_read_b128 v[188:191], v140 offset:50176
	ds_read_b128 v[192:195], v140 offset:51200
	ds_read_b128 v[196:199], v140 offset:52224
	ds_read_b128 v[200:203], v140 offset:53248
	ds_read_b128 v[204:207], v140 offset:54272
	ds_read_b128 v[208:211], v140 offset:55296
	ds_read_b128 v[212:215], v140 offset:56320
	global_load_lds_dwordx4 v[146:147], off
	s_add_i32 m0, s6, 0x2000
	s_add_u32 s18, s38, 0xb0080
	v_lshl_add_u64 v[146:147], v[216:217], 0, s[12:13]
	s_addc_u32 s19, s39, 0
	s_add_i32 s6, s43, s28
	global_load_lds_dwordx4 v[146:147], off
	v_lshl_add_u64 v[146:147], s[18:19], 0, v[130:131]
	s_mov_b32 m0, s6
	s_nop 0
	global_load_lds_dwordx4 v[146:147], off
	v_lshl_add_u64 v[146:147], s[18:19], 0, v[134:135]
	s_add_i32 m0, s6, 0x2000
	s_nop 0
	global_load_lds_dwordx4 v[146:147], off
	v_lshl_add_u64 v[146:147], v[218:219], 0, s[12:13]
	s_mov_b32 m0, s78
	s_nop 0
	global_load_lds_dwordx4 v[146:147], off
	v_lshl_add_u64 v[146:147], v[220:221], 0, s[12:13]
	s_mov_b32 m0, s79
	s_nop 0
	global_load_lds_dwordx4 v[146:147], off
	s_waitcnt vmcnt(8)
	s_waitcnt lgkmcnt(0)
	s_barrier
	s_setprio 1
	s_waitcnt lgkmcnt(0)
	v_mfma_f32_16x16x32_bf16 v[60:63], v[142:145], v[184:187], v[60:63]
	v_mfma_f32_16x16x32_bf16 v[56:59], v[160:163], v[184:187], v[56:59]
	v_mfma_f32_16x16x32_bf16 v[44:47], v[142:145], v[192:195], v[44:47]
	v_mfma_f32_16x16x32_bf16 v[40:43], v[160:163], v[192:195], v[40:43]
	v_mfma_f32_16x16x32_bf16 v[28:31], v[142:145], v[200:203], v[28:31]
	v_mfma_f32_16x16x32_bf16 v[24:27], v[160:163], v[200:203], v[24:27]
	v_mfma_f32_16x16x32_bf16 v[12:15], v[142:145], v[208:211], v[12:15]
	v_mfma_f32_16x16x32_bf16 v[8:11], v[160:163], v[208:211], v[8:11]
	v_mfma_f32_16x16x32_bf16 v[60:63], v[156:159], v[188:191], v[60:63]
	v_mfma_f32_16x16x32_bf16 v[56:59], v[164:167], v[188:191], v[56:59]
	v_mfma_f32_16x16x32_bf16 v[44:47], v[156:159], v[196:199], v[44:47]
	v_mfma_f32_16x16x32_bf16 v[40:43], v[164:167], v[196:199], v[40:43]
	v_mfma_f32_16x16x32_bf16 v[28:31], v[156:159], v[204:207], v[28:31]
	v_mfma_f32_16x16x32_bf16 v[24:27], v[164:167], v[204:207], v[24:27]
	v_mfma_f32_16x16x32_bf16 v[12:15], v[156:159], v[212:215], v[12:15]
	v_mfma_f32_16x16x32_bf16 v[8:11], v[164:167], v[212:215], v[8:11]
	s_setprio 0
	s_setprio 1
	v_mfma_f32_16x16x32_bf16 v[52:55], v[168:171], v[184:187], v[52:55]
	v_mfma_f32_16x16x32_bf16 v[48:51], v[176:179], v[184:187], v[48:51]
	v_mfma_f32_16x16x32_bf16 v[36:39], v[168:171], v[192:195], v[36:39]
	v_mfma_f32_16x16x32_bf16 v[32:35], v[176:179], v[192:195], v[32:35]
	v_mfma_f32_16x16x32_bf16 v[20:23], v[168:171], v[200:203], v[20:23]
	v_mfma_f32_16x16x32_bf16 v[16:19], v[176:179], v[200:203], v[16:19]
	v_mfma_f32_16x16x32_bf16 v[4:7], v[168:171], v[208:211], v[4:7]
	v_mfma_f32_16x16x32_bf16 v[0:3], v[176:179], v[208:211], v[0:3]
	v_mfma_f32_16x16x32_bf16 v[52:55], v[172:175], v[188:191], v[52:55]
	v_mfma_f32_16x16x32_bf16 v[48:51], v[180:183], v[188:191], v[48:51]
	v_mfma_f32_16x16x32_bf16 v[36:39], v[172:175], v[196:199], v[36:39]
	v_mfma_f32_16x16x32_bf16 v[32:35], v[180:183], v[196:199], v[32:35]
	v_mfma_f32_16x16x32_bf16 v[20:23], v[172:175], v[204:207], v[20:23]
	v_mfma_f32_16x16x32_bf16 v[16:19], v[180:183], v[204:207], v[16:19]
	v_mfma_f32_16x16x32_bf16 v[4:7], v[172:175], v[212:215], v[4:7]
	v_mfma_f32_16x16x32_bf16 v[0:3], v[180:183], v[212:215], v[0:3]
	s_setprio 0
	s_barrier
	s_cmp_ge_i32 s70, s77
	s_cbranch_scc1 .LBB0_2382

.LBB0_2384:
	s_mul_hi_i32 s6, s17, 0x2e8ba2e9
	s_lshr_b32 s18, s6, 31
	s_ashr_i32 s6, s6, 1
	s_add_i32 s6, s6, s18
	s_mul_i32 s18, s6, 11
	s_sub_i32 s17, s17, s18
	s_mul_i32 s18, s17, 0x300
	v_lshl_add_u32 v142, s16, 8, v139
	s_ashr_i32 s19, s18, 31
	v_ashrrev_i32_e32 v143, 31, v142
	v_lshl_add_u64 v[142:143], v[142:143], 0, s[18:19]
	v_readlane_b32 s18, v254, 51
	v_lshlrev_b64 v[142:143], 11, v[142:143]
	v_readlane_b32 s19, v254, 52
	s_mov_b32 s35, s7
	v_cvt_pk_bf16_f32 v120, v120, v121
	v_cvt_pk_bf16_f32 v121, v122, v123
	v_cvt_pk_bf16_f32 v122, v124, v125
	v_cvt_pk_bf16_f32 v123, v126, v127
	s_nop 0
	v_lshl_add_u64 v[142:143], s[18:19], 0, v[142:143]
	s_lshl_b32 s18, s6, 8
	s_ashr_i32 s19, s18, 31
	v_lshl_add_u64 v[142:143], s[18:19], 1, v[142:143]
	v_lshl_add_u64 v[142:143], v[142:143], 0, s[34:35]
	v_lshl_add_u64 v[142:143], v[142:143], 0, v[136:137]
	s_mov_b64 s[18:19], 0x100
	global_store_dwordx4 v[142:143], v[120:123], off sc0 sc1
	s_nop 1
	v_cvt_pk_bf16_f32 v116, v116, v117
	v_cvt_pk_bf16_f32 v117, v118, v119
	v_cvt_pk_bf16_f32 v118, v112, v113
	v_lshl_add_u64 v[112:113], v[142:143], 0, s[18:19]
	s_mov_b64 s[18:19], 0x8000
	v_cvt_pk_bf16_f32 v119, v114, v115
	s_nop 0
	global_store_dwordx4 v[112:113], v[116:119], off sc0 sc1
	s_nop 1
	v_lshl_add_u64 v[112:113], v[142:143], 0, s[18:19]
	s_mov_b64 s[18:19], 0x8100
	v_cvt_pk_bf16_f32 v108, v108, v109
	v_cvt_pk_bf16_f32 v109, v110, v111
	v_cvt_pk_bf16_f32 v110, v104, v105
	v_cvt_pk_bf16_f32 v111, v106, v107
	s_nop 0
	global_store_dwordx4 v[112:113], v[108:111], off sc0 sc1
	s_nop 1
	v_cvt_pk_bf16_f32 v100, v100, v101
	v_cvt_pk_bf16_f32 v101, v102, v103
	v_cvt_pk_bf16_f32 v102, v96, v97
	v_lshl_add_u64 v[96:97], v[142:143], 0, s[18:19]
	s_mov_b64 s[18:19], 0x10000
	v_cvt_pk_bf16_f32 v103, v98, v99
	s_nop 0
	global_store_dwordx4 v[96:97], v[100:103], off sc0 sc1
	s_nop 1
	v_lshl_add_u64 v[96:97], v[142:143], 0, s[18:19]
	s_mov_b64 s[18:19], 0x10100
	v_cvt_pk_bf16_f32 v92, v92, v93
	v_cvt_pk_bf16_f32 v93, v94, v95
	v_cvt_pk_bf16_f32 v94, v88, v89
	v_cvt_pk_bf16_f32 v95, v90, v91
	s_nop 0
	global_store_dwordx4 v[96:97], v[92:95], off sc0 sc1
	s_nop 1
	v_cvt_pk_bf16_f32 v84, v84, v85
	v_cvt_pk_bf16_f32 v85, v86, v87
	v_cvt_pk_bf16_f32 v86, v80, v81
	v_lshl_add_u64 v[80:81], v[142:143], 0, s[18:19]
	s_mov_b64 s[18:19], 0x18000
	v_cvt_pk_bf16_f32 v87, v82, v83
	s_nop 0
	global_store_dwordx4 v[80:81], v[84:87], off sc0 sc1
	s_nop 1
	v_lshl_add_u64 v[80:81], v[142:143], 0, s[18:19]
	s_mov_b64 s[18:19], 0x18100
	v_cvt_pk_bf16_f32 v76, v76, v77
	v_cvt_pk_bf16_f32 v77, v78, v79
	v_cvt_pk_bf16_f32 v78, v72, v73
	v_cvt_pk_bf16_f32 v79, v74, v75
	s_nop 0
	global_store_dwordx4 v[80:81], v[76:79], off sc0 sc1
	s_nop 1
	v_cvt_pk_bf16_f32 v68, v68, v69
	v_cvt_pk_bf16_f32 v69, v70, v71
	v_cvt_pk_bf16_f32 v70, v64, v65
	v_lshl_add_u64 v[64:65], v[142:143], 0, s[18:19]
	s_mov_b64 s[18:19], 0x40000
	v_cvt_pk_bf16_f32 v71, v66, v67
	s_nop 0
	global_store_dwordx4 v[64:65], v[68:71], off sc0 sc1
	s_nop 1
	v_lshl_add_u64 v[64:65], v[142:143], 0, s[18:19]
	s_mov_b64 s[18:19], 0x40100
	v_cvt_pk_bf16_f32 v60, v60, v61
	v_cvt_pk_bf16_f32 v61, v62, v63
	v_cvt_pk_bf16_f32 v62, v56, v57
	v_cvt_pk_bf16_f32 v63, v58, v59
	s_nop 0
	global_store_dwordx4 v[64:65], v[60:63], off sc0 sc1
	s_nop 1
	v_cvt_pk_bf16_f32 v52, v52, v53
	v_cvt_pk_bf16_f32 v53, v54, v55
	v_cvt_pk_bf16_f32 v54, v48, v49
	v_lshl_add_u64 v[48:49], v[142:143], 0, s[18:19]
	v_cvt_pk_bf16_f32 v55, v50, v51
	s_nop 0
	global_store_dwordx4 v[48:49], v[52:55], off sc0 sc1
	s_nop 1
	v_lshl_add_u64 v[48:49], v[142:143], 0, s[36:37]
	v_cvt_pk_bf16_f32 v44, v44, v45
	v_cvt_pk_bf16_f32 v45, v46, v47
	v_cvt_pk_bf16_f32 v46, v40, v41
	v_cvt_pk_bf16_f32 v47, v42, v43
	s_nop 0
	global_store_dwordx4 v[48:49], v[44:47], off sc0 sc1
	s_nop 1
	v_cvt_pk_bf16_f32 v36, v36, v37
	v_cvt_pk_bf16_f32 v37, v38, v39
	v_cvt_pk_bf16_f32 v38, v32, v33
	v_lshl_add_u64 v[32:33], v[142:143], 0, s[40:41]
	v_cvt_pk_bf16_f32 v39, v34, v35
	s_nop 0
	global_store_dwordx4 v[32:33], v[36:39], off sc0 sc1
	s_nop 1
	v_lshl_add_u64 v[32:33], v[142:143], 0, s[50:51]
	v_cvt_pk_bf16_f32 v28, v28, v29
	v_cvt_pk_bf16_f32 v29, v30, v31
	v_cvt_pk_bf16_f32 v30, v24, v25
	v_cvt_pk_bf16_f32 v31, v26, v27
	s_nop 0
	global_store_dwordx4 v[32:33], v[28:31], off sc0 sc1
	s_nop 1
	v_cvt_pk_bf16_f32 v20, v20, v21
	v_cvt_pk_bf16_f32 v21, v22, v23
	v_cvt_pk_bf16_f32 v22, v16, v17
	v_lshl_add_u64 v[16:17], v[142:143], 0, s[52:53]
	v_cvt_pk_bf16_f32 v23, v18, v19
	s_nop 0
	global_store_dwordx4 v[16:17], v[20:23], off sc0 sc1
	s_nop 1
	v_lshl_add_u64 v[16:17], v[142:143], 0, s[54:55]
	v_cvt_pk_bf16_f32 v12, v12, v13
	v_cvt_pk_bf16_f32 v13, v14, v15
	v_cvt_pk_bf16_f32 v14, v8, v9
	v_cvt_pk_bf16_f32 v15, v10, v11
	s_nop 0
	global_store_dwordx4 v[16:17], v[12:15], off sc0 sc1
	s_nop 1
	v_cvt_pk_bf16_f32 v4, v4, v5
	v_cvt_pk_bf16_f32 v5, v6, v7
	v_cvt_pk_bf16_f32 v6, v0, v1
	v_cvt_pk_bf16_f32 v7, v2, v3
	v_lshl_add_u64 v[0:1], v[142:143], 0, s[56:57]
	global_store_dwordx4 v[0:1], v[4:7], off sc0 sc1
	s_nop 1
	s_nop 0
	s_mov_b64 s[38:39], exec
	v_readlane_b32 s18, v254, 0
	v_readlane_b32 s19, v254, 1
	s_and_b64 s[18:19], s[38:39], s[18:19]
	s_mov_b64 exec, s[18:19]
	s_cbranch_execz .LBB0_2387
	s_mov_b64 s[48:49], exec
	v_mbcnt_lo_u32_b32 v0, s48, 0
	v_mbcnt_hi_u32_b32 v0, s49, v0
	v_cmp_eq_u32_e32 vcc, 0, v0
	s_and_b64 s[18:19], exec, vcc
	s_mov_b64 exec, s[18:19]
	s_cbranch_execz .LBB0_2387
	s_lshl_b32 s16, s16, 6
	s_ashr_i32 s17, s16, 31
	s_lshl_b64 s[16:17], s[16:17], 2
	s_add_u32 s16, s10, s16
	s_addc_u32 s17, s11, s17
	s_bcnt1_i32_b64 s6, s[48:49]
	v_mov_b32_e32 v0, s6
	s_sub_u32 s98, s16, 1
	s_subb_u32 s99, s17, 0

.Ldp_12_x:
	s_barrier
.LBB0_2391:
	v_readlane_b32 s48, v254, 4
	v_readlane_b32 s50, v254, 6
	v_ashrrev_i32_e32 v153, 31, v152
	v_readlane_b32 s51, v254, 7
	s_mov_b64 s[0:1], 0x1000
	v_readlane_b32 s55, v254, 11
	s_waitcnt lgkmcnt(0)
	v_lshl_add_u64 v[0:1], v[152:153], 4, s[50:51]
	v_lshl_add_u64 v[16:17], v[0:1], 0, s[0:1]
	v_add_co_u32_e32 v18, vcc, 0x1000, v0
	s_add_u32 s6, s24, 0x74600
	s_nop 0
	v_addc_co_u32_e32 v19, vcc, 0, v1, vcc
	global_load_dwordx4 v[0:3], v[16:17], off offset:1024
	global_load_dwordx4 v[4:7], v[16:17], off offset:2048
	global_load_dwordx4 v[8:11], v[18:19], off
	global_load_dwordx4 v[12:15], v[16:17], off offset:3072
	v_readlane_b32 s4, v254, 60
	v_readlane_b32 s54, v254, 10
	v_readlane_b32 s56, v254, 12
	v_readlane_b32 s57, v254, 13
	v_readlane_b32 s58, v254, 14
	v_readlane_b32 s59, v254, 15
	v_readlane_b32 s60, v254, 16
	v_readlane_b32 s61, v254, 17
	v_readlane_b32 s62, v254, 18
	v_readlane_b32 s63, v254, 19
	s_addc_u32 s7, s25, 0
	v_readlane_b32 s5, v254, 61
	v_lshlrev_b64 v[20:21], 3, v[152:153]
	s_add_i32 s55, 0, 0x20080
	s_mov_b32 s3, 0
	v_cmp_gt_i32_e64 s[0:1], 16, v152
	v_lshl_add_u64 v[16:17], v[152:153], 2, s[4:5]
	v_lshl_add_u64 v[18:19], s[20:21], 0, v[20:21]
	v_lshl_add_u64 v[20:21], s[24:25], 0, v[20:21]
	v_mov_b32_e32 v23, 0
	s_movk_i32 s33, 0x214
	s_movk_i32 s54, 0x200
	s_mov_b32 s56, 0xda00000
	s_mov_b32 s57, 0xdb80000
	s_mov_b32 s58, 0xdd00000
	s_mov_b32 s59, 0xde80000
	s_mov_b32 s60, 0xe000000
	s_mov_b32 s61, 0xe180000
	s_mov_b32 s62, 0xe300000
	s_mov_b32 s63, 0xe480000
	s_mov_b32 s64, 0xe600000
	s_mov_b32 s65, 0xe780000
	s_mov_b32 s66, 0xe900000
	v_mov_b32_e32 v122, 0x358637bd
	s_mov_b32 s67, 0x800000
	v_mov_b32_e32 v123, 0x160
	v_mov_b32_e32 v124, s55
	v_readlane_b32 s49, v254, 5
	v_readlane_b32 s52, v254, 8
	v_readlane_b32 s53, v254, 9
	s_branch .LBB0_2395

	.amdhsa_kernel _Z10fwd_kernel4Args
		.amdhsa_group_segment_fixed_size 0
		.amdhsa_private_segment_fixed_size 0
		.amdhsa_kernarg_size 472
		.amdhsa_user_sgpr_count 2
		.amdhsa_user_sgpr_dispatch_ptr 0
		.amdhsa_user_sgpr_queue_ptr 0
		.amdhsa_user_sgpr_kernarg_segment_ptr 1
		.amdhsa_user_sgpr_dispatch_id 0
		.amdhsa_user_sgpr_kernarg_preload_length 0
		.amdhsa_user_sgpr_kernarg_preload_offset 0
		.amdhsa_user_sgpr_private_segment_size 0
		.amdhsa_uses_dynamic_stack 0
		.amdhsa_enable_private_segment 0
		.amdhsa_system_sgpr_workgroup_id_x 1
		.amdhsa_system_sgpr_workgroup_id_y 0
		.amdhsa_system_sgpr_workgroup_id_z 0
		.amdhsa_system_sgpr_workgroup_info 0
		.amdhsa_system_vgpr_workitem_id 2
		.amdhsa_next_free_vgpr 256
		.amdhsa_next_free_sgpr 102
		.amdhsa_accum_offset 256
		.amdhsa_reserve_vcc 1
		.amdhsa_float_round_mode_32 0
		.amdhsa_float_round_mode_16_64 0
		.amdhsa_float_denorm_mode_32 3
		.amdhsa_float_denorm_mode_16_64 3
		.amdhsa_dx10_clamp 1
		.amdhsa_ieee_mode 1
		.amdhsa_fp16_overflow 0
		.amdhsa_tg_split 0
		.amdhsa_exception_fp_ieee_invalid_op 0
		.amdhsa_exception_fp_denorm_src 0
		.amdhsa_exception_fp_ieee_div_zero 0
		.amdhsa_exception_fp_ieee_overflow 0
		.amdhsa_exception_fp_ieee_underflow 0
		.amdhsa_exception_fp_ieee_inexact 0
		.amdhsa_exception_int_div_zero 0
	.end_amdhsa_kernel

amdhsa.kernels:
  - .agpr_count:     0
    .args:
      - .offset:         0
        .size:           216
        .value_kind:     by_value
      - .offset:         216
        .size:           4
        .value_kind:     hidden_block_count_x
      - .offset:         220
        .size:           4
        .value_kind:     hidden_block_count_y
      - .offset:         224
        .size:           4
        .value_kind:     hidden_block_count_z
      - .offset:         228
        .size:           2
        .value_kind:     hidden_group_size_x
      - .offset:         230
        .size:           2
        .value_kind:     hidden_group_size_y
      - .offset:         232
        .size:           2
        .value_kind:     hidden_group_size_z
      - .offset:         234
        .size:           2
        .value_kind:     hidden_remainder_x
      - .offset:         236
        .size:           2
        .value_kind:     hidden_remainder_y
      - .offset:         238
        .size:           2
        .value_kind:     hidden_remainder_z
      - .offset:         256
        .size:           8
        .value_kind:     hidden_global_offset_x
      - .offset:         264
        .size:           8
        .value_kind:     hidden_global_offset_y
      - .offset:         272
        .size:           8
        .value_kind:     hidden_global_offset_z
      - .offset:         280
        .size:           2
        .value_kind:     hidden_grid_dims
      - .offset:         304
        .size:           8
        .value_kind:     hidden_multigrid_sync_arg
      - .offset:         336
        .size:           4
        .value_kind:     hidden_dynamic_lds_size
    .group_segment_fixed_size: 0
    .kernarg_segment_align: 8
    .kernarg_segment_size: 472
    .language:       OpenCL C
    .language_version:
      - 2
      - 0
    .max_flat_workgroup_size: 512
    .name:           _Z10fwd_kernel4Args
    .private_segment_fixed_size: 0
    .sgpr_count:     108
    .sgpr_spill_count: 89
    .symbol:         _Z10fwd_kernel4Args.kd
    .uniform_work_group_size: 1
    .uses_dynamic_stack: false
    .vgpr_count:     256
    .vgpr_spill_count: 0
    .wavefront_size: 64
